# v37: v36 plus first K-loop trip peeled at 17 GEMM sites so accumulators start from SrcC=0 (removes the 64 zeroing moves per unit)
# speedup vs baseline: 1.0029x; 1.0029x over previous
.LBB0_277:
	s_ashr_i32 s23, s22, 31
	s_lshl_b64 s[0:1], s[22:23], 19
	v_cmp_lt_i64_e32 vcc, s[24:25], v[150:151]
	s_add_u32 s24, s5, s0
	s_addc_u32 s25, s38, s1
	s_and_b64 s[0:1], vcc, exec
	s_cselect_b32 s23, s25, s35
	s_cselect_b32 s56, s24, s34
	s_ashr_i32 s21, s20, 31
	s_lshl_b64 s[0:1], s[20:21], 19
	s_add_u32 s26, s39, s0
	s_addc_u32 s27, s40, s1
	s_and_b64 s[0:1], vcc, exec
	s_cselect_b32 s21, s27, s31
	s_cselect_b32 s57, s26, s30
	s_add_u32 s58, s30, 0x100
	s_addc_u32 s59, s31, 0
	s_add_u32 s30, s34, 0x40080
	s_addc_u32 s31, s35, 0
	s_mov_b32 s60, -2
	ds_read_b128 v[130:133], v158
	ds_read_b128 v[134:137], v158 offset:1024
	ds_read_b128 v[162:165], v158 offset:2048
	ds_read_b128 v[166:169], v158 offset:3072
	s_add_u32 s0, s30, 0xfffc0080
	s_addc_u32 s1, s31, -1
	s_cmp_eq_u32 s60, 12
	s_cselect_b32 s37, s23, s1
	s_cselect_b32 s36, s56, s0
	s_cselect_b32 s35, s21, s59
	s_cselect_b32 s34, s57, s58
	v_lshl_add_u64 v[154:155], s[30:31], 0, v[148:149]
	s_add_i32 m0, s29, 0xc000
	ds_read_b128 v[170:173], v159
	ds_read_b128 v[174:177], v159 offset:1024
	ds_read_b128 v[178:181], v159 offset:2048
	ds_read_b128 v[182:185], v159 offset:3072
	ds_read_b128 v[186:189], v159 offset:4096
	ds_read_b128 v[190:193], v159 offset:5120
	ds_read_b128 v[194:197], v159 offset:6144
	ds_read_b128 v[198:201], v159 offset:7168
	global_load_lds_dwordx4 v[154:155], off
	v_lshl_add_u64 v[154:155], s[30:31], 0, v[146:147]
	s_add_i32 m0, s29, 0xe000
	s_nop 0
	global_load_lds_dwordx4 v[154:155], off
	s_waitcnt lgkmcnt(8)
	s_waitcnt vmcnt(10)
	s_barrier
	s_waitcnt lgkmcnt(0)
	s_waitcnt lgkmcnt(0)
	v_mfma_f32_16x16x32_bf16 v[126:129], v[130:133], v[170:173], 0
	v_mfma_f32_16x16x32_bf16 v[122:125], v[162:165], v[170:173], 0
	v_mfma_f32_16x16x32_bf16 v[118:121], v[130:133], v[178:181], 0
	v_mfma_f32_16x16x32_bf16 v[110:113], v[162:165], v[178:181], 0
	v_mfma_f32_16x16x32_bf16 v[102:105], v[130:133], v[186:189], 0
	v_mfma_f32_16x16x32_bf16 v[94:97], v[162:165], v[186:189], 0
	v_mfma_f32_16x16x32_bf16 v[86:89], v[130:133], v[194:197], 0
	v_mfma_f32_16x16x32_bf16 v[78:81], v[162:165], v[194:197], 0
	v_mfma_f32_16x16x32_bf16 v[126:129], v[134:137], v[174:177], v[126:129]
	v_mfma_f32_16x16x32_bf16 v[122:125], v[166:169], v[174:177], v[122:125]
	v_mfma_f32_16x16x32_bf16 v[118:121], v[134:137], v[182:185], v[118:121]
	v_mfma_f32_16x16x32_bf16 v[110:113], v[166:169], v[182:185], v[110:113]
	v_mfma_f32_16x16x32_bf16 v[102:105], v[134:137], v[190:193], v[102:105]
	v_mfma_f32_16x16x32_bf16 v[94:97], v[166:169], v[190:193], v[94:97]
	v_mfma_f32_16x16x32_bf16 v[86:89], v[134:137], v[198:201], v[86:89]
	v_mfma_f32_16x16x32_bf16 v[78:81], v[166:169], v[198:201], v[78:81]
	s_barrier
	s_add_i32 s0, s52, s41
	v_lshl_add_u64 v[154:155], s[34:35], 0, v[142:143]
	s_mov_b32 m0, s0
	ds_read_b128 v[202:205], v160
	ds_read_b128 v[206:209], v160 offset:1024
	ds_read_b128 v[210:213], v160 offset:2048
	ds_read_b128 v[214:217], v160 offset:3072
	global_load_lds_dwordx4 v[154:155], off
	v_lshl_add_u64 v[218:219], s[34:35], 0, v[138:139]
	s_add_i32 m0, s0, 0x2000
	s_nop 0
	global_load_lds_dwordx4 v[218:219], off
	s_waitcnt vmcnt(10)
	s_barrier
	s_waitcnt lgkmcnt(0)
	s_waitcnt lgkmcnt(0)
	v_mfma_f32_16x16x32_bf16 v[114:117], v[202:205], v[170:173], 0
	v_mfma_f32_16x16x32_bf16 v[106:109], v[210:213], v[170:173], 0
	v_mfma_f32_16x16x32_bf16 v[98:101], v[202:205], v[178:181], 0
	v_mfma_f32_16x16x32_bf16 v[90:93], v[210:213], v[178:181], 0
	v_mfma_f32_16x16x32_bf16 v[82:85], v[202:205], v[186:189], 0
	v_mfma_f32_16x16x32_bf16 v[74:77], v[210:213], v[186:189], 0
	v_mfma_f32_16x16x32_bf16 v[70:73], v[202:205], v[194:197], 0
	v_mfma_f32_16x16x32_bf16 v[66:69], v[210:213], v[194:197], 0
	v_mfma_f32_16x16x32_bf16 v[114:117], v[206:209], v[174:177], v[114:117]
	v_mfma_f32_16x16x32_bf16 v[106:109], v[214:217], v[174:177], v[106:109]
	v_mfma_f32_16x16x32_bf16 v[98:101], v[206:209], v[182:185], v[98:101]
	v_mfma_f32_16x16x32_bf16 v[90:93], v[214:217], v[182:185], v[90:93]
	v_mfma_f32_16x16x32_bf16 v[82:85], v[206:209], v[190:193], v[82:85]
	v_mfma_f32_16x16x32_bf16 v[74:77], v[214:217], v[190:193], v[74:77]
	v_mfma_f32_16x16x32_bf16 v[70:73], v[206:209], v[198:201], v[70:73]
	v_mfma_f32_16x16x32_bf16 v[66:69], v[214:217], v[198:201], v[66:69]
	s_mov_b32 m0, s29
	v_lshl_add_u64 v[220:221], s[36:37], 0, v[144:145]
	s_barrier
	ds_read_b128 v[170:173], v159 offset:16384
	ds_read_b128 v[174:177], v159 offset:17408
	ds_read_b128 v[178:181], v159 offset:18432
	ds_read_b128 v[182:185], v159 offset:19456
	ds_read_b128 v[186:189], v159 offset:20480
	ds_read_b128 v[190:193], v159 offset:21504
	ds_read_b128 v[194:197], v159 offset:22528
	ds_read_b128 v[198:201], v159 offset:23552
	global_load_lds_dwordx4 v[220:221], off
	v_lshl_add_u64 v[222:223], s[36:37], 0, v[140:141]
	s_mov_b32 m0, s43
	s_nop 0
	global_load_lds_dwordx4 v[222:223], off
	s_waitcnt vmcnt(10)
	s_barrier
	s_waitcnt lgkmcnt(0)
	s_waitcnt lgkmcnt(0)
	v_mfma_f32_16x16x32_bf16 v[62:65], v[130:133], v[170:173], 0
	v_mfma_f32_16x16x32_bf16 v[58:61], v[162:165], v[170:173], 0
	v_mfma_f32_16x16x32_bf16 v[54:57], v[130:133], v[178:181], 0
	v_mfma_f32_16x16x32_bf16 v[46:49], v[162:165], v[178:181], 0
	v_mfma_f32_16x16x32_bf16 v[38:41], v[130:133], v[186:189], 0
	v_mfma_f32_16x16x32_bf16 v[30:33], v[162:165], v[186:189], 0
	v_mfma_f32_16x16x32_bf16 v[22:25], v[130:133], v[194:197], 0
	v_mfma_f32_16x16x32_bf16 v[14:17], v[162:165], v[194:197], 0
	v_mfma_f32_16x16x32_bf16 v[62:65], v[134:137], v[174:177], v[62:65]
	v_mfma_f32_16x16x32_bf16 v[58:61], v[166:169], v[174:177], v[58:61]
	v_mfma_f32_16x16x32_bf16 v[54:57], v[134:137], v[182:185], v[54:57]
	v_mfma_f32_16x16x32_bf16 v[46:49], v[166:169], v[182:185], v[46:49]
	v_mfma_f32_16x16x32_bf16 v[38:41], v[134:137], v[190:193], v[38:41]
	v_mfma_f32_16x16x32_bf16 v[30:33], v[166:169], v[190:193], v[30:33]
	v_mfma_f32_16x16x32_bf16 v[22:25], v[134:137], v[198:201], v[22:25]
	v_mfma_f32_16x16x32_bf16 v[14:17], v[166:169], v[198:201], v[14:17]
	s_barrier
	s_add_u32 s0, s34, 0x40000
	s_addc_u32 s1, s35, 0
	s_add_i32 s61, s53, s41
	v_lshl_add_u64 v[130:131], s[0:1], 0, v[142:143]
	s_mov_b32 m0, s61
	s_nop 0
	global_load_lds_dwordx4 v[130:131], off
	v_lshl_add_u64 v[130:131], s[0:1], 0, v[138:139]
	s_add_i32 m0, s61, 0x2000
	s_nop 0
	global_load_lds_dwordx4 v[130:131], off
	s_waitcnt vmcnt(10)
	s_barrier
	v_mfma_f32_16x16x32_bf16 v[50:53], v[202:205], v[170:173], 0
	v_mfma_f32_16x16x32_bf16 v[42:45], v[210:213], v[170:173], 0
	v_mfma_f32_16x16x32_bf16 v[34:37], v[202:205], v[178:181], 0
	v_mfma_f32_16x16x32_bf16 v[26:29], v[210:213], v[178:181], 0
	v_mfma_f32_16x16x32_bf16 v[18:21], v[202:205], v[186:189], 0
	v_mfma_f32_16x16x32_bf16 v[10:13], v[210:213], v[186:189], 0
	v_mfma_f32_16x16x32_bf16 v[6:9], v[202:205], v[194:197], 0
	v_mfma_f32_16x16x32_bf16 v[2:5], v[210:213], v[194:197], 0
	v_mfma_f32_16x16x32_bf16 v[50:53], v[206:209], v[174:177], v[50:53]
	v_mfma_f32_16x16x32_bf16 v[42:45], v[214:217], v[174:177], v[42:45]
	v_mfma_f32_16x16x32_bf16 v[34:37], v[206:209], v[182:185], v[34:37]
	v_mfma_f32_16x16x32_bf16 v[26:29], v[214:217], v[182:185], v[26:29]
	v_mfma_f32_16x16x32_bf16 v[18:21], v[206:209], v[190:193], v[18:21]
	v_mfma_f32_16x16x32_bf16 v[10:13], v[214:217], v[190:193], v[10:13]
	v_mfma_f32_16x16x32_bf16 v[6:9], v[206:209], v[198:201], v[6:9]
	v_mfma_f32_16x16x32_bf16 v[2:5], v[214:217], v[198:201], v[2:5]
	s_add_i32 s61, 0, 0x18000
	v_add_u32_e32 v166, s61, v157
	s_barrier
	ds_read_b128 v[130:133], v166
	ds_read_b128 v[134:137], v166 offset:1024
	ds_read_b128 v[162:165], v166 offset:2048
	ds_read_b128 v[166:169], v166 offset:3072
	s_add_u32 s0, s36, 0x40000
	s_addc_u32 s1, s37, 0
	s_mov_b32 m0, s44
	v_lshl_add_u64 v[202:203], s[0:1], 0, v[144:145]
	ds_read_b128 v[170:173], v159 offset:32768
	ds_read_b128 v[174:177], v159 offset:33792
	ds_read_b128 v[178:181], v159 offset:34816
	ds_read_b128 v[182:185], v159 offset:35840
	ds_read_b128 v[186:189], v159 offset:36864
	ds_read_b128 v[190:193], v159 offset:37888
	ds_read_b128 v[194:197], v159 offset:38912
	ds_read_b128 v[198:201], v159 offset:39936
	global_load_lds_dwordx4 v[202:203], off
	v_lshl_add_u64 v[202:203], s[0:1], 0, v[140:141]
	s_mov_b32 m0, s45
	s_nop 0
	global_load_lds_dwordx4 v[202:203], off
	s_waitcnt lgkmcnt(8)
	s_waitcnt vmcnt(10)
	s_barrier
	s_waitcnt lgkmcnt(0)
	s_waitcnt lgkmcnt(0)
	v_mfma_f32_16x16x32_bf16 v[126:129], v[130:133], v[170:173], v[126:129]
	v_mfma_f32_16x16x32_bf16 v[122:125], v[162:165], v[170:173], v[122:125]
	v_mfma_f32_16x16x32_bf16 v[118:121], v[130:133], v[178:181], v[118:121]
	v_mfma_f32_16x16x32_bf16 v[110:113], v[162:165], v[178:181], v[110:113]
	v_mfma_f32_16x16x32_bf16 v[102:105], v[130:133], v[186:189], v[102:105]
	v_mfma_f32_16x16x32_bf16 v[94:97], v[162:165], v[186:189], v[94:97]
	v_mfma_f32_16x16x32_bf16 v[86:89], v[130:133], v[194:197], v[86:89]
	v_mfma_f32_16x16x32_bf16 v[78:81], v[162:165], v[194:197], v[78:81]
	v_mfma_f32_16x16x32_bf16 v[126:129], v[134:137], v[174:177], v[126:129]
	v_mfma_f32_16x16x32_bf16 v[122:125], v[166:169], v[174:177], v[122:125]
	v_mfma_f32_16x16x32_bf16 v[118:121], v[134:137], v[182:185], v[118:121]
	v_mfma_f32_16x16x32_bf16 v[110:113], v[166:169], v[182:185], v[110:113]
	v_mfma_f32_16x16x32_bf16 v[102:105], v[134:137], v[190:193], v[102:105]
	v_mfma_f32_16x16x32_bf16 v[94:97], v[166:169], v[190:193], v[94:97]
	v_mfma_f32_16x16x32_bf16 v[86:89], v[134:137], v[198:201], v[86:89]
	v_mfma_f32_16x16x32_bf16 v[78:81], v[166:169], v[198:201], v[78:81]
	s_barrier
	s_add_i32 s36, 0, 0x1c000
	s_add_i32 s0, s61, s41
	v_add_u32_e32 v214, s36, v157
	v_lshl_add_u64 v[154:155], v[154:155], 0, s[16:17]
	s_mov_b32 m0, s0
	ds_read_b128 v[202:205], v214
	ds_read_b128 v[206:209], v214 offset:1024
	ds_read_b128 v[210:213], v214 offset:2048
	ds_read_b128 v[214:217], v214 offset:3072
	global_load_lds_dwordx4 v[154:155], off
	v_lshl_add_u64 v[154:155], v[218:219], 0, s[16:17]
	s_add_i32 m0, s0, 0x2000
	s_nop 0
	global_load_lds_dwordx4 v[154:155], off
	s_waitcnt vmcnt(10)
	s_barrier
	s_waitcnt lgkmcnt(0)
	s_waitcnt lgkmcnt(0)
	v_mfma_f32_16x16x32_bf16 v[114:117], v[202:205], v[170:173], v[114:117]
	v_mfma_f32_16x16x32_bf16 v[106:109], v[210:213], v[170:173], v[106:109]
	v_mfma_f32_16x16x32_bf16 v[98:101], v[202:205], v[178:181], v[98:101]
	v_mfma_f32_16x16x32_bf16 v[90:93], v[210:213], v[178:181], v[90:93]
	v_mfma_f32_16x16x32_bf16 v[82:85], v[202:205], v[186:189], v[82:85]
	v_mfma_f32_16x16x32_bf16 v[74:77], v[210:213], v[186:189], v[74:77]
	v_mfma_f32_16x16x32_bf16 v[70:73], v[202:205], v[194:197], v[70:73]
	v_mfma_f32_16x16x32_bf16 v[66:69], v[210:213], v[194:197], v[66:69]
	v_mfma_f32_16x16x32_bf16 v[114:117], v[206:209], v[174:177], v[114:117]
	v_mfma_f32_16x16x32_bf16 v[106:109], v[214:217], v[174:177], v[106:109]
	v_mfma_f32_16x16x32_bf16 v[98:101], v[206:209], v[182:185], v[98:101]
	v_mfma_f32_16x16x32_bf16 v[90:93], v[214:217], v[182:185], v[90:93]
	v_mfma_f32_16x16x32_bf16 v[82:85], v[206:209], v[190:193], v[82:85]
	v_mfma_f32_16x16x32_bf16 v[74:77], v[214:217], v[190:193], v[74:77]
	v_mfma_f32_16x16x32_bf16 v[70:73], v[206:209], v[198:201], v[70:73]
	v_mfma_f32_16x16x32_bf16 v[66:69], v[214:217], v[198:201], v[66:69]
	s_mov_b32 m0, s49
	v_lshl_add_u64 v[154:155], v[220:221], 0, s[16:17]
	s_barrier
	ds_read_b128 v[170:173], v159 offset:49152
	ds_read_b128 v[174:177], v159 offset:50176
	ds_read_b128 v[178:181], v159 offset:51200
	ds_read_b128 v[182:185], v159 offset:52224
	ds_read_b128 v[186:189], v159 offset:53248
	ds_read_b128 v[190:193], v159 offset:54272
	ds_read_b128 v[194:197], v159 offset:55296
	ds_read_b128 v[198:201], v159 offset:56320
	global_load_lds_dwordx4 v[154:155], off
	v_lshl_add_u64 v[154:155], v[222:223], 0, s[16:17]
	s_mov_b32 m0, s51
	s_nop 0
	global_load_lds_dwordx4 v[154:155], off
	s_waitcnt vmcnt(10)
	s_barrier
	s_waitcnt lgkmcnt(0)
	s_waitcnt lgkmcnt(0)
	v_mfma_f32_16x16x32_bf16 v[62:65], v[130:133], v[170:173], v[62:65]
	v_mfma_f32_16x16x32_bf16 v[58:61], v[162:165], v[170:173], v[58:61]
	v_mfma_f32_16x16x32_bf16 v[54:57], v[130:133], v[178:181], v[54:57]
	v_mfma_f32_16x16x32_bf16 v[46:49], v[162:165], v[178:181], v[46:49]
	v_mfma_f32_16x16x32_bf16 v[38:41], v[130:133], v[186:189], v[38:41]
	v_mfma_f32_16x16x32_bf16 v[30:33], v[162:165], v[186:189], v[30:33]
	v_mfma_f32_16x16x32_bf16 v[22:25], v[130:133], v[194:197], v[22:25]
	v_mfma_f32_16x16x32_bf16 v[14:17], v[162:165], v[194:197], v[14:17]
	v_mfma_f32_16x16x32_bf16 v[62:65], v[134:137], v[174:177], v[62:65]
	v_mfma_f32_16x16x32_bf16 v[58:61], v[166:169], v[174:177], v[58:61]
	v_mfma_f32_16x16x32_bf16 v[54:57], v[134:137], v[182:185], v[54:57]
	v_mfma_f32_16x16x32_bf16 v[46:49], v[166:169], v[182:185], v[46:49]
	v_mfma_f32_16x16x32_bf16 v[38:41], v[134:137], v[190:193], v[38:41]
	v_mfma_f32_16x16x32_bf16 v[30:33], v[166:169], v[190:193], v[30:33]
	v_mfma_f32_16x16x32_bf16 v[22:25], v[134:137], v[198:201], v[22:25]
	v_mfma_f32_16x16x32_bf16 v[14:17], v[166:169], v[198:201], v[14:17]
	s_barrier
	s_add_u32 s0, s34, 0x40080
	s_addc_u32 s1, s35, 0
	s_add_i32 s34, s36, s41
	v_lshl_add_u64 v[130:131], s[0:1], 0, v[142:143]
	s_mov_b32 m0, s34
	s_nop 0
	global_load_lds_dwordx4 v[130:131], off
	v_lshl_add_u64 v[130:131], s[0:1], 0, v[138:139]
	s_add_i32 m0, s34, 0x2000
	s_nop 0
	global_load_lds_dwordx4 v[130:131], off
	s_waitcnt vmcnt(10)
	s_barrier
	v_mfma_f32_16x16x32_bf16 v[50:53], v[202:205], v[170:173], v[50:53]
	v_mfma_f32_16x16x32_bf16 v[42:45], v[210:213], v[170:173], v[42:45]
	v_mfma_f32_16x16x32_bf16 v[34:37], v[202:205], v[178:181], v[34:37]
	v_mfma_f32_16x16x32_bf16 v[26:29], v[210:213], v[178:181], v[26:29]
	v_mfma_f32_16x16x32_bf16 v[18:21], v[202:205], v[186:189], v[18:21]
	v_mfma_f32_16x16x32_bf16 v[10:13], v[210:213], v[186:189], v[10:13]
	v_mfma_f32_16x16x32_bf16 v[6:9], v[202:205], v[194:197], v[6:9]
	v_mfma_f32_16x16x32_bf16 v[2:5], v[210:213], v[194:197], v[2:5]
	v_mfma_f32_16x16x32_bf16 v[50:53], v[206:209], v[174:177], v[50:53]
	v_mfma_f32_16x16x32_bf16 v[42:45], v[214:217], v[174:177], v[42:45]
	v_mfma_f32_16x16x32_bf16 v[34:37], v[206:209], v[182:185], v[34:37]
	v_mfma_f32_16x16x32_bf16 v[26:29], v[214:217], v[182:185], v[26:29]
	v_mfma_f32_16x16x32_bf16 v[18:21], v[206:209], v[190:193], v[18:21]
	v_mfma_f32_16x16x32_bf16 v[10:13], v[214:217], v[190:193], v[10:13]
	v_mfma_f32_16x16x32_bf16 v[6:9], v[206:209], v[198:201], v[6:9]
	v_mfma_f32_16x16x32_bf16 v[2:5], v[214:217], v[198:201], v[2:5]
	s_add_i32 s60, s60, 2
	s_add_u32 s58, s58, 0x100
	s_addc_u32 s59, s59, 0
	s_add_u32 s30, s30, 0x100
	s_addc_u32 s31, s31, 0
	s_cmp_gt_u32 s60, 13
	s_barrier
	s_cbranch_scc1 .Lpeel_exit_0

.Lpeel_exit_0:
	v_mov_b32_e32 v162, v1
	v_mov_b32_e32 v163, v156
	s_cmp_gt_i32 s55, 11
	s_mov_b64 s[30:31], -1
	s_cbranch_scc0 .LBB0_286
	s_cmp_eq_u32 s55, 12
	s_cselect_b64 s[0:1], -1, 0
	s_and_b64 s[0:1], s[0:1], s[18:19]
	v_cmp_gt_i32_e32 vcc, 2, v163
	s_and_b64 s[0:1], s[0:1], vcc
	s_and_saveexec_b64 s[30:31], s[0:1]
	s_cbranch_execz .LBB0_285
	v_lshlrev_b32_e32 v154, 3, v163
	s_andn2_b64 vcc, exec, s[12:13]
	v_ashrrev_i32_e32 v155, 31, v154
	s_cbranch_vccnz .LBB0_283
	v_lshl_add_u64 v[134:135], v[154:155], 2, s[8:9]
	global_load_dwordx4 v[130:133], v[134:135], off
	s_nop 0
	global_load_dwordx4 v[134:137], v[134:135], off offset:16
	s_branch .LBB0_284

.LBB0_433:
	s_add_i32 s55, s55, 1
	s_mov_b64 s[0:1], s[14:15]
	s_lshr_b32 s14, s55, 2
	s_mul_i32 s14, s14, s74
	s_mov_b64 s[36:37], s[34:35]
	s_mov_b32 s35, s56
	s_add_i32 s56, s14, s2
	s_cmpk_lt_i32 s56, 0x100
	s_cselect_b64 s[38:39], -1, 0
	s_cmpk_gt_i32 s56, 0xff
	s_mov_b32 s34, s57
	s_cselect_b64 s[30:31], -1, 0
	s_and_b32 s57, s55, 3
	s_and_b64 s[14:15], s[38:39], exec
	s_cselect_b32 s14, s56, s35
	s_cselect_b32 s34, s57, s34
	s_ashr_i32 s15, s14, 31
	s_lshl_b64 s[14:15], s[14:15], 19
	s_add_u32 s14, s20, s14
	s_addc_u32 s15, s21, s15
	s_and_b64 s[40:41], s[38:39], exec
	s_cselect_b32 s60, s15, s1
	s_cselect_b32 s61, s14, s0
	s_ashr_i32 s35, s34, 31
	s_lshl_b64 s[34:35], s[34:35], 19
	s_add_u32 s34, s8, s34
	s_addc_u32 s35, s9, s35
	s_and_b64 s[38:39], s[38:39], exec
	s_cselect_b32 s62, s35, s37
	s_cselect_b32 s63, s34, s36
	s_add_u32 s66, s36, 0x100
	s_addc_u32 s67, s37, 0
	s_add_u32 s36, s0, 0x40080
	s_addc_u32 s37, s1, 0
	s_mov_b32 s69, -2
	s_waitcnt vmcnt(0)
	ds_read_b128 v[146:149], v152
	ds_read_b128 v[156:159], v152 offset:1024
	ds_read_b128 v[160:163], v152 offset:2048
	ds_read_b128 v[164:167], v152 offset:3072
	s_add_u32 s0, s36, 0xfffc0080
	s_addc_u32 s1, s37, -1
	s_cmp_eq_u32 s69, 12
	s_cselect_b32 s41, s60, s1
	s_cselect_b32 s40, s61, s0
	s_cselect_b32 s39, s62, s67
	s_cselect_b32 s38, s63, s66
	s_mov_b32 m0, s50
	v_lshl_add_u64 v[200:201], s[36:37], 0, v[144:145]
	ds_read_b128 v[168:171], v153
	ds_read_b128 v[172:175], v153 offset:1024
	ds_read_b128 v[176:179], v153 offset:2048
	ds_read_b128 v[180:183], v153 offset:3072
	ds_read_b128 v[184:187], v153 offset:4096
	ds_read_b128 v[188:191], v153 offset:5120
	ds_read_b128 v[192:195], v153 offset:6144
	ds_read_b128 v[196:199], v153 offset:7168
	global_load_lds_dwordx4 v[200:201], off
	v_lshl_add_u64 v[200:201], s[36:37], 0, v[142:143]
	s_mov_b32 m0, s51
	s_nop 0
	global_load_lds_dwordx4 v[200:201], off
	s_waitcnt lgkmcnt(8)
	s_waitcnt vmcnt(10)
	s_barrier
	s_waitcnt lgkmcnt(0)
	s_waitcnt lgkmcnt(0)
	v_mfma_f32_16x16x32_bf16 v[126:129], v[146:149], v[168:171], 0
	v_mfma_f32_16x16x32_bf16 v[122:125], v[160:163], v[168:171], 0
	v_mfma_f32_16x16x32_bf16 v[114:117], v[146:149], v[176:179], 0
	v_mfma_f32_16x16x32_bf16 v[106:109], v[160:163], v[176:179], 0
	v_mfma_f32_16x16x32_bf16 v[98:101], v[146:149], v[184:187], 0
	v_mfma_f32_16x16x32_bf16 v[90:93], v[160:163], v[184:187], 0
	v_mfma_f32_16x16x32_bf16 v[82:85], v[146:149], v[192:195], 0
	v_mfma_f32_16x16x32_bf16 v[74:77], v[160:163], v[192:195], 0
	v_mfma_f32_16x16x32_bf16 v[126:129], v[156:159], v[172:175], v[126:129]
	v_mfma_f32_16x16x32_bf16 v[122:125], v[164:167], v[172:175], v[122:125]
	v_mfma_f32_16x16x32_bf16 v[114:117], v[156:159], v[180:183], v[114:117]
	v_mfma_f32_16x16x32_bf16 v[106:109], v[164:167], v[180:183], v[106:109]
	v_mfma_f32_16x16x32_bf16 v[98:101], v[156:159], v[188:191], v[98:101]
	v_mfma_f32_16x16x32_bf16 v[90:93], v[164:167], v[188:191], v[90:93]
	v_mfma_f32_16x16x32_bf16 v[82:85], v[156:159], v[196:199], v[82:85]
	v_mfma_f32_16x16x32_bf16 v[74:77], v[164:167], v[196:199], v[74:77]
	s_barrier
	s_mov_b32 m0, s52
	v_lshl_add_u64 v[216:217], s[38:39], 0, v[138:139]
	ds_read_b128 v[200:203], v154
	ds_read_b128 v[204:207], v154 offset:1024
	ds_read_b128 v[208:211], v154 offset:2048
	ds_read_b128 v[212:215], v154 offset:3072
	global_load_lds_dwordx4 v[216:217], off
	v_lshl_add_u64 v[218:219], s[38:39], 0, v[134:135]
	s_mov_b32 m0, s53
	s_nop 0
	global_load_lds_dwordx4 v[218:219], off
	s_waitcnt vmcnt(10)
	s_barrier
	s_waitcnt lgkmcnt(0)
	s_waitcnt lgkmcnt(0)
	v_mfma_f32_16x16x32_bf16 v[118:121], v[200:203], v[168:171], 0
	v_mfma_f32_16x16x32_bf16 v[110:113], v[208:211], v[168:171], 0
	v_mfma_f32_16x16x32_bf16 v[102:105], v[200:203], v[176:179], 0
	v_mfma_f32_16x16x32_bf16 v[94:97], v[208:211], v[176:179], 0
	v_mfma_f32_16x16x32_bf16 v[86:89], v[200:203], v[184:187], 0
	v_mfma_f32_16x16x32_bf16 v[78:81], v[208:211], v[184:187], 0
	v_mfma_f32_16x16x32_bf16 v[70:73], v[200:203], v[192:195], 0
	v_mfma_f32_16x16x32_bf16 v[66:69], v[208:211], v[192:195], 0
	v_mfma_f32_16x16x32_bf16 v[118:121], v[204:207], v[172:175], v[118:121]
	v_mfma_f32_16x16x32_bf16 v[110:113], v[212:215], v[172:175], v[110:113]
	v_mfma_f32_16x16x32_bf16 v[102:105], v[204:207], v[180:183], v[102:105]
	v_mfma_f32_16x16x32_bf16 v[94:97], v[212:215], v[180:183], v[94:97]
	v_mfma_f32_16x16x32_bf16 v[86:89], v[204:207], v[188:191], v[86:89]
	v_mfma_f32_16x16x32_bf16 v[78:81], v[212:215], v[188:191], v[78:81]
	v_mfma_f32_16x16x32_bf16 v[70:73], v[204:207], v[196:199], v[70:73]
	v_mfma_f32_16x16x32_bf16 v[66:69], v[212:215], v[196:199], v[66:69]
	s_mov_b32 m0, s6
	v_lshl_add_u64 v[220:221], s[40:41], 0, v[140:141]
	s_barrier
	ds_read_b128 v[168:171], v153 offset:16384
	ds_read_b128 v[172:175], v153 offset:17408
	ds_read_b128 v[176:179], v153 offset:18432
	ds_read_b128 v[180:183], v153 offset:19456
	ds_read_b128 v[184:187], v153 offset:20480
	ds_read_b128 v[188:191], v153 offset:21504
	ds_read_b128 v[192:195], v153 offset:22528
	ds_read_b128 v[196:199], v153 offset:23552
	global_load_lds_dwordx4 v[220:221], off
	v_lshl_add_u64 v[222:223], s[40:41], 0, v[136:137]
	s_mov_b32 m0, s7
	s_nop 0
	global_load_lds_dwordx4 v[222:223], off
	s_waitcnt vmcnt(10)
	s_barrier
	s_waitcnt lgkmcnt(0)
	s_waitcnt lgkmcnt(0)
	v_mfma_f32_16x16x32_bf16 v[62:65], v[146:149], v[168:171], 0
	v_mfma_f32_16x16x32_bf16 v[58:61], v[160:163], v[168:171], 0
	v_mfma_f32_16x16x32_bf16 v[50:53], v[146:149], v[176:179], 0
	v_mfma_f32_16x16x32_bf16 v[42:45], v[160:163], v[176:179], 0
	v_mfma_f32_16x16x32_bf16 v[34:37], v[146:149], v[184:187], 0
	v_mfma_f32_16x16x32_bf16 v[26:29], v[160:163], v[184:187], 0
	v_mfma_f32_16x16x32_bf16 v[18:21], v[146:149], v[192:195], 0
	v_mfma_f32_16x16x32_bf16 v[10:13], v[160:163], v[192:195], 0
	v_mfma_f32_16x16x32_bf16 v[62:65], v[156:159], v[172:175], v[62:65]
	v_mfma_f32_16x16x32_bf16 v[58:61], v[164:167], v[172:175], v[58:61]
	v_mfma_f32_16x16x32_bf16 v[50:53], v[156:159], v[180:183], v[50:53]
	v_mfma_f32_16x16x32_bf16 v[42:45], v[164:167], v[180:183], v[42:45]
	v_mfma_f32_16x16x32_bf16 v[34:37], v[156:159], v[188:191], v[34:37]
	v_mfma_f32_16x16x32_bf16 v[26:29], v[164:167], v[188:191], v[26:29]
	v_mfma_f32_16x16x32_bf16 v[18:21], v[156:159], v[196:199], v[18:21]
	v_mfma_f32_16x16x32_bf16 v[10:13], v[164:167], v[196:199], v[10:13]
	s_barrier
	s_add_u32 s0, s38, 0x40000
	s_addc_u32 s1, s39, 0
	s_mov_b32 m0, s54
	v_lshl_add_u64 v[146:147], s[0:1], 0, v[138:139]
	global_load_lds_dwordx4 v[146:147], off
	v_lshl_add_u64 v[146:147], s[0:1], 0, v[134:135]
	s_add_i32 m0, s54, 0x2000
	s_nop 0
	global_load_lds_dwordx4 v[146:147], off
	s_waitcnt vmcnt(10)
	s_barrier
	v_mfma_f32_16x16x32_bf16 v[54:57], v[200:203], v[168:171], 0
	v_mfma_f32_16x16x32_bf16 v[46:49], v[208:211], v[168:171], 0
	v_mfma_f32_16x16x32_bf16 v[38:41], v[200:203], v[176:179], 0
	v_mfma_f32_16x16x32_bf16 v[30:33], v[208:211], v[176:179], 0
	v_mfma_f32_16x16x32_bf16 v[22:25], v[200:203], v[184:187], 0
	v_mfma_f32_16x16x32_bf16 v[14:17], v[208:211], v[184:187], 0
	v_mfma_f32_16x16x32_bf16 v[6:9], v[200:203], v[192:195], 0
	v_mfma_f32_16x16x32_bf16 v[2:5], v[208:211], v[192:195], 0
	v_mfma_f32_16x16x32_bf16 v[54:57], v[204:207], v[172:175], v[54:57]
	v_mfma_f32_16x16x32_bf16 v[46:49], v[212:215], v[172:175], v[46:49]
	v_mfma_f32_16x16x32_bf16 v[38:41], v[204:207], v[180:183], v[38:41]
	v_mfma_f32_16x16x32_bf16 v[30:33], v[212:215], v[180:183], v[30:33]
	v_mfma_f32_16x16x32_bf16 v[22:25], v[204:207], v[188:191], v[22:25]
	v_mfma_f32_16x16x32_bf16 v[14:17], v[212:215], v[188:191], v[14:17]
	v_mfma_f32_16x16x32_bf16 v[6:9], v[204:207], v[196:199], v[6:9]
	v_mfma_f32_16x16x32_bf16 v[2:5], v[212:215], v[196:199], v[2:5]
	s_add_i32 s70, 0, 0x18000
	v_add_u32_e32 v155, s70, v151
	s_barrier
	ds_read_b128 v[146:149], v155
	ds_read_b128 v[156:159], v155 offset:1024
	ds_read_b128 v[160:163], v155 offset:2048
	ds_read_b128 v[164:167], v155 offset:3072
	s_add_u32 s0, s40, 0x40000
	s_addc_u32 s1, s41, 0
	s_mov_b32 m0, s29
	v_lshl_add_u64 v[200:201], s[0:1], 0, v[140:141]
	ds_read_b128 v[168:171], v153 offset:32768
	ds_read_b128 v[172:175], v153 offset:33792
	ds_read_b128 v[176:179], v153 offset:34816
	ds_read_b128 v[180:183], v153 offset:35840
	ds_read_b128 v[184:187], v153 offset:36864
	ds_read_b128 v[188:191], v153 offset:37888
	ds_read_b128 v[192:195], v153 offset:38912
	ds_read_b128 v[196:199], v153 offset:39936
	global_load_lds_dwordx4 v[200:201], off
	v_lshl_add_u64 v[200:201], s[0:1], 0, v[136:137]
	s_mov_b32 m0, s42
	s_nop 0
	global_load_lds_dwordx4 v[200:201], off
	s_waitcnt lgkmcnt(8)
	s_waitcnt vmcnt(10)
	s_barrier
	s_waitcnt lgkmcnt(0)
	s_waitcnt lgkmcnt(0)
	v_mfma_f32_16x16x32_bf16 v[126:129], v[146:149], v[168:171], v[126:129]
	v_mfma_f32_16x16x32_bf16 v[122:125], v[160:163], v[168:171], v[122:125]
	v_mfma_f32_16x16x32_bf16 v[114:117], v[146:149], v[176:179], v[114:117]
	v_mfma_f32_16x16x32_bf16 v[106:109], v[160:163], v[176:179], v[106:109]
	v_mfma_f32_16x16x32_bf16 v[98:101], v[146:149], v[184:187], v[98:101]
	v_mfma_f32_16x16x32_bf16 v[90:93], v[160:163], v[184:187], v[90:93]
	v_mfma_f32_16x16x32_bf16 v[82:85], v[146:149], v[192:195], v[82:85]
	v_mfma_f32_16x16x32_bf16 v[74:77], v[160:163], v[192:195], v[74:77]
	v_mfma_f32_16x16x32_bf16 v[126:129], v[156:159], v[172:175], v[126:129]
	v_mfma_f32_16x16x32_bf16 v[122:125], v[164:167], v[172:175], v[122:125]
	v_mfma_f32_16x16x32_bf16 v[114:117], v[156:159], v[180:183], v[114:117]
	v_mfma_f32_16x16x32_bf16 v[106:109], v[164:167], v[180:183], v[106:109]
	v_mfma_f32_16x16x32_bf16 v[98:101], v[156:159], v[188:191], v[98:101]
	v_mfma_f32_16x16x32_bf16 v[90:93], v[164:167], v[188:191], v[90:93]
	v_mfma_f32_16x16x32_bf16 v[82:85], v[156:159], v[196:199], v[82:85]
	v_mfma_f32_16x16x32_bf16 v[74:77], v[164:167], v[196:199], v[74:77]
	s_barrier
	s_add_i32 s40, 0, 0x1c000
	s_add_i32 s0, s70, s5
	v_add_u32_e32 v155, s40, v151
	v_lshl_add_u64 v[216:217], v[216:217], 0, s[26:27]
	s_mov_b32 m0, s0
	ds_read_b128 v[200:203], v155
	ds_read_b128 v[204:207], v155 offset:1024
	ds_read_b128 v[208:211], v155 offset:2048
	ds_read_b128 v[212:215], v155 offset:3072
	global_load_lds_dwordx4 v[216:217], off
	v_lshl_add_u64 v[216:217], v[218:219], 0, s[26:27]
	s_add_i32 m0, s0, 0x2000
	s_nop 0
	global_load_lds_dwordx4 v[216:217], off
	s_waitcnt vmcnt(10)
	s_barrier
	s_waitcnt lgkmcnt(0)
	s_waitcnt lgkmcnt(0)
	v_mfma_f32_16x16x32_bf16 v[118:121], v[200:203], v[168:171], v[118:121]
	v_mfma_f32_16x16x32_bf16 v[110:113], v[208:211], v[168:171], v[110:113]
	v_mfma_f32_16x16x32_bf16 v[102:105], v[200:203], v[176:179], v[102:105]
	v_mfma_f32_16x16x32_bf16 v[94:97], v[208:211], v[176:179], v[94:97]
	v_mfma_f32_16x16x32_bf16 v[86:89], v[200:203], v[184:187], v[86:89]
	v_mfma_f32_16x16x32_bf16 v[78:81], v[208:211], v[184:187], v[78:81]
	v_mfma_f32_16x16x32_bf16 v[70:73], v[200:203], v[192:195], v[70:73]
	v_mfma_f32_16x16x32_bf16 v[66:69], v[208:211], v[192:195], v[66:69]
	v_mfma_f32_16x16x32_bf16 v[118:121], v[204:207], v[172:175], v[118:121]
	v_mfma_f32_16x16x32_bf16 v[110:113], v[212:215], v[172:175], v[110:113]
	v_mfma_f32_16x16x32_bf16 v[102:105], v[204:207], v[180:183], v[102:105]
	v_mfma_f32_16x16x32_bf16 v[94:97], v[212:215], v[180:183], v[94:97]
	v_mfma_f32_16x16x32_bf16 v[86:89], v[204:207], v[188:191], v[86:89]
	v_mfma_f32_16x16x32_bf16 v[78:81], v[212:215], v[188:191], v[78:81]
	v_mfma_f32_16x16x32_bf16 v[70:73], v[204:207], v[196:199], v[70:73]
	v_mfma_f32_16x16x32_bf16 v[66:69], v[212:215], v[196:199], v[66:69]
	s_mov_b32 m0, s46
	v_lshl_add_u64 v[216:217], v[220:221], 0, s[26:27]
	s_barrier
	ds_read_b128 v[168:171], v153 offset:49152
	ds_read_b128 v[172:175], v153 offset:50176
	ds_read_b128 v[176:179], v153 offset:51200
	ds_read_b128 v[180:183], v153 offset:52224
	ds_read_b128 v[184:187], v153 offset:53248
	ds_read_b128 v[188:191], v153 offset:54272
	ds_read_b128 v[192:195], v153 offset:55296
	ds_read_b128 v[196:199], v153 offset:56320
	global_load_lds_dwordx4 v[216:217], off
	v_lshl_add_u64 v[216:217], v[222:223], 0, s[26:27]
	s_mov_b32 m0, s47
	s_nop 0
	global_load_lds_dwordx4 v[216:217], off
	s_waitcnt vmcnt(10)
	s_barrier
	s_waitcnt lgkmcnt(0)
	s_waitcnt lgkmcnt(0)
	v_mfma_f32_16x16x32_bf16 v[62:65], v[146:149], v[168:171], v[62:65]
	v_mfma_f32_16x16x32_bf16 v[58:61], v[160:163], v[168:171], v[58:61]
	v_mfma_f32_16x16x32_bf16 v[50:53], v[146:149], v[176:179], v[50:53]
	v_mfma_f32_16x16x32_bf16 v[42:45], v[160:163], v[176:179], v[42:45]
	v_mfma_f32_16x16x32_bf16 v[34:37], v[146:149], v[184:187], v[34:37]
	v_mfma_f32_16x16x32_bf16 v[26:29], v[160:163], v[184:187], v[26:29]
	v_mfma_f32_16x16x32_bf16 v[18:21], v[146:149], v[192:195], v[18:21]
	v_mfma_f32_16x16x32_bf16 v[10:13], v[160:163], v[192:195], v[10:13]
	v_mfma_f32_16x16x32_bf16 v[62:65], v[156:159], v[172:175], v[62:65]
	v_mfma_f32_16x16x32_bf16 v[58:61], v[164:167], v[172:175], v[58:61]
	v_mfma_f32_16x16x32_bf16 v[50:53], v[156:159], v[180:183], v[50:53]
	v_mfma_f32_16x16x32_bf16 v[42:45], v[164:167], v[180:183], v[42:45]
	v_mfma_f32_16x16x32_bf16 v[34:37], v[156:159], v[188:191], v[34:37]
	v_mfma_f32_16x16x32_bf16 v[26:29], v[164:167], v[188:191], v[26:29]
	v_mfma_f32_16x16x32_bf16 v[18:21], v[156:159], v[196:199], v[18:21]
	v_mfma_f32_16x16x32_bf16 v[10:13], v[164:167], v[196:199], v[10:13]
	s_barrier
	s_add_u32 s0, s38, 0x40080
	s_addc_u32 s1, s39, 0
	s_add_i32 s38, s40, s5
	v_lshl_add_u64 v[146:147], s[0:1], 0, v[138:139]
	s_mov_b32 m0, s38
	s_nop 0
	global_load_lds_dwordx4 v[146:147], off
	v_lshl_add_u64 v[146:147], s[0:1], 0, v[134:135]
	s_add_i32 m0, s38, 0x2000
	s_nop 0
	global_load_lds_dwordx4 v[146:147], off
	s_waitcnt vmcnt(10)
	s_barrier
	v_mfma_f32_16x16x32_bf16 v[54:57], v[200:203], v[168:171], v[54:57]
	v_mfma_f32_16x16x32_bf16 v[46:49], v[208:211], v[168:171], v[46:49]
	v_mfma_f32_16x16x32_bf16 v[38:41], v[200:203], v[176:179], v[38:41]
	v_mfma_f32_16x16x32_bf16 v[30:33], v[208:211], v[176:179], v[30:33]
	v_mfma_f32_16x16x32_bf16 v[22:25], v[200:203], v[184:187], v[22:25]
	v_mfma_f32_16x16x32_bf16 v[14:17], v[208:211], v[184:187], v[14:17]
	v_mfma_f32_16x16x32_bf16 v[6:9], v[200:203], v[192:195], v[6:9]
	v_mfma_f32_16x16x32_bf16 v[2:5], v[208:211], v[192:195], v[2:5]
	v_mfma_f32_16x16x32_bf16 v[54:57], v[204:207], v[172:175], v[54:57]
	v_mfma_f32_16x16x32_bf16 v[46:49], v[212:215], v[172:175], v[46:49]
	v_mfma_f32_16x16x32_bf16 v[38:41], v[204:207], v[180:183], v[38:41]
	v_mfma_f32_16x16x32_bf16 v[30:33], v[212:215], v[180:183], v[30:33]
	v_mfma_f32_16x16x32_bf16 v[22:25], v[204:207], v[188:191], v[22:25]
	v_mfma_f32_16x16x32_bf16 v[14:17], v[212:215], v[188:191], v[14:17]
	v_mfma_f32_16x16x32_bf16 v[6:9], v[204:207], v[196:199], v[6:9]
	v_mfma_f32_16x16x32_bf16 v[2:5], v[212:215], v[196:199], v[2:5]
	s_add_i32 s69, s69, 2
	s_add_u32 s66, s66, 0x100
	s_addc_u32 s67, s67, 0
	s_add_u32 s36, s36, 0x100
	s_addc_u32 s37, s37, 0
	s_cmp_gt_u32 s69, 13
	s_barrier
	s_cbranch_scc1 .Lpeel_exit_1

.Lpeel_exit_1:
	v_mov_b32_e32 v147, v131
	v_mov_b32_e32 v146, v133
	s_lshl_b32 s0, s58, 8
	s_or_b32 s0, s0, s45
	v_lshl_add_u32 v146, v146, 3, s0
	s_lshl_b32 s0, s59, 8
	s_add_i32 s0, s0, s44
	v_add_u32_e32 v155, s0, v147
	v_mov_b32_e32 v148, v155
	v_ashrrev_i32_e32 v147, 31, v146
	v_ashrrev_i32_e32 v149, 31, v148
	v_lshlrev_b64 v[148:149], 10, v[148:149]
	v_lshl_add_u64 v[148:149], v[148:149], 0, v[146:147]
	v_lshlrev_b64 v[148:149], 1, v[148:149]
	v_lshl_add_u64 v[176:177], s[10:11], 0, v[148:149]
	global_load_dwordx4 v[156:159], v[176:177], off
	global_load_dwordx4 v[160:163], v[176:177], off offset:256
	v_add_co_u32_e32 v168, vcc, s49, v176
	v_lshl_add_u64 v[148:149], s[12:13], 0, v[148:149]
	s_nop 0
	v_addc_co_u32_e32 v169, vcc, 0, v177, vcc
	global_load_dwordx4 v[164:167], v[168:169], off
	s_nop 0
	global_load_dwordx4 v[168:171], v[168:169], off offset:256
	v_add_co_u32_e32 v178, vcc, s43, v176
	s_mov_b32 s58, s57
	s_nop 0
	v_addc_co_u32_e32 v179, vcc, 0, v177, vcc
	global_load_dwordx4 v[172:175], v[178:179], off
	v_add_co_u32_e32 v184, vcc, s48, v176
	s_mov_b32 s59, s56
	s_nop 0
	v_addc_co_u32_e32 v185, vcc, 0, v177, vcc
	global_load_dwordx4 v[176:179], v[178:179], off offset:256
	s_nop 0
	global_load_dwordx4 v[180:183], v[184:185], off
	s_nop 0
	global_load_dwordx4 v[184:187], v[184:185], off offset:256
	v_add_co_u32_e32 v188, vcc, s49, v148
	s_waitcnt vmcnt(0) lgkmcnt(0)
	v_lshlrev_b32_e32 v190, 16, v156
	v_and_b32_e32 v191, 0xffff0000, v156
	v_lshlrev_b32_e32 v156, 16, v157
	v_and_b32_e32 v157, 0xffff0000, v157
	v_lshlrev_b32_e32 v192, 16, v158
	v_and_b32_e32 v193, 0xffff0000, v158
	v_lshlrev_b32_e32 v194, 16, v160
	v_and_b32_e32 v195, 0xffff0000, v160
	v_lshlrev_b32_e32 v160, 16, v161
	v_and_b32_e32 v161, 0xffff0000, v161
	v_lshlrev_b32_e32 v196, 16, v162
	v_and_b32_e32 v197, 0xffff0000, v162
	v_lshlrev_b32_e32 v162, 16, v163
	v_and_b32_e32 v163, 0xffff0000, v163
	v_lshlrev_b32_e32 v158, 16, v159
	v_and_b32_e32 v159, 0xffff0000, v159
	v_pk_fma_f32 v[128:129], v[156:157], s[28:29], v[128:129] op_sel_hi:[1,0,1]
	v_pk_fma_f32 v[122:123], v[192:193], s[28:29], v[122:123] op_sel_hi:[1,0,1]
	v_pk_fma_f32 v[120:121], v[160:161], s[28:29], v[120:121] op_sel_hi:[1,0,1]
	v_pk_fma_f32 v[156:157], v[162:163], s[28:29], v[112:113] op_sel_hi:[1,0,1]
	v_lshlrev_b32_e32 v160, 16, v164
	v_and_b32_e32 v161, 0xffff0000, v164
	v_lshlrev_b32_e32 v162, 16, v165
	v_and_b32_e32 v163, 0xffff0000, v165
	v_lshlrev_b32_e32 v164, 16, v166
	v_and_b32_e32 v165, 0xffff0000, v166
	v_lshlrev_b32_e32 v166, 16, v167
	v_and_b32_e32 v167, 0xffff0000, v167
	v_pk_fma_f32 v[126:127], v[190:191], s[28:29], v[126:127] op_sel_hi:[1,0,1]
	v_pk_fma_f32 v[124:125], v[158:159], s[28:29], v[124:125] op_sel_hi:[1,0,1]
	v_cvt_pk_bf16_f32 v112, v122, v123
	v_pk_fma_f32 v[116:117], v[162:163], s[28:29], v[116:117] op_sel_hi:[1,0,1]
	v_pk_fma_f32 v[114:115], v[160:161], s[28:29], v[114:115] op_sel_hi:[1,0,1]
	v_pk_fma_f32 v[122:123], v[166:167], s[28:29], v[108:109] op_sel_hi:[1,0,1]
	v_pk_fma_f32 v[108:109], v[164:165], s[28:29], v[106:107] op_sel_hi:[1,0,1]
	v_addc_co_u32_e32 v189, vcc, 0, v149, vcc
	v_pk_fma_f32 v[118:119], v[194:195], s[28:29], v[118:119] op_sel_hi:[1,0,1]
	v_pk_fma_f32 v[158:159], v[196:197], s[28:29], v[110:111] op_sel_hi:[1,0,1]
	v_cvt_pk_bf16_f32 v110, v126, v127
	v_cvt_pk_bf16_f32 v111, v128, v129
	v_cvt_pk_bf16_f32 v113, v124, v125
	v_cvt_pk_bf16_f32 v106, v114, v115
	v_cvt_pk_bf16_f32 v107, v116, v117
	v_cvt_pk_bf16_f32 v108, v108, v109
	v_cvt_pk_bf16_f32 v109, v122, v123
	v_lshlrev_b32_e32 v190, 16, v168
	v_cvt_pk_bf16_f32 v118, v118, v119
	v_cvt_pk_bf16_f32 v119, v120, v121
	v_cvt_pk_bf16_f32 v120, v158, v159
	v_cvt_pk_bf16_f32 v121, v156, v157
	global_store_dwordx4 v[148:149], v[110:113], off
	global_store_dwordx4 v[148:149], v[118:121], off offset:256
	global_store_dwordx4 v[188:189], v[106:109], off
	v_and_b32_e32 v191, 0xffff0000, v168
	v_lshlrev_b32_e32 v110, 16, v171
	v_lshlrev_b32_e32 v106, 16, v169
	v_and_b32_e32 v107, 0xffff0000, v169
	v_lshlrev_b32_e32 v108, 16, v170
	v_and_b32_e32 v109, 0xffff0000, v170
	v_and_b32_e32 v111, 0xffff0000, v171
	v_pk_fma_f32 v[104:105], v[106:107], s[28:29], v[104:105] op_sel_hi:[1,0,1]
	v_pk_fma_f32 v[102:103], v[190:191], s[28:29], v[102:103] op_sel_hi:[1,0,1]
	v_pk_fma_f32 v[106:107], v[110:111], s[28:29], v[96:97] op_sel_hi:[1,0,1]
	v_pk_fma_f32 v[96:97], v[108:109], s[28:29], v[94:95] op_sel_hi:[1,0,1]
	v_cvt_pk_bf16_f32 v94, v102, v103
	v_cvt_pk_bf16_f32 v95, v104, v105
	v_cvt_pk_bf16_f32 v96, v96, v97
	v_cvt_pk_bf16_f32 v97, v106, v107
	global_store_dwordx4 v[188:189], v[94:97], off offset:256
	v_lshlrev_b32_e32 v102, 16, v174
	v_and_b32_e32 v103, 0xffff0000, v174
	v_lshlrev_b32_e32 v94, 16, v172
	v_and_b32_e32 v95, 0xffff0000, v172
	v_lshlrev_b32_e32 v96, 16, v173
	v_and_b32_e32 v97, 0xffff0000, v173
	v_lshlrev_b32_e32 v104, 16, v175
	v_and_b32_e32 v105, 0xffff0000, v175
	v_pk_fma_f32 v[94:95], v[94:95], s[28:29], v[98:99] op_sel_hi:[1,0,1]
	v_pk_fma_f32 v[96:97], v[96:97], s[28:29], v[100:101] op_sel_hi:[1,0,1]
	v_pk_fma_f32 v[98:99], v[104:105], s[28:29], v[92:93] op_sel_hi:[1,0,1]
	v_pk_fma_f32 v[92:93], v[102:103], s[28:29], v[90:91] op_sel_hi:[1,0,1]
	v_cvt_pk_bf16_f32 v90, v94, v95
	v_add_co_u32_e32 v94, vcc, s43, v148
	v_cvt_pk_bf16_f32 v91, v96, v97
	v_cvt_pk_bf16_f32 v92, v92, v93
	v_cvt_pk_bf16_f32 v93, v98, v99
	v_addc_co_u32_e32 v95, vcc, 0, v149, vcc
	global_store_dwordx4 v[94:95], v[90:93], off
	v_lshlrev_b32_e32 v96, 16, v178
	v_and_b32_e32 v97, 0xffff0000, v178
	v_lshlrev_b32_e32 v90, 16, v176
	v_and_b32_e32 v91, 0xffff0000, v176
	v_lshlrev_b32_e32 v92, 16, v177
	v_and_b32_e32 v93, 0xffff0000, v177
	v_lshlrev_b32_e32 v98, 16, v179
	v_and_b32_e32 v99, 0xffff0000, v179
	v_pk_fma_f32 v[88:89], v[92:93], s[28:29], v[88:89] op_sel_hi:[1,0,1]
	v_pk_fma_f32 v[86:87], v[90:91], s[28:29], v[86:87] op_sel_hi:[1,0,1]
	v_pk_fma_f32 v[90:91], v[98:99], s[28:29], v[80:81] op_sel_hi:[1,0,1]
	v_pk_fma_f32 v[80:81], v[96:97], s[28:29], v[78:79] op_sel_hi:[1,0,1]
	v_cvt_pk_bf16_f32 v78, v86, v87
	v_cvt_pk_bf16_f32 v79, v88, v89
	v_cvt_pk_bf16_f32 v80, v80, v81
	v_cvt_pk_bf16_f32 v81, v90, v91
	global_store_dwordx4 v[94:95], v[78:81], off offset:256
	v_lshlrev_b32_e32 v86, 16, v182
	v_and_b32_e32 v87, 0xffff0000, v182
	v_lshlrev_b32_e32 v78, 16, v180
	v_and_b32_e32 v79, 0xffff0000, v180
	v_lshlrev_b32_e32 v80, 16, v181
	v_and_b32_e32 v81, 0xffff0000, v181
	v_lshlrev_b32_e32 v88, 16, v183
	v_and_b32_e32 v89, 0xffff0000, v183
	v_pk_fma_f32 v[78:79], v[78:79], s[28:29], v[82:83] op_sel_hi:[1,0,1]
	v_pk_fma_f32 v[80:81], v[80:81], s[28:29], v[84:85] op_sel_hi:[1,0,1]
	v_pk_fma_f32 v[82:83], v[88:89], s[28:29], v[76:77] op_sel_hi:[1,0,1]
	v_pk_fma_f32 v[76:77], v[86:87], s[28:29], v[74:75] op_sel_hi:[1,0,1]
	v_cvt_pk_bf16_f32 v74, v78, v79
	v_add_co_u32_e32 v78, vcc, s48, v148
	v_cvt_pk_bf16_f32 v75, v80, v81
	v_cvt_pk_bf16_f32 v76, v76, v77
	v_cvt_pk_bf16_f32 v77, v82, v83
	v_addc_co_u32_e32 v79, vcc, 0, v149, vcc
	global_store_dwordx4 v[78:79], v[74:77], off
	v_lshlrev_b32_e32 v80, 16, v186
	v_and_b32_e32 v81, 0xffff0000, v186
	v_lshlrev_b32_e32 v74, 16, v184
	v_and_b32_e32 v75, 0xffff0000, v184
	v_lshlrev_b32_e32 v76, 16, v185
	v_and_b32_e32 v77, 0xffff0000, v185
	v_lshlrev_b32_e32 v82, 16, v187
	v_and_b32_e32 v83, 0xffff0000, v187
	v_pk_fma_f32 v[72:73], v[76:77], s[28:29], v[72:73] op_sel_hi:[1,0,1]
	v_pk_fma_f32 v[70:71], v[74:75], s[28:29], v[70:71] op_sel_hi:[1,0,1]
	v_pk_fma_f32 v[74:75], v[82:83], s[28:29], v[68:69] op_sel_hi:[1,0,1]
	v_pk_fma_f32 v[68:69], v[80:81], s[28:29], v[66:67] op_sel_hi:[1,0,1]
	v_cvt_pk_bf16_f32 v66, v70, v71
	v_cvt_pk_bf16_f32 v67, v72, v73
	v_cvt_pk_bf16_f32 v68, v68, v69
	v_cvt_pk_bf16_f32 v69, v74, v75
	global_store_dwordx4 v[78:79], v[66:69], off offset:256
	s_nop 1
	v_add_u32_e32 v66, 0x80, v155
	s_nop 0
	v_ashrrev_i32_e32 v67, 31, v66
	v_lshlrev_b64 v[66:67], 10, v[66:67]
	v_lshl_add_u64 v[66:67], v[66:67], 0, v[146:147]
	v_lshlrev_b64 v[98:99], 1, v[66:67]
	v_lshl_add_u64 v[90:91], s[10:11], 0, v[98:99]
	global_load_dwordx4 v[66:69], v[90:91], off
	global_load_dwordx4 v[70:73], v[90:91], off offset:256
	v_add_co_u32_e32 v78, vcc, s49, v90
	s_waitcnt vmcnt(0) lgkmcnt(0)
	v_lshlrev_b32_e32 v100, 16, v66
	v_addc_co_u32_e32 v79, vcc, 0, v91, vcc
	global_load_dwordx4 v[74:77], v[78:79], off
	s_nop 0
	global_load_dwordx4 v[78:81], v[78:79], off offset:256
	v_add_co_u32_e32 v86, vcc, s43, v90
	v_and_b32_e32 v101, 0xffff0000, v66
	s_nop 0
	v_addc_co_u32_e32 v87, vcc, 0, v91, vcc
	global_load_dwordx4 v[82:85], v[86:87], off
	s_nop 0
	global_load_dwordx4 v[86:89], v[86:87], off offset:256
	v_add_co_u32_e32 v94, vcc, s48, v90
	v_lshlrev_b32_e32 v66, 16, v67
	s_nop 0
	v_addc_co_u32_e32 v95, vcc, 0, v91, vcc
	global_load_dwordx4 v[90:93], v[94:95], off
	s_nop 0
	global_load_dwordx4 v[94:97], v[94:95], off offset:256
	v_and_b32_e32 v67, 0xffff0000, v67
	v_lshlrev_b32_e32 v102, 16, v68
	v_and_b32_e32 v103, 0xffff0000, v68
	v_lshlrev_b32_e32 v68, 16, v69
	v_and_b32_e32 v69, 0xffff0000, v69
	v_pk_fma_f32 v[64:65], v[66:67], s[28:29], v[64:65] op_sel_hi:[1,0,1]
	v_pk_fma_f32 v[62:63], v[100:101], s[28:29], v[62:63] op_sel_hi:[1,0,1]
	v_pk_fma_f32 v[66:67], v[68:69], s[28:29], v[60:61] op_sel_hi:[1,0,1]
	v_pk_fma_f32 v[60:61], v[102:103], s[28:29], v[58:59] op_sel_hi:[1,0,1]
	v_cvt_pk_bf16_f32 v58, v62, v63
	v_cvt_pk_bf16_f32 v59, v64, v65
	v_cvt_pk_bf16_f32 v60, v60, v61
	v_cvt_pk_bf16_f32 v61, v66, v67
	v_lshl_add_u64 v[62:63], s[12:13], 0, v[98:99]
	global_store_dwordx4 v[62:63], v[58:61], off
	v_lshlrev_b32_e32 v64, 16, v72
	v_and_b32_e32 v65, 0xffff0000, v72
	v_lshlrev_b32_e32 v58, 16, v70
	v_and_b32_e32 v59, 0xffff0000, v70
	v_lshlrev_b32_e32 v60, 16, v71
	v_and_b32_e32 v61, 0xffff0000, v71
	v_lshlrev_b32_e32 v66, 16, v73
	v_and_b32_e32 v67, 0xffff0000, v73
	v_pk_fma_f32 v[56:57], v[60:61], s[28:29], v[56:57] op_sel_hi:[1,0,1]
	v_pk_fma_f32 v[54:55], v[58:59], s[28:29], v[54:55] op_sel_hi:[1,0,1]
	v_pk_fma_f32 v[58:59], v[66:67], s[28:29], v[48:49] op_sel_hi:[1,0,1]
	v_pk_fma_f32 v[48:49], v[64:65], s[28:29], v[46:47] op_sel_hi:[1,0,1]
	v_cvt_pk_bf16_f32 v46, v54, v55
	v_cvt_pk_bf16_f32 v47, v56, v57
	v_cvt_pk_bf16_f32 v48, v48, v49
	v_cvt_pk_bf16_f32 v49, v58, v59
	global_store_dwordx4 v[62:63], v[46:49], off offset:256
	s_waitcnt vmcnt(0) lgkmcnt(0)
	v_lshlrev_b32_e32 v54, 16, v76
	v_lshlrev_b32_e32 v46, 16, v74
	v_and_b32_e32 v47, 0xffff0000, v74
	v_lshlrev_b32_e32 v48, 16, v75
	v_and_b32_e32 v49, 0xffff0000, v75
	v_and_b32_e32 v55, 0xffff0000, v76
	v_lshlrev_b32_e32 v56, 16, v77
	v_and_b32_e32 v57, 0xffff0000, v77
	v_pk_fma_f32 v[46:47], v[46:47], s[28:29], v[50:51] op_sel_hi:[1,0,1]
	v_pk_fma_f32 v[48:49], v[48:49], s[28:29], v[52:53] op_sel_hi:[1,0,1]
	v_pk_fma_f32 v[50:51], v[56:57], s[28:29], v[44:45] op_sel_hi:[1,0,1]
	v_pk_fma_f32 v[44:45], v[54:55], s[28:29], v[42:43] op_sel_hi:[1,0,1]
	v_cvt_pk_bf16_f32 v42, v46, v47
	v_add_co_u32_e32 v46, vcc, s49, v62
	v_cvt_pk_bf16_f32 v43, v48, v49
	v_cvt_pk_bf16_f32 v44, v44, v45
	v_cvt_pk_bf16_f32 v45, v50, v51
	v_addc_co_u32_e32 v47, vcc, 0, v63, vcc
	global_store_dwordx4 v[46:47], v[42:45], off
	v_lshlrev_b32_e32 v48, 16, v80
	v_and_b32_e32 v49, 0xffff0000, v80
	v_lshlrev_b32_e32 v42, 16, v78
	v_and_b32_e32 v43, 0xffff0000, v78
	v_lshlrev_b32_e32 v44, 16, v79
	v_and_b32_e32 v45, 0xffff0000, v79
	v_lshlrev_b32_e32 v50, 16, v81
	v_and_b32_e32 v51, 0xffff0000, v81
	v_pk_fma_f32 v[40:41], v[44:45], s[28:29], v[40:41] op_sel_hi:[1,0,1]
	v_pk_fma_f32 v[38:39], v[42:43], s[28:29], v[38:39] op_sel_hi:[1,0,1]
	v_pk_fma_f32 v[42:43], v[50:51], s[28:29], v[32:33] op_sel_hi:[1,0,1]
	v_pk_fma_f32 v[32:33], v[48:49], s[28:29], v[30:31] op_sel_hi:[1,0,1]
	v_cvt_pk_bf16_f32 v30, v38, v39
	v_cvt_pk_bf16_f32 v31, v40, v41
	v_cvt_pk_bf16_f32 v32, v32, v33
	v_cvt_pk_bf16_f32 v33, v42, v43
	global_store_dwordx4 v[46:47], v[30:33], off offset:256
	v_lshlrev_b32_e32 v38, 16, v84
	v_and_b32_e32 v39, 0xffff0000, v84
	v_lshlrev_b32_e32 v30, 16, v82
	v_and_b32_e32 v31, 0xffff0000, v82
	v_lshlrev_b32_e32 v32, 16, v83
	v_and_b32_e32 v33, 0xffff0000, v83
	v_lshlrev_b32_e32 v40, 16, v85
	v_and_b32_e32 v41, 0xffff0000, v85
	v_pk_fma_f32 v[30:31], v[30:31], s[28:29], v[34:35] op_sel_hi:[1,0,1]
	v_pk_fma_f32 v[32:33], v[32:33], s[28:29], v[36:37] op_sel_hi:[1,0,1]
	v_pk_fma_f32 v[34:35], v[40:41], s[28:29], v[28:29] op_sel_hi:[1,0,1]
	v_pk_fma_f32 v[28:29], v[38:39], s[28:29], v[26:27] op_sel_hi:[1,0,1]
	v_cvt_pk_bf16_f32 v26, v30, v31
	v_add_co_u32_e32 v30, vcc, s43, v62
	v_cvt_pk_bf16_f32 v27, v32, v33
	v_cvt_pk_bf16_f32 v28, v28, v29
	v_cvt_pk_bf16_f32 v29, v34, v35
	v_addc_co_u32_e32 v31, vcc, 0, v63, vcc
	global_store_dwordx4 v[30:31], v[26:29], off
	v_lshlrev_b32_e32 v32, 16, v88
	v_and_b32_e32 v33, 0xffff0000, v88
	v_lshlrev_b32_e32 v26, 16, v86
	v_and_b32_e32 v27, 0xffff0000, v86
	v_lshlrev_b32_e32 v28, 16, v87
	v_and_b32_e32 v29, 0xffff0000, v87
	v_lshlrev_b32_e32 v34, 16, v89
	v_and_b32_e32 v35, 0xffff0000, v89
	v_pk_fma_f32 v[24:25], v[28:29], s[28:29], v[24:25] op_sel_hi:[1,0,1]
	v_pk_fma_f32 v[22:23], v[26:27], s[28:29], v[22:23] op_sel_hi:[1,0,1]
	v_pk_fma_f32 v[26:27], v[34:35], s[28:29], v[16:17] op_sel_hi:[1,0,1]
	v_pk_fma_f32 v[16:17], v[32:33], s[28:29], v[14:15] op_sel_hi:[1,0,1]
	v_cvt_pk_bf16_f32 v14, v22, v23
	v_cvt_pk_bf16_f32 v15, v24, v25
	v_cvt_pk_bf16_f32 v16, v16, v17
	v_cvt_pk_bf16_f32 v17, v26, v27
	global_store_dwordx4 v[30:31], v[14:17], off offset:256
	v_lshlrev_b32_e32 v22, 16, v92
	v_and_b32_e32 v23, 0xffff0000, v92
	v_lshlrev_b32_e32 v14, 16, v90
	v_and_b32_e32 v15, 0xffff0000, v90
	v_lshlrev_b32_e32 v16, 16, v91
	v_and_b32_e32 v17, 0xffff0000, v91
	v_lshlrev_b32_e32 v24, 16, v93
	v_and_b32_e32 v25, 0xffff0000, v93
	v_pk_fma_f32 v[14:15], v[14:15], s[28:29], v[18:19] op_sel_hi:[1,0,1]
	v_pk_fma_f32 v[16:17], v[16:17], s[28:29], v[20:21] op_sel_hi:[1,0,1]
	v_pk_fma_f32 v[18:19], v[24:25], s[28:29], v[12:13] op_sel_hi:[1,0,1]
	v_pk_fma_f32 v[12:13], v[22:23], s[28:29], v[10:11] op_sel_hi:[1,0,1]
	v_cvt_pk_bf16_f32 v10, v14, v15
	v_add_co_u32_e32 v14, vcc, s48, v62
	v_cvt_pk_bf16_f32 v11, v16, v17
	v_cvt_pk_bf16_f32 v12, v12, v13
	v_cvt_pk_bf16_f32 v13, v18, v19
	v_addc_co_u32_e32 v15, vcc, 0, v63, vcc
	global_store_dwordx4 v[14:15], v[10:13], off
	v_lshlrev_b32_e32 v16, 16, v96
	v_and_b32_e32 v17, 0xffff0000, v96
	v_lshlrev_b32_e32 v10, 16, v94
	v_and_b32_e32 v11, 0xffff0000, v94
	v_lshlrev_b32_e32 v12, 16, v95
	v_and_b32_e32 v13, 0xffff0000, v95
	v_lshlrev_b32_e32 v18, 16, v97
	v_and_b32_e32 v19, 0xffff0000, v97
	v_pk_fma_f32 v[8:9], v[12:13], s[28:29], v[8:9] op_sel_hi:[1,0,1]
	v_pk_fma_f32 v[6:7], v[10:11], s[28:29], v[6:7] op_sel_hi:[1,0,1]
	v_pk_fma_f32 v[10:11], v[18:19], s[28:29], v[4:5] op_sel_hi:[1,0,1]
	v_pk_fma_f32 v[4:5], v[16:17], s[28:29], v[2:3] op_sel_hi:[1,0,1]
	v_cvt_pk_bf16_f32 v2, v6, v7
	v_cvt_pk_bf16_f32 v3, v8, v9
	v_cvt_pk_bf16_f32 v4, v4, v5
	v_cvt_pk_bf16_f32 v5, v10, v11
	s_and_b64 vcc, exec, s[30:31]
	global_store_dwordx4 v[14:15], v[2:5], off offset:256
	s_cbranch_vccz .LBB0_433
	s_waitcnt vmcnt(0)
	s_cmpk_gt_u32 s4, 0xff
	s_cbranch_scc1 .LBB0_438
	s_barrier

.LBB0_687:
	s_ashr_i32 s0, s54, 5
	s_ashr_i32 s1, s0, 31
	s_lshl_b64 s[0:1], s[0:1], 21
	s_add_u32 s12, s4, s0
	s_addc_u32 s13, s5, s1
	s_ashr_i32 s25, s24, 31
	s_lshl_b64 s[0:1], s[24:25], 18
	s_add_u32 s12, s12, s0
	s_addc_u32 s13, s13, s1
	s_and_b64 s[0:1], s[10:11], exec
	s_cselect_b32 s25, s13, s31
	s_cselect_b32 s27, s12, s30
	v_mov_b32_e32 v173, v163
	v_mov_b32_e32 v175, v163
	s_add_u32 s29, s30, 0x100
	s_addc_u32 s55, s31, 0
	v_lshl_add_u64 v[176:177], s[18:19], 0, v[174:175]
	v_lshl_add_u64 v[178:179], s[18:19], 0, v[172:173]
	s_mov_b32 s56, -2
	s_mov_b64 s[34:35], 0
	s_add_u32 s10, s34, 0x100
	s_addc_u32 s11, s35, 0
	s_add_u32 s30, s29, s34
	s_addc_u32 s31, s55, s35
	s_cmpk_eq_i32 s34, 0x300
	s_cselect_b64 vcc, -1, 0
	s_and_b64 s[0:1], vcc, exec
	s_cselect_b32 s1, 0, s10
	s_cselect_b32 s0, 0, s11
	s_cselect_b32 s30, s27, s30
	s_cselect_b32 s31, s25, s31
	s_add_u32 s36, s14, s1
	s_addc_u32 s37, s15, s0
	s_add_i32 s1, 0, 0x10000
	v_add_u32_e32 v14, s1, v197
	ds_read_b128 v[2:5], v14
	ds_read_b128 v[6:9], v14 offset:1024
	ds_read_b128 v[10:13], v14 offset:2048
	ds_read_b128 v[14:17], v14 offset:3072
	v_cndmask_b32_e32 v162, v168, v171, vcc
	v_cndmask_b32_e32 v184, v170, v198, vcc
	v_cndmask_b32_e32 v175, v172, v199, vcc
	v_cndmask_b32_e32 v173, v174, v200, vcc
	v_lshl_add_u64 v[18:19], v[178:179], 0, s[34:35]
	s_add_i32 m0, s45, 0xc000
	ds_read_b128 v[202:205], v169
	ds_read_b128 v[206:209], v169 offset:1024
	ds_read_b128 v[210:213], v169 offset:2048
	ds_read_b128 v[214:217], v169 offset:3072
	ds_read_b128 v[218:221], v169 offset:4096
	ds_read_b128 v[222:225], v169 offset:5120
	ds_read_b128 v[226:229], v169 offset:6144
	ds_read_b128 v[230:233], v169 offset:7168
	global_load_lds_dwordx4 v[18:19], off
	v_lshl_add_u64 v[18:19], v[176:177], 0, s[34:35]
	s_add_i32 m0, s45, 0xe000
	s_nop 0
	global_load_lds_dwordx4 v[18:19], off
	s_waitcnt lgkmcnt(8)
	s_waitcnt vmcnt(10)
	s_barrier
	s_waitcnt lgkmcnt(0)
	s_waitcnt lgkmcnt(0)
	v_mfma_scale_f32_16x16x128_f8f6f4 v[158:161], v[2:9], v[202:209], 0, v188, v188 op_sel_hi:[0,0,0]
	v_mfma_scale_f32_16x16x128_f8f6f4 v[150:153], v[10:17], v[202:209], 0, v188, v188 op_sel_hi:[0,0,0]
	v_mfma_scale_f32_16x16x128_f8f6f4 v[142:145], v[2:9], v[210:217], 0, v188, v188 op_sel_hi:[0,0,0]
	v_mfma_scale_f32_16x16x128_f8f6f4 v[134:137], v[10:17], v[210:217], 0, v188, v188 op_sel_hi:[0,0,0]
	v_mfma_scale_f32_16x16x128_f8f6f4 v[126:129], v[2:9], v[218:225], 0, v188, v188 op_sel_hi:[0,0,0]
	v_mfma_scale_f32_16x16x128_f8f6f4 v[118:121], v[10:17], v[218:225], 0, v188, v188 op_sel_hi:[0,0,0]
	v_mfma_scale_f32_16x16x128_f8f6f4 v[110:113], v[2:9], v[226:233], 0, v188, v188 op_sel_hi:[0,0,0]
	v_mfma_scale_f32_16x16x128_f8f6f4 v[102:105], v[10:17], v[226:233], 0, v188, v188 op_sel_hi:[0,0,0]
	s_barrier
	s_add_i32 s0, 0, 0x14000
	s_add_i32 s1, s1, s43
	v_add_u32_e32 v30, s0, v197
	v_lshl_add_u64 v[180:181], s[30:31], 0, v[164:165]
	s_mov_b32 m0, s1
	ds_read_b128 v[18:21], v30
	ds_read_b128 v[22:25], v30 offset:1024
	ds_read_b128 v[26:29], v30 offset:2048
	ds_read_b128 v[30:33], v30 offset:3072
	global_load_lds_dwordx4 v[180:181], off
	v_lshl_add_u64 v[182:183], s[30:31], 0, v[166:167]
	s_add_i32 m0, s1, 0x2000
	s_nop 0
	global_load_lds_dwordx4 v[182:183], off
	s_waitcnt vmcnt(10)
	s_barrier
	s_waitcnt lgkmcnt(0)
	s_waitcnt lgkmcnt(0)
	v_mfma_scale_f32_16x16x128_f8f6f4 v[154:157], v[18:25], v[202:209], 0, v188, v188 op_sel_hi:[0,0,0]
	v_mfma_scale_f32_16x16x128_f8f6f4 v[146:149], v[26:33], v[202:209], 0, v188, v188 op_sel_hi:[0,0,0]
	v_mfma_scale_f32_16x16x128_f8f6f4 v[138:141], v[18:25], v[210:217], 0, v188, v188 op_sel_hi:[0,0,0]
	v_mfma_scale_f32_16x16x128_f8f6f4 v[130:133], v[26:33], v[210:217], 0, v188, v188 op_sel_hi:[0,0,0]
	v_mfma_scale_f32_16x16x128_f8f6f4 v[122:125], v[18:25], v[218:225], 0, v188, v188 op_sel_hi:[0,0,0]
	v_mfma_scale_f32_16x16x128_f8f6f4 v[114:117], v[26:33], v[218:225], 0, v188, v188 op_sel_hi:[0,0,0]
	v_mfma_scale_f32_16x16x128_f8f6f4 v[106:109], v[18:25], v[226:233], 0, v188, v188 op_sel_hi:[0,0,0]
	v_mfma_scale_f32_16x16x128_f8f6f4 v[98:101], v[26:33], v[226:233], 0, v188, v188 op_sel_hi:[0,0,0]
	s_mov_b32 m0, s45
	s_barrier
	ds_read_b128 v[202:205], v169 offset:16384
	ds_read_b128 v[206:209], v169 offset:17408
	ds_read_b128 v[210:213], v169 offset:18432
	ds_read_b128 v[214:217], v169 offset:19456
	ds_read_b128 v[218:221], v169 offset:20480
	ds_read_b128 v[222:225], v169 offset:21504
	ds_read_b128 v[226:229], v169 offset:22528
	ds_read_b128 v[230:233], v169 offset:23552
	global_load_lds_dwordx4 v162, s[36:37]
	s_mov_b32 m0, s46
	v_mov_b32_e32 v185, v163
	global_load_lds_dwordx4 v184, s[36:37]
	s_waitcnt vmcnt(10)
	s_barrier
	s_waitcnt lgkmcnt(0)
	v_lshl_add_u64 v[186:187], s[36:37], 0, v[162:163]
	v_lshl_add_u64 v[184:185], s[36:37], 0, v[184:185]
	s_waitcnt lgkmcnt(0)
	v_mfma_scale_f32_16x16x128_f8f6f4 v[94:97], v[2:9], v[202:209], 0, v188, v188 op_sel_hi:[0,0,0]
	v_mfma_scale_f32_16x16x128_f8f6f4 v[86:89], v[10:17], v[202:209], 0, v188, v188 op_sel_hi:[0,0,0]
	v_mfma_scale_f32_16x16x128_f8f6f4 v[78:81], v[2:9], v[210:217], 0, v188, v188 op_sel_hi:[0,0,0]
	v_mfma_scale_f32_16x16x128_f8f6f4 v[70:73], v[10:17], v[210:217], 0, v188, v188 op_sel_hi:[0,0,0]
	v_mfma_scale_f32_16x16x128_f8f6f4 v[62:65], v[2:9], v[218:225], 0, v188, v188 op_sel_hi:[0,0,0]
	v_mfma_scale_f32_16x16x128_f8f6f4 v[54:57], v[10:17], v[218:225], 0, v188, v188 op_sel_hi:[0,0,0]
	v_mfma_scale_f32_16x16x128_f8f6f4 v[46:49], v[2:9], v[226:233], 0, v188, v188 op_sel_hi:[0,0,0]
	v_mfma_scale_f32_16x16x128_f8f6f4 v[38:41], v[10:17], v[226:233], 0, v188, v188 op_sel_hi:[0,0,0]
	s_barrier
	s_add_u32 s34, s30, 0x20000
	s_addc_u32 s35, s31, 0
	s_add_i32 s0, s0, s43
	v_lshl_add_u64 v[2:3], s[34:35], 0, v[164:165]
	s_mov_b32 m0, s0
	s_nop 0
	global_load_lds_dwordx4 v[2:3], off
	v_lshl_add_u64 v[2:3], s[34:35], 0, v[166:167]
	s_add_i32 m0, s0, 0x2000
	s_nop 0
	global_load_lds_dwordx4 v[2:3], off
	s_waitcnt vmcnt(10)
	s_barrier
	v_mfma_scale_f32_16x16x128_f8f6f4 v[90:93], v[18:25], v[202:209], 0, v188, v188 op_sel_hi:[0,0,0]
	v_mfma_scale_f32_16x16x128_f8f6f4 v[82:85], v[26:33], v[202:209], 0, v188, v188 op_sel_hi:[0,0,0]
	v_mfma_scale_f32_16x16x128_f8f6f4 v[74:77], v[18:25], v[210:217], 0, v188, v188 op_sel_hi:[0,0,0]
	v_mfma_scale_f32_16x16x128_f8f6f4 v[66:69], v[26:33], v[210:217], 0, v188, v188 op_sel_hi:[0,0,0]
	v_mfma_scale_f32_16x16x128_f8f6f4 v[58:61], v[18:25], v[218:225], 0, v188, v188 op_sel_hi:[0,0,0]
	v_mfma_scale_f32_16x16x128_f8f6f4 v[50:53], v[26:33], v[218:225], 0, v188, v188 op_sel_hi:[0,0,0]
	v_mfma_scale_f32_16x16x128_f8f6f4 v[42:45], v[18:25], v[226:233], 0, v188, v188 op_sel_hi:[0,0,0]
	v_mfma_scale_f32_16x16x128_f8f6f4 v[34:37], v[26:33], v[226:233], 0, v188, v188 op_sel_hi:[0,0,0]
	s_add_i32 s0, 0, 0x18000
	v_add_u32_e32 v14, s0, v197
	s_barrier
	ds_read_b128 v[2:5], v14
	ds_read_b128 v[6:9], v14 offset:1024
	ds_read_b128 v[10:13], v14 offset:2048
	ds_read_b128 v[14:17], v14 offset:3072
	s_mov_b32 m0, s47
	ds_read_b128 v[18:21], v169 offset:32768
	ds_read_b128 v[22:25], v169 offset:33792
	ds_read_b128 v[26:29], v169 offset:34816
	ds_read_b128 v[30:33], v169 offset:35840
	ds_read_b128 v[202:205], v169 offset:36864
	ds_read_b128 v[206:209], v169 offset:37888
	ds_read_b128 v[210:213], v169 offset:38912
	ds_read_b128 v[214:217], v169 offset:39936
	global_load_lds_dwordx4 v175, s[36:37]
	s_mov_b32 m0, s48
	s_nop 0
	global_load_lds_dwordx4 v173, s[36:37]
	s_waitcnt lgkmcnt(8)
	s_waitcnt vmcnt(10)
	s_barrier
	s_waitcnt lgkmcnt(0)
	s_waitcnt lgkmcnt(0)
	v_mfma_scale_f32_16x16x128_f8f6f4 v[158:161], v[2:9], v[18:25], v[158:161], v188, v188 op_sel_hi:[0,0,0]
	v_mfma_scale_f32_16x16x128_f8f6f4 v[150:153], v[10:17], v[18:25], v[150:153], v188, v188 op_sel_hi:[0,0,0]
	v_mfma_scale_f32_16x16x128_f8f6f4 v[142:145], v[2:9], v[26:33], v[142:145], v188, v188 op_sel_hi:[0,0,0]
	v_mfma_scale_f32_16x16x128_f8f6f4 v[134:137], v[10:17], v[26:33], v[134:137], v188, v188 op_sel_hi:[0,0,0]
	v_mfma_scale_f32_16x16x128_f8f6f4 v[126:129], v[2:9], v[202:209], v[126:129], v188, v188 op_sel_hi:[0,0,0]
	v_mfma_scale_f32_16x16x128_f8f6f4 v[118:121], v[10:17], v[202:209], v[118:121], v188, v188 op_sel_hi:[0,0,0]
	v_mfma_scale_f32_16x16x128_f8f6f4 v[110:113], v[2:9], v[210:217], v[110:113], v188, v188 op_sel_hi:[0,0,0]
	v_mfma_scale_f32_16x16x128_f8f6f4 v[102:105], v[10:17], v[210:217], v[102:105], v188, v188 op_sel_hi:[0,0,0]
	s_barrier
	s_add_i32 s34, 0, 0x1c000
	s_add_i32 s0, s0, s43
	v_add_u32_e32 v162, s34, v197
	v_lshl_add_u64 v[180:181], v[180:181], 0, s[20:21]
	s_mov_b32 m0, s0
	ds_read_b128 v[218:221], v162
	ds_read_b128 v[222:225], v162 offset:1024
	ds_read_b128 v[226:229], v162 offset:2048
	ds_read_b128 v[230:233], v162 offset:3072
	global_load_lds_dwordx4 v[180:181], off
	v_lshl_add_u64 v[180:181], v[182:183], 0, s[20:21]
	s_add_i32 m0, s0, 0x2000
	s_nop 0
	global_load_lds_dwordx4 v[180:181], off
	s_waitcnt vmcnt(10)
	s_barrier
	s_waitcnt lgkmcnt(0)
	s_waitcnt lgkmcnt(0)
	v_mfma_scale_f32_16x16x128_f8f6f4 v[154:157], v[218:225], v[18:25], v[154:157], v188, v188 op_sel_hi:[0,0,0]
	v_mfma_scale_f32_16x16x128_f8f6f4 v[146:149], v[226:233], v[18:25], v[146:149], v188, v188 op_sel_hi:[0,0,0]
	v_mfma_scale_f32_16x16x128_f8f6f4 v[138:141], v[218:225], v[26:33], v[138:141], v188, v188 op_sel_hi:[0,0,0]
	v_mfma_scale_f32_16x16x128_f8f6f4 v[130:133], v[226:233], v[26:33], v[130:133], v188, v188 op_sel_hi:[0,0,0]
	v_mfma_scale_f32_16x16x128_f8f6f4 v[122:125], v[218:225], v[202:209], v[122:125], v188, v188 op_sel_hi:[0,0,0]
	v_mfma_scale_f32_16x16x128_f8f6f4 v[114:117], v[226:233], v[202:209], v[114:117], v188, v188 op_sel_hi:[0,0,0]
	v_mfma_scale_f32_16x16x128_f8f6f4 v[106:109], v[218:225], v[210:217], v[106:109], v188, v188 op_sel_hi:[0,0,0]
	v_mfma_scale_f32_16x16x128_f8f6f4 v[98:101], v[226:233], v[210:217], v[98:101], v188, v188 op_sel_hi:[0,0,0]
	s_mov_b32 m0, s51
	v_lshl_add_u64 v[180:181], v[186:187], 0, s[20:21]
	s_barrier
	ds_read_b128 v[18:21], v169 offset:49152
	ds_read_b128 v[22:25], v169 offset:50176
	ds_read_b128 v[26:29], v169 offset:51200
	ds_read_b128 v[30:33], v169 offset:52224
	ds_read_b128 v[202:205], v169 offset:53248
	ds_read_b128 v[206:209], v169 offset:54272
	ds_read_b128 v[210:213], v169 offset:55296
	ds_read_b128 v[214:217], v169 offset:56320
	global_load_lds_dwordx4 v[180:181], off
	v_lshl_add_u64 v[180:181], v[184:185], 0, s[20:21]
	s_mov_b32 m0, s52
	s_nop 0
	global_load_lds_dwordx4 v[180:181], off
	s_waitcnt vmcnt(10)
	s_barrier
	s_waitcnt lgkmcnt(0)
	s_waitcnt lgkmcnt(0)
	v_mfma_scale_f32_16x16x128_f8f6f4 v[94:97], v[2:9], v[18:25], v[94:97], v188, v188 op_sel_hi:[0,0,0]
	v_mfma_scale_f32_16x16x128_f8f6f4 v[86:89], v[10:17], v[18:25], v[86:89], v188, v188 op_sel_hi:[0,0,0]
	v_mfma_scale_f32_16x16x128_f8f6f4 v[78:81], v[2:9], v[26:33], v[78:81], v188, v188 op_sel_hi:[0,0,0]
	v_mfma_scale_f32_16x16x128_f8f6f4 v[70:73], v[10:17], v[26:33], v[70:73], v188, v188 op_sel_hi:[0,0,0]
	v_mfma_scale_f32_16x16x128_f8f6f4 v[62:65], v[2:9], v[202:209], v[62:65], v188, v188 op_sel_hi:[0,0,0]
	v_mfma_scale_f32_16x16x128_f8f6f4 v[54:57], v[10:17], v[202:209], v[54:57], v188, v188 op_sel_hi:[0,0,0]
	v_mfma_scale_f32_16x16x128_f8f6f4 v[46:49], v[2:9], v[210:217], v[46:49], v188, v188 op_sel_hi:[0,0,0]
	v_mfma_scale_f32_16x16x128_f8f6f4 v[38:41], v[10:17], v[210:217], v[38:41], v188, v188 op_sel_hi:[0,0,0]
	s_barrier
	s_add_u32 s0, s30, 0x20080
	s_addc_u32 s1, s31, 0
	s_add_i32 s30, s34, s43
	v_lshl_add_u64 v[2:3], s[0:1], 0, v[164:165]
	s_mov_b32 m0, s30
	s_nop 0
	global_load_lds_dwordx4 v[2:3], off
	v_lshl_add_u64 v[2:3], s[0:1], 0, v[166:167]
	s_add_i32 m0, s30, 0x2000
	s_nop 0
	global_load_lds_dwordx4 v[2:3], off
	s_waitcnt vmcnt(10)
	s_barrier
	v_mfma_scale_f32_16x16x128_f8f6f4 v[90:93], v[218:225], v[18:25], v[90:93], v188, v188 op_sel_hi:[0,0,0]
	v_mfma_scale_f32_16x16x128_f8f6f4 v[82:85], v[226:233], v[18:25], v[82:85], v188, v188 op_sel_hi:[0,0,0]
	v_mfma_scale_f32_16x16x128_f8f6f4 v[74:77], v[218:225], v[26:33], v[74:77], v188, v188 op_sel_hi:[0,0,0]
	v_mfma_scale_f32_16x16x128_f8f6f4 v[66:69], v[226:233], v[26:33], v[66:69], v188, v188 op_sel_hi:[0,0,0]
	v_mfma_scale_f32_16x16x128_f8f6f4 v[58:61], v[218:225], v[202:209], v[58:61], v188, v188 op_sel_hi:[0,0,0]
	v_mfma_scale_f32_16x16x128_f8f6f4 v[50:53], v[226:233], v[202:209], v[50:53], v188, v188 op_sel_hi:[0,0,0]
	v_mfma_scale_f32_16x16x128_f8f6f4 v[42:45], v[218:225], v[210:217], v[42:45], v188, v188 op_sel_hi:[0,0,0]
	v_mfma_scale_f32_16x16x128_f8f6f4 v[34:37], v[226:233], v[210:217], v[34:37], v188, v188 op_sel_hi:[0,0,0]
	s_add_i32 s56, s56, 2
	s_cmp_gt_u32 s56, 5
	s_mov_b64 s[34:35], s[10:11]
	s_barrier
	s_cbranch_scc1 .Lpeel_exit_2

.Lpeel_exit_2:
	v_mul_f32_e32 v5, 0x3b000000, v158
	v_mul_f32_e32 v6, 0xbcb8aa3b, v158
	v_exp_f32_e32 v6, v6
	s_ashr_i32 s29, s28, 31
	s_ashr_i32 s27, s26, 31
	s_lshl_b64 s[10:11], s[28:29], 18
	v_add_f32_e32 v6, 1.0, v6
	v_rcp_f32_e32 v6, v6
	s_lshl_b64 s[26:27], s[26:27], 15
	v_mov_b32_e32 v3, v195
	s_add_u32 s0, s6, s10
	v_mul_f32_e32 v5, v5, v6
	v_mul_f32_e32 v6, 0x3b000000, v159
	v_mul_f32_e32 v7, 0xbcb8aa3b, v159
	v_exp_f32_e32 v7, v7
	v_mul_f32_e32 v5, v5, v154
	v_med3_f32 v5, v5, s40, v190
	v_add_f32_e32 v7, 1.0, v7
	v_rcp_f32_e32 v7, v7
	s_nop 15
	s_nop 15
	v_mov_b32_e32 v2, v196
	v_mul_f32_e32 v6, v6, v7
	v_mul_f32_e32 v7, 0x3b000000, v160
	v_mul_f32_e32 v8, 0xbcb8aa3b, v160
	v_exp_f32_e32 v8, v8
	v_mul_f32_e32 v6, v6, v155
	v_add_u32_e32 v4, s49, v3
	v_add_f32_e32 v8, 1.0, v8
	v_rcp_f32_e32 v8, v8
	s_addc_u32 s1, s7, s11
	s_add_u32 s10, s0, s26
	v_mul_f32_e32 v7, v7, v8
	v_mul_f32_e32 v8, 0x3b000000, v161
	v_mul_f32_e32 v9, 0xbcb8aa3b, v161
	v_exp_f32_e32 v9, v9
	v_mul_f32_e32 v7, v7, v156
	v_lshl_add_u32 v2, v2, 3, s50
	v_add_f32_e32 v9, 1.0, v9
	v_rcp_f32_e32 v9, v9
	s_addc_u32 s11, s1, s27
	v_ashrrev_i32_e32 v3, 31, v2
	s_and_b64 vcc, exec, s[8:9]
	v_mul_f32_e32 v8, v8, v9
	v_mul_f32_e32 v9, 0x3b000000, v150
	v_mul_f32_e32 v10, 0xbcb8aa3b, v150
	v_exp_f32_e32 v10, v10
	v_mul_f32_e32 v8, v8, v157
	v_mov_b32_e32 v174, v200
	v_add_f32_e32 v10, 1.0, v10
	v_rcp_f32_e32 v10, v10
	v_mov_b32_e32 v172, v199
	v_mov_b32_e32 v170, v198
	v_mov_b32_e32 v168, v171
	v_mul_f32_e32 v9, v9, v10
	v_mul_f32_e32 v10, 0x3b000000, v151
	v_mul_f32_e32 v11, 0xbcb8aa3b, v151
	v_exp_f32_e32 v11, v11
	v_mul_f32_e32 v9, v9, v146
	s_mov_b32 s26, s24
	v_add_f32_e32 v11, 1.0, v11
	v_rcp_f32_e32 v11, v11
	s_mov_b32 s28, s54
	s_mov_b64 s[30:31], s[12:13]
	v_mul_f32_e32 v10, v10, v11
	v_mul_f32_e32 v11, 0x3b000000, v152
	v_mul_f32_e32 v12, 0xbcb8aa3b, v152
	v_exp_f32_e32 v12, v12
	v_mul_f32_e32 v10, v10, v147
	v_add_f32_e32 v12, 1.0, v12
	v_rcp_f32_e32 v12, v12
	s_nop 0
	v_mul_f32_e32 v11, v11, v12
	v_mul_f32_e32 v12, 0x3b000000, v153
	v_mul_f32_e32 v13, 0xbcb8aa3b, v153
	v_exp_f32_e32 v13, v13
	v_mul_f32_e32 v11, v11, v148
	v_add_f32_e32 v13, 1.0, v13
	v_rcp_f32_e32 v13, v13
	s_nop 0
	v_mul_f32_e32 v12, v12, v13
	v_med3_f32 v13, v6, s40, v190
	v_mov_b32_e32 v6, v163
	v_cvt_pk_fp8_f32 v6, v5, v13
	v_med3_f32 v5, v7, s40, v190
	v_med3_f32 v7, v8, s40, v190
	v_med3_f32 v8, v10, s40, v190
	v_cvt_pk_fp8_f32 v6, v5, v7 op_sel:[0,0,1]
	v_med3_f32 v5, v9, s40, v190
	v_mov_b32_e32 v7, v163
	v_cvt_pk_fp8_f32 v7, v5, v8
	v_mul_f32_e32 v12, v12, v149
	v_med3_f32 v5, v11, s40, v190
	v_med3_f32 v8, v12, s40, v190
	v_cvt_pk_fp8_f32 v7, v5, v8 op_sel:[0,0,1]
	v_ashrrev_i32_e32 v5, 31, v4
	v_lshlrev_b64 v[8:9], 7, v[4:5]
	v_lshl_add_u64 v[8:9], s[10:11], 0, v[8:9]
	v_lshl_add_u64 v[8:9], v[8:9], 0, v[2:3]
	v_mul_f32_e32 v5, 0x3b000000, v142
	global_store_dwordx2 v[8:9], v[6:7], off
	v_mul_f32_e32 v6, 0xbcb8aa3b, v142
	v_exp_f32_e32 v6, v6
	s_nop 0
	v_add_f32_e32 v6, 1.0, v6
	v_rcp_f32_e32 v6, v6
	s_nop 0
	v_mul_f32_e32 v5, v5, v6
	v_mul_f32_e32 v6, 0x3b000000, v143
	v_mul_f32_e32 v7, 0xbcb8aa3b, v143
	v_exp_f32_e32 v7, v7
	v_mul_f32_e32 v5, v5, v138
	v_med3_f32 v5, v5, s40, v190
	v_add_f32_e32 v7, 1.0, v7
	v_rcp_f32_e32 v7, v7
	s_nop 0
	v_mul_f32_e32 v6, v6, v7
	v_mul_f32_e32 v7, v6, v139
	v_mul_f32_e32 v6, 0x3b000000, v144
	v_mul_f32_e32 v8, 0xbcb8aa3b, v144
	v_exp_f32_e32 v8, v8
	v_med3_f32 v7, v7, s40, v190
	v_add_f32_e32 v8, 1.0, v8
	v_rcp_f32_e32 v8, v8
	s_nop 0
	v_mul_f32_e32 v6, v6, v8
	v_mul_f32_e32 v9, v6, v140
	v_mul_f32_e32 v6, 0x3b000000, v145
	v_mul_f32_e32 v8, 0xbcb8aa3b, v145
	v_exp_f32_e32 v8, v8
	s_nop 0
	v_add_f32_e32 v8, 1.0, v8
	v_rcp_f32_e32 v8, v8
	s_nop 0
	v_mul_f32_e32 v6, v6, v8
	v_mul_f32_e32 v10, v6, v141
	v_mul_f32_e32 v6, 0x3b000000, v134
	v_mul_f32_e32 v8, 0xbcb8aa3b, v134
	v_exp_f32_e32 v8, v8
	s_nop 0
	v_add_f32_e32 v8, 1.0, v8
	v_rcp_f32_e32 v8, v8
	s_nop 0
	v_mul_f32_e32 v6, v6, v8
	v_mul_f32_e32 v11, v6, v130
	v_mul_f32_e32 v6, 0x3b000000, v135
	v_mul_f32_e32 v8, 0xbcb8aa3b, v135
	v_exp_f32_e32 v8, v8
	s_nop 0
	v_add_f32_e32 v8, 1.0, v8
	v_rcp_f32_e32 v8, v8
	s_nop 0
	v_mul_f32_e32 v6, v6, v8
	v_mul_f32_e32 v12, v6, v131
	v_mul_f32_e32 v6, 0x3b000000, v136
	v_mul_f32_e32 v8, 0xbcb8aa3b, v136
	v_exp_f32_e32 v8, v8
	s_nop 0
	v_add_f32_e32 v8, 1.0, v8
	v_rcp_f32_e32 v8, v8
	s_nop 0
	v_mul_f32_e32 v6, v6, v8
	v_mul_f32_e32 v13, v6, v132
	v_mul_f32_e32 v6, 0x3b000000, v137
	v_mul_f32_e32 v8, 0xbcb8aa3b, v137
	v_exp_f32_e32 v8, v8
	s_nop 0
	v_add_f32_e32 v8, 1.0, v8
	v_rcp_f32_e32 v8, v8
	s_nop 0
	v_mul_f32_e32 v6, v6, v8
	v_mov_b32_e32 v8, v163
	v_cvt_pk_fp8_f32 v8, v5, v7
	v_med3_f32 v5, v9, s40, v190
	v_med3_f32 v7, v10, s40, v190
	v_mov_b32_e32 v9, v163
	v_cvt_pk_fp8_f32 v8, v5, v7 op_sel:[0,0,1]
	v_med3_f32 v5, v11, s40, v190
	v_med3_f32 v7, v12, s40, v190
	v_cvt_pk_fp8_f32 v9, v5, v7
	v_mul_f32_e32 v14, v6, v133
	v_add_u32_e32 v6, 16, v4
	v_med3_f32 v5, v13, s40, v190
	v_med3_f32 v7, v14, s40, v190
	v_cvt_pk_fp8_f32 v9, v5, v7 op_sel:[0,0,1]
	v_ashrrev_i32_e32 v7, 31, v6
	v_lshlrev_b64 v[6:7], 7, v[6:7]
	v_lshl_add_u64 v[6:7], s[10:11], 0, v[6:7]
	v_lshl_add_u64 v[6:7], v[6:7], 0, v[2:3]
	v_mul_f32_e32 v5, 0x3b000000, v126
	global_store_dwordx2 v[6:7], v[8:9], off
	v_mul_f32_e32 v6, 0xbcb8aa3b, v126
	v_exp_f32_e32 v6, v6
	s_nop 0
	v_add_f32_e32 v6, 1.0, v6
	v_rcp_f32_e32 v6, v6
	s_nop 0
	v_mul_f32_e32 v5, v5, v6
	v_mul_f32_e32 v6, 0x3b000000, v127
	v_mul_f32_e32 v7, 0xbcb8aa3b, v127
	v_exp_f32_e32 v7, v7
	v_mul_f32_e32 v5, v5, v122
	v_med3_f32 v5, v5, s40, v190
	v_add_f32_e32 v7, 1.0, v7
	v_rcp_f32_e32 v7, v7
	s_nop 0
	v_mul_f32_e32 v6, v6, v7
	v_mul_f32_e32 v7, v6, v123
	v_mul_f32_e32 v6, 0x3b000000, v128
	v_mul_f32_e32 v8, 0xbcb8aa3b, v128
	v_exp_f32_e32 v8, v8
	v_med3_f32 v7, v7, s40, v190
	v_add_f32_e32 v8, 1.0, v8
	v_rcp_f32_e32 v8, v8
	s_nop 0
	v_mul_f32_e32 v6, v6, v8
	v_mul_f32_e32 v9, v6, v124
	v_mul_f32_e32 v6, 0x3b000000, v129
	v_mul_f32_e32 v8, 0xbcb8aa3b, v129
	v_exp_f32_e32 v8, v8
	s_nop 0
	v_add_f32_e32 v8, 1.0, v8
	v_rcp_f32_e32 v8, v8
	s_nop 0
	v_mul_f32_e32 v6, v6, v8
	v_mul_f32_e32 v10, v6, v125
	v_mul_f32_e32 v6, 0x3b000000, v118
	v_mul_f32_e32 v8, 0xbcb8aa3b, v118
	v_exp_f32_e32 v8, v8
	s_nop 0
	v_add_f32_e32 v8, 1.0, v8
	v_rcp_f32_e32 v8, v8
	s_nop 0
	v_mul_f32_e32 v6, v6, v8
	v_mul_f32_e32 v11, v6, v114
	v_mul_f32_e32 v6, 0x3b000000, v119
	v_mul_f32_e32 v8, 0xbcb8aa3b, v119
	v_exp_f32_e32 v8, v8
	s_nop 0
	v_add_f32_e32 v8, 1.0, v8
	v_rcp_f32_e32 v8, v8
	s_nop 0
	v_mul_f32_e32 v6, v6, v8
	v_mul_f32_e32 v12, v6, v115
	v_mul_f32_e32 v6, 0x3b000000, v120
	v_mul_f32_e32 v8, 0xbcb8aa3b, v120
	v_exp_f32_e32 v8, v8
	s_nop 0
	v_add_f32_e32 v8, 1.0, v8
	v_rcp_f32_e32 v8, v8
	s_nop 0
	v_mul_f32_e32 v6, v6, v8
	v_mul_f32_e32 v13, v6, v116
	v_mul_f32_e32 v6, 0x3b000000, v121
	v_mul_f32_e32 v8, 0xbcb8aa3b, v121
	v_exp_f32_e32 v8, v8
	s_nop 0
	v_add_f32_e32 v8, 1.0, v8
	v_rcp_f32_e32 v8, v8
	s_nop 0
	v_mul_f32_e32 v6, v6, v8
	v_mov_b32_e32 v8, v163
	v_cvt_pk_fp8_f32 v8, v5, v7
	v_med3_f32 v5, v9, s40, v190
	v_med3_f32 v7, v10, s40, v190
	v_mov_b32_e32 v9, v163
	v_cvt_pk_fp8_f32 v8, v5, v7 op_sel:[0,0,1]
	v_med3_f32 v5, v11, s40, v190
	v_med3_f32 v7, v12, s40, v190
	v_cvt_pk_fp8_f32 v9, v5, v7
	v_mul_f32_e32 v14, v6, v117
	v_add_u32_e32 v6, 32, v4
	v_med3_f32 v5, v13, s40, v190
	v_med3_f32 v7, v14, s40, v190
	v_cvt_pk_fp8_f32 v9, v5, v7 op_sel:[0,0,1]
	v_ashrrev_i32_e32 v7, 31, v6
	v_lshlrev_b64 v[6:7], 7, v[6:7]
	v_lshl_add_u64 v[6:7], s[10:11], 0, v[6:7]
	v_lshl_add_u64 v[6:7], v[6:7], 0, v[2:3]
	v_mul_f32_e32 v5, 0x3b000000, v110
	global_store_dwordx2 v[6:7], v[8:9], off
	v_mul_f32_e32 v6, 0xbcb8aa3b, v110
	v_exp_f32_e32 v6, v6
	s_nop 0
	v_add_f32_e32 v6, 1.0, v6
	v_rcp_f32_e32 v6, v6
	s_nop 0
	v_mul_f32_e32 v5, v5, v6
	v_mul_f32_e32 v6, 0x3b000000, v111
	v_mul_f32_e32 v7, 0xbcb8aa3b, v111
	v_exp_f32_e32 v7, v7
	v_mul_f32_e32 v5, v5, v106
	v_med3_f32 v5, v5, s40, v190
	v_add_f32_e32 v7, 1.0, v7
	v_rcp_f32_e32 v7, v7
	s_nop 0
	v_mul_f32_e32 v6, v6, v7
	v_mul_f32_e32 v7, v6, v107
	v_mul_f32_e32 v6, 0x3b000000, v112
	v_mul_f32_e32 v8, 0xbcb8aa3b, v112
	v_exp_f32_e32 v8, v8
	v_med3_f32 v7, v7, s40, v190
	v_add_f32_e32 v8, 1.0, v8
	v_rcp_f32_e32 v8, v8
	s_nop 0
	v_mul_f32_e32 v6, v6, v8
	v_mul_f32_e32 v9, v6, v108
	v_mul_f32_e32 v6, 0x3b000000, v113
	v_mul_f32_e32 v8, 0xbcb8aa3b, v113
	v_exp_f32_e32 v8, v8
	s_nop 0
	v_add_f32_e32 v8, 1.0, v8
	v_rcp_f32_e32 v8, v8
	s_nop 0
	v_mul_f32_e32 v6, v6, v8
	v_mul_f32_e32 v10, v6, v109
	v_mul_f32_e32 v6, 0x3b000000, v102
	v_mul_f32_e32 v8, 0xbcb8aa3b, v102
	v_exp_f32_e32 v8, v8
	s_nop 0
	v_add_f32_e32 v8, 1.0, v8
	v_rcp_f32_e32 v8, v8
	s_nop 0
	v_mul_f32_e32 v6, v6, v8
	v_mul_f32_e32 v11, v6, v98
	v_mul_f32_e32 v6, 0x3b000000, v103
	v_mul_f32_e32 v8, 0xbcb8aa3b, v103
	v_exp_f32_e32 v8, v8
	s_nop 0
	v_add_f32_e32 v8, 1.0, v8
	v_rcp_f32_e32 v8, v8
	s_nop 0
	v_mul_f32_e32 v6, v6, v8
	v_mul_f32_e32 v12, v6, v99
	v_mul_f32_e32 v6, 0x3b000000, v104
	v_mul_f32_e32 v8, 0xbcb8aa3b, v104
	v_exp_f32_e32 v8, v8
	s_nop 0
	v_add_f32_e32 v8, 1.0, v8
	v_rcp_f32_e32 v8, v8
	s_nop 0
	v_mul_f32_e32 v6, v6, v8
	v_mul_f32_e32 v13, v6, v100
	v_mul_f32_e32 v6, 0x3b000000, v105
	v_mul_f32_e32 v8, 0xbcb8aa3b, v105
	v_exp_f32_e32 v8, v8
	s_nop 0
	v_add_f32_e32 v8, 1.0, v8
	v_rcp_f32_e32 v8, v8
	s_nop 0
	v_mul_f32_e32 v6, v6, v8
	v_mov_b32_e32 v8, v163
	v_cvt_pk_fp8_f32 v8, v5, v7
	v_med3_f32 v5, v9, s40, v190
	v_med3_f32 v7, v10, s40, v190
	v_mov_b32_e32 v9, v163
	v_cvt_pk_fp8_f32 v8, v5, v7 op_sel:[0,0,1]
	v_med3_f32 v5, v11, s40, v190
	v_med3_f32 v7, v12, s40, v190
	v_cvt_pk_fp8_f32 v9, v5, v7
	v_mul_f32_e32 v14, v6, v101
	v_add_u32_e32 v6, 48, v4
	v_med3_f32 v5, v13, s40, v190
	v_med3_f32 v7, v14, s40, v190
	v_cvt_pk_fp8_f32 v9, v5, v7 op_sel:[0,0,1]
	v_ashrrev_i32_e32 v7, 31, v6
	v_lshlrev_b64 v[6:7], 7, v[6:7]
	v_lshl_add_u64 v[6:7], s[10:11], 0, v[6:7]
	v_lshl_add_u64 v[6:7], v[6:7], 0, v[2:3]
	v_mul_f32_e32 v5, 0x3b000000, v94
	global_store_dwordx2 v[6:7], v[8:9], off
	v_mul_f32_e32 v7, 0xbcb8aa3b, v94
	v_exp_f32_e32 v7, v7
	v_add_u32_e32 v6, 0x80, v4
	v_add_f32_e32 v7, 1.0, v7
	v_rcp_f32_e32 v7, v7
	s_nop 0
	v_mul_f32_e32 v5, v5, v7
	v_mul_f32_e32 v7, 0x3b000000, v95
	v_mul_f32_e32 v8, 0xbcb8aa3b, v95
	v_exp_f32_e32 v8, v8
	v_mul_f32_e32 v5, v5, v90
	v_med3_f32 v5, v5, s40, v190
	v_add_f32_e32 v8, 1.0, v8
	v_rcp_f32_e32 v8, v8
	s_nop 0
	v_mul_f32_e32 v7, v7, v8
	v_mul_f32_e32 v8, 0x3b000000, v96
	v_mul_f32_e32 v9, 0xbcb8aa3b, v96
	v_exp_f32_e32 v9, v9
	v_mul_f32_e32 v7, v7, v91
	v_med3_f32 v7, v7, s40, v190
	v_add_f32_e32 v9, 1.0, v9
	v_rcp_f32_e32 v9, v9
	s_nop 0
	v_mul_f32_e32 v8, v8, v9
	v_mul_f32_e32 v9, v8, v92
	v_mul_f32_e32 v8, 0x3b000000, v97
	v_mul_f32_e32 v10, 0xbcb8aa3b, v97
	v_exp_f32_e32 v10, v10
	s_nop 0
	v_add_f32_e32 v10, 1.0, v10
	v_rcp_f32_e32 v10, v10
	s_nop 0
	v_mul_f32_e32 v8, v8, v10
	v_mul_f32_e32 v10, v8, v93
	v_mul_f32_e32 v8, 0x3b000000, v86
	v_mul_f32_e32 v11, 0xbcb8aa3b, v86
	v_exp_f32_e32 v11, v11
	s_nop 0
	v_add_f32_e32 v11, 1.0, v11
	v_rcp_f32_e32 v11, v11
	s_nop 0
	v_mul_f32_e32 v8, v8, v11
	v_mul_f32_e32 v11, v8, v82
	v_mul_f32_e32 v8, 0x3b000000, v87
	v_mul_f32_e32 v12, 0xbcb8aa3b, v87
	v_exp_f32_e32 v12, v12
	s_nop 0
	v_add_f32_e32 v12, 1.0, v12
	v_rcp_f32_e32 v12, v12
	s_nop 0
	v_mul_f32_e32 v8, v8, v12
	v_mul_f32_e32 v12, v8, v83
	v_mul_f32_e32 v8, 0x3b000000, v88
	v_mul_f32_e32 v13, 0xbcb8aa3b, v88
	v_exp_f32_e32 v13, v13
	s_nop 0
	v_add_f32_e32 v13, 1.0, v13
	v_rcp_f32_e32 v13, v13
	s_nop 0
	v_mul_f32_e32 v8, v8, v13
	v_mul_f32_e32 v13, v8, v84
	v_mul_f32_e32 v8, 0x3b000000, v89
	v_mul_f32_e32 v14, 0xbcb8aa3b, v89
	v_exp_f32_e32 v14, v14
	s_nop 0
	v_add_f32_e32 v14, 1.0, v14
	v_rcp_f32_e32 v14, v14
	s_nop 0
	v_mul_f32_e32 v8, v8, v14
	v_mul_f32_e32 v14, v8, v85
	v_mov_b32_e32 v8, v163
	v_cvt_pk_fp8_f32 v8, v5, v7
	v_med3_f32 v5, v9, s40, v190
	v_med3_f32 v7, v10, s40, v190
	v_mov_b32_e32 v9, v163
	v_cvt_pk_fp8_f32 v8, v5, v7 op_sel:[0,0,1]
	v_med3_f32 v5, v11, s40, v190
	v_med3_f32 v7, v12, s40, v190
	v_cvt_pk_fp8_f32 v9, v5, v7
	v_med3_f32 v5, v13, s40, v190
	v_med3_f32 v7, v14, s40, v190
	v_cvt_pk_fp8_f32 v9, v5, v7 op_sel:[0,0,1]
	v_ashrrev_i32_e32 v7, 31, v6
	v_lshlrev_b64 v[6:7], 7, v[6:7]
	v_lshl_add_u64 v[6:7], s[10:11], 0, v[6:7]
	v_lshl_add_u64 v[6:7], v[6:7], 0, v[2:3]
	v_mul_f32_e32 v5, 0x3b000000, v78
	global_store_dwordx2 v[6:7], v[8:9], off
	v_mul_f32_e32 v6, 0xbcb8aa3b, v78
	v_exp_f32_e32 v6, v6
	s_nop 0
	v_add_f32_e32 v6, 1.0, v6
	v_rcp_f32_e32 v6, v6
	s_nop 0
	v_mul_f32_e32 v5, v5, v6
	v_mul_f32_e32 v6, 0x3b000000, v79
	v_mul_f32_e32 v7, 0xbcb8aa3b, v79
	v_exp_f32_e32 v7, v7
	v_mul_f32_e32 v5, v5, v74
	v_med3_f32 v5, v5, s40, v190
	v_add_f32_e32 v7, 1.0, v7
	v_rcp_f32_e32 v7, v7
	s_nop 0
	v_mul_f32_e32 v6, v6, v7
	v_mul_f32_e32 v7, v6, v75
	v_mul_f32_e32 v6, 0x3b000000, v80
	v_mul_f32_e32 v8, 0xbcb8aa3b, v80
	v_exp_f32_e32 v8, v8
	v_med3_f32 v7, v7, s40, v190
	v_add_f32_e32 v8, 1.0, v8
	v_rcp_f32_e32 v8, v8
	s_nop 0
	v_mul_f32_e32 v6, v6, v8
	v_mul_f32_e32 v9, v6, v76
	v_mul_f32_e32 v6, 0x3b000000, v81
	v_mul_f32_e32 v8, 0xbcb8aa3b, v81
	v_exp_f32_e32 v8, v8
	s_nop 0
	v_add_f32_e32 v8, 1.0, v8
	v_rcp_f32_e32 v8, v8
	s_nop 0
	v_mul_f32_e32 v6, v6, v8
	v_mul_f32_e32 v10, v6, v77
	v_mul_f32_e32 v6, 0x3b000000, v70
	v_mul_f32_e32 v8, 0xbcb8aa3b, v70
	v_exp_f32_e32 v8, v8
	s_nop 0
	v_add_f32_e32 v8, 1.0, v8
	v_rcp_f32_e32 v8, v8
	s_nop 0
	v_mul_f32_e32 v6, v6, v8
	v_mul_f32_e32 v11, v6, v66
	v_mul_f32_e32 v6, 0x3b000000, v71
	v_mul_f32_e32 v8, 0xbcb8aa3b, v71
	v_exp_f32_e32 v8, v8
	s_nop 0
	v_add_f32_e32 v8, 1.0, v8
	v_rcp_f32_e32 v8, v8
	s_nop 0
	v_mul_f32_e32 v6, v6, v8
	v_mul_f32_e32 v12, v6, v67
	v_mul_f32_e32 v6, 0x3b000000, v72
	v_mul_f32_e32 v8, 0xbcb8aa3b, v72
	v_exp_f32_e32 v8, v8
	s_nop 0
	v_add_f32_e32 v8, 1.0, v8
	v_rcp_f32_e32 v8, v8
	s_nop 0
	v_mul_f32_e32 v6, v6, v8
	v_mul_f32_e32 v13, v6, v68
	v_mul_f32_e32 v6, 0x3b000000, v73
	v_mul_f32_e32 v8, 0xbcb8aa3b, v73
	v_exp_f32_e32 v8, v8
	s_nop 0
	v_add_f32_e32 v8, 1.0, v8
	v_rcp_f32_e32 v8, v8
	s_nop 0
	v_mul_f32_e32 v6, v6, v8
	v_mov_b32_e32 v8, v163
	v_cvt_pk_fp8_f32 v8, v5, v7
	v_med3_f32 v5, v9, s40, v190
	v_med3_f32 v7, v10, s40, v190
	v_mov_b32_e32 v9, v163
	v_cvt_pk_fp8_f32 v8, v5, v7 op_sel:[0,0,1]
	v_med3_f32 v5, v11, s40, v190
	v_med3_f32 v7, v12, s40, v190
	v_cvt_pk_fp8_f32 v9, v5, v7
	v_mul_f32_e32 v14, v6, v69
	v_add_u32_e32 v6, 0x90, v4
	v_med3_f32 v5, v13, s40, v190
	v_med3_f32 v7, v14, s40, v190
	v_cvt_pk_fp8_f32 v9, v5, v7 op_sel:[0,0,1]
	v_ashrrev_i32_e32 v7, 31, v6
	v_lshlrev_b64 v[6:7], 7, v[6:7]
	v_lshl_add_u64 v[6:7], s[10:11], 0, v[6:7]
	v_lshl_add_u64 v[6:7], v[6:7], 0, v[2:3]
	v_mul_f32_e32 v5, 0x3b000000, v62
	global_store_dwordx2 v[6:7], v[8:9], off
	v_mul_f32_e32 v6, 0xbcb8aa3b, v62
	v_exp_f32_e32 v6, v6
	s_nop 0
	v_add_f32_e32 v6, 1.0, v6
	v_rcp_f32_e32 v6, v6
	s_nop 0
	v_mul_f32_e32 v5, v5, v6
	v_mul_f32_e32 v6, 0x3b000000, v63
	v_mul_f32_e32 v7, 0xbcb8aa3b, v63
	v_exp_f32_e32 v7, v7
	v_mul_f32_e32 v5, v5, v58
	v_med3_f32 v5, v5, s40, v190
	v_add_f32_e32 v7, 1.0, v7
	v_rcp_f32_e32 v7, v7
	s_nop 0
	v_mul_f32_e32 v6, v6, v7
	v_mul_f32_e32 v7, v6, v59
	v_mul_f32_e32 v6, 0x3b000000, v64
	v_mul_f32_e32 v8, 0xbcb8aa3b, v64
	v_exp_f32_e32 v8, v8
	v_med3_f32 v7, v7, s40, v190
	v_add_f32_e32 v8, 1.0, v8
	v_rcp_f32_e32 v8, v8
	s_nop 0
	v_mul_f32_e32 v6, v6, v8
	v_mul_f32_e32 v9, v6, v60
	v_mul_f32_e32 v6, 0x3b000000, v65
	v_mul_f32_e32 v8, 0xbcb8aa3b, v65
	v_exp_f32_e32 v8, v8
	s_nop 0
	v_add_f32_e32 v8, 1.0, v8
	v_rcp_f32_e32 v8, v8
	s_nop 0
	v_mul_f32_e32 v6, v6, v8
	v_mul_f32_e32 v10, v6, v61
	v_mul_f32_e32 v6, 0x3b000000, v54
	v_mul_f32_e32 v8, 0xbcb8aa3b, v54
	v_exp_f32_e32 v8, v8
	s_nop 0
	v_add_f32_e32 v8, 1.0, v8
	v_rcp_f32_e32 v8, v8
	s_nop 0
	v_mul_f32_e32 v6, v6, v8
	v_mul_f32_e32 v11, v6, v50
	v_mul_f32_e32 v6, 0x3b000000, v55
	v_mul_f32_e32 v8, 0xbcb8aa3b, v55
	v_exp_f32_e32 v8, v8
	s_nop 0
	v_add_f32_e32 v8, 1.0, v8
	v_rcp_f32_e32 v8, v8
	s_nop 0
	v_mul_f32_e32 v6, v6, v8
	v_mul_f32_e32 v12, v6, v51
	v_mul_f32_e32 v6, 0x3b000000, v56
	v_mul_f32_e32 v8, 0xbcb8aa3b, v56
	v_exp_f32_e32 v8, v8
	s_nop 0
	v_add_f32_e32 v8, 1.0, v8
	v_rcp_f32_e32 v8, v8
	s_nop 0
	v_mul_f32_e32 v6, v6, v8
	v_mul_f32_e32 v13, v6, v52
	v_mul_f32_e32 v6, 0x3b000000, v57
	v_mul_f32_e32 v8, 0xbcb8aa3b, v57
	v_exp_f32_e32 v8, v8
	s_nop 0
	v_add_f32_e32 v8, 1.0, v8
	v_rcp_f32_e32 v8, v8
	s_nop 0
	v_mul_f32_e32 v6, v6, v8
	v_mov_b32_e32 v8, v163
	v_cvt_pk_fp8_f32 v8, v5, v7
	v_med3_f32 v5, v9, s40, v190
	v_med3_f32 v7, v10, s40, v190
	v_mov_b32_e32 v9, v163
	v_cvt_pk_fp8_f32 v8, v5, v7 op_sel:[0,0,1]
	v_med3_f32 v5, v11, s40, v190
	v_med3_f32 v7, v12, s40, v190
	v_cvt_pk_fp8_f32 v9, v5, v7
	v_mul_f32_e32 v14, v6, v53
	v_add_u32_e32 v6, 0xa0, v4
	v_med3_f32 v5, v13, s40, v190
	v_med3_f32 v7, v14, s40, v190
	v_cvt_pk_fp8_f32 v9, v5, v7 op_sel:[0,0,1]
	v_ashrrev_i32_e32 v7, 31, v6
	v_lshlrev_b64 v[6:7], 7, v[6:7]
	v_lshl_add_u64 v[6:7], s[10:11], 0, v[6:7]
	v_lshl_add_u64 v[6:7], v[6:7], 0, v[2:3]
	v_mul_f32_e32 v5, 0x3b000000, v46
	global_store_dwordx2 v[6:7], v[8:9], off
	v_mul_f32_e32 v6, 0xbcb8aa3b, v46
	v_exp_f32_e32 v6, v6
	v_add_u32_e32 v4, 0xb0, v4
	v_add_f32_e32 v6, 1.0, v6
	v_rcp_f32_e32 v6, v6
	s_nop 0
	v_mul_f32_e32 v5, v5, v6
	v_mul_f32_e32 v6, 0x3b000000, v47
	v_mul_f32_e32 v7, 0xbcb8aa3b, v47
	v_exp_f32_e32 v7, v7
	v_mul_f32_e32 v5, v5, v42
	v_med3_f32 v5, v5, s40, v190
	v_add_f32_e32 v7, 1.0, v7
	v_rcp_f32_e32 v7, v7
	s_nop 0
	v_mul_f32_e32 v6, v6, v7
	v_mul_f32_e32 v7, 0x3b000000, v48
	v_mul_f32_e32 v8, 0xbcb8aa3b, v48
	v_exp_f32_e32 v8, v8
	v_mul_f32_e32 v6, v6, v43
	v_add_f32_e32 v8, 1.0, v8
	v_rcp_f32_e32 v8, v8
	s_nop 0
	v_mul_f32_e32 v7, v7, v8
	v_mul_f32_e32 v8, 0x3b000000, v49
	v_mul_f32_e32 v9, 0xbcb8aa3b, v49
	v_exp_f32_e32 v9, v9
	v_mul_f32_e32 v7, v7, v44
	v_add_f32_e32 v9, 1.0, v9
	v_rcp_f32_e32 v9, v9
	s_nop 0
	v_mul_f32_e32 v8, v8, v9
	v_mul_f32_e32 v9, 0x3b000000, v38
	v_mul_f32_e32 v10, 0xbcb8aa3b, v38
	v_exp_f32_e32 v10, v10
	v_mul_f32_e32 v8, v8, v45
	v_add_f32_e32 v10, 1.0, v10
	v_rcp_f32_e32 v10, v10
	s_nop 0
	v_mul_f32_e32 v9, v9, v10
	v_mul_f32_e32 v10, 0x3b000000, v39
	v_mul_f32_e32 v11, 0xbcb8aa3b, v39
	v_exp_f32_e32 v11, v11
	v_mul_f32_e32 v9, v9, v34
	v_add_f32_e32 v11, 1.0, v11
	v_rcp_f32_e32 v11, v11
	s_nop 0
	v_mul_f32_e32 v10, v10, v11
	v_mul_f32_e32 v11, 0x3b000000, v40
	v_mul_f32_e32 v12, 0xbcb8aa3b, v40
	v_exp_f32_e32 v12, v12
	v_mul_f32_e32 v10, v10, v35
	v_add_f32_e32 v12, 1.0, v12
	v_rcp_f32_e32 v12, v12
	s_nop 0
	v_mul_f32_e32 v11, v11, v12
	v_mul_f32_e32 v12, 0x3b000000, v41
	v_mul_f32_e32 v13, 0xbcb8aa3b, v41
	v_exp_f32_e32 v13, v13
	v_mul_f32_e32 v11, v11, v36
	v_add_f32_e32 v13, 1.0, v13
	v_rcp_f32_e32 v13, v13
	s_nop 0
	v_mul_f32_e32 v12, v12, v13
	v_med3_f32 v13, v6, s40, v190
	v_mov_b32_e32 v6, v163
	v_cvt_pk_fp8_f32 v6, v5, v13
	v_med3_f32 v5, v7, s40, v190
	v_med3_f32 v7, v8, s40, v190
	v_med3_f32 v8, v10, s40, v190
	v_cvt_pk_fp8_f32 v6, v5, v7 op_sel:[0,0,1]
	v_med3_f32 v5, v9, s40, v190
	v_mov_b32_e32 v7, v163
	v_cvt_pk_fp8_f32 v7, v5, v8
	v_mul_f32_e32 v12, v12, v37
	v_med3_f32 v5, v11, s40, v190
	v_med3_f32 v8, v12, s40, v190
	v_cvt_pk_fp8_f32 v7, v5, v8 op_sel:[0,0,1]
	v_ashrrev_i32_e32 v5, 31, v4
	v_lshlrev_b64 v[4:5], 7, v[4:5]
	v_lshl_add_u64 v[4:5], s[10:11], 0, v[4:5]
	v_lshl_add_u64 v[2:3], v[4:5], 0, v[2:3]
	global_store_dwordx2 v[2:3], v[6:7], off
	s_cbranch_vccz .LBB0_677
	s_waitcnt vmcnt(0)
	s_cmpk_gt_u32 s42, 0xff
	s_cbranch_scc1 .LBB0_623
	s_barrier
	s_branch .LBB0_623

.LBB0_754:
	s_ashr_i32 s19, s18, 31
	s_lshl_b64 s[0:1], s[18:19], 18
	v_cmp_lt_i64_e32 vcc, s[20:21], v[158:159]
	s_add_u32 s20, s5, s0
	s_addc_u32 s21, s6, s1
	s_and_b64 s[0:1], vcc, exec
	s_cselect_b32 s19, s21, s29
	s_cselect_b32 s49, s20, s28
	s_ashr_i32 s0, s18, 5
	s_ashr_i32 s1, s0, 31
	s_lshl_b64 s[0:1], s[0:1], 20
	s_add_u32 s22, s7, s0
	s_addc_u32 s23, s15, s1
	s_ashr_i32 s17, s16, 31
	s_lshl_b64 s[0:1], s[16:17], 18
	s_add_u32 s22, s22, s0
	s_addc_u32 s23, s23, s1
	s_and_b64 s[0:1], vcc, exec
	s_cselect_b32 s17, s23, s27
	s_cselect_b32 s50, s22, s26
	s_add_u32 s51, s26, 0x100
	s_addc_u32 s52, s27, 0
	s_add_u32 s26, s28, 0xc000
	s_addc_u32 s27, s29, 0
	s_mov_b32 s53, -2
	ds_read_b128 v[2:5], v169
	ds_read_b128 v[6:9], v169 offset:1024
	ds_read_b128 v[10:13], v169 offset:2048
	ds_read_b128 v[14:17], v169 offset:3072
	s_add_u32 s0, s26, 0x4000
	s_addc_u32 s1, s27, 0
	s_cmp_eq_u32 s53, 4
	s_cselect_b32 s34, s49, s0
	s_cselect_b32 s35, s19, s1
	s_cselect_b32 s28, s50, s51
	s_cselect_b32 s29, s17, s52
	s_add_u32 s30, s34, 0x8000
	s_addc_u32 s31, s35, 0
	v_lshl_add_u64 v[162:163], s[26:27], 0, v[156:157]
	s_add_i32 m0, s25, 0xc000
	ds_read_b128 v[174:177], v170
	ds_read_b128 v[178:181], v170 offset:1024
	ds_read_b128 v[182:185], v170 offset:2048
	ds_read_b128 v[186:189], v170 offset:3072
	ds_read_b128 v[190:193], v170 offset:4096
	ds_read_b128 v[194:197], v170 offset:5120
	ds_read_b128 v[198:201], v170 offset:6144
	ds_read_b128 v[202:205], v170 offset:7168
	global_load_lds_dwordx4 v[162:163], off
	v_lshl_add_u64 v[162:163], s[26:27], 0, v[154:155]
	s_add_i32 m0, s25, 0xe000
	s_nop 0
	global_load_lds_dwordx4 v[162:163], off
	s_waitcnt lgkmcnt(8)
	s_waitcnt vmcnt(10)
	s_barrier
	s_waitcnt lgkmcnt(0)
	s_waitcnt lgkmcnt(0)
	v_mfma_scale_f32_16x16x128_f8f6f4 v[142:145], v[2:9], v[174:181], 0, v171, v171 op_sel_hi:[0,0,0]
	v_mfma_scale_f32_16x16x128_f8f6f4 v[138:141], v[10:17], v[174:181], 0, v171, v171 op_sel_hi:[0,0,0]
	v_mfma_scale_f32_16x16x128_f8f6f4 v[126:129], v[2:9], v[182:189], 0, v171, v171 op_sel_hi:[0,0,0]
	v_mfma_scale_f32_16x16x128_f8f6f4 v[122:125], v[10:17], v[182:189], 0, v171, v171 op_sel_hi:[0,0,0]
	v_mfma_scale_f32_16x16x128_f8f6f4 v[110:113], v[2:9], v[190:197], 0, v171, v171 op_sel_hi:[0,0,0]
	v_mfma_scale_f32_16x16x128_f8f6f4 v[106:109], v[10:17], v[190:197], 0, v171, v171 op_sel_hi:[0,0,0]
	v_mfma_scale_f32_16x16x128_f8f6f4 v[94:97], v[2:9], v[198:205], 0, v171, v171 op_sel_hi:[0,0,0]
	v_mfma_scale_f32_16x16x128_f8f6f4 v[90:93], v[10:17], v[198:205], 0, v171, v171 op_sel_hi:[0,0,0]
	s_barrier
	s_add_i32 s0, s45, s36
	v_lshl_add_u64 v[162:163], s[28:29], 0, v[150:151]
	s_mov_b32 m0, s0
	ds_read_b128 v[206:209], v172
	ds_read_b128 v[210:213], v172 offset:1024
	ds_read_b128 v[214:217], v172 offset:2048
	ds_read_b128 v[218:221], v172 offset:3072
	global_load_lds_dwordx4 v[162:163], off
	v_lshl_add_u64 v[164:165], s[28:29], 0, v[146:147]
	s_add_i32 m0, s0, 0x2000
	s_nop 0
	global_load_lds_dwordx4 v[164:165], off
	s_waitcnt vmcnt(10)
	s_barrier
	s_waitcnt lgkmcnt(0)
	s_waitcnt lgkmcnt(0)
	v_mfma_scale_f32_16x16x128_f8f6f4 v[134:137], v[206:213], v[174:181], 0, v171, v171 op_sel_hi:[0,0,0]
	v_mfma_scale_f32_16x16x128_f8f6f4 v[130:133], v[214:221], v[174:181], 0, v171, v171 op_sel_hi:[0,0,0]
	v_mfma_scale_f32_16x16x128_f8f6f4 v[118:121], v[206:213], v[182:189], 0, v171, v171 op_sel_hi:[0,0,0]
	v_mfma_scale_f32_16x16x128_f8f6f4 v[114:117], v[214:221], v[182:189], 0, v171, v171 op_sel_hi:[0,0,0]
	v_mfma_scale_f32_16x16x128_f8f6f4 v[102:105], v[206:213], v[190:197], 0, v171, v171 op_sel_hi:[0,0,0]
	v_mfma_scale_f32_16x16x128_f8f6f4 v[98:101], v[214:221], v[190:197], 0, v171, v171 op_sel_hi:[0,0,0]
	v_mfma_scale_f32_16x16x128_f8f6f4 v[86:89], v[206:213], v[198:205], 0, v171, v171 op_sel_hi:[0,0,0]
	v_mfma_scale_f32_16x16x128_f8f6f4 v[82:85], v[214:221], v[198:205], 0, v171, v171 op_sel_hi:[0,0,0]
	s_mov_b32 m0, s25
	v_lshl_add_u64 v[222:223], s[34:35], 0, v[152:153]
	s_barrier
	ds_read_b128 v[174:177], v170 offset:16384
	ds_read_b128 v[178:181], v170 offset:17408
	ds_read_b128 v[182:185], v170 offset:18432
	ds_read_b128 v[186:189], v170 offset:19456
	ds_read_b128 v[190:193], v170 offset:20480
	ds_read_b128 v[194:197], v170 offset:21504
	ds_read_b128 v[198:201], v170 offset:22528
	ds_read_b128 v[202:205], v170 offset:23552
	global_load_lds_dwordx4 v[222:223], off
	v_lshl_add_u64 v[222:223], s[34:35], 0, v[148:149]
	s_mov_b32 m0, s37
	s_nop 0
	global_load_lds_dwordx4 v[222:223], off
	s_waitcnt vmcnt(10)
	s_barrier
	s_waitcnt lgkmcnt(0)
	s_waitcnt lgkmcnt(0)
	v_mfma_scale_f32_16x16x128_f8f6f4 v[78:81], v[2:9], v[174:181], 0, v171, v171 op_sel_hi:[0,0,0]
	v_mfma_scale_f32_16x16x128_f8f6f4 v[74:77], v[10:17], v[174:181], 0, v171, v171 op_sel_hi:[0,0,0]
	v_mfma_scale_f32_16x16x128_f8f6f4 v[62:65], v[2:9], v[182:189], 0, v171, v171 op_sel_hi:[0,0,0]
	v_mfma_scale_f32_16x16x128_f8f6f4 v[58:61], v[10:17], v[182:189], 0, v171, v171 op_sel_hi:[0,0,0]
	v_mfma_scale_f32_16x16x128_f8f6f4 v[46:49], v[2:9], v[190:197], 0, v171, v171 op_sel_hi:[0,0,0]
	v_mfma_scale_f32_16x16x128_f8f6f4 v[42:45], v[10:17], v[190:197], 0, v171, v171 op_sel_hi:[0,0,0]
	v_mfma_scale_f32_16x16x128_f8f6f4 v[30:33], v[2:9], v[198:205], 0, v171, v171 op_sel_hi:[0,0,0]
	v_mfma_scale_f32_16x16x128_f8f6f4 v[26:29], v[10:17], v[198:205], 0, v171, v171 op_sel_hi:[0,0,0]
	s_barrier
	s_add_u32 s0, s28, 0x20000
	s_addc_u32 s1, s29, 0
	s_add_i32 s54, s46, s36
	v_lshl_add_u64 v[2:3], s[0:1], 0, v[150:151]
	s_mov_b32 m0, s54
	s_nop 0
	global_load_lds_dwordx4 v[2:3], off
	v_lshl_add_u64 v[2:3], s[0:1], 0, v[146:147]
	s_add_i32 m0, s54, 0x2000
	s_nop 0
	global_load_lds_dwordx4 v[2:3], off
	s_waitcnt vmcnt(10)
	s_barrier
	v_mfma_scale_f32_16x16x128_f8f6f4 v[70:73], v[206:213], v[174:181], 0, v171, v171 op_sel_hi:[0,0,0]
	v_mfma_scale_f32_16x16x128_f8f6f4 v[66:69], v[214:221], v[174:181], 0, v171, v171 op_sel_hi:[0,0,0]
	v_mfma_scale_f32_16x16x128_f8f6f4 v[54:57], v[206:213], v[182:189], 0, v171, v171 op_sel_hi:[0,0,0]
	v_mfma_scale_f32_16x16x128_f8f6f4 v[50:53], v[214:221], v[182:189], 0, v171, v171 op_sel_hi:[0,0,0]
	v_mfma_scale_f32_16x16x128_f8f6f4 v[38:41], v[206:213], v[190:197], 0, v171, v171 op_sel_hi:[0,0,0]
	v_mfma_scale_f32_16x16x128_f8f6f4 v[34:37], v[214:221], v[190:197], 0, v171, v171 op_sel_hi:[0,0,0]
	v_mfma_scale_f32_16x16x128_f8f6f4 v[22:25], v[206:213], v[198:205], 0, v171, v171 op_sel_hi:[0,0,0]
	v_mfma_scale_f32_16x16x128_f8f6f4 v[18:21], v[214:221], v[198:205], 0, v171, v171 op_sel_hi:[0,0,0]
	s_add_i32 s54, 0, 0x18000
	v_add_u32_e32 v14, s54, v168
	s_barrier
	ds_read_b128 v[2:5], v14
	ds_read_b128 v[6:9], v14 offset:1024
	ds_read_b128 v[10:13], v14 offset:2048
	ds_read_b128 v[14:17], v14 offset:3072
	s_add_u32 s0, s34, 0x4000
	s_addc_u32 s1, s35, 0
	s_mov_b32 m0, s38
	v_lshl_add_u64 v[206:207], s[0:1], 0, v[152:153]
	ds_read_b128 v[174:177], v170 offset:32768
	ds_read_b128 v[178:181], v170 offset:33792
	ds_read_b128 v[182:185], v170 offset:34816
	ds_read_b128 v[186:189], v170 offset:35840
	ds_read_b128 v[190:193], v170 offset:36864
	ds_read_b128 v[194:197], v170 offset:37888
	ds_read_b128 v[198:201], v170 offset:38912
	ds_read_b128 v[202:205], v170 offset:39936
	global_load_lds_dwordx4 v[206:207], off
	v_lshl_add_u64 v[206:207], s[0:1], 0, v[148:149]
	s_mov_b32 m0, s39
	s_nop 0
	global_load_lds_dwordx4 v[206:207], off
	s_waitcnt lgkmcnt(8)
	s_waitcnt vmcnt(10)
	s_barrier
	s_waitcnt lgkmcnt(0)
	s_waitcnt lgkmcnt(0)
	v_mfma_scale_f32_16x16x128_f8f6f4 v[142:145], v[2:9], v[174:181], v[142:145], v171, v171 op_sel_hi:[0,0,0]
	v_mfma_scale_f32_16x16x128_f8f6f4 v[138:141], v[10:17], v[174:181], v[138:141], v171, v171 op_sel_hi:[0,0,0]
	v_mfma_scale_f32_16x16x128_f8f6f4 v[126:129], v[2:9], v[182:189], v[126:129], v171, v171 op_sel_hi:[0,0,0]
	v_mfma_scale_f32_16x16x128_f8f6f4 v[122:125], v[10:17], v[182:189], v[122:125], v171, v171 op_sel_hi:[0,0,0]
	v_mfma_scale_f32_16x16x128_f8f6f4 v[110:113], v[2:9], v[190:197], v[110:113], v171, v171 op_sel_hi:[0,0,0]
	v_mfma_scale_f32_16x16x128_f8f6f4 v[106:109], v[10:17], v[190:197], v[106:109], v171, v171 op_sel_hi:[0,0,0]
	v_mfma_scale_f32_16x16x128_f8f6f4 v[94:97], v[2:9], v[198:205], v[94:97], v171, v171 op_sel_hi:[0,0,0]
	v_mfma_scale_f32_16x16x128_f8f6f4 v[90:93], v[10:17], v[198:205], v[90:93], v171, v171 op_sel_hi:[0,0,0]
	s_barrier
	s_add_i32 s34, 0, 0x1c000
	s_add_i32 s0, s54, s36
	v_add_u32_e32 v218, s34, v168
	v_lshl_add_u64 v[162:163], v[162:163], 0, s[12:13]
	s_mov_b32 m0, s0
	ds_read_b128 v[206:209], v218
	ds_read_b128 v[210:213], v218 offset:1024
	ds_read_b128 v[214:217], v218 offset:2048
	ds_read_b128 v[218:221], v218 offset:3072
	global_load_lds_dwordx4 v[162:163], off
	v_lshl_add_u64 v[162:163], v[164:165], 0, s[12:13]
	s_add_i32 m0, s0, 0x2000
	s_nop 0
	global_load_lds_dwordx4 v[162:163], off
	s_waitcnt vmcnt(10)
	s_barrier
	s_waitcnt lgkmcnt(0)
	s_waitcnt lgkmcnt(0)
	v_mfma_scale_f32_16x16x128_f8f6f4 v[134:137], v[206:213], v[174:181], v[134:137], v171, v171 op_sel_hi:[0,0,0]
	v_mfma_scale_f32_16x16x128_f8f6f4 v[130:133], v[214:221], v[174:181], v[130:133], v171, v171 op_sel_hi:[0,0,0]
	v_mfma_scale_f32_16x16x128_f8f6f4 v[118:121], v[206:213], v[182:189], v[118:121], v171, v171 op_sel_hi:[0,0,0]
	v_mfma_scale_f32_16x16x128_f8f6f4 v[114:117], v[214:221], v[182:189], v[114:117], v171, v171 op_sel_hi:[0,0,0]
	v_mfma_scale_f32_16x16x128_f8f6f4 v[102:105], v[206:213], v[190:197], v[102:105], v171, v171 op_sel_hi:[0,0,0]
	v_mfma_scale_f32_16x16x128_f8f6f4 v[98:101], v[214:221], v[190:197], v[98:101], v171, v171 op_sel_hi:[0,0,0]
	v_mfma_scale_f32_16x16x128_f8f6f4 v[86:89], v[206:213], v[198:205], v[86:89], v171, v171 op_sel_hi:[0,0,0]
	v_mfma_scale_f32_16x16x128_f8f6f4 v[82:85], v[214:221], v[198:205], v[82:85], v171, v171 op_sel_hi:[0,0,0]
	s_mov_b32 m0, s43
	v_lshl_add_u64 v[162:163], s[30:31], 0, v[152:153]
	s_barrier
	ds_read_b128 v[174:177], v170 offset:49152
	ds_read_b128 v[178:181], v170 offset:50176
	ds_read_b128 v[182:185], v170 offset:51200
	ds_read_b128 v[186:189], v170 offset:52224
	ds_read_b128 v[190:193], v170 offset:53248
	ds_read_b128 v[194:197], v170 offset:54272
	ds_read_b128 v[198:201], v170 offset:55296
	ds_read_b128 v[202:205], v170 offset:56320
	global_load_lds_dwordx4 v[162:163], off
	v_lshl_add_u64 v[162:163], s[30:31], 0, v[148:149]
	s_mov_b32 m0, s44
	s_nop 0
	global_load_lds_dwordx4 v[162:163], off
	s_waitcnt vmcnt(10)
	s_barrier
	s_waitcnt lgkmcnt(0)
	s_waitcnt lgkmcnt(0)
	v_mfma_scale_f32_16x16x128_f8f6f4 v[78:81], v[2:9], v[174:181], v[78:81], v171, v171 op_sel_hi:[0,0,0]
	v_mfma_scale_f32_16x16x128_f8f6f4 v[74:77], v[10:17], v[174:181], v[74:77], v171, v171 op_sel_hi:[0,0,0]
	v_mfma_scale_f32_16x16x128_f8f6f4 v[62:65], v[2:9], v[182:189], v[62:65], v171, v171 op_sel_hi:[0,0,0]
	v_mfma_scale_f32_16x16x128_f8f6f4 v[58:61], v[10:17], v[182:189], v[58:61], v171, v171 op_sel_hi:[0,0,0]
	v_mfma_scale_f32_16x16x128_f8f6f4 v[46:49], v[2:9], v[190:197], v[46:49], v171, v171 op_sel_hi:[0,0,0]
	v_mfma_scale_f32_16x16x128_f8f6f4 v[42:45], v[10:17], v[190:197], v[42:45], v171, v171 op_sel_hi:[0,0,0]
	v_mfma_scale_f32_16x16x128_f8f6f4 v[30:33], v[2:9], v[198:205], v[30:33], v171, v171 op_sel_hi:[0,0,0]
	v_mfma_scale_f32_16x16x128_f8f6f4 v[26:29], v[10:17], v[198:205], v[26:29], v171, v171 op_sel_hi:[0,0,0]
	s_barrier
	s_add_u32 s0, s28, 0x20080
	s_addc_u32 s1, s29, 0
	s_add_i32 s28, s34, s36
	v_lshl_add_u64 v[2:3], s[0:1], 0, v[150:151]
	s_mov_b32 m0, s28
	s_nop 0
	global_load_lds_dwordx4 v[2:3], off
	v_lshl_add_u64 v[2:3], s[0:1], 0, v[146:147]
	s_add_i32 m0, s28, 0x2000
	s_nop 0
	global_load_lds_dwordx4 v[2:3], off
	s_waitcnt vmcnt(10)
	s_barrier
	v_mfma_scale_f32_16x16x128_f8f6f4 v[70:73], v[206:213], v[174:181], v[70:73], v171, v171 op_sel_hi:[0,0,0]
	v_mfma_scale_f32_16x16x128_f8f6f4 v[66:69], v[214:221], v[174:181], v[66:69], v171, v171 op_sel_hi:[0,0,0]
	v_mfma_scale_f32_16x16x128_f8f6f4 v[54:57], v[206:213], v[182:189], v[54:57], v171, v171 op_sel_hi:[0,0,0]
	v_mfma_scale_f32_16x16x128_f8f6f4 v[50:53], v[214:221], v[182:189], v[50:53], v171, v171 op_sel_hi:[0,0,0]
	v_mfma_scale_f32_16x16x128_f8f6f4 v[38:41], v[206:213], v[190:197], v[38:41], v171, v171 op_sel_hi:[0,0,0]
	v_mfma_scale_f32_16x16x128_f8f6f4 v[34:37], v[214:221], v[190:197], v[34:37], v171, v171 op_sel_hi:[0,0,0]
	v_mfma_scale_f32_16x16x128_f8f6f4 v[22:25], v[206:213], v[198:205], v[22:25], v171, v171 op_sel_hi:[0,0,0]
	v_mfma_scale_f32_16x16x128_f8f6f4 v[18:21], v[214:221], v[198:205], v[18:21], v171, v171 op_sel_hi:[0,0,0]
	s_add_i32 s53, s53, 2
	s_add_u32 s51, s51, 0x100
	s_addc_u32 s52, s52, 0
	s_add_u32 s26, s26, 0x10000
	s_addc_u32 s27, s27, 0
	s_cmp_gt_u32 s53, 5
	s_barrier
	s_cbranch_scc1 .Lpeel_exit_3

.Lpeel_exit_3:
	v_pk_mul_f32 v[10:11], v[142:143], s[14:15] op_sel_hi:[1,0]
	v_pk_mul_f32 v[8:9], v[144:145], s[14:15] op_sel_hi:[1,0]
	v_med3_f32 v5, v10, s47, v173
	v_med3_f32 v11, v11, s47, v173
	v_mov_b32_e32 v10, 0
	v_cvt_pk_fp8_f32 v10, v5, v11
	v_mov_b32_e32 v3, v166
	v_mov_b32_e32 v2, v167
	s_lshl_b32 s0, s48, 8
	v_pk_mul_f32 v[14:15], v[138:139], s[14:15] op_sel_hi:[1,0]
	v_med3_f32 v5, v8, s47, v173
	v_med3_f32 v8, v9, s47, v173
	s_nop 15
	s_nop 15
	s_or_b32 s0, s0, s42
	v_cvt_pk_fp8_f32 v10, v5, v8 op_sel:[0,0,1]
	v_med3_f32 v5, v14, s47, v173
	v_med3_f32 v8, v15, s47, v173
	v_mov_b32_e32 v11, 0
	v_lshl_add_u32 v2, v2, 3, s0
	s_lshl_b32 s0, s24, 8
	v_cvt_pk_fp8_f32 v11, v5, v8
	s_add_i32 s0, s0, s41
	v_add_u32_e32 v4, s0, v3
	v_pk_mul_f32 v[12:13], v[140:141], s[14:15] op_sel_hi:[1,0]
	v_mov_b32_e32 v6, v4
	v_med3_f32 v5, v12, s47, v173
	v_med3_f32 v8, v13, s47, v173
	v_cvt_pk_fp8_f32 v11, v5, v8 op_sel:[0,0,1]
	v_ashrrev_i32_e32 v7, 31, v6
	v_lshlrev_b64 v[6:7], 10, v[6:7]
	v_ashrrev_i32_e32 v3, 31, v2
	v_lshl_add_u64 v[6:7], s[10:11], 0, v[6:7]
	v_lshl_add_u64 v[6:7], v[6:7], 0, v[2:3]
	global_store_dwordx2 v[6:7], v[10:11], off
	v_pk_mul_f32 v[10:11], v[134:135], s[14:15] op_sel_hi:[1,0]
	v_pk_mul_f32 v[8:9], v[136:137], s[14:15] op_sel_hi:[1,0]
	v_med3_f32 v5, v10, s47, v173
	v_med3_f32 v11, v11, s47, v173
	v_mov_b32_e32 v10, 0
	v_cvt_pk_fp8_f32 v10, v5, v11
	v_pk_mul_f32 v[14:15], v[130:131], s[14:15] op_sel_hi:[1,0]
	v_med3_f32 v5, v8, s47, v173
	v_med3_f32 v8, v9, s47, v173
	v_cvt_pk_fp8_f32 v10, v5, v8 op_sel:[0,0,1]
	v_med3_f32 v5, v14, s47, v173
	v_med3_f32 v8, v15, s47, v173
	v_mov_b32_e32 v11, 0
	v_cvt_pk_fp8_f32 v11, v5, v8
	v_pk_mul_f32 v[12:13], v[132:133], s[14:15] op_sel_hi:[1,0]
	v_pk_mul_f32 v[14:15], v[122:123], s[14:15] op_sel_hi:[1,0]
	v_med3_f32 v5, v12, s47, v173
	v_med3_f32 v8, v13, s47, v173
	v_cvt_pk_fp8_f32 v11, v5, v8 op_sel:[0,0,1]
	v_pk_mul_f32 v[8:9], v[128:129], s[14:15] op_sel_hi:[1,0]
	v_pk_mul_f32 v[12:13], v[124:125], s[14:15] op_sel_hi:[1,0]
	s_and_b64 vcc, exec, s[8:9]
	global_store_dwordx2 v[6:7], v[10:11], off offset:128
	v_pk_mul_f32 v[10:11], v[126:127], s[14:15] op_sel_hi:[1,0]
	v_add_u32_e32 v6, 16, v4
	v_med3_f32 v5, v10, s47, v173
	v_med3_f32 v11, v11, s47, v173
	v_mov_b32_e32 v10, 0
	v_cvt_pk_fp8_f32 v10, v5, v11
	v_med3_f32 v5, v8, s47, v173
	v_med3_f32 v8, v9, s47, v173
	v_mov_b32_e32 v11, 0
	v_cvt_pk_fp8_f32 v10, v5, v8 op_sel:[0,0,1]
	v_med3_f32 v5, v14, s47, v173
	v_med3_f32 v8, v15, s47, v173
	v_cvt_pk_fp8_f32 v11, v5, v8
	v_med3_f32 v5, v12, s47, v173
	v_med3_f32 v8, v13, s47, v173
	v_cvt_pk_fp8_f32 v11, v5, v8 op_sel:[0,0,1]
	v_ashrrev_i32_e32 v7, 31, v6
	v_lshlrev_b64 v[6:7], 10, v[6:7]
	v_lshl_add_u64 v[6:7], s[10:11], 0, v[6:7]
	v_lshl_add_u64 v[6:7], v[6:7], 0, v[2:3]
	global_store_dwordx2 v[6:7], v[10:11], off
	v_pk_mul_f32 v[10:11], v[118:119], s[14:15] op_sel_hi:[1,0]
	v_pk_mul_f32 v[8:9], v[120:121], s[14:15] op_sel_hi:[1,0]
	v_med3_f32 v5, v10, s47, v173
	v_med3_f32 v11, v11, s47, v173
	v_mov_b32_e32 v10, 0
	v_cvt_pk_fp8_f32 v10, v5, v11
	v_pk_mul_f32 v[14:15], v[114:115], s[14:15] op_sel_hi:[1,0]
	v_med3_f32 v5, v8, s47, v173
	v_med3_f32 v8, v9, s47, v173
	v_cvt_pk_fp8_f32 v10, v5, v8 op_sel:[0,0,1]
	v_med3_f32 v5, v14, s47, v173
	v_med3_f32 v8, v15, s47, v173
	v_mov_b32_e32 v11, 0
	v_cvt_pk_fp8_f32 v11, v5, v8
	v_pk_mul_f32 v[12:13], v[116:117], s[14:15] op_sel_hi:[1,0]
	v_pk_mul_f32 v[14:15], v[106:107], s[14:15] op_sel_hi:[1,0]
	v_med3_f32 v5, v12, s47, v173
	v_med3_f32 v8, v13, s47, v173
	v_cvt_pk_fp8_f32 v11, v5, v8 op_sel:[0,0,1]
	v_pk_mul_f32 v[8:9], v[112:113], s[14:15] op_sel_hi:[1,0]
	v_pk_mul_f32 v[12:13], v[108:109], s[14:15] op_sel_hi:[1,0]
	s_mov_b32 s48, s16
	global_store_dwordx2 v[6:7], v[10:11], off offset:128
	v_pk_mul_f32 v[10:11], v[110:111], s[14:15] op_sel_hi:[1,0]
	v_add_u32_e32 v6, 32, v4
	v_med3_f32 v5, v10, s47, v173
	v_med3_f32 v11, v11, s47, v173
	v_mov_b32_e32 v10, 0
	v_cvt_pk_fp8_f32 v10, v5, v11
	v_med3_f32 v5, v8, s47, v173
	v_med3_f32 v8, v9, s47, v173
	v_mov_b32_e32 v11, 0
	v_cvt_pk_fp8_f32 v10, v5, v8 op_sel:[0,0,1]
	v_med3_f32 v5, v14, s47, v173
	v_med3_f32 v8, v15, s47, v173
	v_cvt_pk_fp8_f32 v11, v5, v8
	v_med3_f32 v5, v12, s47, v173
	v_med3_f32 v8, v13, s47, v173
	v_cvt_pk_fp8_f32 v11, v5, v8 op_sel:[0,0,1]
	v_ashrrev_i32_e32 v7, 31, v6
	v_lshlrev_b64 v[6:7], 10, v[6:7]
	v_lshl_add_u64 v[6:7], s[10:11], 0, v[6:7]
	v_lshl_add_u64 v[6:7], v[6:7], 0, v[2:3]
	global_store_dwordx2 v[6:7], v[10:11], off
	v_pk_mul_f32 v[10:11], v[102:103], s[14:15] op_sel_hi:[1,0]
	v_pk_mul_f32 v[8:9], v[104:105], s[14:15] op_sel_hi:[1,0]
	v_med3_f32 v5, v10, s47, v173
	v_med3_f32 v11, v11, s47, v173
	v_mov_b32_e32 v10, 0
	v_cvt_pk_fp8_f32 v10, v5, v11
	v_pk_mul_f32 v[14:15], v[98:99], s[14:15] op_sel_hi:[1,0]
	v_med3_f32 v5, v8, s47, v173
	v_med3_f32 v8, v9, s47, v173
	v_cvt_pk_fp8_f32 v10, v5, v8 op_sel:[0,0,1]
	v_med3_f32 v5, v14, s47, v173
	v_med3_f32 v8, v15, s47, v173
	v_mov_b32_e32 v11, 0
	v_cvt_pk_fp8_f32 v11, v5, v8
	v_pk_mul_f32 v[12:13], v[100:101], s[14:15] op_sel_hi:[1,0]
	v_pk_mul_f32 v[14:15], v[90:91], s[14:15] op_sel_hi:[1,0]
	v_med3_f32 v5, v12, s47, v173
	v_med3_f32 v8, v13, s47, v173
	v_cvt_pk_fp8_f32 v11, v5, v8 op_sel:[0,0,1]
	v_pk_mul_f32 v[8:9], v[96:97], s[14:15] op_sel_hi:[1,0]
	v_pk_mul_f32 v[12:13], v[92:93], s[14:15] op_sel_hi:[1,0]
	s_mov_b32 s24, s18
	global_store_dwordx2 v[6:7], v[10:11], off offset:128
	v_pk_mul_f32 v[10:11], v[94:95], s[14:15] op_sel_hi:[1,0]
	v_add_u32_e32 v6, 48, v4
	v_med3_f32 v5, v10, s47, v173
	v_med3_f32 v11, v11, s47, v173
	v_mov_b32_e32 v10, 0
	v_cvt_pk_fp8_f32 v10, v5, v11
	v_med3_f32 v5, v8, s47, v173
	v_med3_f32 v8, v9, s47, v173
	v_mov_b32_e32 v11, 0
	v_cvt_pk_fp8_f32 v10, v5, v8 op_sel:[0,0,1]
	v_med3_f32 v5, v14, s47, v173
	v_med3_f32 v8, v15, s47, v173
	v_cvt_pk_fp8_f32 v11, v5, v8
	v_med3_f32 v5, v12, s47, v173
	v_med3_f32 v8, v13, s47, v173
	v_cvt_pk_fp8_f32 v11, v5, v8 op_sel:[0,0,1]
	v_ashrrev_i32_e32 v7, 31, v6
	v_lshlrev_b64 v[6:7], 10, v[6:7]
	v_lshl_add_u64 v[6:7], s[10:11], 0, v[6:7]
	v_lshl_add_u64 v[6:7], v[6:7], 0, v[2:3]
	global_store_dwordx2 v[6:7], v[10:11], off
	v_pk_mul_f32 v[10:11], v[86:87], s[14:15] op_sel_hi:[1,0]
	v_pk_mul_f32 v[8:9], v[88:89], s[14:15] op_sel_hi:[1,0]
	v_med3_f32 v5, v10, s47, v173
	v_med3_f32 v11, v11, s47, v173
	v_mov_b32_e32 v10, 0
	v_cvt_pk_fp8_f32 v10, v5, v11
	v_pk_mul_f32 v[14:15], v[82:83], s[14:15] op_sel_hi:[1,0]
	v_med3_f32 v5, v8, s47, v173
	v_med3_f32 v8, v9, s47, v173
	v_cvt_pk_fp8_f32 v10, v5, v8 op_sel:[0,0,1]
	v_med3_f32 v5, v14, s47, v173
	v_med3_f32 v8, v15, s47, v173
	v_mov_b32_e32 v11, 0
	v_cvt_pk_fp8_f32 v11, v5, v8
	v_pk_mul_f32 v[12:13], v[84:85], s[14:15] op_sel_hi:[1,0]
	v_pk_mul_f32 v[14:15], v[74:75], s[14:15] op_sel_hi:[1,0]
	v_med3_f32 v5, v12, s47, v173
	v_med3_f32 v8, v13, s47, v173
	v_cvt_pk_fp8_f32 v11, v5, v8 op_sel:[0,0,1]
	v_pk_mul_f32 v[8:9], v[80:81], s[14:15] op_sel_hi:[1,0]
	v_pk_mul_f32 v[12:13], v[76:77], s[14:15] op_sel_hi:[1,0]
	s_mov_b64 s[26:27], s[22:23]
	global_store_dwordx2 v[6:7], v[10:11], off offset:128
	v_pk_mul_f32 v[10:11], v[78:79], s[14:15] op_sel_hi:[1,0]
	v_add_u32_e32 v6, 0x80, v4
	v_med3_f32 v5, v10, s47, v173
	v_med3_f32 v11, v11, s47, v173
	v_mov_b32_e32 v10, 0
	v_cvt_pk_fp8_f32 v10, v5, v11
	v_med3_f32 v5, v8, s47, v173
	v_med3_f32 v8, v9, s47, v173
	v_mov_b32_e32 v11, 0
	v_cvt_pk_fp8_f32 v10, v5, v8 op_sel:[0,0,1]
	v_med3_f32 v5, v14, s47, v173
	v_med3_f32 v8, v15, s47, v173
	v_cvt_pk_fp8_f32 v11, v5, v8
	v_med3_f32 v5, v12, s47, v173
	v_med3_f32 v8, v13, s47, v173
	v_cvt_pk_fp8_f32 v11, v5, v8 op_sel:[0,0,1]
	v_ashrrev_i32_e32 v7, 31, v6
	v_lshlrev_b64 v[6:7], 10, v[6:7]
	v_lshl_add_u64 v[6:7], s[10:11], 0, v[6:7]
	v_lshl_add_u64 v[6:7], v[6:7], 0, v[2:3]
	global_store_dwordx2 v[6:7], v[10:11], off
	v_pk_mul_f32 v[10:11], v[70:71], s[14:15] op_sel_hi:[1,0]
	v_pk_mul_f32 v[8:9], v[72:73], s[14:15] op_sel_hi:[1,0]
	v_med3_f32 v5, v10, s47, v173
	v_med3_f32 v11, v11, s47, v173
	v_mov_b32_e32 v10, 0
	v_cvt_pk_fp8_f32 v10, v5, v11
	v_pk_mul_f32 v[14:15], v[66:67], s[14:15] op_sel_hi:[1,0]
	v_med3_f32 v5, v8, s47, v173
	v_med3_f32 v8, v9, s47, v173
	v_cvt_pk_fp8_f32 v10, v5, v8 op_sel:[0,0,1]
	v_med3_f32 v5, v14, s47, v173
	v_med3_f32 v8, v15, s47, v173
	v_mov_b32_e32 v11, 0
	v_cvt_pk_fp8_f32 v11, v5, v8
	v_pk_mul_f32 v[12:13], v[68:69], s[14:15] op_sel_hi:[1,0]
	v_pk_mul_f32 v[14:15], v[58:59], s[14:15] op_sel_hi:[1,0]
	v_med3_f32 v5, v12, s47, v173
	v_med3_f32 v8, v13, s47, v173
	v_cvt_pk_fp8_f32 v11, v5, v8 op_sel:[0,0,1]
	v_pk_mul_f32 v[8:9], v[64:65], s[14:15] op_sel_hi:[1,0]
	v_pk_mul_f32 v[12:13], v[60:61], s[14:15] op_sel_hi:[1,0]
	s_mov_b64 s[28:29], s[20:21]
	global_store_dwordx2 v[6:7], v[10:11], off offset:128
	v_pk_mul_f32 v[10:11], v[62:63], s[14:15] op_sel_hi:[1,0]
	v_add_u32_e32 v6, 0x90, v4
	v_med3_f32 v5, v10, s47, v173
	v_med3_f32 v11, v11, s47, v173
	v_mov_b32_e32 v10, 0
	v_cvt_pk_fp8_f32 v10, v5, v11
	v_med3_f32 v5, v8, s47, v173
	v_med3_f32 v8, v9, s47, v173
	v_mov_b32_e32 v11, 0
	v_cvt_pk_fp8_f32 v10, v5, v8 op_sel:[0,0,1]
	v_med3_f32 v5, v14, s47, v173
	v_med3_f32 v8, v15, s47, v173
	v_cvt_pk_fp8_f32 v11, v5, v8
	v_med3_f32 v5, v12, s47, v173
	v_med3_f32 v8, v13, s47, v173
	v_cvt_pk_fp8_f32 v11, v5, v8 op_sel:[0,0,1]
	v_ashrrev_i32_e32 v7, 31, v6
	v_lshlrev_b64 v[6:7], 10, v[6:7]
	v_lshl_add_u64 v[6:7], s[10:11], 0, v[6:7]
	v_lshl_add_u64 v[6:7], v[6:7], 0, v[2:3]
	global_store_dwordx2 v[6:7], v[10:11], off
	v_pk_mul_f32 v[10:11], v[54:55], s[14:15] op_sel_hi:[1,0]
	v_pk_mul_f32 v[8:9], v[56:57], s[14:15] op_sel_hi:[1,0]
	v_med3_f32 v5, v10, s47, v173
	v_med3_f32 v11, v11, s47, v173
	v_mov_b32_e32 v10, 0
	v_cvt_pk_fp8_f32 v10, v5, v11
	v_pk_mul_f32 v[14:15], v[50:51], s[14:15] op_sel_hi:[1,0]
	v_med3_f32 v5, v8, s47, v173
	v_med3_f32 v8, v9, s47, v173
	v_cvt_pk_fp8_f32 v10, v5, v8 op_sel:[0,0,1]
	v_med3_f32 v5, v14, s47, v173
	v_med3_f32 v8, v15, s47, v173
	v_mov_b32_e32 v11, 0
	v_cvt_pk_fp8_f32 v11, v5, v8
	v_pk_mul_f32 v[12:13], v[52:53], s[14:15] op_sel_hi:[1,0]
	v_pk_mul_f32 v[14:15], v[42:43], s[14:15] op_sel_hi:[1,0]
	v_med3_f32 v5, v12, s47, v173
	v_med3_f32 v8, v13, s47, v173
	v_cvt_pk_fp8_f32 v11, v5, v8 op_sel:[0,0,1]
	v_pk_mul_f32 v[8:9], v[48:49], s[14:15] op_sel_hi:[1,0]
	v_pk_mul_f32 v[12:13], v[44:45], s[14:15] op_sel_hi:[1,0]
	global_store_dwordx2 v[6:7], v[10:11], off offset:128
	v_pk_mul_f32 v[10:11], v[46:47], s[14:15] op_sel_hi:[1,0]
	v_add_u32_e32 v6, 0xa0, v4
	v_med3_f32 v5, v10, s47, v173
	v_med3_f32 v11, v11, s47, v173
	v_mov_b32_e32 v10, 0
	v_cvt_pk_fp8_f32 v10, v5, v11
	v_med3_f32 v5, v8, s47, v173
	v_med3_f32 v8, v9, s47, v173
	v_mov_b32_e32 v11, 0
	v_cvt_pk_fp8_f32 v10, v5, v8 op_sel:[0,0,1]
	v_med3_f32 v5, v14, s47, v173
	v_med3_f32 v8, v15, s47, v173
	v_cvt_pk_fp8_f32 v11, v5, v8
	v_med3_f32 v5, v12, s47, v173
	v_med3_f32 v8, v13, s47, v173
	v_cvt_pk_fp8_f32 v11, v5, v8 op_sel:[0,0,1]
	v_ashrrev_i32_e32 v7, 31, v6
	v_lshlrev_b64 v[6:7], 10, v[6:7]
	v_lshl_add_u64 v[6:7], s[10:11], 0, v[6:7]
	v_lshl_add_u64 v[6:7], v[6:7], 0, v[2:3]
	global_store_dwordx2 v[6:7], v[10:11], off
	v_pk_mul_f32 v[10:11], v[38:39], s[14:15] op_sel_hi:[1,0]
	v_pk_mul_f32 v[8:9], v[40:41], s[14:15] op_sel_hi:[1,0]
	v_med3_f32 v5, v10, s47, v173
	v_med3_f32 v11, v11, s47, v173
	v_mov_b32_e32 v10, 0
	v_cvt_pk_fp8_f32 v10, v5, v11
	v_pk_mul_f32 v[14:15], v[34:35], s[14:15] op_sel_hi:[1,0]
	v_med3_f32 v5, v8, s47, v173
	v_med3_f32 v8, v9, s47, v173
	v_cvt_pk_fp8_f32 v10, v5, v8 op_sel:[0,0,1]
	v_med3_f32 v5, v14, s47, v173
	v_med3_f32 v8, v15, s47, v173
	v_mov_b32_e32 v11, 0
	v_cvt_pk_fp8_f32 v11, v5, v8
	v_pk_mul_f32 v[12:13], v[36:37], s[14:15] op_sel_hi:[1,0]
	v_add_u32_e32 v4, 0xb0, v4
	v_med3_f32 v5, v12, s47, v173
	v_med3_f32 v8, v13, s47, v173
	v_cvt_pk_fp8_f32 v11, v5, v8 op_sel:[0,0,1]
	v_pk_mul_f32 v[8:9], v[28:29], s[14:15] op_sel_hi:[1,0]
	global_store_dwordx2 v[6:7], v[10:11], off offset:128
	v_pk_mul_f32 v[6:7], v[30:31], s[14:15] op_sel_hi:[1,0]
	v_pk_mul_f32 v[10:11], v[26:27], s[14:15] op_sel_hi:[1,0]
	v_ashrrev_i32_e32 v5, 31, v4
	v_med3_f32 v12, v6, s47, v173
	v_med3_f32 v7, v7, s47, v173
	v_mov_b32_e32 v6, 0
	v_lshlrev_b64 v[4:5], 10, v[4:5]
	v_cvt_pk_fp8_f32 v6, v12, v7
	v_lshl_add_u64 v[4:5], s[10:11], 0, v[4:5]
	v_lshl_add_u64 v[2:3], v[4:5], 0, v[2:3]
	v_pk_mul_f32 v[4:5], v[32:33], s[14:15] op_sel_hi:[1,0]
	v_mov_b32_e32 v7, 0
	v_med3_f32 v4, v4, s47, v173
	v_med3_f32 v5, v5, s47, v173
	v_cvt_pk_fp8_f32 v6, v4, v5 op_sel:[0,0,1]
	v_med3_f32 v4, v10, s47, v173
	v_med3_f32 v5, v11, s47, v173
	v_cvt_pk_fp8_f32 v7, v4, v5
	v_med3_f32 v4, v8, s47, v173
	v_med3_f32 v5, v9, s47, v173
	v_pk_mul_f32 v[10:11], v[18:19], s[14:15] op_sel_hi:[1,0]
	v_cvt_pk_fp8_f32 v7, v4, v5 op_sel:[0,0,1]
	v_pk_mul_f32 v[4:5], v[24:25], s[14:15] op_sel_hi:[1,0]
	v_pk_mul_f32 v[8:9], v[20:21], s[14:15] op_sel_hi:[1,0]
	v_med3_f32 v4, v4, s47, v173
	global_store_dwordx2 v[2:3], v[6:7], off
	v_pk_mul_f32 v[6:7], v[22:23], s[14:15] op_sel_hi:[1,0]
	v_med3_f32 v5, v5, s47, v173
	v_med3_f32 v12, v6, s47, v173
	v_med3_f32 v7, v7, s47, v173
	v_mov_b32_e32 v6, 0
	v_cvt_pk_fp8_f32 v6, v12, v7
	v_mov_b32_e32 v7, 0
	v_cvt_pk_fp8_f32 v6, v4, v5 op_sel:[0,0,1]
	v_med3_f32 v4, v10, s47, v173
	v_med3_f32 v5, v11, s47, v173
	v_cvt_pk_fp8_f32 v7, v4, v5
	v_med3_f32 v4, v8, s47, v173
	v_med3_f32 v5, v9, s47, v173
	v_cvt_pk_fp8_f32 v7, v4, v5 op_sel:[0,0,1]
	global_store_dwordx2 v[2:3], v[6:7], off offset:128
	s_cbranch_vccz .LBB0_748
	s_waitcnt vmcnt(0)
	s_cmpk_gt_u32 s4, 0xff
	s_cbranch_scc1 .LBB0_759
	s_barrier

.LBB0_894:
	s_ashr_i32 s23, s22, 31
	s_lshl_b64 s[0:1], s[22:23], 19
	v_cmp_lt_i64_e32 vcc, s[26:27], v[142:143]
	s_add_u32 s26, s5, s0
	s_addc_u32 s27, s6, s1
	s_and_b64 s[0:1], vcc, exec
	s_cselect_b32 s23, s27, s35
	s_cselect_b32 s51, s26, s34
	s_ashr_i32 s21, s20, 31
	s_lshl_b64 s[0:1], s[20:21], 19
	s_add_u32 s28, s7, s0
	s_addc_u32 s29, s10, s1
	s_and_b64 s[0:1], vcc, exec
	s_cselect_b32 s21, s29, s31
	s_cselect_b32 s52, s28, s30
	s_add_u32 s53, s30, 0x100
	s_addc_u32 s54, s31, 0
	s_add_u32 s30, s34, 0x40080
	s_addc_u32 s31, s35, 0
	s_mov_b32 s55, -2
	ds_read_b128 v[156:159], v152
	ds_read_b128 v[160:163], v152 offset:1024
	ds_read_b128 v[164:167], v152 offset:2048
	ds_read_b128 v[168:171], v152 offset:3072
	s_add_u32 s0, s30, 0xfffc0080
	s_addc_u32 s1, s31, -1
	s_cmp_eq_u32 s55, 12
	s_cselect_b32 s37, s23, s1
	s_cselect_b32 s36, s51, s0
	s_cselect_b32 s35, s21, s54
	s_cselect_b32 s34, s52, s53
	v_lshl_add_u64 v[148:149], s[30:31], 0, v[140:141]
	s_add_i32 m0, s25, 0xc000
	ds_read_b128 v[172:175], v153
	ds_read_b128 v[176:179], v153 offset:1024
	ds_read_b128 v[180:183], v153 offset:2048
	ds_read_b128 v[184:187], v153 offset:3072
	ds_read_b128 v[188:191], v153 offset:4096
	ds_read_b128 v[192:195], v153 offset:5120
	ds_read_b128 v[196:199], v153 offset:6144
	ds_read_b128 v[200:203], v153 offset:7168
	global_load_lds_dwordx4 v[148:149], off
	v_lshl_add_u64 v[148:149], s[30:31], 0, v[138:139]
	s_add_i32 m0, s25, 0xe000
	s_nop 0
	global_load_lds_dwordx4 v[148:149], off
	s_waitcnt lgkmcnt(8)
	s_waitcnt vmcnt(10)
	s_barrier
	s_waitcnt lgkmcnt(0)
	s_waitcnt lgkmcnt(0)
	v_mfma_f32_16x16x32_bf16 v[126:129], v[156:159], v[172:175], 0
	v_mfma_f32_16x16x32_bf16 v[122:125], v[164:167], v[172:175], 0
	v_mfma_f32_16x16x32_bf16 v[118:121], v[156:159], v[180:183], 0
	v_mfma_f32_16x16x32_bf16 v[110:113], v[164:167], v[180:183], 0
	v_mfma_f32_16x16x32_bf16 v[102:105], v[156:159], v[188:191], 0
	v_mfma_f32_16x16x32_bf16 v[94:97], v[164:167], v[188:191], 0
	v_mfma_f32_16x16x32_bf16 v[86:89], v[156:159], v[196:199], 0
	v_mfma_f32_16x16x32_bf16 v[78:81], v[164:167], v[196:199], 0
	v_mfma_f32_16x16x32_bf16 v[126:129], v[160:163], v[176:179], v[126:129]
	v_mfma_f32_16x16x32_bf16 v[122:125], v[168:171], v[176:179], v[122:125]
	v_mfma_f32_16x16x32_bf16 v[118:121], v[160:163], v[184:187], v[118:121]
	v_mfma_f32_16x16x32_bf16 v[110:113], v[168:171], v[184:187], v[110:113]
	v_mfma_f32_16x16x32_bf16 v[102:105], v[160:163], v[192:195], v[102:105]
	v_mfma_f32_16x16x32_bf16 v[94:97], v[168:171], v[192:195], v[94:97]
	v_mfma_f32_16x16x32_bf16 v[86:89], v[160:163], v[200:203], v[86:89]
	v_mfma_f32_16x16x32_bf16 v[78:81], v[168:171], v[200:203], v[78:81]
	s_barrier
	s_add_i32 s0, s47, s11
	v_lshl_add_u64 v[148:149], s[34:35], 0, v[134:135]
	s_mov_b32 m0, s0
	ds_read_b128 v[204:207], v154
	ds_read_b128 v[208:211], v154 offset:1024
	ds_read_b128 v[212:215], v154 offset:2048
	ds_read_b128 v[216:219], v154 offset:3072
	global_load_lds_dwordx4 v[148:149], off
	v_lshl_add_u64 v[220:221], s[34:35], 0, v[130:131]
	s_add_i32 m0, s0, 0x2000
	s_nop 0
	global_load_lds_dwordx4 v[220:221], off
	s_waitcnt vmcnt(10)
	s_barrier
	s_waitcnt lgkmcnt(0)
	s_waitcnt lgkmcnt(0)
	v_mfma_f32_16x16x32_bf16 v[114:117], v[204:207], v[172:175], 0
	v_mfma_f32_16x16x32_bf16 v[106:109], v[212:215], v[172:175], 0
	v_mfma_f32_16x16x32_bf16 v[98:101], v[204:207], v[180:183], 0
	v_mfma_f32_16x16x32_bf16 v[90:93], v[212:215], v[180:183], 0
	v_mfma_f32_16x16x32_bf16 v[82:85], v[204:207], v[188:191], 0
	v_mfma_f32_16x16x32_bf16 v[74:77], v[212:215], v[188:191], 0
	v_mfma_f32_16x16x32_bf16 v[70:73], v[204:207], v[196:199], 0
	v_mfma_f32_16x16x32_bf16 v[66:69], v[212:215], v[196:199], 0
	v_mfma_f32_16x16x32_bf16 v[114:117], v[208:211], v[176:179], v[114:117]
	v_mfma_f32_16x16x32_bf16 v[106:109], v[216:219], v[176:179], v[106:109]
	v_mfma_f32_16x16x32_bf16 v[98:101], v[208:211], v[184:187], v[98:101]
	v_mfma_f32_16x16x32_bf16 v[90:93], v[216:219], v[184:187], v[90:93]
	v_mfma_f32_16x16x32_bf16 v[82:85], v[208:211], v[192:195], v[82:85]
	v_mfma_f32_16x16x32_bf16 v[74:77], v[216:219], v[192:195], v[74:77]
	v_mfma_f32_16x16x32_bf16 v[70:73], v[208:211], v[200:203], v[70:73]
	v_mfma_f32_16x16x32_bf16 v[66:69], v[216:219], v[200:203], v[66:69]
	s_mov_b32 m0, s25
	v_lshl_add_u64 v[222:223], s[36:37], 0, v[136:137]
	s_barrier
	ds_read_b128 v[172:175], v153 offset:16384
	ds_read_b128 v[176:179], v153 offset:17408
	ds_read_b128 v[180:183], v153 offset:18432
	ds_read_b128 v[184:187], v153 offset:19456
	ds_read_b128 v[188:191], v153 offset:20480
	ds_read_b128 v[192:195], v153 offset:21504
	ds_read_b128 v[196:199], v153 offset:22528
	ds_read_b128 v[200:203], v153 offset:23552
	global_load_lds_dwordx4 v[222:223], off
	v_lshl_add_u64 v[224:225], s[36:37], 0, v[132:133]
	s_mov_b32 m0, s39
	s_nop 0
	global_load_lds_dwordx4 v[224:225], off
	s_waitcnt vmcnt(10)
	s_barrier
	s_waitcnt lgkmcnt(0)
	s_waitcnt lgkmcnt(0)
	v_mfma_f32_16x16x32_bf16 v[62:65], v[156:159], v[172:175], 0
	v_mfma_f32_16x16x32_bf16 v[58:61], v[164:167], v[172:175], 0
	v_mfma_f32_16x16x32_bf16 v[54:57], v[156:159], v[180:183], 0
	v_mfma_f32_16x16x32_bf16 v[46:49], v[164:167], v[180:183], 0
	v_mfma_f32_16x16x32_bf16 v[38:41], v[156:159], v[188:191], 0
	v_mfma_f32_16x16x32_bf16 v[30:33], v[164:167], v[188:191], 0
	v_mfma_f32_16x16x32_bf16 v[22:25], v[156:159], v[196:199], 0
	v_mfma_f32_16x16x32_bf16 v[14:17], v[164:167], v[196:199], 0
	v_mfma_f32_16x16x32_bf16 v[62:65], v[160:163], v[176:179], v[62:65]
	v_mfma_f32_16x16x32_bf16 v[58:61], v[168:171], v[176:179], v[58:61]
	v_mfma_f32_16x16x32_bf16 v[54:57], v[160:163], v[184:187], v[54:57]
	v_mfma_f32_16x16x32_bf16 v[46:49], v[168:171], v[184:187], v[46:49]
	v_mfma_f32_16x16x32_bf16 v[38:41], v[160:163], v[192:195], v[38:41]
	v_mfma_f32_16x16x32_bf16 v[30:33], v[168:171], v[192:195], v[30:33]
	v_mfma_f32_16x16x32_bf16 v[22:25], v[160:163], v[200:203], v[22:25]
	v_mfma_f32_16x16x32_bf16 v[14:17], v[168:171], v[200:203], v[14:17]
	s_barrier
	s_add_u32 s0, s34, 0x40000
	s_addc_u32 s1, s35, 0
	s_add_i32 s56, s48, s11
	v_lshl_add_u64 v[156:157], s[0:1], 0, v[134:135]
	s_mov_b32 m0, s56
	s_nop 0
	global_load_lds_dwordx4 v[156:157], off
	v_lshl_add_u64 v[156:157], s[0:1], 0, v[130:131]
	s_add_i32 m0, s56, 0x2000
	s_nop 0
	global_load_lds_dwordx4 v[156:157], off
	s_waitcnt vmcnt(10)
	s_barrier
	v_mfma_f32_16x16x32_bf16 v[50:53], v[204:207], v[172:175], 0
	v_mfma_f32_16x16x32_bf16 v[42:45], v[212:215], v[172:175], 0
	v_mfma_f32_16x16x32_bf16 v[34:37], v[204:207], v[180:183], 0
	v_mfma_f32_16x16x32_bf16 v[26:29], v[212:215], v[180:183], 0
	v_mfma_f32_16x16x32_bf16 v[18:21], v[204:207], v[188:191], 0
	v_mfma_f32_16x16x32_bf16 v[10:13], v[212:215], v[188:191], 0
	v_mfma_f32_16x16x32_bf16 v[6:9], v[204:207], v[196:199], 0
	v_mfma_f32_16x16x32_bf16 v[2:5], v[212:215], v[196:199], 0
	v_mfma_f32_16x16x32_bf16 v[50:53], v[208:211], v[176:179], v[50:53]
	v_mfma_f32_16x16x32_bf16 v[42:45], v[216:219], v[176:179], v[42:45]
	v_mfma_f32_16x16x32_bf16 v[34:37], v[208:211], v[184:187], v[34:37]
	v_mfma_f32_16x16x32_bf16 v[26:29], v[216:219], v[184:187], v[26:29]
	v_mfma_f32_16x16x32_bf16 v[18:21], v[208:211], v[192:195], v[18:21]
	v_mfma_f32_16x16x32_bf16 v[10:13], v[216:219], v[192:195], v[10:13]
	v_mfma_f32_16x16x32_bf16 v[6:9], v[208:211], v[200:203], v[6:9]
	v_mfma_f32_16x16x32_bf16 v[2:5], v[216:219], v[200:203], v[2:5]
	s_add_i32 s56, 0, 0x18000
	v_add_u32_e32 v146, s56, v151
	s_barrier
	ds_read_b128 v[156:159], v146
	ds_read_b128 v[160:163], v146 offset:1024
	ds_read_b128 v[164:167], v146 offset:2048
	ds_read_b128 v[168:171], v146 offset:3072
	s_add_u32 s0, s36, 0x40000
	s_addc_u32 s1, s37, 0
	s_mov_b32 m0, s40
	v_lshl_add_u64 v[204:205], s[0:1], 0, v[136:137]
	ds_read_b128 v[172:175], v153 offset:32768
	ds_read_b128 v[176:179], v153 offset:33792
	ds_read_b128 v[180:183], v153 offset:34816
	ds_read_b128 v[184:187], v153 offset:35840
	ds_read_b128 v[188:191], v153 offset:36864
	ds_read_b128 v[192:195], v153 offset:37888
	ds_read_b128 v[196:199], v153 offset:38912
	ds_read_b128 v[200:203], v153 offset:39936
	global_load_lds_dwordx4 v[204:205], off
	v_lshl_add_u64 v[204:205], s[0:1], 0, v[132:133]
	s_mov_b32 m0, s41
	s_nop 0
	global_load_lds_dwordx4 v[204:205], off
	s_waitcnt lgkmcnt(8)
	s_waitcnt vmcnt(10)
	s_barrier
	s_waitcnt lgkmcnt(0)
	s_waitcnt lgkmcnt(0)
	v_mfma_f32_16x16x32_bf16 v[126:129], v[156:159], v[172:175], v[126:129]
	v_mfma_f32_16x16x32_bf16 v[122:125], v[164:167], v[172:175], v[122:125]
	v_mfma_f32_16x16x32_bf16 v[118:121], v[156:159], v[180:183], v[118:121]
	v_mfma_f32_16x16x32_bf16 v[110:113], v[164:167], v[180:183], v[110:113]
	v_mfma_f32_16x16x32_bf16 v[102:105], v[156:159], v[188:191], v[102:105]
	v_mfma_f32_16x16x32_bf16 v[94:97], v[164:167], v[188:191], v[94:97]
	v_mfma_f32_16x16x32_bf16 v[86:89], v[156:159], v[196:199], v[86:89]
	v_mfma_f32_16x16x32_bf16 v[78:81], v[164:167], v[196:199], v[78:81]
	v_mfma_f32_16x16x32_bf16 v[126:129], v[160:163], v[176:179], v[126:129]
	v_mfma_f32_16x16x32_bf16 v[122:125], v[168:171], v[176:179], v[122:125]
	v_mfma_f32_16x16x32_bf16 v[118:121], v[160:163], v[184:187], v[118:121]
	v_mfma_f32_16x16x32_bf16 v[110:113], v[168:171], v[184:187], v[110:113]
	v_mfma_f32_16x16x32_bf16 v[102:105], v[160:163], v[192:195], v[102:105]
	v_mfma_f32_16x16x32_bf16 v[94:97], v[168:171], v[192:195], v[94:97]
	v_mfma_f32_16x16x32_bf16 v[86:89], v[160:163], v[200:203], v[86:89]
	v_mfma_f32_16x16x32_bf16 v[78:81], v[168:171], v[200:203], v[78:81]
	s_barrier
	s_add_i32 s36, 0, 0x1c000
	s_add_i32 s0, s56, s11
	v_add_u32_e32 v146, s36, v151
	v_lshl_add_u64 v[148:149], v[148:149], 0, s[16:17]
	s_mov_b32 m0, s0
	ds_read_b128 v[204:207], v146
	ds_read_b128 v[208:211], v146 offset:1024
	ds_read_b128 v[212:215], v146 offset:2048
	ds_read_b128 v[216:219], v146 offset:3072
	global_load_lds_dwordx4 v[148:149], off
	v_lshl_add_u64 v[148:149], v[220:221], 0, s[16:17]
	s_add_i32 m0, s0, 0x2000
	s_nop 0
	global_load_lds_dwordx4 v[148:149], off
	s_waitcnt vmcnt(10)
	s_barrier
	s_waitcnt lgkmcnt(0)
	s_waitcnt lgkmcnt(0)
	v_mfma_f32_16x16x32_bf16 v[114:117], v[204:207], v[172:175], v[114:117]
	v_mfma_f32_16x16x32_bf16 v[106:109], v[212:215], v[172:175], v[106:109]
	v_mfma_f32_16x16x32_bf16 v[98:101], v[204:207], v[180:183], v[98:101]
	v_mfma_f32_16x16x32_bf16 v[90:93], v[212:215], v[180:183], v[90:93]
	v_mfma_f32_16x16x32_bf16 v[82:85], v[204:207], v[188:191], v[82:85]
	v_mfma_f32_16x16x32_bf16 v[74:77], v[212:215], v[188:191], v[74:77]
	v_mfma_f32_16x16x32_bf16 v[70:73], v[204:207], v[196:199], v[70:73]
	v_mfma_f32_16x16x32_bf16 v[66:69], v[212:215], v[196:199], v[66:69]
	v_mfma_f32_16x16x32_bf16 v[114:117], v[208:211], v[176:179], v[114:117]
	v_mfma_f32_16x16x32_bf16 v[106:109], v[216:219], v[176:179], v[106:109]
	v_mfma_f32_16x16x32_bf16 v[98:101], v[208:211], v[184:187], v[98:101]
	v_mfma_f32_16x16x32_bf16 v[90:93], v[216:219], v[184:187], v[90:93]
	v_mfma_f32_16x16x32_bf16 v[82:85], v[208:211], v[192:195], v[82:85]
	v_mfma_f32_16x16x32_bf16 v[74:77], v[216:219], v[192:195], v[74:77]
	v_mfma_f32_16x16x32_bf16 v[70:73], v[208:211], v[200:203], v[70:73]
	v_mfma_f32_16x16x32_bf16 v[66:69], v[216:219], v[200:203], v[66:69]
	s_mov_b32 m0, s45
	v_lshl_add_u64 v[148:149], v[222:223], 0, s[16:17]
	s_barrier
	ds_read_b128 v[172:175], v153 offset:49152
	ds_read_b128 v[176:179], v153 offset:50176
	ds_read_b128 v[180:183], v153 offset:51200
	ds_read_b128 v[184:187], v153 offset:52224
	ds_read_b128 v[188:191], v153 offset:53248
	ds_read_b128 v[192:195], v153 offset:54272
	ds_read_b128 v[196:199], v153 offset:55296
	ds_read_b128 v[200:203], v153 offset:56320
	global_load_lds_dwordx4 v[148:149], off
	v_lshl_add_u64 v[148:149], v[224:225], 0, s[16:17]
	s_mov_b32 m0, s46
	s_nop 0
	global_load_lds_dwordx4 v[148:149], off
	s_waitcnt vmcnt(10)
	s_barrier
	s_waitcnt lgkmcnt(0)
	s_waitcnt lgkmcnt(0)
	v_mfma_f32_16x16x32_bf16 v[62:65], v[156:159], v[172:175], v[62:65]
	v_mfma_f32_16x16x32_bf16 v[58:61], v[164:167], v[172:175], v[58:61]
	v_mfma_f32_16x16x32_bf16 v[54:57], v[156:159], v[180:183], v[54:57]
	v_mfma_f32_16x16x32_bf16 v[46:49], v[164:167], v[180:183], v[46:49]
	v_mfma_f32_16x16x32_bf16 v[38:41], v[156:159], v[188:191], v[38:41]
	v_mfma_f32_16x16x32_bf16 v[30:33], v[164:167], v[188:191], v[30:33]
	v_mfma_f32_16x16x32_bf16 v[22:25], v[156:159], v[196:199], v[22:25]
	v_mfma_f32_16x16x32_bf16 v[14:17], v[164:167], v[196:199], v[14:17]
	v_mfma_f32_16x16x32_bf16 v[62:65], v[160:163], v[176:179], v[62:65]
	v_mfma_f32_16x16x32_bf16 v[58:61], v[168:171], v[176:179], v[58:61]
	v_mfma_f32_16x16x32_bf16 v[54:57], v[160:163], v[184:187], v[54:57]
	v_mfma_f32_16x16x32_bf16 v[46:49], v[168:171], v[184:187], v[46:49]
	v_mfma_f32_16x16x32_bf16 v[38:41], v[160:163], v[192:195], v[38:41]
	v_mfma_f32_16x16x32_bf16 v[30:33], v[168:171], v[192:195], v[30:33]
	v_mfma_f32_16x16x32_bf16 v[22:25], v[160:163], v[200:203], v[22:25]
	v_mfma_f32_16x16x32_bf16 v[14:17], v[168:171], v[200:203], v[14:17]
	s_barrier
	s_add_u32 s0, s34, 0x40080
	s_addc_u32 s1, s35, 0
	s_add_i32 s34, s36, s11
	v_lshl_add_u64 v[148:149], s[0:1], 0, v[134:135]
	s_mov_b32 m0, s34
	s_nop 0
	global_load_lds_dwordx4 v[148:149], off
	v_lshl_add_u64 v[148:149], s[0:1], 0, v[130:131]
	s_add_i32 m0, s34, 0x2000
	s_nop 0
	global_load_lds_dwordx4 v[148:149], off
	s_waitcnt vmcnt(10)
	s_barrier
	v_mfma_f32_16x16x32_bf16 v[50:53], v[204:207], v[172:175], v[50:53]
	v_mfma_f32_16x16x32_bf16 v[42:45], v[212:215], v[172:175], v[42:45]
	v_mfma_f32_16x16x32_bf16 v[34:37], v[204:207], v[180:183], v[34:37]
	v_mfma_f32_16x16x32_bf16 v[26:29], v[212:215], v[180:183], v[26:29]
	v_mfma_f32_16x16x32_bf16 v[18:21], v[204:207], v[188:191], v[18:21]
	v_mfma_f32_16x16x32_bf16 v[10:13], v[212:215], v[188:191], v[10:13]
	v_mfma_f32_16x16x32_bf16 v[6:9], v[204:207], v[196:199], v[6:9]
	v_mfma_f32_16x16x32_bf16 v[2:5], v[212:215], v[196:199], v[2:5]
	v_mfma_f32_16x16x32_bf16 v[50:53], v[208:211], v[176:179], v[50:53]
	v_mfma_f32_16x16x32_bf16 v[42:45], v[216:219], v[176:179], v[42:45]
	v_mfma_f32_16x16x32_bf16 v[34:37], v[208:211], v[184:187], v[34:37]
	v_mfma_f32_16x16x32_bf16 v[26:29], v[216:219], v[184:187], v[26:29]
	v_mfma_f32_16x16x32_bf16 v[18:21], v[208:211], v[192:195], v[18:21]
	v_mfma_f32_16x16x32_bf16 v[10:13], v[216:219], v[192:195], v[10:13]
	v_mfma_f32_16x16x32_bf16 v[6:9], v[208:211], v[200:203], v[6:9]
	v_mfma_f32_16x16x32_bf16 v[2:5], v[216:219], v[200:203], v[2:5]
	s_add_i32 s55, s55, 2
	s_add_u32 s53, s53, 0x100
	s_addc_u32 s54, s54, 0
	s_add_u32 s30, s30, 0x100
	s_addc_u32 s31, s31, 0
	s_cmp_gt_u32 s55, 13
	s_barrier
	s_cbranch_scc1 .Lpeel_exit_4

.Lpeel_exit_4:
	v_mov_b32_e32 v156, v147
	v_mov_b32_e32 v146, v150
	s_cmp_gt_i32 s50, 11
	s_mov_b64 s[30:31], -1
	s_cbranch_scc0 .LBB0_900
	s_cmp_eq_u32 s50, 12
	s_cselect_b64 s[0:1], -1, 0
	s_and_b64 s[0:1], s[0:1], s[18:19]
	v_cmp_gt_i32_e32 vcc, 4, v146
	s_and_b64 s[0:1], s[0:1], vcc
	s_and_saveexec_b64 s[30:31], s[0:1]
	s_cbranch_execz .LBB0_899
	s_lshl_b32 s0, s24, 8
	s_add_i32 s0, s0, s43
	v_add_u32_e32 v157, s0, v156
	v_mov_b32_e32 v158, v157
	v_lshlrev_b32_e32 v148, 3, v146
	v_ashrrev_i32_e32 v149, 31, v148
	v_ashrrev_i32_e32 v159, 31, v158
	v_lshlrev_b64 v[158:159], 7, v[158:159]
	v_lshl_add_u64 v[158:159], s[14:15], 0, v[158:159]
	v_lshlrev_b64 v[148:149], 2, v[148:149]
	v_lshl_add_u64 v[162:163], v[158:159], 0, v[148:149]
	v_pk_add_f32 v[160:161], v[128:129], 0 op_sel_hi:[1,0]
	v_pk_add_f32 v[158:159], v[126:127], 0 op_sel_hi:[1,0]
	global_store_dwordx4 v[162:163], v[158:161], off
	s_nop 1
	v_pk_add_f32 v[160:161], v[124:125], 0 op_sel_hi:[1,0]
	v_pk_add_f32 v[158:159], v[122:123], 0 op_sel_hi:[1,0]
	global_store_dwordx4 v[162:163], v[158:161], off offset:16
	s_nop 1
	v_add_u32_e32 v158, 16, v157
	v_pk_add_f32 v[160:161], v[120:121], 0 op_sel_hi:[1,0]
	v_ashrrev_i32_e32 v159, 31, v158
	v_lshlrev_b64 v[158:159], 7, v[158:159]
	v_lshl_add_u64 v[158:159], s[14:15], 0, v[158:159]
	v_lshl_add_u64 v[162:163], v[158:159], 0, v[148:149]
	v_pk_add_f32 v[158:159], v[118:119], 0 op_sel_hi:[1,0]
	global_store_dwordx4 v[162:163], v[158:161], off
	s_nop 1
	v_pk_add_f32 v[160:161], v[112:113], 0 op_sel_hi:[1,0]
	v_pk_add_f32 v[158:159], v[110:111], 0 op_sel_hi:[1,0]
	global_store_dwordx4 v[162:163], v[158:161], off offset:16
	s_nop 1
	v_add_u32_e32 v158, 32, v157
	v_pk_add_f32 v[160:161], v[104:105], 0 op_sel_hi:[1,0]
	v_ashrrev_i32_e32 v159, 31, v158
	v_lshlrev_b64 v[158:159], 7, v[158:159]
	v_lshl_add_u64 v[158:159], s[14:15], 0, v[158:159]
	v_lshl_add_u64 v[162:163], v[158:159], 0, v[148:149]
	v_pk_add_f32 v[158:159], v[102:103], 0 op_sel_hi:[1,0]
	global_store_dwordx4 v[162:163], v[158:161], off
	s_nop 1
	v_pk_add_f32 v[160:161], v[96:97], 0 op_sel_hi:[1,0]
	v_pk_add_f32 v[158:159], v[94:95], 0 op_sel_hi:[1,0]
	global_store_dwordx4 v[162:163], v[158:161], off offset:16
	s_nop 1
	v_add_u32_e32 v158, 48, v157
	v_pk_add_f32 v[160:161], v[88:89], 0 op_sel_hi:[1,0]
	v_ashrrev_i32_e32 v159, 31, v158
	v_lshlrev_b64 v[158:159], 7, v[158:159]
	v_lshl_add_u64 v[158:159], s[14:15], 0, v[158:159]
	v_lshl_add_u64 v[162:163], v[158:159], 0, v[148:149]
	v_pk_add_f32 v[158:159], v[86:87], 0 op_sel_hi:[1,0]
	global_store_dwordx4 v[162:163], v[158:161], off
	s_nop 1
	v_pk_add_f32 v[160:161], v[80:81], 0 op_sel_hi:[1,0]
	v_pk_add_f32 v[158:159], v[78:79], 0 op_sel_hi:[1,0]
	global_store_dwordx4 v[162:163], v[158:161], off offset:16
	s_nop 1
	v_add_u32_e32 v158, 0x80, v157
	v_pk_add_f32 v[160:161], v[64:65], 0 op_sel_hi:[1,0]
	v_ashrrev_i32_e32 v159, 31, v158
	v_lshlrev_b64 v[158:159], 7, v[158:159]
	v_lshl_add_u64 v[158:159], s[14:15], 0, v[158:159]
	v_lshl_add_u64 v[162:163], v[158:159], 0, v[148:149]
	v_pk_add_f32 v[158:159], v[62:63], 0 op_sel_hi:[1,0]
	global_store_dwordx4 v[162:163], v[158:161], off
	s_nop 1
	v_pk_add_f32 v[160:161], v[60:61], 0 op_sel_hi:[1,0]
	v_pk_add_f32 v[158:159], v[58:59], 0 op_sel_hi:[1,0]
	global_store_dwordx4 v[162:163], v[158:161], off offset:16
	s_nop 1
	v_add_u32_e32 v158, 0x90, v157
	v_pk_add_f32 v[160:161], v[56:57], 0 op_sel_hi:[1,0]
	v_ashrrev_i32_e32 v159, 31, v158
	v_lshlrev_b64 v[158:159], 7, v[158:159]
	v_lshl_add_u64 v[158:159], s[14:15], 0, v[158:159]
	v_lshl_add_u64 v[162:163], v[158:159], 0, v[148:149]
	v_pk_add_f32 v[158:159], v[54:55], 0 op_sel_hi:[1,0]
	global_store_dwordx4 v[162:163], v[158:161], off
	s_nop 1
	v_pk_add_f32 v[160:161], v[48:49], 0 op_sel_hi:[1,0]
	v_pk_add_f32 v[158:159], v[46:47], 0 op_sel_hi:[1,0]
	global_store_dwordx4 v[162:163], v[158:161], off offset:16
	s_nop 1
	v_add_u32_e32 v158, 0xa0, v157
	v_pk_add_f32 v[160:161], v[40:41], 0 op_sel_hi:[1,0]
	v_ashrrev_i32_e32 v159, 31, v158
	v_lshlrev_b64 v[158:159], 7, v[158:159]
	v_lshl_add_u64 v[158:159], s[14:15], 0, v[158:159]
	v_lshl_add_u64 v[162:163], v[158:159], 0, v[148:149]
	v_pk_add_f32 v[158:159], v[38:39], 0 op_sel_hi:[1,0]
	global_store_dwordx4 v[162:163], v[158:161], off
	s_nop 1
	v_pk_add_f32 v[160:161], v[32:33], 0 op_sel_hi:[1,0]
	v_pk_add_f32 v[158:159], v[30:31], 0 op_sel_hi:[1,0]
	global_store_dwordx4 v[162:163], v[158:161], off offset:16
	s_nop 1
	v_add_u32_e32 v158, 0xb0, v157
	v_pk_add_f32 v[160:161], v[24:25], 0 op_sel_hi:[1,0]
	v_ashrrev_i32_e32 v159, 31, v158
	v_lshlrev_b64 v[158:159], 7, v[158:159]
	v_lshl_add_u64 v[158:159], s[14:15], 0, v[158:159]
	v_lshl_add_u64 v[148:149], v[158:159], 0, v[148:149]
	v_pk_add_f32 v[158:159], v[22:23], 0 op_sel_hi:[1,0]
	global_store_dwordx4 v[148:149], v[158:161], off
	s_nop 1
	v_pk_add_f32 v[160:161], v[16:17], 0 op_sel_hi:[1,0]
	v_pk_add_f32 v[158:159], v[14:15], 0 op_sel_hi:[1,0]
	global_store_dwordx4 v[148:149], v[158:161], off offset:16

.LBB0_1046:
	s_add_i32 s55, s55, 1
	s_mov_b64 s[0:1], s[26:27]
	s_lshr_b32 s26, s55, 2
	s_mul_i32 s26, s26, s74
	s_mov_b64 s[38:39], s[36:37]
	s_mov_b32 s37, s56
	s_add_i32 s56, s26, s2
	s_cmpk_lt_i32 s56, 0x100
	s_cselect_b64 s[40:41], -1, 0
	s_cmpk_gt_i32 s56, 0xff
	s_mov_b32 s36, s57
	s_cselect_b64 s[34:35], -1, 0
	s_and_b32 s57, s55, 3
	s_and_b64 s[26:27], s[40:41], exec
	s_cselect_b32 s26, s56, s37
	s_cselect_b32 s36, s57, s36
	s_ashr_i32 s27, s26, 31
	s_lshl_b64 s[26:27], s[26:27], 19
	s_add_u32 s26, s20, s26
	s_addc_u32 s27, s21, s27
	s_and_b64 s[42:43], s[40:41], exec
	s_cselect_b32 s60, s27, s1
	s_cselect_b32 s61, s26, s0
	s_ashr_i32 s37, s36, 31
	s_lshl_b64 s[36:37], s[36:37], 19
	s_add_u32 s36, s8, s36
	s_addc_u32 s37, s9, s37
	s_and_b64 s[40:41], s[40:41], exec
	s_cselect_b32 s62, s37, s39
	s_cselect_b32 s63, s36, s38
	s_add_u32 s64, s38, 0x100
	s_addc_u32 s65, s39, 0
	s_add_u32 s38, s0, 0x40080
	s_addc_u32 s39, s1, 0
	s_mov_b32 s69, -2
	s_waitcnt vmcnt(0)
	ds_read_b128 v[130:133], v170
	ds_read_b128 v[134:137], v170 offset:1024
	ds_read_b128 v[138:141], v170 offset:2048
	ds_read_b128 v[142:145], v170 offset:3072
	s_add_u32 s0, s38, 0xfffc0080
	s_addc_u32 s1, s39, -1
	s_cmp_eq_u32 s69, 12
	s_cselect_b32 s43, s60, s1
	s_cselect_b32 s42, s61, s0
	s_cselect_b32 s41, s62, s65
	s_cselect_b32 s40, s63, s64
	s_mov_b32 m0, s50
	v_lshl_add_u64 v[166:167], s[38:39], 0, v[164:165]
	ds_read_b128 v[146:149], v171
	ds_read_b128 v[174:177], v171 offset:1024
	ds_read_b128 v[178:181], v171 offset:2048
	ds_read_b128 v[182:185], v171 offset:3072
	ds_read_b128 v[186:189], v171 offset:4096
	ds_read_b128 v[190:193], v171 offset:5120
	ds_read_b128 v[194:197], v171 offset:6144
	ds_read_b128 v[198:201], v171 offset:7168
	global_load_lds_dwordx4 v[166:167], off
	v_lshl_add_u64 v[166:167], s[38:39], 0, v[162:163]
	s_mov_b32 m0, s51
	s_nop 0
	global_load_lds_dwordx4 v[166:167], off
	s_waitcnt lgkmcnt(8)
	s_waitcnt vmcnt(10)
	s_barrier
	s_waitcnt lgkmcnt(0)
	s_waitcnt lgkmcnt(0)
	v_mfma_f32_16x16x32_bf16 v[126:129], v[130:133], v[146:149], 0
	v_mfma_f32_16x16x32_bf16 v[122:125], v[138:141], v[146:149], 0
	v_mfma_f32_16x16x32_bf16 v[118:121], v[130:133], v[178:181], 0
	v_mfma_f32_16x16x32_bf16 v[110:113], v[138:141], v[178:181], 0
	v_mfma_f32_16x16x32_bf16 v[98:101], v[130:133], v[186:189], 0
	v_mfma_f32_16x16x32_bf16 v[90:93], v[138:141], v[186:189], 0
	v_mfma_f32_16x16x32_bf16 v[82:85], v[130:133], v[194:197], 0
	v_mfma_f32_16x16x32_bf16 v[74:77], v[138:141], v[194:197], 0
	v_mfma_f32_16x16x32_bf16 v[126:129], v[134:137], v[174:177], v[126:129]
	v_mfma_f32_16x16x32_bf16 v[122:125], v[142:145], v[174:177], v[122:125]
	v_mfma_f32_16x16x32_bf16 v[118:121], v[134:137], v[182:185], v[118:121]
	v_mfma_f32_16x16x32_bf16 v[110:113], v[142:145], v[182:185], v[110:113]
	v_mfma_f32_16x16x32_bf16 v[98:101], v[134:137], v[190:193], v[98:101]
	v_mfma_f32_16x16x32_bf16 v[90:93], v[142:145], v[190:193], v[90:93]
	v_mfma_f32_16x16x32_bf16 v[82:85], v[134:137], v[198:201], v[82:85]
	v_mfma_f32_16x16x32_bf16 v[74:77], v[142:145], v[198:201], v[74:77]
	s_barrier
	s_mov_b32 m0, s52
	v_lshl_add_u64 v[166:167], s[40:41], 0, v[158:159]
	ds_read_b128 v[202:205], v172
	ds_read_b128 v[206:209], v172 offset:1024
	ds_read_b128 v[210:213], v172 offset:2048
	ds_read_b128 v[214:217], v172 offset:3072
	global_load_lds_dwordx4 v[166:167], off
	v_lshl_add_u64 v[218:219], s[40:41], 0, v[154:155]
	s_mov_b32 m0, s53
	s_nop 0
	global_load_lds_dwordx4 v[218:219], off
	s_waitcnt vmcnt(10)
	s_barrier
	s_waitcnt lgkmcnt(0)
	s_waitcnt lgkmcnt(0)
	v_mfma_f32_16x16x32_bf16 v[114:117], v[202:205], v[146:149], 0
	v_mfma_f32_16x16x32_bf16 v[106:109], v[210:213], v[146:149], 0
	v_mfma_f32_16x16x32_bf16 v[102:105], v[202:205], v[178:181], 0
	v_mfma_f32_16x16x32_bf16 v[94:97], v[210:213], v[178:181], 0
	v_mfma_f32_16x16x32_bf16 v[86:89], v[202:205], v[186:189], 0
	v_mfma_f32_16x16x32_bf16 v[78:81], v[210:213], v[186:189], 0
	v_mfma_f32_16x16x32_bf16 v[70:73], v[202:205], v[194:197], 0
	v_mfma_f32_16x16x32_bf16 v[66:69], v[210:213], v[194:197], 0
	v_mfma_f32_16x16x32_bf16 v[114:117], v[206:209], v[174:177], v[114:117]
	v_mfma_f32_16x16x32_bf16 v[106:109], v[214:217], v[174:177], v[106:109]
	v_mfma_f32_16x16x32_bf16 v[102:105], v[206:209], v[182:185], v[102:105]
	v_mfma_f32_16x16x32_bf16 v[94:97], v[214:217], v[182:185], v[94:97]
	v_mfma_f32_16x16x32_bf16 v[86:89], v[206:209], v[190:193], v[86:89]
	v_mfma_f32_16x16x32_bf16 v[78:81], v[214:217], v[190:193], v[78:81]
	v_mfma_f32_16x16x32_bf16 v[70:73], v[206:209], v[198:201], v[70:73]
	v_mfma_f32_16x16x32_bf16 v[66:69], v[214:217], v[198:201], v[66:69]
	s_mov_b32 m0, s6
	v_lshl_add_u64 v[220:221], s[42:43], 0, v[160:161]
	s_barrier
	ds_read_b128 v[146:149], v171 offset:16384
	ds_read_b128 v[174:177], v171 offset:17408
	ds_read_b128 v[178:181], v171 offset:18432
	ds_read_b128 v[182:185], v171 offset:19456
	ds_read_b128 v[186:189], v171 offset:20480
	ds_read_b128 v[190:193], v171 offset:21504
	ds_read_b128 v[194:197], v171 offset:22528
	ds_read_b128 v[198:201], v171 offset:23552
	global_load_lds_dwordx4 v[220:221], off
	v_lshl_add_u64 v[222:223], s[42:43], 0, v[156:157]
	s_mov_b32 m0, s7
	s_nop 0
	global_load_lds_dwordx4 v[222:223], off
	s_waitcnt vmcnt(10)
	s_barrier
	s_waitcnt lgkmcnt(0)
	s_waitcnt lgkmcnt(0)
	v_mfma_f32_16x16x32_bf16 v[62:65], v[130:133], v[146:149], 0
	v_mfma_f32_16x16x32_bf16 v[58:61], v[138:141], v[146:149], 0
	v_mfma_f32_16x16x32_bf16 v[50:53], v[130:133], v[178:181], 0
	v_mfma_f32_16x16x32_bf16 v[42:45], v[138:141], v[178:181], 0
	v_mfma_f32_16x16x32_bf16 v[34:37], v[130:133], v[186:189], 0
	v_mfma_f32_16x16x32_bf16 v[26:29], v[138:141], v[186:189], 0
	v_mfma_f32_16x16x32_bf16 v[18:21], v[130:133], v[194:197], 0
	v_mfma_f32_16x16x32_bf16 v[10:13], v[138:141], v[194:197], 0
	v_mfma_f32_16x16x32_bf16 v[62:65], v[134:137], v[174:177], v[62:65]
	v_mfma_f32_16x16x32_bf16 v[58:61], v[142:145], v[174:177], v[58:61]
	v_mfma_f32_16x16x32_bf16 v[50:53], v[134:137], v[182:185], v[50:53]
	v_mfma_f32_16x16x32_bf16 v[42:45], v[142:145], v[182:185], v[42:45]
	v_mfma_f32_16x16x32_bf16 v[34:37], v[134:137], v[190:193], v[34:37]
	v_mfma_f32_16x16x32_bf16 v[26:29], v[142:145], v[190:193], v[26:29]
	v_mfma_f32_16x16x32_bf16 v[18:21], v[134:137], v[198:201], v[18:21]
	v_mfma_f32_16x16x32_bf16 v[10:13], v[142:145], v[198:201], v[10:13]
	s_barrier
	s_add_u32 s0, s40, 0x40000
	s_addc_u32 s1, s41, 0
	s_mov_b32 m0, s54
	v_lshl_add_u64 v[130:131], s[0:1], 0, v[158:159]
	global_load_lds_dwordx4 v[130:131], off
	v_lshl_add_u64 v[130:131], s[0:1], 0, v[154:155]
	s_add_i32 m0, s54, 0x2000
	s_nop 0
	global_load_lds_dwordx4 v[130:131], off
	s_waitcnt vmcnt(10)
	s_barrier
	v_mfma_f32_16x16x32_bf16 v[54:57], v[202:205], v[146:149], 0
	v_mfma_f32_16x16x32_bf16 v[46:49], v[210:213], v[146:149], 0
	v_mfma_f32_16x16x32_bf16 v[38:41], v[202:205], v[178:181], 0
	v_mfma_f32_16x16x32_bf16 v[30:33], v[210:213], v[178:181], 0
	v_mfma_f32_16x16x32_bf16 v[22:25], v[202:205], v[186:189], 0
	v_mfma_f32_16x16x32_bf16 v[14:17], v[210:213], v[186:189], 0
	v_mfma_f32_16x16x32_bf16 v[6:9], v[202:205], v[194:197], 0
	v_mfma_f32_16x16x32_bf16 v[2:5], v[210:213], v[194:197], 0
	v_mfma_f32_16x16x32_bf16 v[54:57], v[206:209], v[174:177], v[54:57]
	v_mfma_f32_16x16x32_bf16 v[46:49], v[214:217], v[174:177], v[46:49]
	v_mfma_f32_16x16x32_bf16 v[38:41], v[206:209], v[182:185], v[38:41]
	v_mfma_f32_16x16x32_bf16 v[30:33], v[214:217], v[182:185], v[30:33]
	v_mfma_f32_16x16x32_bf16 v[22:25], v[206:209], v[190:193], v[22:25]
	v_mfma_f32_16x16x32_bf16 v[14:17], v[214:217], v[190:193], v[14:17]
	v_mfma_f32_16x16x32_bf16 v[6:9], v[206:209], v[198:201], v[6:9]
	v_mfma_f32_16x16x32_bf16 v[2:5], v[214:217], v[198:201], v[2:5]
	s_add_i32 s70, 0, 0x18000
	v_add_u32_e32 v142, s70, v169
	s_barrier
	ds_read_b128 v[130:133], v142
	ds_read_b128 v[134:137], v142 offset:1024
	ds_read_b128 v[138:141], v142 offset:2048
	ds_read_b128 v[142:145], v142 offset:3072
	s_add_u32 s0, s42, 0x40000
	s_addc_u32 s1, s43, 0
	s_mov_b32 m0, s10
	v_lshl_add_u64 v[202:203], s[0:1], 0, v[160:161]
	ds_read_b128 v[146:149], v171 offset:32768
	ds_read_b128 v[174:177], v171 offset:33792
	ds_read_b128 v[178:181], v171 offset:34816
	ds_read_b128 v[182:185], v171 offset:35840
	ds_read_b128 v[186:189], v171 offset:36864
	ds_read_b128 v[190:193], v171 offset:37888
	ds_read_b128 v[194:197], v171 offset:38912
	ds_read_b128 v[198:201], v171 offset:39936
	global_load_lds_dwordx4 v[202:203], off
	v_lshl_add_u64 v[202:203], s[0:1], 0, v[156:157]
	s_mov_b32 m0, s11
	s_nop 0
	global_load_lds_dwordx4 v[202:203], off
	s_waitcnt lgkmcnt(8)
	s_waitcnt vmcnt(10)
	s_barrier
	s_waitcnt lgkmcnt(0)
	s_waitcnt lgkmcnt(0)
	v_mfma_f32_16x16x32_bf16 v[126:129], v[130:133], v[146:149], v[126:129]
	v_mfma_f32_16x16x32_bf16 v[122:125], v[138:141], v[146:149], v[122:125]
	v_mfma_f32_16x16x32_bf16 v[118:121], v[130:133], v[178:181], v[118:121]
	v_mfma_f32_16x16x32_bf16 v[110:113], v[138:141], v[178:181], v[110:113]
	v_mfma_f32_16x16x32_bf16 v[98:101], v[130:133], v[186:189], v[98:101]
	v_mfma_f32_16x16x32_bf16 v[90:93], v[138:141], v[186:189], v[90:93]
	v_mfma_f32_16x16x32_bf16 v[82:85], v[130:133], v[194:197], v[82:85]
	v_mfma_f32_16x16x32_bf16 v[74:77], v[138:141], v[194:197], v[74:77]
	v_mfma_f32_16x16x32_bf16 v[126:129], v[134:137], v[174:177], v[126:129]
	v_mfma_f32_16x16x32_bf16 v[122:125], v[142:145], v[174:177], v[122:125]
	v_mfma_f32_16x16x32_bf16 v[118:121], v[134:137], v[182:185], v[118:121]
	v_mfma_f32_16x16x32_bf16 v[110:113], v[142:145], v[182:185], v[110:113]
	v_mfma_f32_16x16x32_bf16 v[98:101], v[134:137], v[190:193], v[98:101]
	v_mfma_f32_16x16x32_bf16 v[90:93], v[142:145], v[190:193], v[90:93]
	v_mfma_f32_16x16x32_bf16 v[82:85], v[134:137], v[198:201], v[82:85]
	v_mfma_f32_16x16x32_bf16 v[74:77], v[142:145], v[198:201], v[74:77]
	s_barrier
	s_add_i32 s42, 0, 0x1c000
	s_add_i32 s0, s70, s5
	v_add_u32_e32 v173, s42, v169
	v_lshl_add_u64 v[166:167], v[166:167], 0, s[28:29]
	s_mov_b32 m0, s0
	ds_read_b128 v[202:205], v173
	ds_read_b128 v[206:209], v173 offset:1024
	ds_read_b128 v[210:213], v173 offset:2048
	ds_read_b128 v[214:217], v173 offset:3072
	global_load_lds_dwordx4 v[166:167], off
	v_lshl_add_u64 v[166:167], v[218:219], 0, s[28:29]
	s_add_i32 m0, s0, 0x2000
	s_nop 0
	global_load_lds_dwordx4 v[166:167], off
	s_waitcnt vmcnt(10)
	s_barrier
	s_waitcnt lgkmcnt(0)
	s_waitcnt lgkmcnt(0)
	v_mfma_f32_16x16x32_bf16 v[114:117], v[202:205], v[146:149], v[114:117]
	v_mfma_f32_16x16x32_bf16 v[106:109], v[210:213], v[146:149], v[106:109]
	v_mfma_f32_16x16x32_bf16 v[102:105], v[202:205], v[178:181], v[102:105]
	v_mfma_f32_16x16x32_bf16 v[94:97], v[210:213], v[178:181], v[94:97]
	v_mfma_f32_16x16x32_bf16 v[86:89], v[202:205], v[186:189], v[86:89]
	v_mfma_f32_16x16x32_bf16 v[78:81], v[210:213], v[186:189], v[78:81]
	v_mfma_f32_16x16x32_bf16 v[70:73], v[202:205], v[194:197], v[70:73]
	v_mfma_f32_16x16x32_bf16 v[66:69], v[210:213], v[194:197], v[66:69]
	v_mfma_f32_16x16x32_bf16 v[114:117], v[206:209], v[174:177], v[114:117]
	v_mfma_f32_16x16x32_bf16 v[106:109], v[214:217], v[174:177], v[106:109]
	v_mfma_f32_16x16x32_bf16 v[102:105], v[206:209], v[182:185], v[102:105]
	v_mfma_f32_16x16x32_bf16 v[94:97], v[214:217], v[182:185], v[94:97]
	v_mfma_f32_16x16x32_bf16 v[86:89], v[206:209], v[190:193], v[86:89]
	v_mfma_f32_16x16x32_bf16 v[78:81], v[214:217], v[190:193], v[78:81]
	v_mfma_f32_16x16x32_bf16 v[70:73], v[206:209], v[198:201], v[70:73]
	v_mfma_f32_16x16x32_bf16 v[66:69], v[214:217], v[198:201], v[66:69]
	s_mov_b32 m0, s48
	v_lshl_add_u64 v[166:167], v[220:221], 0, s[28:29]
	s_barrier
	ds_read_b128 v[146:149], v171 offset:49152
	ds_read_b128 v[174:177], v171 offset:50176
	ds_read_b128 v[178:181], v171 offset:51200
	ds_read_b128 v[182:185], v171 offset:52224
	ds_read_b128 v[186:189], v171 offset:53248
	ds_read_b128 v[190:193], v171 offset:54272
	ds_read_b128 v[194:197], v171 offset:55296
	ds_read_b128 v[198:201], v171 offset:56320
	global_load_lds_dwordx4 v[166:167], off
	v_lshl_add_u64 v[166:167], v[222:223], 0, s[28:29]
	s_mov_b32 m0, s49
	s_nop 0
	global_load_lds_dwordx4 v[166:167], off
	s_waitcnt vmcnt(10)
	s_barrier
	s_waitcnt lgkmcnt(0)
	s_waitcnt lgkmcnt(0)
	v_mfma_f32_16x16x32_bf16 v[62:65], v[130:133], v[146:149], v[62:65]
	v_mfma_f32_16x16x32_bf16 v[58:61], v[138:141], v[146:149], v[58:61]
	v_mfma_f32_16x16x32_bf16 v[50:53], v[130:133], v[178:181], v[50:53]
	v_mfma_f32_16x16x32_bf16 v[42:45], v[138:141], v[178:181], v[42:45]
	v_mfma_f32_16x16x32_bf16 v[34:37], v[130:133], v[186:189], v[34:37]
	v_mfma_f32_16x16x32_bf16 v[26:29], v[138:141], v[186:189], v[26:29]
	v_mfma_f32_16x16x32_bf16 v[18:21], v[130:133], v[194:197], v[18:21]
	v_mfma_f32_16x16x32_bf16 v[10:13], v[138:141], v[194:197], v[10:13]
	v_mfma_f32_16x16x32_bf16 v[62:65], v[134:137], v[174:177], v[62:65]
	v_mfma_f32_16x16x32_bf16 v[58:61], v[142:145], v[174:177], v[58:61]
	v_mfma_f32_16x16x32_bf16 v[50:53], v[134:137], v[182:185], v[50:53]
	v_mfma_f32_16x16x32_bf16 v[42:45], v[142:145], v[182:185], v[42:45]
	v_mfma_f32_16x16x32_bf16 v[34:37], v[134:137], v[190:193], v[34:37]
	v_mfma_f32_16x16x32_bf16 v[26:29], v[142:145], v[190:193], v[26:29]
	v_mfma_f32_16x16x32_bf16 v[18:21], v[134:137], v[198:201], v[18:21]
	v_mfma_f32_16x16x32_bf16 v[10:13], v[142:145], v[198:201], v[10:13]
	s_barrier
	s_add_u32 s0, s40, 0x40080
	s_addc_u32 s1, s41, 0
	s_add_i32 s40, s42, s5
	v_lshl_add_u64 v[130:131], s[0:1], 0, v[158:159]
	s_mov_b32 m0, s40
	s_nop 0
	global_load_lds_dwordx4 v[130:131], off
	v_lshl_add_u64 v[130:131], s[0:1], 0, v[154:155]
	s_add_i32 m0, s40, 0x2000
	s_nop 0
	global_load_lds_dwordx4 v[130:131], off
	s_waitcnt vmcnt(10)
	s_barrier
	v_mfma_f32_16x16x32_bf16 v[54:57], v[202:205], v[146:149], v[54:57]
	v_mfma_f32_16x16x32_bf16 v[46:49], v[210:213], v[146:149], v[46:49]
	v_mfma_f32_16x16x32_bf16 v[38:41], v[202:205], v[178:181], v[38:41]
	v_mfma_f32_16x16x32_bf16 v[30:33], v[210:213], v[178:181], v[30:33]
	v_mfma_f32_16x16x32_bf16 v[22:25], v[202:205], v[186:189], v[22:25]
	v_mfma_f32_16x16x32_bf16 v[14:17], v[210:213], v[186:189], v[14:17]
	v_mfma_f32_16x16x32_bf16 v[6:9], v[202:205], v[194:197], v[6:9]
	v_mfma_f32_16x16x32_bf16 v[2:5], v[210:213], v[194:197], v[2:5]
	v_mfma_f32_16x16x32_bf16 v[54:57], v[206:209], v[174:177], v[54:57]
	v_mfma_f32_16x16x32_bf16 v[46:49], v[214:217], v[174:177], v[46:49]
	v_mfma_f32_16x16x32_bf16 v[38:41], v[206:209], v[182:185], v[38:41]
	v_mfma_f32_16x16x32_bf16 v[30:33], v[214:217], v[182:185], v[30:33]
	v_mfma_f32_16x16x32_bf16 v[22:25], v[206:209], v[190:193], v[22:25]
	v_mfma_f32_16x16x32_bf16 v[14:17], v[214:217], v[190:193], v[14:17]
	v_mfma_f32_16x16x32_bf16 v[6:9], v[206:209], v[198:201], v[6:9]
	v_mfma_f32_16x16x32_bf16 v[2:5], v[214:217], v[198:201], v[2:5]
	s_add_i32 s69, s69, 2
	s_add_u32 s64, s64, 0x100
	s_addc_u32 s65, s65, 0
	s_add_u32 s38, s38, 0x100
	s_addc_u32 s39, s39, 0
	s_cmp_gt_u32 s69, 13
	s_barrier
	s_cbranch_scc1 .Lpeel_exit_5

.Lpeel_exit_5:
	s_lshl_b32 s0, s58, 8
	v_mov_b32_e32 v130, v151
	v_mov_b32_e32 v131, v153
	s_or_b32 s0, s0, s45
	s_mov_b32 s58, s57
	v_lshl_add_u32 v166, v131, 3, s0
	s_lshl_b32 s0, s59, 8
	s_add_i32 s0, s0, s44
	v_add_u32_e32 v173, s0, v130
	v_mov_b32_e32 v130, v173
	v_ashrrev_i32_e32 v167, 31, v166
	v_ashrrev_i32_e32 v131, 31, v130
	v_lshlrev_b64 v[130:131], 10, v[130:131]
	v_lshl_add_u64 v[130:131], v[130:131], 0, v[166:167]
	v_lshlrev_b64 v[186:187], 1, v[130:131]
	v_lshl_add_u64 v[130:131], s[12:13], 0, v[186:187]
	global_load_dwordx4 v[174:177], v[130:131], off
	global_load_dwordx4 v[178:181], v[130:131], off offset:256
	v_add_co_u32_e32 v132, vcc, s47, v130
	s_mov_b32 s59, s56
	s_nop 0
	v_addc_co_u32_e32 v133, vcc, 0, v131, vcc
	global_load_dwordx4 v[182:185], v[132:133], off
	global_load_dwordx4 v[146:149], v[132:133], off offset:256
	v_add_co_u32_e32 v132, vcc, s31, v130
	s_waitcnt vmcnt(0) lgkmcnt(0)
	v_lshlrev_b32_e32 v188, 16, v174
	v_addc_co_u32_e32 v133, vcc, 0, v131, vcc
	global_load_dwordx4 v[142:145], v[132:133], off
	global_load_dwordx4 v[138:141], v[132:133], off offset:256
	v_add_co_u32_e32 v130, vcc, s46, v130
	v_and_b32_e32 v189, 0xffff0000, v174
	s_nop 0
	v_addc_co_u32_e32 v131, vcc, 0, v131, vcc
	global_load_dwordx4 v[134:137], v[130:131], off
	s_nop 0
	global_load_dwordx4 v[130:133], v[130:131], off offset:256
	v_lshlrev_b32_e32 v174, 16, v175
	v_and_b32_e32 v175, 0xffff0000, v175
	v_lshlrev_b32_e32 v190, 16, v176
	v_and_b32_e32 v191, 0xffff0000, v176
	v_lshlrev_b32_e32 v176, 16, v177
	v_and_b32_e32 v177, 0xffff0000, v177
	v_pk_fma_f32 v[128:129], v[174:175], s[30:31], v[128:129] op_sel_hi:[1,0,1]
	v_pk_fma_f32 v[126:127], v[188:189], s[30:31], v[126:127] op_sel_hi:[1,0,1]
	v_pk_fma_f32 v[174:175], v[176:177], s[30:31], v[124:125] op_sel_hi:[1,0,1]
	v_pk_fma_f32 v[122:123], v[190:191], s[30:31], v[122:123] op_sel_hi:[1,0,1]
	v_cvt_pk_bf16_f32 v124, v126, v127
	v_cvt_pk_bf16_f32 v125, v128, v129
	v_cvt_pk_bf16_f32 v126, v122, v123
	v_cvt_pk_bf16_f32 v127, v174, v175
	v_lshl_add_u64 v[122:123], s[24:25], 0, v[186:187]
	global_store_dwordx4 v[122:123], v[124:127], off
	v_lshlrev_b32_e32 v128, 16, v180
	v_and_b32_e32 v129, 0xffff0000, v180
	v_lshlrev_b32_e32 v124, 16, v178
	v_and_b32_e32 v125, 0xffff0000, v178
	v_lshlrev_b32_e32 v126, 16, v179
	v_and_b32_e32 v127, 0xffff0000, v179
	v_lshlrev_b32_e32 v174, 16, v181
	v_and_b32_e32 v175, 0xffff0000, v181
	v_pk_fma_f32 v[116:117], v[126:127], s[30:31], v[116:117] op_sel_hi:[1,0,1]
	v_pk_fma_f32 v[114:115], v[124:125], s[30:31], v[114:115] op_sel_hi:[1,0,1]
	v_pk_fma_f32 v[124:125], v[174:175], s[30:31], v[108:109] op_sel_hi:[1,0,1]
	v_pk_fma_f32 v[108:109], v[128:129], s[30:31], v[106:107] op_sel_hi:[1,0,1]
	v_cvt_pk_bf16_f32 v106, v114, v115
	v_cvt_pk_bf16_f32 v107, v116, v117
	v_cvt_pk_bf16_f32 v108, v108, v109
	v_cvt_pk_bf16_f32 v109, v124, v125
	global_store_dwordx4 v[122:123], v[106:109], off offset:256
	v_lshlrev_b32_e32 v114, 16, v184
	v_and_b32_e32 v115, 0xffff0000, v184
	v_lshlrev_b32_e32 v106, 16, v182
	v_and_b32_e32 v107, 0xffff0000, v182
	v_lshlrev_b32_e32 v108, 16, v183
	v_and_b32_e32 v109, 0xffff0000, v183
	v_lshlrev_b32_e32 v116, 16, v185
	v_and_b32_e32 v117, 0xffff0000, v185
	v_pk_fma_f32 v[108:109], v[108:109], s[30:31], v[120:121] op_sel_hi:[1,0,1]
	v_pk_fma_f32 v[106:107], v[106:107], s[30:31], v[118:119] op_sel_hi:[1,0,1]
	v_pk_fma_f32 v[110:111], v[114:115], s[30:31], v[110:111] op_sel_hi:[1,0,1]
	v_pk_fma_f32 v[112:113], v[116:117], s[30:31], v[112:113] op_sel_hi:[1,0,1]
	v_cvt_pk_bf16_f32 v106, v106, v107
	v_cvt_pk_bf16_f32 v107, v108, v109
	v_cvt_pk_bf16_f32 v108, v110, v111
	v_add_co_u32_e32 v110, vcc, s47, v122
	v_cvt_pk_bf16_f32 v109, v112, v113
	s_nop 0
	v_addc_co_u32_e32 v111, vcc, 0, v123, vcc
	global_store_dwordx4 v[110:111], v[106:109], off
	v_lshlrev_b32_e32 v112, 16, v148
	v_and_b32_e32 v113, 0xffff0000, v148
	v_lshlrev_b32_e32 v106, 16, v146
	v_and_b32_e32 v107, 0xffff0000, v146
	v_lshlrev_b32_e32 v108, 16, v147
	v_and_b32_e32 v109, 0xffff0000, v147
	v_lshlrev_b32_e32 v114, 16, v149
	v_and_b32_e32 v115, 0xffff0000, v149
	v_pk_fma_f32 v[104:105], v[108:109], s[30:31], v[104:105] op_sel_hi:[1,0,1]
	v_pk_fma_f32 v[102:103], v[106:107], s[30:31], v[102:103] op_sel_hi:[1,0,1]
	v_pk_fma_f32 v[106:107], v[114:115], s[30:31], v[96:97] op_sel_hi:[1,0,1]
	v_pk_fma_f32 v[96:97], v[112:113], s[30:31], v[94:95] op_sel_hi:[1,0,1]
	v_cvt_pk_bf16_f32 v94, v102, v103
	v_cvt_pk_bf16_f32 v95, v104, v105
	v_cvt_pk_bf16_f32 v96, v96, v97
	v_cvt_pk_bf16_f32 v97, v106, v107
	global_store_dwordx4 v[110:111], v[94:97], off offset:256
	s_waitcnt vmcnt(0) lgkmcnt(0)
	v_lshlrev_b32_e32 v102, 16, v144
	v_lshlrev_b32_e32 v94, 16, v142
	v_and_b32_e32 v95, 0xffff0000, v142
	v_lshlrev_b32_e32 v96, 16, v143
	v_and_b32_e32 v97, 0xffff0000, v143
	v_and_b32_e32 v103, 0xffff0000, v144
	v_lshlrev_b32_e32 v104, 16, v145
	v_and_b32_e32 v105, 0xffff0000, v145
	v_pk_fma_f32 v[94:95], v[94:95], s[30:31], v[98:99] op_sel_hi:[1,0,1]
	v_pk_fma_f32 v[96:97], v[96:97], s[30:31], v[100:101] op_sel_hi:[1,0,1]
	v_pk_fma_f32 v[98:99], v[104:105], s[30:31], v[92:93] op_sel_hi:[1,0,1]
	v_pk_fma_f32 v[92:93], v[102:103], s[30:31], v[90:91] op_sel_hi:[1,0,1]
	v_cvt_pk_bf16_f32 v90, v94, v95
	v_add_co_u32_e32 v94, vcc, s31, v122
	v_cvt_pk_bf16_f32 v91, v96, v97
	v_cvt_pk_bf16_f32 v92, v92, v93
	v_cvt_pk_bf16_f32 v93, v98, v99
	v_addc_co_u32_e32 v95, vcc, 0, v123, vcc
	global_store_dwordx4 v[94:95], v[90:93], off
	v_lshlrev_b32_e32 v96, 16, v140
	v_and_b32_e32 v97, 0xffff0000, v140
	v_lshlrev_b32_e32 v90, 16, v138
	v_and_b32_e32 v91, 0xffff0000, v138
	v_lshlrev_b32_e32 v92, 16, v139
	v_and_b32_e32 v93, 0xffff0000, v139
	v_lshlrev_b32_e32 v98, 16, v141
	v_and_b32_e32 v99, 0xffff0000, v141
	v_pk_fma_f32 v[88:89], v[92:93], s[30:31], v[88:89] op_sel_hi:[1,0,1]
	v_pk_fma_f32 v[86:87], v[90:91], s[30:31], v[86:87] op_sel_hi:[1,0,1]
	v_pk_fma_f32 v[90:91], v[98:99], s[30:31], v[80:81] op_sel_hi:[1,0,1]
	v_pk_fma_f32 v[80:81], v[96:97], s[30:31], v[78:79] op_sel_hi:[1,0,1]
	v_cvt_pk_bf16_f32 v78, v86, v87
	v_cvt_pk_bf16_f32 v79, v88, v89
	v_cvt_pk_bf16_f32 v80, v80, v81
	v_cvt_pk_bf16_f32 v81, v90, v91
	global_store_dwordx4 v[94:95], v[78:81], off offset:256
	v_lshlrev_b32_e32 v86, 16, v136
	v_and_b32_e32 v87, 0xffff0000, v136
	v_lshlrev_b32_e32 v78, 16, v134
	v_and_b32_e32 v79, 0xffff0000, v134
	v_lshlrev_b32_e32 v80, 16, v135
	v_and_b32_e32 v81, 0xffff0000, v135
	v_lshlrev_b32_e32 v88, 16, v137
	v_and_b32_e32 v89, 0xffff0000, v137
	v_pk_fma_f32 v[78:79], v[78:79], s[30:31], v[82:83] op_sel_hi:[1,0,1]
	v_pk_fma_f32 v[80:81], v[80:81], s[30:31], v[84:85] op_sel_hi:[1,0,1]
	v_pk_fma_f32 v[82:83], v[88:89], s[30:31], v[76:77] op_sel_hi:[1,0,1]
	v_pk_fma_f32 v[76:77], v[86:87], s[30:31], v[74:75] op_sel_hi:[1,0,1]
	v_cvt_pk_bf16_f32 v74, v78, v79
	v_add_co_u32_e32 v78, vcc, s46, v122
	v_cvt_pk_bf16_f32 v75, v80, v81
	v_cvt_pk_bf16_f32 v76, v76, v77
	v_cvt_pk_bf16_f32 v77, v82, v83
	v_addc_co_u32_e32 v79, vcc, 0, v123, vcc
	global_store_dwordx4 v[78:79], v[74:77], off
	v_lshlrev_b32_e32 v80, 16, v132
	v_and_b32_e32 v81, 0xffff0000, v132
	v_lshlrev_b32_e32 v74, 16, v130
	v_and_b32_e32 v75, 0xffff0000, v130
	v_lshlrev_b32_e32 v76, 16, v131
	v_and_b32_e32 v77, 0xffff0000, v131
	v_lshlrev_b32_e32 v82, 16, v133
	v_and_b32_e32 v83, 0xffff0000, v133
	v_pk_fma_f32 v[72:73], v[76:77], s[30:31], v[72:73] op_sel_hi:[1,0,1]
	v_pk_fma_f32 v[70:71], v[74:75], s[30:31], v[70:71] op_sel_hi:[1,0,1]
	v_pk_fma_f32 v[74:75], v[82:83], s[30:31], v[68:69] op_sel_hi:[1,0,1]
	v_pk_fma_f32 v[68:69], v[80:81], s[30:31], v[66:67] op_sel_hi:[1,0,1]
	v_cvt_pk_bf16_f32 v66, v70, v71
	v_cvt_pk_bf16_f32 v67, v72, v73
	v_cvt_pk_bf16_f32 v68, v68, v69
	v_cvt_pk_bf16_f32 v69, v74, v75
	global_store_dwordx4 v[78:79], v[66:69], off offset:256
	s_nop 1
	v_add_u32_e32 v66, 0x80, v173
	s_nop 0
	v_ashrrev_i32_e32 v67, 31, v66
	v_lshlrev_b64 v[66:67], 10, v[66:67]
	v_lshl_add_u64 v[66:67], v[66:67], 0, v[166:167]
	v_lshlrev_b64 v[98:99], 1, v[66:67]
	v_lshl_add_u64 v[90:91], s[12:13], 0, v[98:99]
	global_load_dwordx4 v[66:69], v[90:91], off
	global_load_dwordx4 v[70:73], v[90:91], off offset:256
	v_add_co_u32_e32 v78, vcc, s47, v90
	s_waitcnt vmcnt(0) lgkmcnt(0)
	v_lshlrev_b32_e32 v100, 16, v66
	v_addc_co_u32_e32 v79, vcc, 0, v91, vcc
	global_load_dwordx4 v[74:77], v[78:79], off
	s_nop 0
	global_load_dwordx4 v[78:81], v[78:79], off offset:256
	v_add_co_u32_e32 v86, vcc, s31, v90
	v_and_b32_e32 v101, 0xffff0000, v66
	s_nop 0
	v_addc_co_u32_e32 v87, vcc, 0, v91, vcc
	global_load_dwordx4 v[82:85], v[86:87], off
	s_nop 0
	global_load_dwordx4 v[86:89], v[86:87], off offset:256
	v_add_co_u32_e32 v94, vcc, s46, v90
	v_lshlrev_b32_e32 v66, 16, v67
	s_nop 0
	v_addc_co_u32_e32 v95, vcc, 0, v91, vcc
	global_load_dwordx4 v[90:93], v[94:95], off
	s_nop 0
	global_load_dwordx4 v[94:97], v[94:95], off offset:256
	v_and_b32_e32 v67, 0xffff0000, v67
	v_lshlrev_b32_e32 v102, 16, v68
	v_and_b32_e32 v103, 0xffff0000, v68
	v_lshlrev_b32_e32 v68, 16, v69
	v_and_b32_e32 v69, 0xffff0000, v69
	v_pk_fma_f32 v[64:65], v[66:67], s[30:31], v[64:65] op_sel_hi:[1,0,1]
	v_pk_fma_f32 v[62:63], v[100:101], s[30:31], v[62:63] op_sel_hi:[1,0,1]
	v_pk_fma_f32 v[66:67], v[68:69], s[30:31], v[60:61] op_sel_hi:[1,0,1]
	v_pk_fma_f32 v[60:61], v[102:103], s[30:31], v[58:59] op_sel_hi:[1,0,1]
	v_cvt_pk_bf16_f32 v58, v62, v63
	v_cvt_pk_bf16_f32 v59, v64, v65
	v_cvt_pk_bf16_f32 v60, v60, v61
	v_cvt_pk_bf16_f32 v61, v66, v67
	v_lshl_add_u64 v[62:63], s[24:25], 0, v[98:99]
	global_store_dwordx4 v[62:63], v[58:61], off
	v_lshlrev_b32_e32 v64, 16, v72
	v_and_b32_e32 v65, 0xffff0000, v72
	v_lshlrev_b32_e32 v58, 16, v70
	v_and_b32_e32 v59, 0xffff0000, v70
	v_lshlrev_b32_e32 v60, 16, v71
	v_and_b32_e32 v61, 0xffff0000, v71
	v_lshlrev_b32_e32 v66, 16, v73
	v_and_b32_e32 v67, 0xffff0000, v73
	v_pk_fma_f32 v[56:57], v[60:61], s[30:31], v[56:57] op_sel_hi:[1,0,1]
	v_pk_fma_f32 v[54:55], v[58:59], s[30:31], v[54:55] op_sel_hi:[1,0,1]
	v_pk_fma_f32 v[58:59], v[66:67], s[30:31], v[48:49] op_sel_hi:[1,0,1]
	v_pk_fma_f32 v[48:49], v[64:65], s[30:31], v[46:47] op_sel_hi:[1,0,1]
	v_cvt_pk_bf16_f32 v46, v54, v55
	v_cvt_pk_bf16_f32 v47, v56, v57
	v_cvt_pk_bf16_f32 v48, v48, v49
	v_cvt_pk_bf16_f32 v49, v58, v59
	global_store_dwordx4 v[62:63], v[46:49], off offset:256
	s_waitcnt vmcnt(0) lgkmcnt(0)
	v_lshlrev_b32_e32 v54, 16, v76
	v_lshlrev_b32_e32 v46, 16, v74
	v_and_b32_e32 v47, 0xffff0000, v74
	v_lshlrev_b32_e32 v48, 16, v75
	v_and_b32_e32 v49, 0xffff0000, v75
	v_and_b32_e32 v55, 0xffff0000, v76
	v_lshlrev_b32_e32 v56, 16, v77
	v_and_b32_e32 v57, 0xffff0000, v77
	v_pk_fma_f32 v[46:47], v[46:47], s[30:31], v[50:51] op_sel_hi:[1,0,1]
	v_pk_fma_f32 v[48:49], v[48:49], s[30:31], v[52:53] op_sel_hi:[1,0,1]
	v_pk_fma_f32 v[50:51], v[56:57], s[30:31], v[44:45] op_sel_hi:[1,0,1]
	v_pk_fma_f32 v[44:45], v[54:55], s[30:31], v[42:43] op_sel_hi:[1,0,1]
	v_cvt_pk_bf16_f32 v42, v46, v47
	v_add_co_u32_e32 v46, vcc, s47, v62
	v_cvt_pk_bf16_f32 v43, v48, v49
	v_cvt_pk_bf16_f32 v44, v44, v45
	v_cvt_pk_bf16_f32 v45, v50, v51
	v_addc_co_u32_e32 v47, vcc, 0, v63, vcc
	global_store_dwordx4 v[46:47], v[42:45], off
	v_lshlrev_b32_e32 v48, 16, v80
	v_and_b32_e32 v49, 0xffff0000, v80
	v_lshlrev_b32_e32 v42, 16, v78
	v_and_b32_e32 v43, 0xffff0000, v78
	v_lshlrev_b32_e32 v44, 16, v79
	v_and_b32_e32 v45, 0xffff0000, v79
	v_lshlrev_b32_e32 v50, 16, v81
	v_and_b32_e32 v51, 0xffff0000, v81
	v_pk_fma_f32 v[40:41], v[44:45], s[30:31], v[40:41] op_sel_hi:[1,0,1]
	v_pk_fma_f32 v[38:39], v[42:43], s[30:31], v[38:39] op_sel_hi:[1,0,1]
	v_pk_fma_f32 v[42:43], v[50:51], s[30:31], v[32:33] op_sel_hi:[1,0,1]
	v_pk_fma_f32 v[32:33], v[48:49], s[30:31], v[30:31] op_sel_hi:[1,0,1]
	v_cvt_pk_bf16_f32 v30, v38, v39
	v_cvt_pk_bf16_f32 v31, v40, v41
	v_cvt_pk_bf16_f32 v32, v32, v33
	v_cvt_pk_bf16_f32 v33, v42, v43
	global_store_dwordx4 v[46:47], v[30:33], off offset:256
	v_lshlrev_b32_e32 v38, 16, v84
	v_and_b32_e32 v39, 0xffff0000, v84
	v_lshlrev_b32_e32 v30, 16, v82
	v_and_b32_e32 v31, 0xffff0000, v82
	v_lshlrev_b32_e32 v32, 16, v83
	v_and_b32_e32 v33, 0xffff0000, v83
	v_lshlrev_b32_e32 v40, 16, v85
	v_and_b32_e32 v41, 0xffff0000, v85
	v_pk_fma_f32 v[30:31], v[30:31], s[30:31], v[34:35] op_sel_hi:[1,0,1]
	v_pk_fma_f32 v[32:33], v[32:33], s[30:31], v[36:37] op_sel_hi:[1,0,1]
	v_pk_fma_f32 v[34:35], v[40:41], s[30:31], v[28:29] op_sel_hi:[1,0,1]
	v_pk_fma_f32 v[28:29], v[38:39], s[30:31], v[26:27] op_sel_hi:[1,0,1]
	v_cvt_pk_bf16_f32 v26, v30, v31
	v_add_co_u32_e32 v30, vcc, s31, v62
	v_cvt_pk_bf16_f32 v27, v32, v33
	v_cvt_pk_bf16_f32 v28, v28, v29
	v_cvt_pk_bf16_f32 v29, v34, v35
	v_addc_co_u32_e32 v31, vcc, 0, v63, vcc
	global_store_dwordx4 v[30:31], v[26:29], off
	v_lshlrev_b32_e32 v32, 16, v88
	v_and_b32_e32 v33, 0xffff0000, v88
	v_lshlrev_b32_e32 v26, 16, v86
	v_and_b32_e32 v27, 0xffff0000, v86
	v_lshlrev_b32_e32 v28, 16, v87
	v_and_b32_e32 v29, 0xffff0000, v87
	v_lshlrev_b32_e32 v34, 16, v89
	v_and_b32_e32 v35, 0xffff0000, v89
	v_pk_fma_f32 v[24:25], v[28:29], s[30:31], v[24:25] op_sel_hi:[1,0,1]
	v_pk_fma_f32 v[22:23], v[26:27], s[30:31], v[22:23] op_sel_hi:[1,0,1]
	v_pk_fma_f32 v[26:27], v[34:35], s[30:31], v[16:17] op_sel_hi:[1,0,1]
	v_pk_fma_f32 v[16:17], v[32:33], s[30:31], v[14:15] op_sel_hi:[1,0,1]
	v_cvt_pk_bf16_f32 v14, v22, v23
	v_cvt_pk_bf16_f32 v15, v24, v25
	v_cvt_pk_bf16_f32 v16, v16, v17
	v_cvt_pk_bf16_f32 v17, v26, v27
	global_store_dwordx4 v[30:31], v[14:17], off offset:256
	v_lshlrev_b32_e32 v22, 16, v92
	v_and_b32_e32 v23, 0xffff0000, v92
	v_lshlrev_b32_e32 v14, 16, v90
	v_and_b32_e32 v15, 0xffff0000, v90
	v_lshlrev_b32_e32 v16, 16, v91
	v_and_b32_e32 v17, 0xffff0000, v91
	v_lshlrev_b32_e32 v24, 16, v93
	v_and_b32_e32 v25, 0xffff0000, v93
	v_pk_fma_f32 v[14:15], v[14:15], s[30:31], v[18:19] op_sel_hi:[1,0,1]
	v_pk_fma_f32 v[16:17], v[16:17], s[30:31], v[20:21] op_sel_hi:[1,0,1]
	v_pk_fma_f32 v[18:19], v[24:25], s[30:31], v[12:13] op_sel_hi:[1,0,1]
	v_pk_fma_f32 v[12:13], v[22:23], s[30:31], v[10:11] op_sel_hi:[1,0,1]
	v_cvt_pk_bf16_f32 v10, v14, v15
	v_add_co_u32_e32 v14, vcc, s46, v62
	v_cvt_pk_bf16_f32 v11, v16, v17
	v_cvt_pk_bf16_f32 v12, v12, v13
	v_cvt_pk_bf16_f32 v13, v18, v19
	v_addc_co_u32_e32 v15, vcc, 0, v63, vcc
	global_store_dwordx4 v[14:15], v[10:13], off
	v_lshlrev_b32_e32 v16, 16, v96
	v_and_b32_e32 v17, 0xffff0000, v96
	v_lshlrev_b32_e32 v10, 16, v94
	v_and_b32_e32 v11, 0xffff0000, v94
	v_lshlrev_b32_e32 v12, 16, v95
	v_and_b32_e32 v13, 0xffff0000, v95
	v_lshlrev_b32_e32 v18, 16, v97
	v_and_b32_e32 v19, 0xffff0000, v97
	v_pk_fma_f32 v[8:9], v[12:13], s[30:31], v[8:9] op_sel_hi:[1,0,1]
	v_pk_fma_f32 v[6:7], v[10:11], s[30:31], v[6:7] op_sel_hi:[1,0,1]
	v_pk_fma_f32 v[10:11], v[18:19], s[30:31], v[4:5] op_sel_hi:[1,0,1]
	v_pk_fma_f32 v[4:5], v[16:17], s[30:31], v[2:3] op_sel_hi:[1,0,1]
	v_cvt_pk_bf16_f32 v2, v6, v7
	v_cvt_pk_bf16_f32 v3, v8, v9
	v_cvt_pk_bf16_f32 v4, v4, v5
	v_cvt_pk_bf16_f32 v5, v10, v11
	s_and_b64 vcc, exec, s[34:35]
	global_store_dwordx4 v[14:15], v[2:5], off offset:256
	s_cbranch_vccz .LBB0_1046
	s_waitcnt vmcnt(0)
	s_cmpk_gt_u32 s4, 0xff
	s_cbranch_scc1 .LBB0_1051
	s_barrier

.LBB0_1301:
	s_ashr_i32 s0, s54, 5
	s_ashr_i32 s1, s0, 31
	s_lshl_b64 s[0:1], s[0:1], 21
	s_add_u32 s14, s4, s0
	s_addc_u32 s15, s5, s1
	s_ashr_i32 s27, s26, 31
	s_lshl_b64 s[0:1], s[26:27], 18
	s_add_u32 s14, s14, s0
	s_addc_u32 s15, s15, s1
	s_and_b64 s[0:1], s[12:13], exec
	s_cselect_b32 s27, s15, s35
	s_cselect_b32 s29, s14, s34
	v_mov_b32_e32 v173, v163
	v_mov_b32_e32 v175, v163
	s_add_u32 s31, s34, 0x100
	s_addc_u32 s55, s35, 0
	v_lshl_add_u64 v[176:177], s[20:21], 0, v[174:175]
	v_lshl_add_u64 v[178:179], s[20:21], 0, v[172:173]
	s_mov_b32 s56, -2
	s_mov_b64 s[36:37], 0
	s_add_u32 s12, s36, 0x100
	s_addc_u32 s13, s37, 0
	s_add_u32 s34, s31, s36
	s_addc_u32 s35, s55, s37
	s_cmpk_eq_i32 s36, 0x300
	s_cselect_b64 vcc, -1, 0
	s_and_b64 s[0:1], vcc, exec
	s_cselect_b32 s1, 0, s12
	s_cselect_b32 s0, 0, s13
	s_cselect_b32 s34, s29, s34
	s_cselect_b32 s35, s27, s35
	s_add_u32 s38, s16, s1
	s_addc_u32 s39, s17, s0
	s_add_i32 s1, 0, 0x10000
	v_add_u32_e32 v14, s1, v197
	ds_read_b128 v[2:5], v14
	ds_read_b128 v[6:9], v14 offset:1024
	ds_read_b128 v[10:13], v14 offset:2048
	ds_read_b128 v[14:17], v14 offset:3072
	v_cndmask_b32_e32 v162, v168, v171, vcc
	v_cndmask_b32_e32 v184, v170, v198, vcc
	v_cndmask_b32_e32 v175, v172, v199, vcc
	v_cndmask_b32_e32 v173, v174, v200, vcc
	v_lshl_add_u64 v[18:19], v[178:179], 0, s[36:37]
	s_add_i32 m0, s45, 0xc000
	ds_read_b128 v[202:205], v169
	ds_read_b128 v[206:209], v169 offset:1024
	ds_read_b128 v[210:213], v169 offset:2048
	ds_read_b128 v[214:217], v169 offset:3072
	ds_read_b128 v[218:221], v169 offset:4096
	ds_read_b128 v[222:225], v169 offset:5120
	ds_read_b128 v[226:229], v169 offset:6144
	ds_read_b128 v[230:233], v169 offset:7168
	global_load_lds_dwordx4 v[18:19], off
	v_lshl_add_u64 v[18:19], v[176:177], 0, s[36:37]
	s_add_i32 m0, s45, 0xe000
	s_nop 0
	global_load_lds_dwordx4 v[18:19], off
	s_waitcnt lgkmcnt(8)
	s_waitcnt vmcnt(10)
	s_barrier
	s_waitcnt lgkmcnt(0)
	s_waitcnt lgkmcnt(0)
	v_mfma_scale_f32_16x16x128_f8f6f4 v[158:161], v[2:9], v[202:209], 0, v188, v188 op_sel_hi:[0,0,0]
	v_mfma_scale_f32_16x16x128_f8f6f4 v[150:153], v[10:17], v[202:209], 0, v188, v188 op_sel_hi:[0,0,0]
	v_mfma_scale_f32_16x16x128_f8f6f4 v[142:145], v[2:9], v[210:217], 0, v188, v188 op_sel_hi:[0,0,0]
	v_mfma_scale_f32_16x16x128_f8f6f4 v[134:137], v[10:17], v[210:217], 0, v188, v188 op_sel_hi:[0,0,0]
	v_mfma_scale_f32_16x16x128_f8f6f4 v[126:129], v[2:9], v[218:225], 0, v188, v188 op_sel_hi:[0,0,0]
	v_mfma_scale_f32_16x16x128_f8f6f4 v[118:121], v[10:17], v[218:225], 0, v188, v188 op_sel_hi:[0,0,0]
	v_mfma_scale_f32_16x16x128_f8f6f4 v[110:113], v[2:9], v[226:233], 0, v188, v188 op_sel_hi:[0,0,0]
	v_mfma_scale_f32_16x16x128_f8f6f4 v[102:105], v[10:17], v[226:233], 0, v188, v188 op_sel_hi:[0,0,0]
	s_barrier
	s_add_i32 s0, 0, 0x14000
	s_add_i32 s1, s1, s43
	v_add_u32_e32 v30, s0, v197
	v_lshl_add_u64 v[180:181], s[34:35], 0, v[164:165]
	s_mov_b32 m0, s1
	ds_read_b128 v[18:21], v30
	ds_read_b128 v[22:25], v30 offset:1024
	ds_read_b128 v[26:29], v30 offset:2048
	ds_read_b128 v[30:33], v30 offset:3072
	global_load_lds_dwordx4 v[180:181], off
	v_lshl_add_u64 v[182:183], s[34:35], 0, v[166:167]
	s_add_i32 m0, s1, 0x2000
	s_nop 0
	global_load_lds_dwordx4 v[182:183], off
	s_waitcnt vmcnt(10)
	s_barrier
	s_waitcnt lgkmcnt(0)
	s_waitcnt lgkmcnt(0)
	v_mfma_scale_f32_16x16x128_f8f6f4 v[154:157], v[18:25], v[202:209], 0, v188, v188 op_sel_hi:[0,0,0]
	v_mfma_scale_f32_16x16x128_f8f6f4 v[146:149], v[26:33], v[202:209], 0, v188, v188 op_sel_hi:[0,0,0]
	v_mfma_scale_f32_16x16x128_f8f6f4 v[138:141], v[18:25], v[210:217], 0, v188, v188 op_sel_hi:[0,0,0]
	v_mfma_scale_f32_16x16x128_f8f6f4 v[130:133], v[26:33], v[210:217], 0, v188, v188 op_sel_hi:[0,0,0]
	v_mfma_scale_f32_16x16x128_f8f6f4 v[122:125], v[18:25], v[218:225], 0, v188, v188 op_sel_hi:[0,0,0]
	v_mfma_scale_f32_16x16x128_f8f6f4 v[114:117], v[26:33], v[218:225], 0, v188, v188 op_sel_hi:[0,0,0]
	v_mfma_scale_f32_16x16x128_f8f6f4 v[106:109], v[18:25], v[226:233], 0, v188, v188 op_sel_hi:[0,0,0]
	v_mfma_scale_f32_16x16x128_f8f6f4 v[98:101], v[26:33], v[226:233], 0, v188, v188 op_sel_hi:[0,0,0]
	s_mov_b32 m0, s45
	s_barrier
	ds_read_b128 v[202:205], v169 offset:16384
	ds_read_b128 v[206:209], v169 offset:17408
	ds_read_b128 v[210:213], v169 offset:18432
	ds_read_b128 v[214:217], v169 offset:19456
	ds_read_b128 v[218:221], v169 offset:20480
	ds_read_b128 v[222:225], v169 offset:21504
	ds_read_b128 v[226:229], v169 offset:22528
	ds_read_b128 v[230:233], v169 offset:23552
	global_load_lds_dwordx4 v162, s[38:39]
	s_mov_b32 m0, s46
	v_mov_b32_e32 v185, v163
	global_load_lds_dwordx4 v184, s[38:39]
	s_waitcnt vmcnt(10)
	s_barrier
	s_waitcnt lgkmcnt(0)
	v_lshl_add_u64 v[186:187], s[38:39], 0, v[162:163]
	v_lshl_add_u64 v[184:185], s[38:39], 0, v[184:185]
	s_waitcnt lgkmcnt(0)
	v_mfma_scale_f32_16x16x128_f8f6f4 v[94:97], v[2:9], v[202:209], 0, v188, v188 op_sel_hi:[0,0,0]
	v_mfma_scale_f32_16x16x128_f8f6f4 v[86:89], v[10:17], v[202:209], 0, v188, v188 op_sel_hi:[0,0,0]
	v_mfma_scale_f32_16x16x128_f8f6f4 v[78:81], v[2:9], v[210:217], 0, v188, v188 op_sel_hi:[0,0,0]
	v_mfma_scale_f32_16x16x128_f8f6f4 v[70:73], v[10:17], v[210:217], 0, v188, v188 op_sel_hi:[0,0,0]
	v_mfma_scale_f32_16x16x128_f8f6f4 v[62:65], v[2:9], v[218:225], 0, v188, v188 op_sel_hi:[0,0,0]
	v_mfma_scale_f32_16x16x128_f8f6f4 v[54:57], v[10:17], v[218:225], 0, v188, v188 op_sel_hi:[0,0,0]
	v_mfma_scale_f32_16x16x128_f8f6f4 v[46:49], v[2:9], v[226:233], 0, v188, v188 op_sel_hi:[0,0,0]
	v_mfma_scale_f32_16x16x128_f8f6f4 v[38:41], v[10:17], v[226:233], 0, v188, v188 op_sel_hi:[0,0,0]
	s_barrier
	s_add_u32 s36, s34, 0x20000
	s_addc_u32 s37, s35, 0
	s_add_i32 s0, s0, s43
	v_lshl_add_u64 v[2:3], s[36:37], 0, v[164:165]
	s_mov_b32 m0, s0
	s_nop 0
	global_load_lds_dwordx4 v[2:3], off
	v_lshl_add_u64 v[2:3], s[36:37], 0, v[166:167]
	s_add_i32 m0, s0, 0x2000
	s_nop 0
	global_load_lds_dwordx4 v[2:3], off
	s_waitcnt vmcnt(10)
	s_barrier
	v_mfma_scale_f32_16x16x128_f8f6f4 v[90:93], v[18:25], v[202:209], 0, v188, v188 op_sel_hi:[0,0,0]
	v_mfma_scale_f32_16x16x128_f8f6f4 v[82:85], v[26:33], v[202:209], 0, v188, v188 op_sel_hi:[0,0,0]
	v_mfma_scale_f32_16x16x128_f8f6f4 v[74:77], v[18:25], v[210:217], 0, v188, v188 op_sel_hi:[0,0,0]
	v_mfma_scale_f32_16x16x128_f8f6f4 v[66:69], v[26:33], v[210:217], 0, v188, v188 op_sel_hi:[0,0,0]
	v_mfma_scale_f32_16x16x128_f8f6f4 v[58:61], v[18:25], v[218:225], 0, v188, v188 op_sel_hi:[0,0,0]
	v_mfma_scale_f32_16x16x128_f8f6f4 v[50:53], v[26:33], v[218:225], 0, v188, v188 op_sel_hi:[0,0,0]
	v_mfma_scale_f32_16x16x128_f8f6f4 v[42:45], v[18:25], v[226:233], 0, v188, v188 op_sel_hi:[0,0,0]
	v_mfma_scale_f32_16x16x128_f8f6f4 v[34:37], v[26:33], v[226:233], 0, v188, v188 op_sel_hi:[0,0,0]
	s_add_i32 s0, 0, 0x18000
	v_add_u32_e32 v14, s0, v197
	s_barrier
	ds_read_b128 v[2:5], v14
	ds_read_b128 v[6:9], v14 offset:1024
	ds_read_b128 v[10:13], v14 offset:2048
	ds_read_b128 v[14:17], v14 offset:3072
	s_mov_b32 m0, s47
	ds_read_b128 v[18:21], v169 offset:32768
	ds_read_b128 v[22:25], v169 offset:33792
	ds_read_b128 v[26:29], v169 offset:34816
	ds_read_b128 v[30:33], v169 offset:35840
	ds_read_b128 v[202:205], v169 offset:36864
	ds_read_b128 v[206:209], v169 offset:37888
	ds_read_b128 v[210:213], v169 offset:38912
	ds_read_b128 v[214:217], v169 offset:39936
	global_load_lds_dwordx4 v175, s[38:39]
	s_mov_b32 m0, s48
	s_nop 0
	global_load_lds_dwordx4 v173, s[38:39]
	s_waitcnt lgkmcnt(8)
	s_waitcnt vmcnt(10)
	s_barrier
	s_waitcnt lgkmcnt(0)
	s_waitcnt lgkmcnt(0)
	v_mfma_scale_f32_16x16x128_f8f6f4 v[158:161], v[2:9], v[18:25], v[158:161], v188, v188 op_sel_hi:[0,0,0]
	v_mfma_scale_f32_16x16x128_f8f6f4 v[150:153], v[10:17], v[18:25], v[150:153], v188, v188 op_sel_hi:[0,0,0]
	v_mfma_scale_f32_16x16x128_f8f6f4 v[142:145], v[2:9], v[26:33], v[142:145], v188, v188 op_sel_hi:[0,0,0]
	v_mfma_scale_f32_16x16x128_f8f6f4 v[134:137], v[10:17], v[26:33], v[134:137], v188, v188 op_sel_hi:[0,0,0]
	v_mfma_scale_f32_16x16x128_f8f6f4 v[126:129], v[2:9], v[202:209], v[126:129], v188, v188 op_sel_hi:[0,0,0]
	v_mfma_scale_f32_16x16x128_f8f6f4 v[118:121], v[10:17], v[202:209], v[118:121], v188, v188 op_sel_hi:[0,0,0]
	v_mfma_scale_f32_16x16x128_f8f6f4 v[110:113], v[2:9], v[210:217], v[110:113], v188, v188 op_sel_hi:[0,0,0]
	v_mfma_scale_f32_16x16x128_f8f6f4 v[102:105], v[10:17], v[210:217], v[102:105], v188, v188 op_sel_hi:[0,0,0]
	s_barrier
	s_add_i32 s36, 0, 0x1c000
	s_add_i32 s0, s0, s43
	v_add_u32_e32 v162, s36, v197
	v_lshl_add_u64 v[180:181], v[180:181], 0, s[22:23]
	s_mov_b32 m0, s0
	ds_read_b128 v[218:221], v162
	ds_read_b128 v[222:225], v162 offset:1024
	ds_read_b128 v[226:229], v162 offset:2048
	ds_read_b128 v[230:233], v162 offset:3072
	global_load_lds_dwordx4 v[180:181], off
	v_lshl_add_u64 v[180:181], v[182:183], 0, s[22:23]
	s_add_i32 m0, s0, 0x2000
	s_nop 0
	global_load_lds_dwordx4 v[180:181], off
	s_waitcnt vmcnt(10)
	s_barrier
	s_waitcnt lgkmcnt(0)
	s_waitcnt lgkmcnt(0)
	v_mfma_scale_f32_16x16x128_f8f6f4 v[154:157], v[218:225], v[18:25], v[154:157], v188, v188 op_sel_hi:[0,0,0]
	v_mfma_scale_f32_16x16x128_f8f6f4 v[146:149], v[226:233], v[18:25], v[146:149], v188, v188 op_sel_hi:[0,0,0]
	v_mfma_scale_f32_16x16x128_f8f6f4 v[138:141], v[218:225], v[26:33], v[138:141], v188, v188 op_sel_hi:[0,0,0]
	v_mfma_scale_f32_16x16x128_f8f6f4 v[130:133], v[226:233], v[26:33], v[130:133], v188, v188 op_sel_hi:[0,0,0]
	v_mfma_scale_f32_16x16x128_f8f6f4 v[122:125], v[218:225], v[202:209], v[122:125], v188, v188 op_sel_hi:[0,0,0]
	v_mfma_scale_f32_16x16x128_f8f6f4 v[114:117], v[226:233], v[202:209], v[114:117], v188, v188 op_sel_hi:[0,0,0]
	v_mfma_scale_f32_16x16x128_f8f6f4 v[106:109], v[218:225], v[210:217], v[106:109], v188, v188 op_sel_hi:[0,0,0]
	v_mfma_scale_f32_16x16x128_f8f6f4 v[98:101], v[226:233], v[210:217], v[98:101], v188, v188 op_sel_hi:[0,0,0]
	s_mov_b32 m0, s51
	v_lshl_add_u64 v[180:181], v[186:187], 0, s[22:23]
	s_barrier
	ds_read_b128 v[18:21], v169 offset:49152
	ds_read_b128 v[22:25], v169 offset:50176
	ds_read_b128 v[26:29], v169 offset:51200
	ds_read_b128 v[30:33], v169 offset:52224
	ds_read_b128 v[202:205], v169 offset:53248
	ds_read_b128 v[206:209], v169 offset:54272
	ds_read_b128 v[210:213], v169 offset:55296
	ds_read_b128 v[214:217], v169 offset:56320
	global_load_lds_dwordx4 v[180:181], off
	v_lshl_add_u64 v[180:181], v[184:185], 0, s[22:23]
	s_mov_b32 m0, s52
	s_nop 0
	global_load_lds_dwordx4 v[180:181], off
	s_waitcnt vmcnt(10)
	s_barrier
	s_waitcnt lgkmcnt(0)
	s_waitcnt lgkmcnt(0)
	v_mfma_scale_f32_16x16x128_f8f6f4 v[94:97], v[2:9], v[18:25], v[94:97], v188, v188 op_sel_hi:[0,0,0]
	v_mfma_scale_f32_16x16x128_f8f6f4 v[86:89], v[10:17], v[18:25], v[86:89], v188, v188 op_sel_hi:[0,0,0]
	v_mfma_scale_f32_16x16x128_f8f6f4 v[78:81], v[2:9], v[26:33], v[78:81], v188, v188 op_sel_hi:[0,0,0]
	v_mfma_scale_f32_16x16x128_f8f6f4 v[70:73], v[10:17], v[26:33], v[70:73], v188, v188 op_sel_hi:[0,0,0]
	v_mfma_scale_f32_16x16x128_f8f6f4 v[62:65], v[2:9], v[202:209], v[62:65], v188, v188 op_sel_hi:[0,0,0]
	v_mfma_scale_f32_16x16x128_f8f6f4 v[54:57], v[10:17], v[202:209], v[54:57], v188, v188 op_sel_hi:[0,0,0]
	v_mfma_scale_f32_16x16x128_f8f6f4 v[46:49], v[2:9], v[210:217], v[46:49], v188, v188 op_sel_hi:[0,0,0]
	v_mfma_scale_f32_16x16x128_f8f6f4 v[38:41], v[10:17], v[210:217], v[38:41], v188, v188 op_sel_hi:[0,0,0]
	s_barrier
	s_add_u32 s0, s34, 0x20080
	s_addc_u32 s1, s35, 0
	s_add_i32 s34, s36, s43
	v_lshl_add_u64 v[2:3], s[0:1], 0, v[164:165]
	s_mov_b32 m0, s34
	s_nop 0
	global_load_lds_dwordx4 v[2:3], off
	v_lshl_add_u64 v[2:3], s[0:1], 0, v[166:167]
	s_add_i32 m0, s34, 0x2000
	s_nop 0
	global_load_lds_dwordx4 v[2:3], off
	s_waitcnt vmcnt(10)
	s_barrier
	v_mfma_scale_f32_16x16x128_f8f6f4 v[90:93], v[218:225], v[18:25], v[90:93], v188, v188 op_sel_hi:[0,0,0]
	v_mfma_scale_f32_16x16x128_f8f6f4 v[82:85], v[226:233], v[18:25], v[82:85], v188, v188 op_sel_hi:[0,0,0]
	v_mfma_scale_f32_16x16x128_f8f6f4 v[74:77], v[218:225], v[26:33], v[74:77], v188, v188 op_sel_hi:[0,0,0]
	v_mfma_scale_f32_16x16x128_f8f6f4 v[66:69], v[226:233], v[26:33], v[66:69], v188, v188 op_sel_hi:[0,0,0]
	v_mfma_scale_f32_16x16x128_f8f6f4 v[58:61], v[218:225], v[202:209], v[58:61], v188, v188 op_sel_hi:[0,0,0]
	v_mfma_scale_f32_16x16x128_f8f6f4 v[50:53], v[226:233], v[202:209], v[50:53], v188, v188 op_sel_hi:[0,0,0]
	v_mfma_scale_f32_16x16x128_f8f6f4 v[42:45], v[218:225], v[210:217], v[42:45], v188, v188 op_sel_hi:[0,0,0]
	v_mfma_scale_f32_16x16x128_f8f6f4 v[34:37], v[226:233], v[210:217], v[34:37], v188, v188 op_sel_hi:[0,0,0]
	s_add_i32 s56, s56, 2
	s_cmp_gt_u32 s56, 5
	s_mov_b64 s[36:37], s[12:13]
	s_barrier
	s_cbranch_scc1 .Lpeel_exit_6

.Lpeel_exit_6:
	v_mul_f32_e32 v5, 0x3b000000, v158
	v_mul_f32_e32 v6, 0xbcb8aa3b, v158
	v_exp_f32_e32 v6, v6
	s_ashr_i32 s31, s30, 31
	s_ashr_i32 s29, s28, 31
	s_lshl_b64 s[12:13], s[30:31], 18
	v_add_f32_e32 v6, 1.0, v6
	v_rcp_f32_e32 v6, v6
	s_lshl_b64 s[28:29], s[28:29], 15
	v_mov_b32_e32 v3, v195
	s_add_u32 s0, s6, s12
	v_mul_f32_e32 v5, v5, v6
	v_mul_f32_e32 v6, 0x3b000000, v159
	v_mul_f32_e32 v7, 0xbcb8aa3b, v159
	v_exp_f32_e32 v7, v7
	v_mul_f32_e32 v5, v5, v154
	v_med3_f32 v5, v5, s40, v190
	v_add_f32_e32 v7, 1.0, v7
	v_rcp_f32_e32 v7, v7
	s_nop 15
	s_nop 15
	v_mov_b32_e32 v2, v196
	v_mul_f32_e32 v6, v6, v7
	v_mul_f32_e32 v7, 0x3b000000, v160
	v_mul_f32_e32 v8, 0xbcb8aa3b, v160
	v_exp_f32_e32 v8, v8
	v_mul_f32_e32 v6, v6, v155
	v_add_u32_e32 v4, s49, v3
	v_add_f32_e32 v8, 1.0, v8
	v_rcp_f32_e32 v8, v8
	s_addc_u32 s1, s7, s13
	s_add_u32 s12, s0, s28
	v_mul_f32_e32 v7, v7, v8
	v_mul_f32_e32 v8, 0x3b000000, v161
	v_mul_f32_e32 v9, 0xbcb8aa3b, v161
	v_exp_f32_e32 v9, v9
	v_mul_f32_e32 v7, v7, v156
	v_lshl_add_u32 v2, v2, 3, s50
	v_add_f32_e32 v9, 1.0, v9
	v_rcp_f32_e32 v9, v9
	s_addc_u32 s13, s1, s29
	v_ashrrev_i32_e32 v3, 31, v2
	s_and_b64 vcc, exec, s[8:9]
	v_mul_f32_e32 v8, v8, v9
	v_mul_f32_e32 v9, 0x3b000000, v150
	v_mul_f32_e32 v10, 0xbcb8aa3b, v150
	v_exp_f32_e32 v10, v10
	v_mul_f32_e32 v8, v8, v157
	v_mov_b32_e32 v174, v200
	v_add_f32_e32 v10, 1.0, v10
	v_rcp_f32_e32 v10, v10
	v_mov_b32_e32 v172, v199
	v_mov_b32_e32 v170, v198
	v_mov_b32_e32 v168, v171
	v_mul_f32_e32 v9, v9, v10
	v_mul_f32_e32 v10, 0x3b000000, v151
	v_mul_f32_e32 v11, 0xbcb8aa3b, v151
	v_exp_f32_e32 v11, v11
	v_mul_f32_e32 v9, v9, v146
	s_mov_b32 s28, s26
	v_add_f32_e32 v11, 1.0, v11
	v_rcp_f32_e32 v11, v11
	s_mov_b32 s30, s54
	s_mov_b64 s[34:35], s[14:15]
	v_mul_f32_e32 v10, v10, v11
	v_mul_f32_e32 v11, 0x3b000000, v152
	v_mul_f32_e32 v12, 0xbcb8aa3b, v152
	v_exp_f32_e32 v12, v12
	v_mul_f32_e32 v10, v10, v147
	v_add_f32_e32 v12, 1.0, v12
	v_rcp_f32_e32 v12, v12
	s_nop 0
	v_mul_f32_e32 v11, v11, v12
	v_mul_f32_e32 v12, 0x3b000000, v153
	v_mul_f32_e32 v13, 0xbcb8aa3b, v153
	v_exp_f32_e32 v13, v13
	v_mul_f32_e32 v11, v11, v148
	v_add_f32_e32 v13, 1.0, v13
	v_rcp_f32_e32 v13, v13
	s_nop 0
	v_mul_f32_e32 v12, v12, v13
	v_med3_f32 v13, v6, s40, v190
	v_mov_b32_e32 v6, v163
	v_cvt_pk_fp8_f32 v6, v5, v13
	v_med3_f32 v5, v7, s40, v190
	v_med3_f32 v7, v8, s40, v190
	v_med3_f32 v8, v10, s40, v190
	v_cvt_pk_fp8_f32 v6, v5, v7 op_sel:[0,0,1]
	v_med3_f32 v5, v9, s40, v190
	v_mov_b32_e32 v7, v163
	v_cvt_pk_fp8_f32 v7, v5, v8
	v_mul_f32_e32 v12, v12, v149
	v_med3_f32 v5, v11, s40, v190
	v_med3_f32 v8, v12, s40, v190
	v_cvt_pk_fp8_f32 v7, v5, v8 op_sel:[0,0,1]
	v_ashrrev_i32_e32 v5, 31, v4
	v_lshlrev_b64 v[8:9], 7, v[4:5]
	v_lshl_add_u64 v[8:9], s[12:13], 0, v[8:9]
	v_lshl_add_u64 v[8:9], v[8:9], 0, v[2:3]
	v_mul_f32_e32 v5, 0x3b000000, v142
	global_store_dwordx2 v[8:9], v[6:7], off
	v_mul_f32_e32 v6, 0xbcb8aa3b, v142
	v_exp_f32_e32 v6, v6
	s_nop 0
	v_add_f32_e32 v6, 1.0, v6
	v_rcp_f32_e32 v6, v6
	s_nop 0
	v_mul_f32_e32 v5, v5, v6
	v_mul_f32_e32 v6, 0x3b000000, v143
	v_mul_f32_e32 v7, 0xbcb8aa3b, v143
	v_exp_f32_e32 v7, v7
	v_mul_f32_e32 v5, v5, v138
	v_med3_f32 v5, v5, s40, v190
	v_add_f32_e32 v7, 1.0, v7
	v_rcp_f32_e32 v7, v7
	s_nop 0
	v_mul_f32_e32 v6, v6, v7
	v_mul_f32_e32 v7, v6, v139
	v_mul_f32_e32 v6, 0x3b000000, v144
	v_mul_f32_e32 v8, 0xbcb8aa3b, v144
	v_exp_f32_e32 v8, v8
	v_med3_f32 v7, v7, s40, v190
	v_add_f32_e32 v8, 1.0, v8
	v_rcp_f32_e32 v8, v8
	s_nop 0
	v_mul_f32_e32 v6, v6, v8
	v_mul_f32_e32 v9, v6, v140
	v_mul_f32_e32 v6, 0x3b000000, v145
	v_mul_f32_e32 v8, 0xbcb8aa3b, v145
	v_exp_f32_e32 v8, v8
	s_nop 0
	v_add_f32_e32 v8, 1.0, v8
	v_rcp_f32_e32 v8, v8
	s_nop 0
	v_mul_f32_e32 v6, v6, v8
	v_mul_f32_e32 v10, v6, v141
	v_mul_f32_e32 v6, 0x3b000000, v134
	v_mul_f32_e32 v8, 0xbcb8aa3b, v134
	v_exp_f32_e32 v8, v8
	s_nop 0
	v_add_f32_e32 v8, 1.0, v8
	v_rcp_f32_e32 v8, v8
	s_nop 0
	v_mul_f32_e32 v6, v6, v8
	v_mul_f32_e32 v11, v6, v130
	v_mul_f32_e32 v6, 0x3b000000, v135
	v_mul_f32_e32 v8, 0xbcb8aa3b, v135
	v_exp_f32_e32 v8, v8
	s_nop 0
	v_add_f32_e32 v8, 1.0, v8
	v_rcp_f32_e32 v8, v8
	s_nop 0
	v_mul_f32_e32 v6, v6, v8
	v_mul_f32_e32 v12, v6, v131
	v_mul_f32_e32 v6, 0x3b000000, v136
	v_mul_f32_e32 v8, 0xbcb8aa3b, v136
	v_exp_f32_e32 v8, v8
	s_nop 0
	v_add_f32_e32 v8, 1.0, v8
	v_rcp_f32_e32 v8, v8
	s_nop 0
	v_mul_f32_e32 v6, v6, v8
	v_mul_f32_e32 v13, v6, v132
	v_mul_f32_e32 v6, 0x3b000000, v137
	v_mul_f32_e32 v8, 0xbcb8aa3b, v137
	v_exp_f32_e32 v8, v8
	s_nop 0
	v_add_f32_e32 v8, 1.0, v8
	v_rcp_f32_e32 v8, v8
	s_nop 0
	v_mul_f32_e32 v6, v6, v8
	v_mov_b32_e32 v8, v163
	v_cvt_pk_fp8_f32 v8, v5, v7
	v_med3_f32 v5, v9, s40, v190
	v_med3_f32 v7, v10, s40, v190
	v_mov_b32_e32 v9, v163
	v_cvt_pk_fp8_f32 v8, v5, v7 op_sel:[0,0,1]
	v_med3_f32 v5, v11, s40, v190
	v_med3_f32 v7, v12, s40, v190
	v_cvt_pk_fp8_f32 v9, v5, v7
	v_mul_f32_e32 v14, v6, v133
	v_add_u32_e32 v6, 16, v4
	v_med3_f32 v5, v13, s40, v190
	v_med3_f32 v7, v14, s40, v190
	v_cvt_pk_fp8_f32 v9, v5, v7 op_sel:[0,0,1]
	v_ashrrev_i32_e32 v7, 31, v6
	v_lshlrev_b64 v[6:7], 7, v[6:7]
	v_lshl_add_u64 v[6:7], s[12:13], 0, v[6:7]
	v_lshl_add_u64 v[6:7], v[6:7], 0, v[2:3]
	v_mul_f32_e32 v5, 0x3b000000, v126
	global_store_dwordx2 v[6:7], v[8:9], off
	v_mul_f32_e32 v6, 0xbcb8aa3b, v126
	v_exp_f32_e32 v6, v6
	s_nop 0
	v_add_f32_e32 v6, 1.0, v6
	v_rcp_f32_e32 v6, v6
	s_nop 0
	v_mul_f32_e32 v5, v5, v6
	v_mul_f32_e32 v6, 0x3b000000, v127
	v_mul_f32_e32 v7, 0xbcb8aa3b, v127
	v_exp_f32_e32 v7, v7
	v_mul_f32_e32 v5, v5, v122
	v_med3_f32 v5, v5, s40, v190
	v_add_f32_e32 v7, 1.0, v7
	v_rcp_f32_e32 v7, v7
	s_nop 0
	v_mul_f32_e32 v6, v6, v7
	v_mul_f32_e32 v7, v6, v123
	v_mul_f32_e32 v6, 0x3b000000, v128
	v_mul_f32_e32 v8, 0xbcb8aa3b, v128
	v_exp_f32_e32 v8, v8
	v_med3_f32 v7, v7, s40, v190
	v_add_f32_e32 v8, 1.0, v8
	v_rcp_f32_e32 v8, v8
	s_nop 0
	v_mul_f32_e32 v6, v6, v8
	v_mul_f32_e32 v9, v6, v124
	v_mul_f32_e32 v6, 0x3b000000, v129
	v_mul_f32_e32 v8, 0xbcb8aa3b, v129
	v_exp_f32_e32 v8, v8
	s_nop 0
	v_add_f32_e32 v8, 1.0, v8
	v_rcp_f32_e32 v8, v8
	s_nop 0
	v_mul_f32_e32 v6, v6, v8
	v_mul_f32_e32 v10, v6, v125
	v_mul_f32_e32 v6, 0x3b000000, v118
	v_mul_f32_e32 v8, 0xbcb8aa3b, v118
	v_exp_f32_e32 v8, v8
	s_nop 0
	v_add_f32_e32 v8, 1.0, v8
	v_rcp_f32_e32 v8, v8
	s_nop 0
	v_mul_f32_e32 v6, v6, v8
	v_mul_f32_e32 v11, v6, v114
	v_mul_f32_e32 v6, 0x3b000000, v119
	v_mul_f32_e32 v8, 0xbcb8aa3b, v119
	v_exp_f32_e32 v8, v8
	s_nop 0
	v_add_f32_e32 v8, 1.0, v8
	v_rcp_f32_e32 v8, v8
	s_nop 0
	v_mul_f32_e32 v6, v6, v8
	v_mul_f32_e32 v12, v6, v115
	v_mul_f32_e32 v6, 0x3b000000, v120
	v_mul_f32_e32 v8, 0xbcb8aa3b, v120
	v_exp_f32_e32 v8, v8
	s_nop 0
	v_add_f32_e32 v8, 1.0, v8
	v_rcp_f32_e32 v8, v8
	s_nop 0
	v_mul_f32_e32 v6, v6, v8
	v_mul_f32_e32 v13, v6, v116
	v_mul_f32_e32 v6, 0x3b000000, v121
	v_mul_f32_e32 v8, 0xbcb8aa3b, v121
	v_exp_f32_e32 v8, v8
	s_nop 0
	v_add_f32_e32 v8, 1.0, v8
	v_rcp_f32_e32 v8, v8
	s_nop 0
	v_mul_f32_e32 v6, v6, v8
	v_mov_b32_e32 v8, v163
	v_cvt_pk_fp8_f32 v8, v5, v7
	v_med3_f32 v5, v9, s40, v190
	v_med3_f32 v7, v10, s40, v190
	v_mov_b32_e32 v9, v163
	v_cvt_pk_fp8_f32 v8, v5, v7 op_sel:[0,0,1]
	v_med3_f32 v5, v11, s40, v190
	v_med3_f32 v7, v12, s40, v190
	v_cvt_pk_fp8_f32 v9, v5, v7
	v_mul_f32_e32 v14, v6, v117
	v_add_u32_e32 v6, 32, v4
	v_med3_f32 v5, v13, s40, v190
	v_med3_f32 v7, v14, s40, v190
	v_cvt_pk_fp8_f32 v9, v5, v7 op_sel:[0,0,1]
	v_ashrrev_i32_e32 v7, 31, v6
	v_lshlrev_b64 v[6:7], 7, v[6:7]
	v_lshl_add_u64 v[6:7], s[12:13], 0, v[6:7]
	v_lshl_add_u64 v[6:7], v[6:7], 0, v[2:3]
	v_mul_f32_e32 v5, 0x3b000000, v110
	global_store_dwordx2 v[6:7], v[8:9], off
	v_mul_f32_e32 v6, 0xbcb8aa3b, v110
	v_exp_f32_e32 v6, v6
	s_nop 0
	v_add_f32_e32 v6, 1.0, v6
	v_rcp_f32_e32 v6, v6
	s_nop 0
	v_mul_f32_e32 v5, v5, v6
	v_mul_f32_e32 v6, 0x3b000000, v111
	v_mul_f32_e32 v7, 0xbcb8aa3b, v111
	v_exp_f32_e32 v7, v7
	v_mul_f32_e32 v5, v5, v106
	v_med3_f32 v5, v5, s40, v190
	v_add_f32_e32 v7, 1.0, v7
	v_rcp_f32_e32 v7, v7
	s_nop 0
	v_mul_f32_e32 v6, v6, v7
	v_mul_f32_e32 v7, v6, v107
	v_mul_f32_e32 v6, 0x3b000000, v112
	v_mul_f32_e32 v8, 0xbcb8aa3b, v112
	v_exp_f32_e32 v8, v8
	v_med3_f32 v7, v7, s40, v190
	v_add_f32_e32 v8, 1.0, v8
	v_rcp_f32_e32 v8, v8
	s_nop 0
	v_mul_f32_e32 v6, v6, v8
	v_mul_f32_e32 v9, v6, v108
	v_mul_f32_e32 v6, 0x3b000000, v113
	v_mul_f32_e32 v8, 0xbcb8aa3b, v113
	v_exp_f32_e32 v8, v8
	s_nop 0
	v_add_f32_e32 v8, 1.0, v8
	v_rcp_f32_e32 v8, v8
	s_nop 0
	v_mul_f32_e32 v6, v6, v8
	v_mul_f32_e32 v10, v6, v109
	v_mul_f32_e32 v6, 0x3b000000, v102
	v_mul_f32_e32 v8, 0xbcb8aa3b, v102
	v_exp_f32_e32 v8, v8
	s_nop 0
	v_add_f32_e32 v8, 1.0, v8
	v_rcp_f32_e32 v8, v8
	s_nop 0
	v_mul_f32_e32 v6, v6, v8
	v_mul_f32_e32 v11, v6, v98
	v_mul_f32_e32 v6, 0x3b000000, v103
	v_mul_f32_e32 v8, 0xbcb8aa3b, v103
	v_exp_f32_e32 v8, v8
	s_nop 0
	v_add_f32_e32 v8, 1.0, v8
	v_rcp_f32_e32 v8, v8
	s_nop 0
	v_mul_f32_e32 v6, v6, v8
	v_mul_f32_e32 v12, v6, v99
	v_mul_f32_e32 v6, 0x3b000000, v104
	v_mul_f32_e32 v8, 0xbcb8aa3b, v104
	v_exp_f32_e32 v8, v8
	s_nop 0
	v_add_f32_e32 v8, 1.0, v8
	v_rcp_f32_e32 v8, v8
	s_nop 0
	v_mul_f32_e32 v6, v6, v8
	v_mul_f32_e32 v13, v6, v100
	v_mul_f32_e32 v6, 0x3b000000, v105
	v_mul_f32_e32 v8, 0xbcb8aa3b, v105
	v_exp_f32_e32 v8, v8
	s_nop 0
	v_add_f32_e32 v8, 1.0, v8
	v_rcp_f32_e32 v8, v8
	s_nop 0
	v_mul_f32_e32 v6, v6, v8
	v_mov_b32_e32 v8, v163
	v_cvt_pk_fp8_f32 v8, v5, v7
	v_med3_f32 v5, v9, s40, v190
	v_med3_f32 v7, v10, s40, v190
	v_mov_b32_e32 v9, v163
	v_cvt_pk_fp8_f32 v8, v5, v7 op_sel:[0,0,1]
	v_med3_f32 v5, v11, s40, v190
	v_med3_f32 v7, v12, s40, v190
	v_cvt_pk_fp8_f32 v9, v5, v7
	v_mul_f32_e32 v14, v6, v101
	v_add_u32_e32 v6, 48, v4
	v_med3_f32 v5, v13, s40, v190
	v_med3_f32 v7, v14, s40, v190
	v_cvt_pk_fp8_f32 v9, v5, v7 op_sel:[0,0,1]
	v_ashrrev_i32_e32 v7, 31, v6
	v_lshlrev_b64 v[6:7], 7, v[6:7]
	v_lshl_add_u64 v[6:7], s[12:13], 0, v[6:7]
	v_lshl_add_u64 v[6:7], v[6:7], 0, v[2:3]
	v_mul_f32_e32 v5, 0x3b000000, v94
	global_store_dwordx2 v[6:7], v[8:9], off
	v_mul_f32_e32 v7, 0xbcb8aa3b, v94
	v_exp_f32_e32 v7, v7
	v_add_u32_e32 v6, 0x80, v4
	v_add_f32_e32 v7, 1.0, v7
	v_rcp_f32_e32 v7, v7
	s_nop 0
	v_mul_f32_e32 v5, v5, v7
	v_mul_f32_e32 v7, 0x3b000000, v95
	v_mul_f32_e32 v8, 0xbcb8aa3b, v95
	v_exp_f32_e32 v8, v8
	v_mul_f32_e32 v5, v5, v90
	v_med3_f32 v5, v5, s40, v190
	v_add_f32_e32 v8, 1.0, v8
	v_rcp_f32_e32 v8, v8
	s_nop 0
	v_mul_f32_e32 v7, v7, v8
	v_mul_f32_e32 v8, 0x3b000000, v96
	v_mul_f32_e32 v9, 0xbcb8aa3b, v96
	v_exp_f32_e32 v9, v9
	v_mul_f32_e32 v7, v7, v91
	v_med3_f32 v7, v7, s40, v190
	v_add_f32_e32 v9, 1.0, v9
	v_rcp_f32_e32 v9, v9
	s_nop 0
	v_mul_f32_e32 v8, v8, v9
	v_mul_f32_e32 v9, v8, v92
	v_mul_f32_e32 v8, 0x3b000000, v97
	v_mul_f32_e32 v10, 0xbcb8aa3b, v97
	v_exp_f32_e32 v10, v10
	s_nop 0
	v_add_f32_e32 v10, 1.0, v10
	v_rcp_f32_e32 v10, v10
	s_nop 0
	v_mul_f32_e32 v8, v8, v10
	v_mul_f32_e32 v10, v8, v93
	v_mul_f32_e32 v8, 0x3b000000, v86
	v_mul_f32_e32 v11, 0xbcb8aa3b, v86
	v_exp_f32_e32 v11, v11
	s_nop 0
	v_add_f32_e32 v11, 1.0, v11
	v_rcp_f32_e32 v11, v11
	s_nop 0
	v_mul_f32_e32 v8, v8, v11
	v_mul_f32_e32 v11, v8, v82
	v_mul_f32_e32 v8, 0x3b000000, v87
	v_mul_f32_e32 v12, 0xbcb8aa3b, v87
	v_exp_f32_e32 v12, v12
	s_nop 0
	v_add_f32_e32 v12, 1.0, v12
	v_rcp_f32_e32 v12, v12
	s_nop 0
	v_mul_f32_e32 v8, v8, v12
	v_mul_f32_e32 v12, v8, v83
	v_mul_f32_e32 v8, 0x3b000000, v88
	v_mul_f32_e32 v13, 0xbcb8aa3b, v88
	v_exp_f32_e32 v13, v13
	s_nop 0
	v_add_f32_e32 v13, 1.0, v13
	v_rcp_f32_e32 v13, v13
	s_nop 0
	v_mul_f32_e32 v8, v8, v13
	v_mul_f32_e32 v13, v8, v84
	v_mul_f32_e32 v8, 0x3b000000, v89
	v_mul_f32_e32 v14, 0xbcb8aa3b, v89
	v_exp_f32_e32 v14, v14
	s_nop 0
	v_add_f32_e32 v14, 1.0, v14
	v_rcp_f32_e32 v14, v14
	s_nop 0
	v_mul_f32_e32 v8, v8, v14
	v_mul_f32_e32 v14, v8, v85
	v_mov_b32_e32 v8, v163
	v_cvt_pk_fp8_f32 v8, v5, v7
	v_med3_f32 v5, v9, s40, v190
	v_med3_f32 v7, v10, s40, v190
	v_mov_b32_e32 v9, v163
	v_cvt_pk_fp8_f32 v8, v5, v7 op_sel:[0,0,1]
	v_med3_f32 v5, v11, s40, v190
	v_med3_f32 v7, v12, s40, v190
	v_cvt_pk_fp8_f32 v9, v5, v7
	v_med3_f32 v5, v13, s40, v190
	v_med3_f32 v7, v14, s40, v190
	v_cvt_pk_fp8_f32 v9, v5, v7 op_sel:[0,0,1]
	v_ashrrev_i32_e32 v7, 31, v6
	v_lshlrev_b64 v[6:7], 7, v[6:7]
	v_lshl_add_u64 v[6:7], s[12:13], 0, v[6:7]
	v_lshl_add_u64 v[6:7], v[6:7], 0, v[2:3]
	v_mul_f32_e32 v5, 0x3b000000, v78
	global_store_dwordx2 v[6:7], v[8:9], off
	v_mul_f32_e32 v6, 0xbcb8aa3b, v78
	v_exp_f32_e32 v6, v6
	s_nop 0
	v_add_f32_e32 v6, 1.0, v6
	v_rcp_f32_e32 v6, v6
	s_nop 0
	v_mul_f32_e32 v5, v5, v6
	v_mul_f32_e32 v6, 0x3b000000, v79
	v_mul_f32_e32 v7, 0xbcb8aa3b, v79
	v_exp_f32_e32 v7, v7
	v_mul_f32_e32 v5, v5, v74
	v_med3_f32 v5, v5, s40, v190
	v_add_f32_e32 v7, 1.0, v7
	v_rcp_f32_e32 v7, v7
	s_nop 0
	v_mul_f32_e32 v6, v6, v7
	v_mul_f32_e32 v7, v6, v75
	v_mul_f32_e32 v6, 0x3b000000, v80
	v_mul_f32_e32 v8, 0xbcb8aa3b, v80
	v_exp_f32_e32 v8, v8
	v_med3_f32 v7, v7, s40, v190
	v_add_f32_e32 v8, 1.0, v8
	v_rcp_f32_e32 v8, v8
	s_nop 0
	v_mul_f32_e32 v6, v6, v8
	v_mul_f32_e32 v9, v6, v76
	v_mul_f32_e32 v6, 0x3b000000, v81
	v_mul_f32_e32 v8, 0xbcb8aa3b, v81
	v_exp_f32_e32 v8, v8
	s_nop 0
	v_add_f32_e32 v8, 1.0, v8
	v_rcp_f32_e32 v8, v8
	s_nop 0
	v_mul_f32_e32 v6, v6, v8
	v_mul_f32_e32 v10, v6, v77
	v_mul_f32_e32 v6, 0x3b000000, v70
	v_mul_f32_e32 v8, 0xbcb8aa3b, v70
	v_exp_f32_e32 v8, v8
	s_nop 0
	v_add_f32_e32 v8, 1.0, v8
	v_rcp_f32_e32 v8, v8
	s_nop 0
	v_mul_f32_e32 v6, v6, v8
	v_mul_f32_e32 v11, v6, v66
	v_mul_f32_e32 v6, 0x3b000000, v71
	v_mul_f32_e32 v8, 0xbcb8aa3b, v71
	v_exp_f32_e32 v8, v8
	s_nop 0
	v_add_f32_e32 v8, 1.0, v8
	v_rcp_f32_e32 v8, v8
	s_nop 0
	v_mul_f32_e32 v6, v6, v8
	v_mul_f32_e32 v12, v6, v67
	v_mul_f32_e32 v6, 0x3b000000, v72
	v_mul_f32_e32 v8, 0xbcb8aa3b, v72
	v_exp_f32_e32 v8, v8
	s_nop 0
	v_add_f32_e32 v8, 1.0, v8
	v_rcp_f32_e32 v8, v8
	s_nop 0
	v_mul_f32_e32 v6, v6, v8
	v_mul_f32_e32 v13, v6, v68
	v_mul_f32_e32 v6, 0x3b000000, v73
	v_mul_f32_e32 v8, 0xbcb8aa3b, v73
	v_exp_f32_e32 v8, v8
	s_nop 0
	v_add_f32_e32 v8, 1.0, v8
	v_rcp_f32_e32 v8, v8
	s_nop 0
	v_mul_f32_e32 v6, v6, v8
	v_mov_b32_e32 v8, v163
	v_cvt_pk_fp8_f32 v8, v5, v7
	v_med3_f32 v5, v9, s40, v190
	v_med3_f32 v7, v10, s40, v190
	v_mov_b32_e32 v9, v163
	v_cvt_pk_fp8_f32 v8, v5, v7 op_sel:[0,0,1]
	v_med3_f32 v5, v11, s40, v190
	v_med3_f32 v7, v12, s40, v190
	v_cvt_pk_fp8_f32 v9, v5, v7
	v_mul_f32_e32 v14, v6, v69
	v_add_u32_e32 v6, 0x90, v4
	v_med3_f32 v5, v13, s40, v190
	v_med3_f32 v7, v14, s40, v190
	v_cvt_pk_fp8_f32 v9, v5, v7 op_sel:[0,0,1]
	v_ashrrev_i32_e32 v7, 31, v6
	v_lshlrev_b64 v[6:7], 7, v[6:7]
	v_lshl_add_u64 v[6:7], s[12:13], 0, v[6:7]
	v_lshl_add_u64 v[6:7], v[6:7], 0, v[2:3]
	v_mul_f32_e32 v5, 0x3b000000, v62
	global_store_dwordx2 v[6:7], v[8:9], off
	v_mul_f32_e32 v6, 0xbcb8aa3b, v62
	v_exp_f32_e32 v6, v6
	s_nop 0
	v_add_f32_e32 v6, 1.0, v6
	v_rcp_f32_e32 v6, v6
	s_nop 0
	v_mul_f32_e32 v5, v5, v6
	v_mul_f32_e32 v6, 0x3b000000, v63
	v_mul_f32_e32 v7, 0xbcb8aa3b, v63
	v_exp_f32_e32 v7, v7
	v_mul_f32_e32 v5, v5, v58
	v_med3_f32 v5, v5, s40, v190
	v_add_f32_e32 v7, 1.0, v7
	v_rcp_f32_e32 v7, v7
	s_nop 0
	v_mul_f32_e32 v6, v6, v7
	v_mul_f32_e32 v7, v6, v59
	v_mul_f32_e32 v6, 0x3b000000, v64
	v_mul_f32_e32 v8, 0xbcb8aa3b, v64
	v_exp_f32_e32 v8, v8
	v_med3_f32 v7, v7, s40, v190
	v_add_f32_e32 v8, 1.0, v8
	v_rcp_f32_e32 v8, v8
	s_nop 0
	v_mul_f32_e32 v6, v6, v8
	v_mul_f32_e32 v9, v6, v60
	v_mul_f32_e32 v6, 0x3b000000, v65
	v_mul_f32_e32 v8, 0xbcb8aa3b, v65
	v_exp_f32_e32 v8, v8
	s_nop 0
	v_add_f32_e32 v8, 1.0, v8
	v_rcp_f32_e32 v8, v8
	s_nop 0
	v_mul_f32_e32 v6, v6, v8
	v_mul_f32_e32 v10, v6, v61
	v_mul_f32_e32 v6, 0x3b000000, v54
	v_mul_f32_e32 v8, 0xbcb8aa3b, v54
	v_exp_f32_e32 v8, v8
	s_nop 0
	v_add_f32_e32 v8, 1.0, v8
	v_rcp_f32_e32 v8, v8
	s_nop 0
	v_mul_f32_e32 v6, v6, v8
	v_mul_f32_e32 v11, v6, v50
	v_mul_f32_e32 v6, 0x3b000000, v55
	v_mul_f32_e32 v8, 0xbcb8aa3b, v55
	v_exp_f32_e32 v8, v8
	s_nop 0
	v_add_f32_e32 v8, 1.0, v8
	v_rcp_f32_e32 v8, v8
	s_nop 0
	v_mul_f32_e32 v6, v6, v8
	v_mul_f32_e32 v12, v6, v51
	v_mul_f32_e32 v6, 0x3b000000, v56
	v_mul_f32_e32 v8, 0xbcb8aa3b, v56
	v_exp_f32_e32 v8, v8
	s_nop 0
	v_add_f32_e32 v8, 1.0, v8
	v_rcp_f32_e32 v8, v8
	s_nop 0
	v_mul_f32_e32 v6, v6, v8
	v_mul_f32_e32 v13, v6, v52
	v_mul_f32_e32 v6, 0x3b000000, v57
	v_mul_f32_e32 v8, 0xbcb8aa3b, v57
	v_exp_f32_e32 v8, v8
	s_nop 0
	v_add_f32_e32 v8, 1.0, v8
	v_rcp_f32_e32 v8, v8
	s_nop 0
	v_mul_f32_e32 v6, v6, v8
	v_mov_b32_e32 v8, v163
	v_cvt_pk_fp8_f32 v8, v5, v7
	v_med3_f32 v5, v9, s40, v190
	v_med3_f32 v7, v10, s40, v190
	v_mov_b32_e32 v9, v163
	v_cvt_pk_fp8_f32 v8, v5, v7 op_sel:[0,0,1]
	v_med3_f32 v5, v11, s40, v190
	v_med3_f32 v7, v12, s40, v190
	v_cvt_pk_fp8_f32 v9, v5, v7
	v_mul_f32_e32 v14, v6, v53
	v_add_u32_e32 v6, 0xa0, v4
	v_med3_f32 v5, v13, s40, v190
	v_med3_f32 v7, v14, s40, v190
	v_cvt_pk_fp8_f32 v9, v5, v7 op_sel:[0,0,1]
	v_ashrrev_i32_e32 v7, 31, v6
	v_lshlrev_b64 v[6:7], 7, v[6:7]
	v_lshl_add_u64 v[6:7], s[12:13], 0, v[6:7]
	v_lshl_add_u64 v[6:7], v[6:7], 0, v[2:3]
	v_mul_f32_e32 v5, 0x3b000000, v46
	global_store_dwordx2 v[6:7], v[8:9], off
	v_mul_f32_e32 v6, 0xbcb8aa3b, v46
	v_exp_f32_e32 v6, v6
	v_add_u32_e32 v4, 0xb0, v4
	v_add_f32_e32 v6, 1.0, v6
	v_rcp_f32_e32 v6, v6
	s_nop 0
	v_mul_f32_e32 v5, v5, v6
	v_mul_f32_e32 v6, 0x3b000000, v47
	v_mul_f32_e32 v7, 0xbcb8aa3b, v47
	v_exp_f32_e32 v7, v7
	v_mul_f32_e32 v5, v5, v42
	v_med3_f32 v5, v5, s40, v190
	v_add_f32_e32 v7, 1.0, v7
	v_rcp_f32_e32 v7, v7
	s_nop 0
	v_mul_f32_e32 v6, v6, v7
	v_mul_f32_e32 v7, 0x3b000000, v48
	v_mul_f32_e32 v8, 0xbcb8aa3b, v48
	v_exp_f32_e32 v8, v8
	v_mul_f32_e32 v6, v6, v43
	v_add_f32_e32 v8, 1.0, v8
	v_rcp_f32_e32 v8, v8
	s_nop 0
	v_mul_f32_e32 v7, v7, v8
	v_mul_f32_e32 v8, 0x3b000000, v49
	v_mul_f32_e32 v9, 0xbcb8aa3b, v49
	v_exp_f32_e32 v9, v9
	v_mul_f32_e32 v7, v7, v44
	v_add_f32_e32 v9, 1.0, v9
	v_rcp_f32_e32 v9, v9
	s_nop 0
	v_mul_f32_e32 v8, v8, v9
	v_mul_f32_e32 v9, 0x3b000000, v38
	v_mul_f32_e32 v10, 0xbcb8aa3b, v38
	v_exp_f32_e32 v10, v10
	v_mul_f32_e32 v8, v8, v45
	v_add_f32_e32 v10, 1.0, v10
	v_rcp_f32_e32 v10, v10
	s_nop 0
	v_mul_f32_e32 v9, v9, v10
	v_mul_f32_e32 v10, 0x3b000000, v39
	v_mul_f32_e32 v11, 0xbcb8aa3b, v39
	v_exp_f32_e32 v11, v11
	v_mul_f32_e32 v9, v9, v34
	v_add_f32_e32 v11, 1.0, v11
	v_rcp_f32_e32 v11, v11
	s_nop 0
	v_mul_f32_e32 v10, v10, v11
	v_mul_f32_e32 v11, 0x3b000000, v40
	v_mul_f32_e32 v12, 0xbcb8aa3b, v40
	v_exp_f32_e32 v12, v12
	v_mul_f32_e32 v10, v10, v35
	v_add_f32_e32 v12, 1.0, v12
	v_rcp_f32_e32 v12, v12
	s_nop 0
	v_mul_f32_e32 v11, v11, v12
	v_mul_f32_e32 v12, 0x3b000000, v41
	v_mul_f32_e32 v13, 0xbcb8aa3b, v41
	v_exp_f32_e32 v13, v13
	v_mul_f32_e32 v11, v11, v36
	v_add_f32_e32 v13, 1.0, v13
	v_rcp_f32_e32 v13, v13
	s_nop 0
	v_mul_f32_e32 v12, v12, v13
	v_med3_f32 v13, v6, s40, v190
	v_mov_b32_e32 v6, v163
	v_cvt_pk_fp8_f32 v6, v5, v13
	v_med3_f32 v5, v7, s40, v190
	v_med3_f32 v7, v8, s40, v190
	v_med3_f32 v8, v10, s40, v190
	v_cvt_pk_fp8_f32 v6, v5, v7 op_sel:[0,0,1]
	v_med3_f32 v5, v9, s40, v190
	v_mov_b32_e32 v7, v163
	v_cvt_pk_fp8_f32 v7, v5, v8
	v_mul_f32_e32 v12, v12, v37
	v_med3_f32 v5, v11, s40, v190
	v_med3_f32 v8, v12, s40, v190
	v_cvt_pk_fp8_f32 v7, v5, v8 op_sel:[0,0,1]
	v_ashrrev_i32_e32 v5, 31, v4
	v_lshlrev_b64 v[4:5], 7, v[4:5]
	v_lshl_add_u64 v[4:5], s[12:13], 0, v[4:5]
	v_lshl_add_u64 v[2:3], v[4:5], 0, v[2:3]
	global_store_dwordx2 v[2:3], v[6:7], off
	s_cbranch_vccz .LBB0_1291
	s_waitcnt vmcnt(0)
	s_cmpk_gt_u32 s42, 0xff
	s_cbranch_scc1 .LBB0_1237
	s_barrier
	s_branch .LBB0_1237

.LBB0_1368:
	s_ashr_i32 s21, s20, 31
	s_lshl_b64 s[0:1], s[20:21], 18
	v_cmp_lt_i64_e32 vcc, s[22:23], v[158:159]
	s_add_u32 s22, s5, s0
	s_addc_u32 s23, s6, s1
	s_and_b64 s[0:1], vcc, exec
	s_cselect_b32 s21, s23, s31
	s_cselect_b32 s49, s22, s30
	s_ashr_i32 s0, s20, 5
	s_ashr_i32 s1, s0, 31
	s_lshl_b64 s[0:1], s[0:1], 20
	s_add_u32 s24, s7, s0
	s_addc_u32 s25, s10, s1
	s_ashr_i32 s19, s18, 31
	s_lshl_b64 s[0:1], s[18:19], 18
	s_add_u32 s24, s24, s0
	s_addc_u32 s25, s25, s1
	s_and_b64 s[0:1], vcc, exec
	s_cselect_b32 s19, s25, s29
	s_cselect_b32 s50, s24, s28
	s_add_u32 s51, s28, 0x100
	s_addc_u32 s52, s29, 0
	s_add_u32 s28, s30, 0xc000
	s_addc_u32 s29, s31, 0
	s_mov_b32 s53, -2
	ds_read_b128 v[2:5], v169
	ds_read_b128 v[6:9], v169 offset:1024
	ds_read_b128 v[10:13], v169 offset:2048
	ds_read_b128 v[14:17], v169 offset:3072
	s_add_u32 s0, s28, 0x4000
	s_addc_u32 s1, s29, 0
	s_cmp_eq_u32 s53, 4
	s_cselect_b32 s36, s49, s0
	s_cselect_b32 s37, s21, s1
	s_cselect_b32 s30, s50, s51
	s_cselect_b32 s31, s19, s52
	s_add_u32 s34, s36, 0x8000
	s_addc_u32 s35, s37, 0
	v_lshl_add_u64 v[162:163], s[28:29], 0, v[156:157]
	s_add_i32 m0, s17, 0xc000
	ds_read_b128 v[174:177], v170
	ds_read_b128 v[178:181], v170 offset:1024
	ds_read_b128 v[182:185], v170 offset:2048
	ds_read_b128 v[186:189], v170 offset:3072
	ds_read_b128 v[190:193], v170 offset:4096
	ds_read_b128 v[194:197], v170 offset:5120
	ds_read_b128 v[198:201], v170 offset:6144
	ds_read_b128 v[202:205], v170 offset:7168
	global_load_lds_dwordx4 v[162:163], off
	v_lshl_add_u64 v[162:163], s[28:29], 0, v[154:155]
	s_add_i32 m0, s17, 0xe000
	s_nop 0
	global_load_lds_dwordx4 v[162:163], off
	s_waitcnt lgkmcnt(8)
	s_waitcnt vmcnt(10)
	s_barrier
	s_waitcnt lgkmcnt(0)
	s_waitcnt lgkmcnt(0)
	v_mfma_scale_f32_16x16x128_f8f6f4 v[142:145], v[2:9], v[174:181], 0, v171, v171 op_sel_hi:[0,0,0]
	v_mfma_scale_f32_16x16x128_f8f6f4 v[138:141], v[10:17], v[174:181], 0, v171, v171 op_sel_hi:[0,0,0]
	v_mfma_scale_f32_16x16x128_f8f6f4 v[126:129], v[2:9], v[182:189], 0, v171, v171 op_sel_hi:[0,0,0]
	v_mfma_scale_f32_16x16x128_f8f6f4 v[122:125], v[10:17], v[182:189], 0, v171, v171 op_sel_hi:[0,0,0]
	v_mfma_scale_f32_16x16x128_f8f6f4 v[110:113], v[2:9], v[190:197], 0, v171, v171 op_sel_hi:[0,0,0]
	v_mfma_scale_f32_16x16x128_f8f6f4 v[106:109], v[10:17], v[190:197], 0, v171, v171 op_sel_hi:[0,0,0]
	v_mfma_scale_f32_16x16x128_f8f6f4 v[94:97], v[2:9], v[198:205], 0, v171, v171 op_sel_hi:[0,0,0]
	v_mfma_scale_f32_16x16x128_f8f6f4 v[90:93], v[10:17], v[198:205], 0, v171, v171 op_sel_hi:[0,0,0]
	s_barrier
	s_add_i32 s0, s45, s11
	v_lshl_add_u64 v[162:163], s[30:31], 0, v[150:151]
	s_mov_b32 m0, s0
	ds_read_b128 v[206:209], v172
	ds_read_b128 v[210:213], v172 offset:1024
	ds_read_b128 v[214:217], v172 offset:2048
	ds_read_b128 v[218:221], v172 offset:3072
	global_load_lds_dwordx4 v[162:163], off
	v_lshl_add_u64 v[164:165], s[30:31], 0, v[146:147]
	s_add_i32 m0, s0, 0x2000
	s_nop 0
	global_load_lds_dwordx4 v[164:165], off
	s_waitcnt vmcnt(10)
	s_barrier
	s_waitcnt lgkmcnt(0)
	s_waitcnt lgkmcnt(0)
	v_mfma_scale_f32_16x16x128_f8f6f4 v[134:137], v[206:213], v[174:181], 0, v171, v171 op_sel_hi:[0,0,0]
	v_mfma_scale_f32_16x16x128_f8f6f4 v[130:133], v[214:221], v[174:181], 0, v171, v171 op_sel_hi:[0,0,0]
	v_mfma_scale_f32_16x16x128_f8f6f4 v[118:121], v[206:213], v[182:189], 0, v171, v171 op_sel_hi:[0,0,0]
	v_mfma_scale_f32_16x16x128_f8f6f4 v[114:117], v[214:221], v[182:189], 0, v171, v171 op_sel_hi:[0,0,0]
	v_mfma_scale_f32_16x16x128_f8f6f4 v[102:105], v[206:213], v[190:197], 0, v171, v171 op_sel_hi:[0,0,0]
	v_mfma_scale_f32_16x16x128_f8f6f4 v[98:101], v[214:221], v[190:197], 0, v171, v171 op_sel_hi:[0,0,0]
	v_mfma_scale_f32_16x16x128_f8f6f4 v[86:89], v[206:213], v[198:205], 0, v171, v171 op_sel_hi:[0,0,0]
	v_mfma_scale_f32_16x16x128_f8f6f4 v[82:85], v[214:221], v[198:205], 0, v171, v171 op_sel_hi:[0,0,0]
	s_mov_b32 m0, s17
	v_lshl_add_u64 v[222:223], s[36:37], 0, v[152:153]
	s_barrier
	ds_read_b128 v[174:177], v170 offset:16384
	ds_read_b128 v[178:181], v170 offset:17408
	ds_read_b128 v[182:185], v170 offset:18432
	ds_read_b128 v[186:189], v170 offset:19456
	ds_read_b128 v[190:193], v170 offset:20480
	ds_read_b128 v[194:197], v170 offset:21504
	ds_read_b128 v[198:201], v170 offset:22528
	ds_read_b128 v[202:205], v170 offset:23552
	global_load_lds_dwordx4 v[222:223], off
	v_lshl_add_u64 v[222:223], s[36:37], 0, v[148:149]
	s_mov_b32 m0, s27
	s_nop 0
	global_load_lds_dwordx4 v[222:223], off
	s_waitcnt vmcnt(10)
	s_barrier
	s_waitcnt lgkmcnt(0)
	s_waitcnt lgkmcnt(0)
	v_mfma_scale_f32_16x16x128_f8f6f4 v[78:81], v[2:9], v[174:181], 0, v171, v171 op_sel_hi:[0,0,0]
	v_mfma_scale_f32_16x16x128_f8f6f4 v[74:77], v[10:17], v[174:181], 0, v171, v171 op_sel_hi:[0,0,0]
	v_mfma_scale_f32_16x16x128_f8f6f4 v[62:65], v[2:9], v[182:189], 0, v171, v171 op_sel_hi:[0,0,0]
	v_mfma_scale_f32_16x16x128_f8f6f4 v[58:61], v[10:17], v[182:189], 0, v171, v171 op_sel_hi:[0,0,0]
	v_mfma_scale_f32_16x16x128_f8f6f4 v[46:49], v[2:9], v[190:197], 0, v171, v171 op_sel_hi:[0,0,0]
	v_mfma_scale_f32_16x16x128_f8f6f4 v[42:45], v[10:17], v[190:197], 0, v171, v171 op_sel_hi:[0,0,0]
	v_mfma_scale_f32_16x16x128_f8f6f4 v[30:33], v[2:9], v[198:205], 0, v171, v171 op_sel_hi:[0,0,0]
	v_mfma_scale_f32_16x16x128_f8f6f4 v[26:29], v[10:17], v[198:205], 0, v171, v171 op_sel_hi:[0,0,0]
	s_barrier
	s_add_u32 s0, s30, 0x20000
	s_addc_u32 s1, s31, 0
	s_add_i32 s54, s46, s11
	v_lshl_add_u64 v[2:3], s[0:1], 0, v[150:151]
	s_mov_b32 m0, s54
	s_nop 0
	global_load_lds_dwordx4 v[2:3], off
	v_lshl_add_u64 v[2:3], s[0:1], 0, v[146:147]
	s_add_i32 m0, s54, 0x2000
	s_nop 0
	global_load_lds_dwordx4 v[2:3], off
	s_waitcnt vmcnt(10)
	s_barrier
	v_mfma_scale_f32_16x16x128_f8f6f4 v[70:73], v[206:213], v[174:181], 0, v171, v171 op_sel_hi:[0,0,0]
	v_mfma_scale_f32_16x16x128_f8f6f4 v[66:69], v[214:221], v[174:181], 0, v171, v171 op_sel_hi:[0,0,0]
	v_mfma_scale_f32_16x16x128_f8f6f4 v[54:57], v[206:213], v[182:189], 0, v171, v171 op_sel_hi:[0,0,0]
	v_mfma_scale_f32_16x16x128_f8f6f4 v[50:53], v[214:221], v[182:189], 0, v171, v171 op_sel_hi:[0,0,0]
	v_mfma_scale_f32_16x16x128_f8f6f4 v[38:41], v[206:213], v[190:197], 0, v171, v171 op_sel_hi:[0,0,0]
	v_mfma_scale_f32_16x16x128_f8f6f4 v[34:37], v[214:221], v[190:197], 0, v171, v171 op_sel_hi:[0,0,0]
	v_mfma_scale_f32_16x16x128_f8f6f4 v[22:25], v[206:213], v[198:205], 0, v171, v171 op_sel_hi:[0,0,0]
	v_mfma_scale_f32_16x16x128_f8f6f4 v[18:21], v[214:221], v[198:205], 0, v171, v171 op_sel_hi:[0,0,0]
	s_add_i32 s54, 0, 0x18000
	v_add_u32_e32 v14, s54, v168
	s_barrier
	ds_read_b128 v[2:5], v14
	ds_read_b128 v[6:9], v14 offset:1024
	ds_read_b128 v[10:13], v14 offset:2048
	ds_read_b128 v[14:17], v14 offset:3072
	s_add_u32 s0, s36, 0x4000
	s_addc_u32 s1, s37, 0
	s_mov_b32 m0, s38
	v_lshl_add_u64 v[206:207], s[0:1], 0, v[152:153]
	ds_read_b128 v[174:177], v170 offset:32768
	ds_read_b128 v[178:181], v170 offset:33792
	ds_read_b128 v[182:185], v170 offset:34816
	ds_read_b128 v[186:189], v170 offset:35840
	ds_read_b128 v[190:193], v170 offset:36864
	ds_read_b128 v[194:197], v170 offset:37888
	ds_read_b128 v[198:201], v170 offset:38912
	ds_read_b128 v[202:205], v170 offset:39936
	global_load_lds_dwordx4 v[206:207], off
	v_lshl_add_u64 v[206:207], s[0:1], 0, v[148:149]
	s_mov_b32 m0, s39
	s_nop 0
	global_load_lds_dwordx4 v[206:207], off
	s_waitcnt lgkmcnt(8)
	s_waitcnt vmcnt(10)
	s_barrier
	s_waitcnt lgkmcnt(0)
	s_waitcnt lgkmcnt(0)
	v_mfma_scale_f32_16x16x128_f8f6f4 v[142:145], v[2:9], v[174:181], v[142:145], v171, v171 op_sel_hi:[0,0,0]
	v_mfma_scale_f32_16x16x128_f8f6f4 v[138:141], v[10:17], v[174:181], v[138:141], v171, v171 op_sel_hi:[0,0,0]
	v_mfma_scale_f32_16x16x128_f8f6f4 v[126:129], v[2:9], v[182:189], v[126:129], v171, v171 op_sel_hi:[0,0,0]
	v_mfma_scale_f32_16x16x128_f8f6f4 v[122:125], v[10:17], v[182:189], v[122:125], v171, v171 op_sel_hi:[0,0,0]
	v_mfma_scale_f32_16x16x128_f8f6f4 v[110:113], v[2:9], v[190:197], v[110:113], v171, v171 op_sel_hi:[0,0,0]
	v_mfma_scale_f32_16x16x128_f8f6f4 v[106:109], v[10:17], v[190:197], v[106:109], v171, v171 op_sel_hi:[0,0,0]
	v_mfma_scale_f32_16x16x128_f8f6f4 v[94:97], v[2:9], v[198:205], v[94:97], v171, v171 op_sel_hi:[0,0,0]
	v_mfma_scale_f32_16x16x128_f8f6f4 v[90:93], v[10:17], v[198:205], v[90:93], v171, v171 op_sel_hi:[0,0,0]
	s_barrier
	s_add_i32 s36, 0, 0x1c000
	s_add_i32 s0, s54, s11
	v_add_u32_e32 v218, s36, v168
	v_lshl_add_u64 v[162:163], v[162:163], 0, s[14:15]
	s_mov_b32 m0, s0
	ds_read_b128 v[206:209], v218
	ds_read_b128 v[210:213], v218 offset:1024
	ds_read_b128 v[214:217], v218 offset:2048
	ds_read_b128 v[218:221], v218 offset:3072
	global_load_lds_dwordx4 v[162:163], off
	v_lshl_add_u64 v[162:163], v[164:165], 0, s[14:15]
	s_add_i32 m0, s0, 0x2000
	s_nop 0
	global_load_lds_dwordx4 v[162:163], off
	s_waitcnt vmcnt(10)
	s_barrier
	s_waitcnt lgkmcnt(0)
	s_waitcnt lgkmcnt(0)
	v_mfma_scale_f32_16x16x128_f8f6f4 v[134:137], v[206:213], v[174:181], v[134:137], v171, v171 op_sel_hi:[0,0,0]
	v_mfma_scale_f32_16x16x128_f8f6f4 v[130:133], v[214:221], v[174:181], v[130:133], v171, v171 op_sel_hi:[0,0,0]
	v_mfma_scale_f32_16x16x128_f8f6f4 v[118:121], v[206:213], v[182:189], v[118:121], v171, v171 op_sel_hi:[0,0,0]
	v_mfma_scale_f32_16x16x128_f8f6f4 v[114:117], v[214:221], v[182:189], v[114:117], v171, v171 op_sel_hi:[0,0,0]
	v_mfma_scale_f32_16x16x128_f8f6f4 v[102:105], v[206:213], v[190:197], v[102:105], v171, v171 op_sel_hi:[0,0,0]
	v_mfma_scale_f32_16x16x128_f8f6f4 v[98:101], v[214:221], v[190:197], v[98:101], v171, v171 op_sel_hi:[0,0,0]
	v_mfma_scale_f32_16x16x128_f8f6f4 v[86:89], v[206:213], v[198:205], v[86:89], v171, v171 op_sel_hi:[0,0,0]
	v_mfma_scale_f32_16x16x128_f8f6f4 v[82:85], v[214:221], v[198:205], v[82:85], v171, v171 op_sel_hi:[0,0,0]
	s_mov_b32 m0, s43
	v_lshl_add_u64 v[162:163], s[34:35], 0, v[152:153]
	s_barrier
	ds_read_b128 v[174:177], v170 offset:49152
	ds_read_b128 v[178:181], v170 offset:50176
	ds_read_b128 v[182:185], v170 offset:51200
	ds_read_b128 v[186:189], v170 offset:52224
	ds_read_b128 v[190:193], v170 offset:53248
	ds_read_b128 v[194:197], v170 offset:54272
	ds_read_b128 v[198:201], v170 offset:55296
	ds_read_b128 v[202:205], v170 offset:56320
	global_load_lds_dwordx4 v[162:163], off
	v_lshl_add_u64 v[162:163], s[34:35], 0, v[148:149]
	s_mov_b32 m0, s44
	s_nop 0
	global_load_lds_dwordx4 v[162:163], off
	s_waitcnt vmcnt(10)
	s_barrier
	s_waitcnt lgkmcnt(0)
	s_waitcnt lgkmcnt(0)
	v_mfma_scale_f32_16x16x128_f8f6f4 v[78:81], v[2:9], v[174:181], v[78:81], v171, v171 op_sel_hi:[0,0,0]
	v_mfma_scale_f32_16x16x128_f8f6f4 v[74:77], v[10:17], v[174:181], v[74:77], v171, v171 op_sel_hi:[0,0,0]
	v_mfma_scale_f32_16x16x128_f8f6f4 v[62:65], v[2:9], v[182:189], v[62:65], v171, v171 op_sel_hi:[0,0,0]
	v_mfma_scale_f32_16x16x128_f8f6f4 v[58:61], v[10:17], v[182:189], v[58:61], v171, v171 op_sel_hi:[0,0,0]
	v_mfma_scale_f32_16x16x128_f8f6f4 v[46:49], v[2:9], v[190:197], v[46:49], v171, v171 op_sel_hi:[0,0,0]
	v_mfma_scale_f32_16x16x128_f8f6f4 v[42:45], v[10:17], v[190:197], v[42:45], v171, v171 op_sel_hi:[0,0,0]
	v_mfma_scale_f32_16x16x128_f8f6f4 v[30:33], v[2:9], v[198:205], v[30:33], v171, v171 op_sel_hi:[0,0,0]
	v_mfma_scale_f32_16x16x128_f8f6f4 v[26:29], v[10:17], v[198:205], v[26:29], v171, v171 op_sel_hi:[0,0,0]
	s_barrier
	s_add_u32 s0, s30, 0x20080
	s_addc_u32 s1, s31, 0
	s_add_i32 s30, s36, s11
	v_lshl_add_u64 v[2:3], s[0:1], 0, v[150:151]
	s_mov_b32 m0, s30
	s_nop 0
	global_load_lds_dwordx4 v[2:3], off
	v_lshl_add_u64 v[2:3], s[0:1], 0, v[146:147]
	s_add_i32 m0, s30, 0x2000
	s_nop 0
	global_load_lds_dwordx4 v[2:3], off
	s_waitcnt vmcnt(10)
	s_barrier
	v_mfma_scale_f32_16x16x128_f8f6f4 v[70:73], v[206:213], v[174:181], v[70:73], v171, v171 op_sel_hi:[0,0,0]
	v_mfma_scale_f32_16x16x128_f8f6f4 v[66:69], v[214:221], v[174:181], v[66:69], v171, v171 op_sel_hi:[0,0,0]
	v_mfma_scale_f32_16x16x128_f8f6f4 v[54:57], v[206:213], v[182:189], v[54:57], v171, v171 op_sel_hi:[0,0,0]
	v_mfma_scale_f32_16x16x128_f8f6f4 v[50:53], v[214:221], v[182:189], v[50:53], v171, v171 op_sel_hi:[0,0,0]
	v_mfma_scale_f32_16x16x128_f8f6f4 v[38:41], v[206:213], v[190:197], v[38:41], v171, v171 op_sel_hi:[0,0,0]
	v_mfma_scale_f32_16x16x128_f8f6f4 v[34:37], v[214:221], v[190:197], v[34:37], v171, v171 op_sel_hi:[0,0,0]
	v_mfma_scale_f32_16x16x128_f8f6f4 v[22:25], v[206:213], v[198:205], v[22:25], v171, v171 op_sel_hi:[0,0,0]
	v_mfma_scale_f32_16x16x128_f8f6f4 v[18:21], v[214:221], v[198:205], v[18:21], v171, v171 op_sel_hi:[0,0,0]
	s_add_i32 s53, s53, 2
	s_add_u32 s51, s51, 0x100
	s_addc_u32 s52, s52, 0
	s_add_u32 s28, s28, 0x10000
	s_addc_u32 s29, s29, 0
	s_cmp_gt_u32 s53, 5
	s_barrier
	s_cbranch_scc1 .Lpeel_exit_7

.Lpeel_exit_7:
	v_pk_mul_f32 v[10:11], v[142:143], s[16:17] op_sel_hi:[1,0]
	v_pk_mul_f32 v[8:9], v[144:145], s[16:17] op_sel_hi:[1,0]
	v_med3_f32 v5, v10, s47, v173
	v_med3_f32 v11, v11, s47, v173
	v_mov_b32_e32 v10, 0
	v_cvt_pk_fp8_f32 v10, v5, v11
	v_mov_b32_e32 v3, v166
	v_mov_b32_e32 v2, v167
	s_lshl_b32 s0, s48, 8
	v_pk_mul_f32 v[14:15], v[138:139], s[16:17] op_sel_hi:[1,0]
	v_med3_f32 v5, v8, s47, v173
	v_med3_f32 v8, v9, s47, v173
	s_nop 15
	s_nop 15
	s_or_b32 s0, s0, s42
	v_cvt_pk_fp8_f32 v10, v5, v8 op_sel:[0,0,1]
	v_med3_f32 v5, v14, s47, v173
	v_med3_f32 v8, v15, s47, v173
	v_mov_b32_e32 v11, 0
	v_lshl_add_u32 v2, v2, 3, s0
	s_lshl_b32 s0, s26, 8
	v_cvt_pk_fp8_f32 v11, v5, v8
	s_add_i32 s0, s0, s41
	v_add_u32_e32 v4, s0, v3
	v_pk_mul_f32 v[12:13], v[140:141], s[16:17] op_sel_hi:[1,0]
	v_mov_b32_e32 v6, v4
	v_med3_f32 v5, v12, s47, v173
	v_med3_f32 v8, v13, s47, v173
	v_cvt_pk_fp8_f32 v11, v5, v8 op_sel:[0,0,1]
	v_ashrrev_i32_e32 v7, 31, v6
	v_lshlrev_b64 v[6:7], 10, v[6:7]
	v_ashrrev_i32_e32 v3, 31, v2
	v_lshl_add_u64 v[6:7], s[12:13], 0, v[6:7]
	v_lshl_add_u64 v[6:7], v[6:7], 0, v[2:3]
	global_store_dwordx2 v[6:7], v[10:11], off
	v_pk_mul_f32 v[10:11], v[134:135], s[16:17] op_sel_hi:[1,0]
	v_pk_mul_f32 v[8:9], v[136:137], s[16:17] op_sel_hi:[1,0]
	v_med3_f32 v5, v10, s47, v173
	v_med3_f32 v11, v11, s47, v173
	v_mov_b32_e32 v10, 0
	v_cvt_pk_fp8_f32 v10, v5, v11
	v_pk_mul_f32 v[14:15], v[130:131], s[16:17] op_sel_hi:[1,0]
	v_med3_f32 v5, v8, s47, v173
	v_med3_f32 v8, v9, s47, v173
	v_cvt_pk_fp8_f32 v10, v5, v8 op_sel:[0,0,1]
	v_med3_f32 v5, v14, s47, v173
	v_med3_f32 v8, v15, s47, v173
	v_mov_b32_e32 v11, 0
	v_cvt_pk_fp8_f32 v11, v5, v8
	v_pk_mul_f32 v[12:13], v[132:133], s[16:17] op_sel_hi:[1,0]
	v_pk_mul_f32 v[14:15], v[122:123], s[16:17] op_sel_hi:[1,0]
	v_med3_f32 v5, v12, s47, v173
	v_med3_f32 v8, v13, s47, v173
	v_cvt_pk_fp8_f32 v11, v5, v8 op_sel:[0,0,1]
	v_pk_mul_f32 v[8:9], v[128:129], s[16:17] op_sel_hi:[1,0]
	v_pk_mul_f32 v[12:13], v[124:125], s[16:17] op_sel_hi:[1,0]
	s_and_b64 vcc, exec, s[8:9]
	global_store_dwordx2 v[6:7], v[10:11], off offset:128
	v_pk_mul_f32 v[10:11], v[126:127], s[16:17] op_sel_hi:[1,0]
	v_add_u32_e32 v6, 16, v4
	v_med3_f32 v5, v10, s47, v173
	v_med3_f32 v11, v11, s47, v173
	v_mov_b32_e32 v10, 0
	v_cvt_pk_fp8_f32 v10, v5, v11
	v_med3_f32 v5, v8, s47, v173
	v_med3_f32 v8, v9, s47, v173
	v_mov_b32_e32 v11, 0
	v_cvt_pk_fp8_f32 v10, v5, v8 op_sel:[0,0,1]
	v_med3_f32 v5, v14, s47, v173
	v_med3_f32 v8, v15, s47, v173
	v_cvt_pk_fp8_f32 v11, v5, v8
	v_med3_f32 v5, v12, s47, v173
	v_med3_f32 v8, v13, s47, v173
	v_cvt_pk_fp8_f32 v11, v5, v8 op_sel:[0,0,1]
	v_ashrrev_i32_e32 v7, 31, v6
	v_lshlrev_b64 v[6:7], 10, v[6:7]
	v_lshl_add_u64 v[6:7], s[12:13], 0, v[6:7]
	v_lshl_add_u64 v[6:7], v[6:7], 0, v[2:3]
	global_store_dwordx2 v[6:7], v[10:11], off
	v_pk_mul_f32 v[10:11], v[118:119], s[16:17] op_sel_hi:[1,0]
	v_pk_mul_f32 v[8:9], v[120:121], s[16:17] op_sel_hi:[1,0]
	v_med3_f32 v5, v10, s47, v173
	v_med3_f32 v11, v11, s47, v173
	v_mov_b32_e32 v10, 0
	v_cvt_pk_fp8_f32 v10, v5, v11
	v_pk_mul_f32 v[14:15], v[114:115], s[16:17] op_sel_hi:[1,0]
	v_med3_f32 v5, v8, s47, v173
	v_med3_f32 v8, v9, s47, v173
	v_cvt_pk_fp8_f32 v10, v5, v8 op_sel:[0,0,1]
	v_med3_f32 v5, v14, s47, v173
	v_med3_f32 v8, v15, s47, v173
	v_mov_b32_e32 v11, 0
	v_cvt_pk_fp8_f32 v11, v5, v8
	v_pk_mul_f32 v[12:13], v[116:117], s[16:17] op_sel_hi:[1,0]
	v_pk_mul_f32 v[14:15], v[106:107], s[16:17] op_sel_hi:[1,0]
	v_med3_f32 v5, v12, s47, v173
	v_med3_f32 v8, v13, s47, v173
	v_cvt_pk_fp8_f32 v11, v5, v8 op_sel:[0,0,1]
	v_pk_mul_f32 v[8:9], v[112:113], s[16:17] op_sel_hi:[1,0]
	v_pk_mul_f32 v[12:13], v[108:109], s[16:17] op_sel_hi:[1,0]
	s_mov_b32 s48, s18
	global_store_dwordx2 v[6:7], v[10:11], off offset:128
	v_pk_mul_f32 v[10:11], v[110:111], s[16:17] op_sel_hi:[1,0]
	v_add_u32_e32 v6, 32, v4
	v_med3_f32 v5, v10, s47, v173
	v_med3_f32 v11, v11, s47, v173
	v_mov_b32_e32 v10, 0
	v_cvt_pk_fp8_f32 v10, v5, v11
	v_med3_f32 v5, v8, s47, v173
	v_med3_f32 v8, v9, s47, v173
	v_mov_b32_e32 v11, 0
	v_cvt_pk_fp8_f32 v10, v5, v8 op_sel:[0,0,1]
	v_med3_f32 v5, v14, s47, v173
	v_med3_f32 v8, v15, s47, v173
	v_cvt_pk_fp8_f32 v11, v5, v8
	v_med3_f32 v5, v12, s47, v173
	v_med3_f32 v8, v13, s47, v173
	v_cvt_pk_fp8_f32 v11, v5, v8 op_sel:[0,0,1]
	v_ashrrev_i32_e32 v7, 31, v6
	v_lshlrev_b64 v[6:7], 10, v[6:7]
	v_lshl_add_u64 v[6:7], s[12:13], 0, v[6:7]
	v_lshl_add_u64 v[6:7], v[6:7], 0, v[2:3]
	global_store_dwordx2 v[6:7], v[10:11], off
	v_pk_mul_f32 v[10:11], v[102:103], s[16:17] op_sel_hi:[1,0]
	v_pk_mul_f32 v[8:9], v[104:105], s[16:17] op_sel_hi:[1,0]
	v_med3_f32 v5, v10, s47, v173
	v_med3_f32 v11, v11, s47, v173
	v_mov_b32_e32 v10, 0
	v_cvt_pk_fp8_f32 v10, v5, v11
	v_pk_mul_f32 v[14:15], v[98:99], s[16:17] op_sel_hi:[1,0]
	v_med3_f32 v5, v8, s47, v173
	v_med3_f32 v8, v9, s47, v173
	v_cvt_pk_fp8_f32 v10, v5, v8 op_sel:[0,0,1]
	v_med3_f32 v5, v14, s47, v173
	v_med3_f32 v8, v15, s47, v173
	v_mov_b32_e32 v11, 0
	v_cvt_pk_fp8_f32 v11, v5, v8
	v_pk_mul_f32 v[12:13], v[100:101], s[16:17] op_sel_hi:[1,0]
	v_pk_mul_f32 v[14:15], v[90:91], s[16:17] op_sel_hi:[1,0]
	v_med3_f32 v5, v12, s47, v173
	v_med3_f32 v8, v13, s47, v173
	v_cvt_pk_fp8_f32 v11, v5, v8 op_sel:[0,0,1]
	v_pk_mul_f32 v[8:9], v[96:97], s[16:17] op_sel_hi:[1,0]
	v_pk_mul_f32 v[12:13], v[92:93], s[16:17] op_sel_hi:[1,0]
	s_mov_b32 s26, s20
	global_store_dwordx2 v[6:7], v[10:11], off offset:128
	v_pk_mul_f32 v[10:11], v[94:95], s[16:17] op_sel_hi:[1,0]
	v_add_u32_e32 v6, 48, v4
	v_med3_f32 v5, v10, s47, v173
	v_med3_f32 v11, v11, s47, v173
	v_mov_b32_e32 v10, 0
	v_cvt_pk_fp8_f32 v10, v5, v11
	v_med3_f32 v5, v8, s47, v173
	v_med3_f32 v8, v9, s47, v173
	v_mov_b32_e32 v11, 0
	v_cvt_pk_fp8_f32 v10, v5, v8 op_sel:[0,0,1]
	v_med3_f32 v5, v14, s47, v173
	v_med3_f32 v8, v15, s47, v173
	v_cvt_pk_fp8_f32 v11, v5, v8
	v_med3_f32 v5, v12, s47, v173
	v_med3_f32 v8, v13, s47, v173
	v_cvt_pk_fp8_f32 v11, v5, v8 op_sel:[0,0,1]
	v_ashrrev_i32_e32 v7, 31, v6
	v_lshlrev_b64 v[6:7], 10, v[6:7]
	v_lshl_add_u64 v[6:7], s[12:13], 0, v[6:7]
	v_lshl_add_u64 v[6:7], v[6:7], 0, v[2:3]
	global_store_dwordx2 v[6:7], v[10:11], off
	v_pk_mul_f32 v[10:11], v[86:87], s[16:17] op_sel_hi:[1,0]
	v_pk_mul_f32 v[8:9], v[88:89], s[16:17] op_sel_hi:[1,0]
	v_med3_f32 v5, v10, s47, v173
	v_med3_f32 v11, v11, s47, v173
	v_mov_b32_e32 v10, 0
	v_cvt_pk_fp8_f32 v10, v5, v11
	v_pk_mul_f32 v[14:15], v[82:83], s[16:17] op_sel_hi:[1,0]
	v_med3_f32 v5, v8, s47, v173
	v_med3_f32 v8, v9, s47, v173
	v_cvt_pk_fp8_f32 v10, v5, v8 op_sel:[0,0,1]
	v_med3_f32 v5, v14, s47, v173
	v_med3_f32 v8, v15, s47, v173
	v_mov_b32_e32 v11, 0
	v_cvt_pk_fp8_f32 v11, v5, v8
	v_pk_mul_f32 v[12:13], v[84:85], s[16:17] op_sel_hi:[1,0]
	v_pk_mul_f32 v[14:15], v[74:75], s[16:17] op_sel_hi:[1,0]
	v_med3_f32 v5, v12, s47, v173
	v_med3_f32 v8, v13, s47, v173
	v_cvt_pk_fp8_f32 v11, v5, v8 op_sel:[0,0,1]
	v_pk_mul_f32 v[8:9], v[80:81], s[16:17] op_sel_hi:[1,0]
	v_pk_mul_f32 v[12:13], v[76:77], s[16:17] op_sel_hi:[1,0]
	s_mov_b64 s[28:29], s[24:25]
	global_store_dwordx2 v[6:7], v[10:11], off offset:128
	v_pk_mul_f32 v[10:11], v[78:79], s[16:17] op_sel_hi:[1,0]
	v_add_u32_e32 v6, 0x80, v4
	v_med3_f32 v5, v10, s47, v173
	v_med3_f32 v11, v11, s47, v173
	v_mov_b32_e32 v10, 0
	v_cvt_pk_fp8_f32 v10, v5, v11
	v_med3_f32 v5, v8, s47, v173
	v_med3_f32 v8, v9, s47, v173
	v_mov_b32_e32 v11, 0
	v_cvt_pk_fp8_f32 v10, v5, v8 op_sel:[0,0,1]
	v_med3_f32 v5, v14, s47, v173
	v_med3_f32 v8, v15, s47, v173
	v_cvt_pk_fp8_f32 v11, v5, v8
	v_med3_f32 v5, v12, s47, v173
	v_med3_f32 v8, v13, s47, v173
	v_cvt_pk_fp8_f32 v11, v5, v8 op_sel:[0,0,1]
	v_ashrrev_i32_e32 v7, 31, v6
	v_lshlrev_b64 v[6:7], 10, v[6:7]
	v_lshl_add_u64 v[6:7], s[12:13], 0, v[6:7]
	v_lshl_add_u64 v[6:7], v[6:7], 0, v[2:3]
	global_store_dwordx2 v[6:7], v[10:11], off
	v_pk_mul_f32 v[10:11], v[70:71], s[16:17] op_sel_hi:[1,0]
	v_pk_mul_f32 v[8:9], v[72:73], s[16:17] op_sel_hi:[1,0]
	v_med3_f32 v5, v10, s47, v173
	v_med3_f32 v11, v11, s47, v173
	v_mov_b32_e32 v10, 0
	v_cvt_pk_fp8_f32 v10, v5, v11
	v_pk_mul_f32 v[14:15], v[66:67], s[16:17] op_sel_hi:[1,0]
	v_med3_f32 v5, v8, s47, v173
	v_med3_f32 v8, v9, s47, v173
	v_cvt_pk_fp8_f32 v10, v5, v8 op_sel:[0,0,1]
	v_med3_f32 v5, v14, s47, v173
	v_med3_f32 v8, v15, s47, v173
	v_mov_b32_e32 v11, 0
	v_cvt_pk_fp8_f32 v11, v5, v8
	v_pk_mul_f32 v[12:13], v[68:69], s[16:17] op_sel_hi:[1,0]
	v_pk_mul_f32 v[14:15], v[58:59], s[16:17] op_sel_hi:[1,0]
	v_med3_f32 v5, v12, s47, v173
	v_med3_f32 v8, v13, s47, v173
	v_cvt_pk_fp8_f32 v11, v5, v8 op_sel:[0,0,1]
	v_pk_mul_f32 v[8:9], v[64:65], s[16:17] op_sel_hi:[1,0]
	v_pk_mul_f32 v[12:13], v[60:61], s[16:17] op_sel_hi:[1,0]
	s_mov_b64 s[30:31], s[22:23]
	global_store_dwordx2 v[6:7], v[10:11], off offset:128
	v_pk_mul_f32 v[10:11], v[62:63], s[16:17] op_sel_hi:[1,0]
	v_add_u32_e32 v6, 0x90, v4
	v_med3_f32 v5, v10, s47, v173
	v_med3_f32 v11, v11, s47, v173
	v_mov_b32_e32 v10, 0
	v_cvt_pk_fp8_f32 v10, v5, v11
	v_med3_f32 v5, v8, s47, v173
	v_med3_f32 v8, v9, s47, v173
	v_mov_b32_e32 v11, 0
	v_cvt_pk_fp8_f32 v10, v5, v8 op_sel:[0,0,1]
	v_med3_f32 v5, v14, s47, v173
	v_med3_f32 v8, v15, s47, v173
	v_cvt_pk_fp8_f32 v11, v5, v8
	v_med3_f32 v5, v12, s47, v173
	v_med3_f32 v8, v13, s47, v173
	v_cvt_pk_fp8_f32 v11, v5, v8 op_sel:[0,0,1]
	v_ashrrev_i32_e32 v7, 31, v6
	v_lshlrev_b64 v[6:7], 10, v[6:7]
	v_lshl_add_u64 v[6:7], s[12:13], 0, v[6:7]
	v_lshl_add_u64 v[6:7], v[6:7], 0, v[2:3]
	global_store_dwordx2 v[6:7], v[10:11], off
	v_pk_mul_f32 v[10:11], v[54:55], s[16:17] op_sel_hi:[1,0]
	v_pk_mul_f32 v[8:9], v[56:57], s[16:17] op_sel_hi:[1,0]
	v_med3_f32 v5, v10, s47, v173
	v_med3_f32 v11, v11, s47, v173
	v_mov_b32_e32 v10, 0
	v_cvt_pk_fp8_f32 v10, v5, v11
	v_pk_mul_f32 v[14:15], v[50:51], s[16:17] op_sel_hi:[1,0]
	v_med3_f32 v5, v8, s47, v173
	v_med3_f32 v8, v9, s47, v173
	v_cvt_pk_fp8_f32 v10, v5, v8 op_sel:[0,0,1]
	v_med3_f32 v5, v14, s47, v173
	v_med3_f32 v8, v15, s47, v173
	v_mov_b32_e32 v11, 0
	v_cvt_pk_fp8_f32 v11, v5, v8
	v_pk_mul_f32 v[12:13], v[52:53], s[16:17] op_sel_hi:[1,0]
	v_pk_mul_f32 v[14:15], v[42:43], s[16:17] op_sel_hi:[1,0]
	v_med3_f32 v5, v12, s47, v173
	v_med3_f32 v8, v13, s47, v173
	v_cvt_pk_fp8_f32 v11, v5, v8 op_sel:[0,0,1]
	v_pk_mul_f32 v[8:9], v[48:49], s[16:17] op_sel_hi:[1,0]
	v_pk_mul_f32 v[12:13], v[44:45], s[16:17] op_sel_hi:[1,0]
	global_store_dwordx2 v[6:7], v[10:11], off offset:128
	v_pk_mul_f32 v[10:11], v[46:47], s[16:17] op_sel_hi:[1,0]
	v_add_u32_e32 v6, 0xa0, v4
	v_med3_f32 v5, v10, s47, v173
	v_med3_f32 v11, v11, s47, v173
	v_mov_b32_e32 v10, 0
	v_cvt_pk_fp8_f32 v10, v5, v11
	v_med3_f32 v5, v8, s47, v173
	v_med3_f32 v8, v9, s47, v173
	v_mov_b32_e32 v11, 0
	v_cvt_pk_fp8_f32 v10, v5, v8 op_sel:[0,0,1]
	v_med3_f32 v5, v14, s47, v173
	v_med3_f32 v8, v15, s47, v173
	v_cvt_pk_fp8_f32 v11, v5, v8
	v_med3_f32 v5, v12, s47, v173
	v_med3_f32 v8, v13, s47, v173
	v_cvt_pk_fp8_f32 v11, v5, v8 op_sel:[0,0,1]
	v_ashrrev_i32_e32 v7, 31, v6
	v_lshlrev_b64 v[6:7], 10, v[6:7]
	v_lshl_add_u64 v[6:7], s[12:13], 0, v[6:7]
	v_lshl_add_u64 v[6:7], v[6:7], 0, v[2:3]
	global_store_dwordx2 v[6:7], v[10:11], off
	v_pk_mul_f32 v[10:11], v[38:39], s[16:17] op_sel_hi:[1,0]
	v_pk_mul_f32 v[8:9], v[40:41], s[16:17] op_sel_hi:[1,0]
	v_med3_f32 v5, v10, s47, v173
	v_med3_f32 v11, v11, s47, v173
	v_mov_b32_e32 v10, 0
	v_cvt_pk_fp8_f32 v10, v5, v11
	v_pk_mul_f32 v[14:15], v[34:35], s[16:17] op_sel_hi:[1,0]
	v_med3_f32 v5, v8, s47, v173
	v_med3_f32 v8, v9, s47, v173
	v_cvt_pk_fp8_f32 v10, v5, v8 op_sel:[0,0,1]
	v_med3_f32 v5, v14, s47, v173
	v_med3_f32 v8, v15, s47, v173
	v_mov_b32_e32 v11, 0
	v_cvt_pk_fp8_f32 v11, v5, v8
	v_pk_mul_f32 v[12:13], v[36:37], s[16:17] op_sel_hi:[1,0]
	v_add_u32_e32 v4, 0xb0, v4
	v_med3_f32 v5, v12, s47, v173
	v_med3_f32 v8, v13, s47, v173
	v_cvt_pk_fp8_f32 v11, v5, v8 op_sel:[0,0,1]
	v_pk_mul_f32 v[8:9], v[28:29], s[16:17] op_sel_hi:[1,0]
	global_store_dwordx2 v[6:7], v[10:11], off offset:128
	v_pk_mul_f32 v[6:7], v[30:31], s[16:17] op_sel_hi:[1,0]
	v_pk_mul_f32 v[10:11], v[26:27], s[16:17] op_sel_hi:[1,0]
	v_ashrrev_i32_e32 v5, 31, v4
	v_med3_f32 v12, v6, s47, v173
	v_med3_f32 v7, v7, s47, v173
	v_mov_b32_e32 v6, 0
	v_lshlrev_b64 v[4:5], 10, v[4:5]
	v_cvt_pk_fp8_f32 v6, v12, v7
	v_lshl_add_u64 v[4:5], s[12:13], 0, v[4:5]
	v_lshl_add_u64 v[2:3], v[4:5], 0, v[2:3]
	v_pk_mul_f32 v[4:5], v[32:33], s[16:17] op_sel_hi:[1,0]
	v_mov_b32_e32 v7, 0
	v_med3_f32 v4, v4, s47, v173
	v_med3_f32 v5, v5, s47, v173
	v_cvt_pk_fp8_f32 v6, v4, v5 op_sel:[0,0,1]
	v_med3_f32 v4, v10, s47, v173
	v_med3_f32 v5, v11, s47, v173
	v_cvt_pk_fp8_f32 v7, v4, v5
	v_med3_f32 v4, v8, s47, v173
	v_med3_f32 v5, v9, s47, v173
	v_pk_mul_f32 v[10:11], v[18:19], s[16:17] op_sel_hi:[1,0]
	v_cvt_pk_fp8_f32 v7, v4, v5 op_sel:[0,0,1]
	v_pk_mul_f32 v[4:5], v[24:25], s[16:17] op_sel_hi:[1,0]
	v_pk_mul_f32 v[8:9], v[20:21], s[16:17] op_sel_hi:[1,0]
	v_med3_f32 v4, v4, s47, v173
	global_store_dwordx2 v[2:3], v[6:7], off
	v_pk_mul_f32 v[6:7], v[22:23], s[16:17] op_sel_hi:[1,0]
	v_med3_f32 v5, v5, s47, v173
	v_med3_f32 v12, v6, s47, v173
	v_med3_f32 v7, v7, s47, v173
	v_mov_b32_e32 v6, 0
	v_cvt_pk_fp8_f32 v6, v12, v7
	v_mov_b32_e32 v7, 0
	v_cvt_pk_fp8_f32 v6, v4, v5 op_sel:[0,0,1]
	v_med3_f32 v4, v10, s47, v173
	v_med3_f32 v5, v11, s47, v173
	v_cvt_pk_fp8_f32 v7, v4, v5
	v_med3_f32 v4, v8, s47, v173
	v_med3_f32 v5, v9, s47, v173
	v_cvt_pk_fp8_f32 v7, v4, v5 op_sel:[0,0,1]
	global_store_dwordx2 v[2:3], v[6:7], off offset:128
	s_cbranch_vccz .LBB0_1362
	s_waitcnt vmcnt(0)
	s_cmpk_gt_u32 s4, 0xff
	s_cbranch_scc1 .LBB0_1373
	s_barrier

.LBB0_1512:
	s_ashr_i32 s21, s20, 31
	s_lshl_b64 s[0:1], s[20:21], 19
	v_cmp_lt_i64_e32 vcc, s[22:23], v[142:143]
	s_add_u32 s22, s5, s0
	s_addc_u32 s23, s6, s1
	s_and_b64 s[0:1], vcc, exec
	s_cselect_b32 s21, s23, s29
	s_cselect_b32 s45, s22, s28
	s_ashr_i32 s19, s18, 31
	s_lshl_b64 s[0:1], s[18:19], 19
	s_add_u32 s24, s7, s0
	s_addc_u32 s25, s8, s1
	s_and_b64 s[0:1], vcc, exec
	s_cselect_b32 s19, s25, s27
	s_cselect_b32 s46, s24, s26
	s_add_u32 s47, s26, 0x100
	s_addc_u32 s48, s27, 0
	s_add_u32 s26, s28, 0x40080
	s_addc_u32 s27, s29, 0
	s_mov_b32 s49, -2
	ds_read_b128 v[152:155], v149
	ds_read_b128 v[156:159], v149 offset:1024
	ds_read_b128 v[160:163], v149 offset:2048
	ds_read_b128 v[164:167], v149 offset:3072
	s_add_u32 s0, s26, 0xfffc0080
	s_addc_u32 s1, s27, -1
	s_cmp_eq_u32 s49, 12
	s_cselect_b32 s31, s21, s1
	s_cselect_b32 s30, s45, s0
	s_cselect_b32 s29, s19, s48
	s_cselect_b32 s28, s46, s47
	v_lshl_add_u64 v[200:201], s[26:27], 0, v[140:141]
	s_add_i32 m0, s10, 0xc000
	ds_read_b128 v[168:171], v150
	ds_read_b128 v[172:175], v150 offset:1024
	ds_read_b128 v[176:179], v150 offset:2048
	ds_read_b128 v[180:183], v150 offset:3072
	ds_read_b128 v[184:187], v150 offset:4096
	ds_read_b128 v[188:191], v150 offset:5120
	ds_read_b128 v[192:195], v150 offset:6144
	ds_read_b128 v[196:199], v150 offset:7168
	global_load_lds_dwordx4 v[200:201], off
	v_lshl_add_u64 v[200:201], s[26:27], 0, v[138:139]
	s_add_i32 m0, s10, 0xe000
	s_nop 0
	global_load_lds_dwordx4 v[200:201], off
	s_waitcnt lgkmcnt(8)
	s_waitcnt vmcnt(10)
	s_barrier
	s_waitcnt lgkmcnt(0)
	s_waitcnt lgkmcnt(0)
	v_mfma_f32_16x16x32_bf16 v[126:129], v[152:155], v[168:171], 0
	v_mfma_f32_16x16x32_bf16 v[122:125], v[160:163], v[168:171], 0
	v_mfma_f32_16x16x32_bf16 v[118:121], v[152:155], v[176:179], 0
	v_mfma_f32_16x16x32_bf16 v[110:113], v[160:163], v[176:179], 0
	v_mfma_f32_16x16x32_bf16 v[102:105], v[152:155], v[184:187], 0
	v_mfma_f32_16x16x32_bf16 v[94:97], v[160:163], v[184:187], 0
	v_mfma_f32_16x16x32_bf16 v[86:89], v[152:155], v[192:195], 0
	v_mfma_f32_16x16x32_bf16 v[78:81], v[160:163], v[192:195], 0
	v_mfma_f32_16x16x32_bf16 v[126:129], v[156:159], v[172:175], v[126:129]
	v_mfma_f32_16x16x32_bf16 v[122:125], v[164:167], v[172:175], v[122:125]
	v_mfma_f32_16x16x32_bf16 v[118:121], v[156:159], v[180:183], v[118:121]
	v_mfma_f32_16x16x32_bf16 v[110:113], v[164:167], v[180:183], v[110:113]
	v_mfma_f32_16x16x32_bf16 v[102:105], v[156:159], v[188:191], v[102:105]
	v_mfma_f32_16x16x32_bf16 v[94:97], v[164:167], v[188:191], v[94:97]
	v_mfma_f32_16x16x32_bf16 v[86:89], v[156:159], v[196:199], v[86:89]
	v_mfma_f32_16x16x32_bf16 v[78:81], v[164:167], v[196:199], v[78:81]
	s_barrier
	s_add_i32 s0, s42, s9
	v_lshl_add_u64 v[216:217], s[28:29], 0, v[134:135]
	s_mov_b32 m0, s0
	ds_read_b128 v[200:203], v151
	ds_read_b128 v[204:207], v151 offset:1024
	ds_read_b128 v[208:211], v151 offset:2048
	ds_read_b128 v[212:215], v151 offset:3072
	global_load_lds_dwordx4 v[216:217], off
	v_lshl_add_u64 v[218:219], s[28:29], 0, v[130:131]
	s_add_i32 m0, s0, 0x2000
	s_nop 0
	global_load_lds_dwordx4 v[218:219], off
	s_waitcnt vmcnt(10)
	s_barrier
	s_waitcnt lgkmcnt(0)
	s_waitcnt lgkmcnt(0)
	v_mfma_f32_16x16x32_bf16 v[114:117], v[200:203], v[168:171], 0
	v_mfma_f32_16x16x32_bf16 v[106:109], v[208:211], v[168:171], 0
	v_mfma_f32_16x16x32_bf16 v[98:101], v[200:203], v[176:179], 0
	v_mfma_f32_16x16x32_bf16 v[90:93], v[208:211], v[176:179], 0
	v_mfma_f32_16x16x32_bf16 v[82:85], v[200:203], v[184:187], 0
	v_mfma_f32_16x16x32_bf16 v[74:77], v[208:211], v[184:187], 0
	v_mfma_f32_16x16x32_bf16 v[70:73], v[200:203], v[192:195], 0
	v_mfma_f32_16x16x32_bf16 v[66:69], v[208:211], v[192:195], 0
	v_mfma_f32_16x16x32_bf16 v[114:117], v[204:207], v[172:175], v[114:117]
	v_mfma_f32_16x16x32_bf16 v[106:109], v[212:215], v[172:175], v[106:109]
	v_mfma_f32_16x16x32_bf16 v[98:101], v[204:207], v[180:183], v[98:101]
	v_mfma_f32_16x16x32_bf16 v[90:93], v[212:215], v[180:183], v[90:93]
	v_mfma_f32_16x16x32_bf16 v[82:85], v[204:207], v[188:191], v[82:85]
	v_mfma_f32_16x16x32_bf16 v[74:77], v[212:215], v[188:191], v[74:77]
	v_mfma_f32_16x16x32_bf16 v[70:73], v[204:207], v[196:199], v[70:73]
	v_mfma_f32_16x16x32_bf16 v[66:69], v[212:215], v[196:199], v[66:69]
	s_mov_b32 m0, s10
	v_lshl_add_u64 v[220:221], s[30:31], 0, v[136:137]
	s_barrier
	ds_read_b128 v[168:171], v150 offset:16384
	ds_read_b128 v[172:175], v150 offset:17408
	ds_read_b128 v[176:179], v150 offset:18432
	ds_read_b128 v[180:183], v150 offset:19456
	ds_read_b128 v[184:187], v150 offset:20480
	ds_read_b128 v[188:191], v150 offset:21504
	ds_read_b128 v[192:195], v150 offset:22528
	ds_read_b128 v[196:199], v150 offset:23552
	global_load_lds_dwordx4 v[220:221], off
	v_lshl_add_u64 v[222:223], s[30:31], 0, v[132:133]
	s_mov_b32 m0, s11
	s_nop 0
	global_load_lds_dwordx4 v[222:223], off
	s_waitcnt vmcnt(10)
	s_barrier
	s_waitcnt lgkmcnt(0)
	s_waitcnt lgkmcnt(0)
	v_mfma_f32_16x16x32_bf16 v[62:65], v[152:155], v[168:171], 0
	v_mfma_f32_16x16x32_bf16 v[58:61], v[160:163], v[168:171], 0
	v_mfma_f32_16x16x32_bf16 v[54:57], v[152:155], v[176:179], 0
	v_mfma_f32_16x16x32_bf16 v[50:53], v[160:163], v[176:179], 0
	v_mfma_f32_16x16x32_bf16 v[38:41], v[152:155], v[184:187], 0
	v_mfma_f32_16x16x32_bf16 v[34:37], v[160:163], v[184:187], 0
	v_mfma_f32_16x16x32_bf16 v[22:25], v[152:155], v[192:195], 0
	v_mfma_f32_16x16x32_bf16 v[18:21], v[160:163], v[192:195], 0
	v_mfma_f32_16x16x32_bf16 v[62:65], v[156:159], v[172:175], v[62:65]
	v_mfma_f32_16x16x32_bf16 v[58:61], v[164:167], v[172:175], v[58:61]
	v_mfma_f32_16x16x32_bf16 v[54:57], v[156:159], v[180:183], v[54:57]
	v_mfma_f32_16x16x32_bf16 v[50:53], v[164:167], v[180:183], v[50:53]
	v_mfma_f32_16x16x32_bf16 v[38:41], v[156:159], v[188:191], v[38:41]
	v_mfma_f32_16x16x32_bf16 v[34:37], v[164:167], v[188:191], v[34:37]
	v_mfma_f32_16x16x32_bf16 v[22:25], v[156:159], v[196:199], v[22:25]
	v_mfma_f32_16x16x32_bf16 v[18:21], v[164:167], v[196:199], v[18:21]
	s_barrier
	s_add_u32 s0, s28, 0x40000
	s_addc_u32 s1, s29, 0
	s_add_i32 s50, s43, s9
	v_lshl_add_u64 v[152:153], s[0:1], 0, v[134:135]
	s_mov_b32 m0, s50
	s_nop 0
	global_load_lds_dwordx4 v[152:153], off
	v_lshl_add_u64 v[152:153], s[0:1], 0, v[130:131]
	s_add_i32 m0, s50, 0x2000
	s_nop 0
	global_load_lds_dwordx4 v[152:153], off
	s_waitcnt vmcnt(10)
	s_barrier
	v_mfma_f32_16x16x32_bf16 v[46:49], v[200:203], v[168:171], 0
	v_mfma_f32_16x16x32_bf16 v[42:45], v[208:211], v[168:171], 0
	v_mfma_f32_16x16x32_bf16 v[30:33], v[200:203], v[176:179], 0
	v_mfma_f32_16x16x32_bf16 v[26:29], v[208:211], v[176:179], 0
	v_mfma_f32_16x16x32_bf16 v[14:17], v[200:203], v[184:187], 0
	v_mfma_f32_16x16x32_bf16 v[10:13], v[208:211], v[184:187], 0
	v_mfma_f32_16x16x32_bf16 v[6:9], v[200:203], v[192:195], 0
	v_mfma_f32_16x16x32_bf16 v[2:5], v[208:211], v[192:195], 0
	v_mfma_f32_16x16x32_bf16 v[46:49], v[204:207], v[172:175], v[46:49]
	v_mfma_f32_16x16x32_bf16 v[42:45], v[212:215], v[172:175], v[42:45]
	v_mfma_f32_16x16x32_bf16 v[30:33], v[204:207], v[180:183], v[30:33]
	v_mfma_f32_16x16x32_bf16 v[26:29], v[212:215], v[180:183], v[26:29]
	v_mfma_f32_16x16x32_bf16 v[14:17], v[204:207], v[188:191], v[14:17]
	v_mfma_f32_16x16x32_bf16 v[10:13], v[212:215], v[188:191], v[10:13]
	v_mfma_f32_16x16x32_bf16 v[6:9], v[204:207], v[196:199], v[6:9]
	v_mfma_f32_16x16x32_bf16 v[2:5], v[212:215], v[196:199], v[2:5]
	s_add_i32 s50, 0, 0x18000
	v_add_u32_e32 v164, s50, v148
	s_barrier
	ds_read_b128 v[152:155], v164
	ds_read_b128 v[156:159], v164 offset:1024
	ds_read_b128 v[160:163], v164 offset:2048
	ds_read_b128 v[164:167], v164 offset:3072
	s_add_u32 s0, s30, 0x40000
	s_addc_u32 s1, s31, 0
	s_mov_b32 m0, s17
	v_lshl_add_u64 v[200:201], s[0:1], 0, v[136:137]
	ds_read_b128 v[168:171], v150 offset:32768
	ds_read_b128 v[172:175], v150 offset:33792
	ds_read_b128 v[176:179], v150 offset:34816
	ds_read_b128 v[180:183], v150 offset:35840
	ds_read_b128 v[184:187], v150 offset:36864
	ds_read_b128 v[188:191], v150 offset:37888
	ds_read_b128 v[192:195], v150 offset:38912
	ds_read_b128 v[196:199], v150 offset:39936
	global_load_lds_dwordx4 v[200:201], off
	v_lshl_add_u64 v[200:201], s[0:1], 0, v[132:133]
	s_mov_b32 m0, s34
	s_nop 0
	global_load_lds_dwordx4 v[200:201], off
	s_waitcnt lgkmcnt(8)
	s_waitcnt vmcnt(10)
	s_barrier
	s_waitcnt lgkmcnt(0)
	s_waitcnt lgkmcnt(0)
	v_mfma_f32_16x16x32_bf16 v[126:129], v[152:155], v[168:171], v[126:129]
	v_mfma_f32_16x16x32_bf16 v[122:125], v[160:163], v[168:171], v[122:125]
	v_mfma_f32_16x16x32_bf16 v[118:121], v[152:155], v[176:179], v[118:121]
	v_mfma_f32_16x16x32_bf16 v[110:113], v[160:163], v[176:179], v[110:113]
	v_mfma_f32_16x16x32_bf16 v[102:105], v[152:155], v[184:187], v[102:105]
	v_mfma_f32_16x16x32_bf16 v[94:97], v[160:163], v[184:187], v[94:97]
	v_mfma_f32_16x16x32_bf16 v[86:89], v[152:155], v[192:195], v[86:89]
	v_mfma_f32_16x16x32_bf16 v[78:81], v[160:163], v[192:195], v[78:81]
	v_mfma_f32_16x16x32_bf16 v[126:129], v[156:159], v[172:175], v[126:129]
	v_mfma_f32_16x16x32_bf16 v[122:125], v[164:167], v[172:175], v[122:125]
	v_mfma_f32_16x16x32_bf16 v[118:121], v[156:159], v[180:183], v[118:121]
	v_mfma_f32_16x16x32_bf16 v[110:113], v[164:167], v[180:183], v[110:113]
	v_mfma_f32_16x16x32_bf16 v[102:105], v[156:159], v[188:191], v[102:105]
	v_mfma_f32_16x16x32_bf16 v[94:97], v[164:167], v[188:191], v[94:97]
	v_mfma_f32_16x16x32_bf16 v[86:89], v[156:159], v[196:199], v[86:89]
	v_mfma_f32_16x16x32_bf16 v[78:81], v[164:167], v[196:199], v[78:81]
	s_barrier
	s_add_i32 s30, 0, 0x1c000
	s_add_i32 s0, s50, s9
	v_add_u32_e32 v212, s30, v148
	v_lshl_add_u64 v[216:217], v[216:217], 0, s[14:15]
	s_mov_b32 m0, s0
	ds_read_b128 v[200:203], v212
	ds_read_b128 v[204:207], v212 offset:1024
	ds_read_b128 v[208:211], v212 offset:2048
	ds_read_b128 v[212:215], v212 offset:3072
	global_load_lds_dwordx4 v[216:217], off
	v_lshl_add_u64 v[216:217], v[218:219], 0, s[14:15]
	s_add_i32 m0, s0, 0x2000
	s_nop 0
	global_load_lds_dwordx4 v[216:217], off
	s_waitcnt vmcnt(10)
	s_barrier
	s_waitcnt lgkmcnt(0)
	s_waitcnt lgkmcnt(0)
	v_mfma_f32_16x16x32_bf16 v[114:117], v[200:203], v[168:171], v[114:117]
	v_mfma_f32_16x16x32_bf16 v[106:109], v[208:211], v[168:171], v[106:109]
	v_mfma_f32_16x16x32_bf16 v[98:101], v[200:203], v[176:179], v[98:101]
	v_mfma_f32_16x16x32_bf16 v[90:93], v[208:211], v[176:179], v[90:93]
	v_mfma_f32_16x16x32_bf16 v[82:85], v[200:203], v[184:187], v[82:85]
	v_mfma_f32_16x16x32_bf16 v[74:77], v[208:211], v[184:187], v[74:77]
	v_mfma_f32_16x16x32_bf16 v[70:73], v[200:203], v[192:195], v[70:73]
	v_mfma_f32_16x16x32_bf16 v[66:69], v[208:211], v[192:195], v[66:69]
	v_mfma_f32_16x16x32_bf16 v[114:117], v[204:207], v[172:175], v[114:117]
	v_mfma_f32_16x16x32_bf16 v[106:109], v[212:215], v[172:175], v[106:109]
	v_mfma_f32_16x16x32_bf16 v[98:101], v[204:207], v[180:183], v[98:101]
	v_mfma_f32_16x16x32_bf16 v[90:93], v[212:215], v[180:183], v[90:93]
	v_mfma_f32_16x16x32_bf16 v[82:85], v[204:207], v[188:191], v[82:85]
	v_mfma_f32_16x16x32_bf16 v[74:77], v[212:215], v[188:191], v[74:77]
	v_mfma_f32_16x16x32_bf16 v[70:73], v[204:207], v[196:199], v[70:73]
	v_mfma_f32_16x16x32_bf16 v[66:69], v[212:215], v[196:199], v[66:69]
	s_mov_b32 m0, s40
	v_lshl_add_u64 v[216:217], v[220:221], 0, s[14:15]
	s_barrier
	ds_read_b128 v[168:171], v150 offset:49152
	ds_read_b128 v[172:175], v150 offset:50176
	ds_read_b128 v[176:179], v150 offset:51200
	ds_read_b128 v[180:183], v150 offset:52224
	ds_read_b128 v[184:187], v150 offset:53248
	ds_read_b128 v[188:191], v150 offset:54272
	ds_read_b128 v[192:195], v150 offset:55296
	ds_read_b128 v[196:199], v150 offset:56320
	global_load_lds_dwordx4 v[216:217], off
	v_lshl_add_u64 v[216:217], v[222:223], 0, s[14:15]
	s_mov_b32 m0, s41
	s_nop 0
	global_load_lds_dwordx4 v[216:217], off
	s_waitcnt vmcnt(10)
	s_barrier
	s_waitcnt lgkmcnt(0)
	s_waitcnt lgkmcnt(0)
	v_mfma_f32_16x16x32_bf16 v[62:65], v[152:155], v[168:171], v[62:65]
	v_mfma_f32_16x16x32_bf16 v[58:61], v[160:163], v[168:171], v[58:61]
	v_mfma_f32_16x16x32_bf16 v[54:57], v[152:155], v[176:179], v[54:57]
	v_mfma_f32_16x16x32_bf16 v[50:53], v[160:163], v[176:179], v[50:53]
	v_mfma_f32_16x16x32_bf16 v[38:41], v[152:155], v[184:187], v[38:41]
	v_mfma_f32_16x16x32_bf16 v[34:37], v[160:163], v[184:187], v[34:37]
	v_mfma_f32_16x16x32_bf16 v[22:25], v[152:155], v[192:195], v[22:25]
	v_mfma_f32_16x16x32_bf16 v[18:21], v[160:163], v[192:195], v[18:21]
	v_mfma_f32_16x16x32_bf16 v[62:65], v[156:159], v[172:175], v[62:65]
	v_mfma_f32_16x16x32_bf16 v[58:61], v[164:167], v[172:175], v[58:61]
	v_mfma_f32_16x16x32_bf16 v[54:57], v[156:159], v[180:183], v[54:57]
	v_mfma_f32_16x16x32_bf16 v[50:53], v[164:167], v[180:183], v[50:53]
	v_mfma_f32_16x16x32_bf16 v[38:41], v[156:159], v[188:191], v[38:41]
	v_mfma_f32_16x16x32_bf16 v[34:37], v[164:167], v[188:191], v[34:37]
	v_mfma_f32_16x16x32_bf16 v[22:25], v[156:159], v[196:199], v[22:25]
	v_mfma_f32_16x16x32_bf16 v[18:21], v[164:167], v[196:199], v[18:21]
	s_barrier
	s_add_u32 s0, s28, 0x40080
	s_addc_u32 s1, s29, 0
	s_add_i32 s28, s30, s9
	v_lshl_add_u64 v[152:153], s[0:1], 0, v[134:135]
	s_mov_b32 m0, s28
	s_nop 0
	global_load_lds_dwordx4 v[152:153], off
	v_lshl_add_u64 v[152:153], s[0:1], 0, v[130:131]
	s_add_i32 m0, s28, 0x2000
	s_nop 0
	global_load_lds_dwordx4 v[152:153], off
	s_waitcnt vmcnt(10)
	s_barrier
	v_mfma_f32_16x16x32_bf16 v[46:49], v[200:203], v[168:171], v[46:49]
	v_mfma_f32_16x16x32_bf16 v[42:45], v[208:211], v[168:171], v[42:45]
	v_mfma_f32_16x16x32_bf16 v[30:33], v[200:203], v[176:179], v[30:33]
	v_mfma_f32_16x16x32_bf16 v[26:29], v[208:211], v[176:179], v[26:29]
	v_mfma_f32_16x16x32_bf16 v[14:17], v[200:203], v[184:187], v[14:17]
	v_mfma_f32_16x16x32_bf16 v[10:13], v[208:211], v[184:187], v[10:13]
	v_mfma_f32_16x16x32_bf16 v[6:9], v[200:203], v[192:195], v[6:9]
	v_mfma_f32_16x16x32_bf16 v[2:5], v[208:211], v[192:195], v[2:5]
	v_mfma_f32_16x16x32_bf16 v[46:49], v[204:207], v[172:175], v[46:49]
	v_mfma_f32_16x16x32_bf16 v[42:45], v[212:215], v[172:175], v[42:45]
	v_mfma_f32_16x16x32_bf16 v[30:33], v[204:207], v[180:183], v[30:33]
	v_mfma_f32_16x16x32_bf16 v[26:29], v[212:215], v[180:183], v[26:29]
	v_mfma_f32_16x16x32_bf16 v[14:17], v[204:207], v[188:191], v[14:17]
	v_mfma_f32_16x16x32_bf16 v[10:13], v[212:215], v[188:191], v[10:13]
	v_mfma_f32_16x16x32_bf16 v[6:9], v[204:207], v[196:199], v[6:9]
	v_mfma_f32_16x16x32_bf16 v[2:5], v[212:215], v[196:199], v[2:5]
	s_add_i32 s49, s49, 2
	s_add_u32 s47, s47, 0x100
	s_addc_u32 s48, s48, 0
	s_add_u32 s26, s26, 0x100
	s_addc_u32 s27, s27, 0
	s_cmp_gt_u32 s49, 13
	s_barrier
	s_cbranch_scc1 .Lpeel_exit_8

.Lpeel_exit_8:
	v_mov_b32_e32 v152, v146
	v_mov_b32_e32 v153, v147
	s_cmp_gt_i32 s44, 7
	s_cbranch_scc1 .LBB0_1505
	s_ashr_i32 s0, s44, 31
	s_lshr_b32 s0, s0, 30
	s_add_i32 s0, s44, s0
	s_ashr_i32 s0, s0, 2
	s_ashr_i32 s1, s0, 31
	s_lshl_b32 s19, s44, 8
	s_lshl_b64 s[26:27], s[0:1], 27
	s_add_u32 s26, s36, s26
	s_addc_u32 s27, s37, s27
	s_or_b32 s1, s19, s39
	s_lshl_b32 s0, s0, 10
	s_sub_i32 s0, s1, s0
	v_lshl_add_u32 v154, v153, 3, s0
	s_lshl_b32 s0, s16, 8
	s_add_i32 s0, s0, s38
	v_add_u32_e32 v156, s0, v152
	v_mov_b32_e32 v152, v156
	v_ashrrev_i32_e32 v155, 31, v154
	v_lshl_add_u64 v[154:155], v[154:155], 1, s[26:27]
	v_ashrrev_i32_e32 v153, 31, v152
	v_lshlrev_b64 v[152:153], 11, v[152:153]
	v_lshl_add_u64 v[152:153], v[154:155], 0, v[152:153]
	v_cvt_pk_bf16_f32 v126, v126, v127
	v_cvt_pk_bf16_f32 v127, v128, v129
	v_cvt_pk_bf16_f32 v128, v122, v123
	v_cvt_pk_bf16_f32 v129, v124, v125
	v_cvt_pk_bf16_f32 v114, v114, v115
	v_cvt_pk_bf16_f32 v115, v116, v117
	v_cvt_pk_bf16_f32 v116, v106, v107
	v_cvt_pk_bf16_f32 v117, v108, v109
	v_add_u32_e32 v106, 16, v156
	global_store_dwordx4 v[152:153], v[126:129], off
	global_store_dwordx4 v[152:153], v[114:117], off offset:256
	v_cvt_pk_bf16_f32 v108, v110, v111
	v_ashrrev_i32_e32 v107, 31, v106
	v_lshlrev_b64 v[106:107], 11, v[106:107]
	v_lshl_add_u64 v[114:115], v[154:155], 0, v[106:107]
	v_cvt_pk_bf16_f32 v106, v118, v119
	v_cvt_pk_bf16_f32 v107, v120, v121
	v_cvt_pk_bf16_f32 v109, v112, v113
	v_cvt_pk_bf16_f32 v98, v98, v99
	v_cvt_pk_bf16_f32 v99, v100, v101
	v_cvt_pk_bf16_f32 v100, v90, v91
	v_cvt_pk_bf16_f32 v101, v92, v93
	v_add_u32_e32 v90, 32, v156
	global_store_dwordx4 v[114:115], v[106:109], off
	global_store_dwordx4 v[114:115], v[98:101], off offset:256
	v_cvt_pk_bf16_f32 v92, v94, v95
	v_ashrrev_i32_e32 v91, 31, v90
	v_lshlrev_b64 v[90:91], 11, v[90:91]
	v_lshl_add_u64 v[98:99], v[154:155], 0, v[90:91]
	v_cvt_pk_bf16_f32 v90, v102, v103
	v_cvt_pk_bf16_f32 v91, v104, v105
	v_cvt_pk_bf16_f32 v93, v96, v97
	v_cvt_pk_bf16_f32 v82, v82, v83
	v_cvt_pk_bf16_f32 v83, v84, v85
	v_cvt_pk_bf16_f32 v84, v74, v75
	v_cvt_pk_bf16_f32 v85, v76, v77
	v_add_u32_e32 v74, 48, v156
	global_store_dwordx4 v[98:99], v[90:93], off
	global_store_dwordx4 v[98:99], v[82:85], off offset:256
	v_cvt_pk_bf16_f32 v76, v78, v79
	v_ashrrev_i32_e32 v75, 31, v74
	v_lshlrev_b64 v[74:75], 11, v[74:75]
	v_lshl_add_u64 v[82:83], v[154:155], 0, v[74:75]
	v_cvt_pk_bf16_f32 v74, v86, v87
	v_cvt_pk_bf16_f32 v75, v88, v89
	v_cvt_pk_bf16_f32 v77, v80, v81
	v_cvt_pk_bf16_f32 v70, v70, v71
	v_cvt_pk_bf16_f32 v71, v72, v73
	v_cvt_pk_bf16_f32 v72, v66, v67
	v_cvt_pk_bf16_f32 v73, v68, v69
	v_add_u32_e32 v66, 0x80, v156
	global_store_dwordx4 v[82:83], v[74:77], off
	global_store_dwordx4 v[82:83], v[70:73], off offset:256
	v_cvt_pk_bf16_f32 v62, v62, v63
	v_ashrrev_i32_e32 v67, 31, v66
	v_lshlrev_b64 v[66:67], 11, v[66:67]
	v_lshl_add_u64 v[66:67], v[154:155], 0, v[66:67]
	v_cvt_pk_bf16_f32 v63, v64, v65
	v_cvt_pk_bf16_f32 v64, v58, v59
	v_cvt_pk_bf16_f32 v65, v60, v61
	v_cvt_pk_bf16_f32 v46, v46, v47
	v_cvt_pk_bf16_f32 v47, v48, v49
	v_cvt_pk_bf16_f32 v48, v42, v43
	v_cvt_pk_bf16_f32 v49, v44, v45
	v_add_u32_e32 v42, 0x90, v156
	global_store_dwordx4 v[66:67], v[62:65], off
	global_store_dwordx4 v[66:67], v[46:49], off offset:256
	v_cvt_pk_bf16_f32 v44, v50, v51
	v_ashrrev_i32_e32 v43, 31, v42
	v_lshlrev_b64 v[42:43], 11, v[42:43]
	v_lshl_add_u64 v[46:47], v[154:155], 0, v[42:43]
	v_cvt_pk_bf16_f32 v42, v54, v55
	v_cvt_pk_bf16_f32 v43, v56, v57
	v_cvt_pk_bf16_f32 v45, v52, v53
	v_cvt_pk_bf16_f32 v30, v30, v31
	v_cvt_pk_bf16_f32 v31, v32, v33
	v_cvt_pk_bf16_f32 v32, v26, v27
	v_cvt_pk_bf16_f32 v33, v28, v29
	v_add_u32_e32 v26, 0xa0, v156
	global_store_dwordx4 v[46:47], v[42:45], off
	global_store_dwordx4 v[46:47], v[30:33], off offset:256
	v_cvt_pk_bf16_f32 v28, v34, v35
	v_ashrrev_i32_e32 v27, 31, v26
	v_lshlrev_b64 v[26:27], 11, v[26:27]
	v_lshl_add_u64 v[30:31], v[154:155], 0, v[26:27]
	v_cvt_pk_bf16_f32 v26, v38, v39
	v_cvt_pk_bf16_f32 v27, v40, v41
	v_cvt_pk_bf16_f32 v29, v36, v37
	v_cvt_pk_bf16_f32 v14, v14, v15
	v_cvt_pk_bf16_f32 v15, v16, v17
	v_cvt_pk_bf16_f32 v16, v10, v11
	v_cvt_pk_bf16_f32 v17, v12, v13
	v_add_u32_e32 v10, 0xb0, v156
	global_store_dwordx4 v[30:31], v[26:29], off
	global_store_dwordx4 v[30:31], v[14:17], off offset:256
	v_cvt_pk_bf16_f32 v12, v18, v19
	v_ashrrev_i32_e32 v11, 31, v10
	v_lshlrev_b64 v[10:11], 11, v[10:11]
	v_lshl_add_u64 v[14:15], v[154:155], 0, v[10:11]
	v_cvt_pk_bf16_f32 v10, v22, v23
	v_cvt_pk_bf16_f32 v11, v24, v25
	v_cvt_pk_bf16_f32 v13, v20, v21
	v_cvt_pk_bf16_f32 v6, v6, v7
	v_cvt_pk_bf16_f32 v7, v8, v9
	v_cvt_pk_bf16_f32 v8, v2, v3
	v_cvt_pk_bf16_f32 v9, v4, v5
	global_store_dwordx4 v[14:15], v[10:13], off
	global_store_dwordx4 v[14:15], v[6:9], off offset:256
	s_branch .LBB0_1505

.LBB0_1785:
	s_add_i32 s55, s55, 1
	s_mov_b64 s[0:1], s[26:27]
	s_lshr_b32 s26, s55, 2
	s_mul_i32 s26, s26, s74
	s_mov_b64 s[38:39], s[36:37]
	s_mov_b32 s37, s56
	s_add_i32 s56, s26, s2
	s_cmpk_lt_i32 s56, 0x100
	s_cselect_b64 s[40:41], -1, 0
	s_cmpk_gt_i32 s56, 0xff
	s_mov_b32 s36, s57
	s_cselect_b64 s[34:35], -1, 0
	s_and_b32 s57, s55, 3
	s_and_b64 s[26:27], s[40:41], exec
	s_cselect_b32 s26, s56, s37
	s_cselect_b32 s36, s57, s36
	s_ashr_i32 s27, s26, 31
	s_lshl_b64 s[26:27], s[26:27], 19
	s_add_u32 s26, s5, s26
	s_addc_u32 s27, s6, s27
	s_and_b64 s[42:43], s[40:41], exec
	s_cselect_b32 s60, s27, s1
	s_cselect_b32 s61, s26, s0
	s_ashr_i32 s37, s36, 31
	s_lshl_b64 s[36:37], s[36:37], 19
	s_add_u32 s36, s24, s36
	s_addc_u32 s37, s25, s37
	s_and_b64 s[40:41], s[40:41], exec
	s_cselect_b32 s62, s37, s39
	s_cselect_b32 s63, s36, s38
	s_add_u32 s64, s38, 0x100
	s_addc_u32 s65, s39, 0
	s_add_u32 s38, s0, 0x40080
	s_addc_u32 s39, s1, 0
	s_mov_b32 s66, -2
	ds_read_b128 v[130:133], v168
	ds_read_b128 v[134:137], v168 offset:1024
	ds_read_b128 v[138:141], v168 offset:2048
	ds_read_b128 v[142:145], v168 offset:3072
	s_add_u32 s0, s38, 0xfffc0080
	s_addc_u32 s1, s39, -1
	s_cmp_eq_u32 s66, 12
	s_cselect_b32 s43, s60, s1
	s_cselect_b32 s42, s61, s0
	s_cselect_b32 s41, s62, s65
	s_cselect_b32 s40, s63, s64
	s_mov_b32 m0, s50
	v_lshl_add_u64 v[164:165], s[38:39], 0, v[162:163]
	ds_read_b128 v[146:149], v169
	ds_read_b128 v[172:175], v169 offset:1024
	ds_read_b128 v[176:179], v169 offset:2048
	ds_read_b128 v[180:183], v169 offset:3072
	ds_read_b128 v[184:187], v169 offset:4096
	ds_read_b128 v[188:191], v169 offset:5120
	ds_read_b128 v[192:195], v169 offset:6144
	ds_read_b128 v[196:199], v169 offset:7168
	global_load_lds_dwordx4 v[164:165], off
	v_lshl_add_u64 v[164:165], s[38:39], 0, v[160:161]
	s_mov_b32 m0, s51
	s_nop 0
	global_load_lds_dwordx4 v[164:165], off
	s_waitcnt lgkmcnt(8)
	s_waitcnt vmcnt(10)
	s_barrier
	s_waitcnt lgkmcnt(0)
	s_waitcnt lgkmcnt(0)
	v_mfma_f32_16x16x32_bf16 v[126:129], v[130:133], v[146:149], 0
	v_mfma_f32_16x16x32_bf16 v[122:125], v[138:141], v[146:149], 0
	v_mfma_f32_16x16x32_bf16 v[118:121], v[130:133], v[176:179], 0
	v_mfma_f32_16x16x32_bf16 v[110:113], v[138:141], v[176:179], 0
	v_mfma_f32_16x16x32_bf16 v[98:101], v[130:133], v[184:187], 0
	v_mfma_f32_16x16x32_bf16 v[90:93], v[138:141], v[184:187], 0
	v_mfma_f32_16x16x32_bf16 v[82:85], v[130:133], v[192:195], 0
	v_mfma_f32_16x16x32_bf16 v[74:77], v[138:141], v[192:195], 0
	v_mfma_f32_16x16x32_bf16 v[126:129], v[134:137], v[172:175], v[126:129]
	v_mfma_f32_16x16x32_bf16 v[122:125], v[142:145], v[172:175], v[122:125]
	v_mfma_f32_16x16x32_bf16 v[118:121], v[134:137], v[180:183], v[118:121]
	v_mfma_f32_16x16x32_bf16 v[110:113], v[142:145], v[180:183], v[110:113]
	v_mfma_f32_16x16x32_bf16 v[98:101], v[134:137], v[188:191], v[98:101]
	v_mfma_f32_16x16x32_bf16 v[90:93], v[142:145], v[188:191], v[90:93]
	v_mfma_f32_16x16x32_bf16 v[82:85], v[134:137], v[196:199], v[82:85]
	v_mfma_f32_16x16x32_bf16 v[74:77], v[142:145], v[196:199], v[74:77]
	s_barrier
	s_mov_b32 m0, s52
	v_lshl_add_u64 v[164:165], s[40:41], 0, v[156:157]
	ds_read_b128 v[200:203], v170
	ds_read_b128 v[204:207], v170 offset:1024
	ds_read_b128 v[208:211], v170 offset:2048
	ds_read_b128 v[212:215], v170 offset:3072
	global_load_lds_dwordx4 v[164:165], off
	v_lshl_add_u64 v[216:217], s[40:41], 0, v[152:153]
	s_mov_b32 m0, s53
	s_nop 0
	global_load_lds_dwordx4 v[216:217], off
	s_waitcnt vmcnt(10)
	s_barrier
	s_waitcnt lgkmcnt(0)
	s_waitcnt lgkmcnt(0)
	v_mfma_f32_16x16x32_bf16 v[114:117], v[200:203], v[146:149], 0
	v_mfma_f32_16x16x32_bf16 v[106:109], v[208:211], v[146:149], 0
	v_mfma_f32_16x16x32_bf16 v[102:105], v[200:203], v[176:179], 0
	v_mfma_f32_16x16x32_bf16 v[94:97], v[208:211], v[176:179], 0
	v_mfma_f32_16x16x32_bf16 v[86:89], v[200:203], v[184:187], 0
	v_mfma_f32_16x16x32_bf16 v[78:81], v[208:211], v[184:187], 0
	v_mfma_f32_16x16x32_bf16 v[70:73], v[200:203], v[192:195], 0
	v_mfma_f32_16x16x32_bf16 v[66:69], v[208:211], v[192:195], 0
	v_mfma_f32_16x16x32_bf16 v[114:117], v[204:207], v[172:175], v[114:117]
	v_mfma_f32_16x16x32_bf16 v[106:109], v[212:215], v[172:175], v[106:109]
	v_mfma_f32_16x16x32_bf16 v[102:105], v[204:207], v[180:183], v[102:105]
	v_mfma_f32_16x16x32_bf16 v[94:97], v[212:215], v[180:183], v[94:97]
	v_mfma_f32_16x16x32_bf16 v[86:89], v[204:207], v[188:191], v[86:89]
	v_mfma_f32_16x16x32_bf16 v[78:81], v[212:215], v[188:191], v[78:81]
	v_mfma_f32_16x16x32_bf16 v[70:73], v[204:207], v[196:199], v[70:73]
	v_mfma_f32_16x16x32_bf16 v[66:69], v[212:215], v[196:199], v[66:69]
	s_mov_b32 m0, s8
	v_lshl_add_u64 v[218:219], s[42:43], 0, v[158:159]
	s_barrier
	ds_read_b128 v[146:149], v169 offset:16384
	ds_read_b128 v[172:175], v169 offset:17408
	ds_read_b128 v[176:179], v169 offset:18432
	ds_read_b128 v[180:183], v169 offset:19456
	ds_read_b128 v[184:187], v169 offset:20480
	ds_read_b128 v[188:191], v169 offset:21504
	ds_read_b128 v[192:195], v169 offset:22528
	ds_read_b128 v[196:199], v169 offset:23552
	global_load_lds_dwordx4 v[218:219], off
	v_lshl_add_u64 v[220:221], s[42:43], 0, v[154:155]
	s_mov_b32 m0, s9
	s_nop 0
	global_load_lds_dwordx4 v[220:221], off
	s_waitcnt vmcnt(10)
	s_barrier
	s_waitcnt lgkmcnt(0)
	s_waitcnt lgkmcnt(0)
	v_mfma_f32_16x16x32_bf16 v[62:65], v[130:133], v[146:149], 0
	v_mfma_f32_16x16x32_bf16 v[58:61], v[138:141], v[146:149], 0
	v_mfma_f32_16x16x32_bf16 v[50:53], v[130:133], v[176:179], 0
	v_mfma_f32_16x16x32_bf16 v[42:45], v[138:141], v[176:179], 0
	v_mfma_f32_16x16x32_bf16 v[34:37], v[130:133], v[184:187], 0
	v_mfma_f32_16x16x32_bf16 v[26:29], v[138:141], v[184:187], 0
	v_mfma_f32_16x16x32_bf16 v[18:21], v[130:133], v[192:195], 0
	v_mfma_f32_16x16x32_bf16 v[10:13], v[138:141], v[192:195], 0
	v_mfma_f32_16x16x32_bf16 v[62:65], v[134:137], v[172:175], v[62:65]
	v_mfma_f32_16x16x32_bf16 v[58:61], v[142:145], v[172:175], v[58:61]
	v_mfma_f32_16x16x32_bf16 v[50:53], v[134:137], v[180:183], v[50:53]
	v_mfma_f32_16x16x32_bf16 v[42:45], v[142:145], v[180:183], v[42:45]
	v_mfma_f32_16x16x32_bf16 v[34:37], v[134:137], v[188:191], v[34:37]
	v_mfma_f32_16x16x32_bf16 v[26:29], v[142:145], v[188:191], v[26:29]
	v_mfma_f32_16x16x32_bf16 v[18:21], v[134:137], v[196:199], v[18:21]
	v_mfma_f32_16x16x32_bf16 v[10:13], v[142:145], v[196:199], v[10:13]
	s_barrier
	s_add_u32 s0, s40, 0x40000
	s_addc_u32 s1, s41, 0
	s_mov_b32 m0, s54
	v_lshl_add_u64 v[130:131], s[0:1], 0, v[156:157]
	global_load_lds_dwordx4 v[130:131], off
	v_lshl_add_u64 v[130:131], s[0:1], 0, v[152:153]
	s_add_i32 m0, s54, 0x2000
	s_nop 0
	global_load_lds_dwordx4 v[130:131], off
	s_waitcnt vmcnt(10)
	s_barrier
	v_mfma_f32_16x16x32_bf16 v[54:57], v[200:203], v[146:149], 0
	v_mfma_f32_16x16x32_bf16 v[46:49], v[208:211], v[146:149], 0
	v_mfma_f32_16x16x32_bf16 v[38:41], v[200:203], v[176:179], 0
	v_mfma_f32_16x16x32_bf16 v[30:33], v[208:211], v[176:179], 0
	v_mfma_f32_16x16x32_bf16 v[22:25], v[200:203], v[184:187], 0
	v_mfma_f32_16x16x32_bf16 v[14:17], v[208:211], v[184:187], 0
	v_mfma_f32_16x16x32_bf16 v[6:9], v[200:203], v[192:195], 0
	v_mfma_f32_16x16x32_bf16 v[2:5], v[208:211], v[192:195], 0
	v_mfma_f32_16x16x32_bf16 v[54:57], v[204:207], v[172:175], v[54:57]
	v_mfma_f32_16x16x32_bf16 v[46:49], v[212:215], v[172:175], v[46:49]
	v_mfma_f32_16x16x32_bf16 v[38:41], v[204:207], v[180:183], v[38:41]
	v_mfma_f32_16x16x32_bf16 v[30:33], v[212:215], v[180:183], v[30:33]
	v_mfma_f32_16x16x32_bf16 v[22:25], v[204:207], v[188:191], v[22:25]
	v_mfma_f32_16x16x32_bf16 v[14:17], v[212:215], v[188:191], v[14:17]
	v_mfma_f32_16x16x32_bf16 v[6:9], v[204:207], v[196:199], v[6:9]
	v_mfma_f32_16x16x32_bf16 v[2:5], v[212:215], v[196:199], v[2:5]
	s_add_i32 s67, 0, 0x18000
	v_add_u32_e32 v142, s67, v167
	s_barrier
	ds_read_b128 v[130:133], v142
	ds_read_b128 v[134:137], v142 offset:1024
	ds_read_b128 v[138:141], v142 offset:2048
	ds_read_b128 v[142:145], v142 offset:3072
	s_add_u32 s0, s42, 0x40000
	s_addc_u32 s1, s43, 0
	s_mov_b32 m0, s10
	v_lshl_add_u64 v[200:201], s[0:1], 0, v[158:159]
	ds_read_b128 v[146:149], v169 offset:32768
	ds_read_b128 v[172:175], v169 offset:33792
	ds_read_b128 v[176:179], v169 offset:34816
	ds_read_b128 v[180:183], v169 offset:35840
	ds_read_b128 v[184:187], v169 offset:36864
	ds_read_b128 v[188:191], v169 offset:37888
	ds_read_b128 v[192:195], v169 offset:38912
	ds_read_b128 v[196:199], v169 offset:39936
	global_load_lds_dwordx4 v[200:201], off
	v_lshl_add_u64 v[200:201], s[0:1], 0, v[154:155]
	s_mov_b32 m0, s11
	s_nop 0
	global_load_lds_dwordx4 v[200:201], off
	s_waitcnt lgkmcnt(8)
	s_waitcnt vmcnt(10)
	s_barrier
	s_waitcnt lgkmcnt(0)
	s_waitcnt lgkmcnt(0)
	v_mfma_f32_16x16x32_bf16 v[126:129], v[130:133], v[146:149], v[126:129]
	v_mfma_f32_16x16x32_bf16 v[122:125], v[138:141], v[146:149], v[122:125]
	v_mfma_f32_16x16x32_bf16 v[118:121], v[130:133], v[176:179], v[118:121]
	v_mfma_f32_16x16x32_bf16 v[110:113], v[138:141], v[176:179], v[110:113]
	v_mfma_f32_16x16x32_bf16 v[98:101], v[130:133], v[184:187], v[98:101]
	v_mfma_f32_16x16x32_bf16 v[90:93], v[138:141], v[184:187], v[90:93]
	v_mfma_f32_16x16x32_bf16 v[82:85], v[130:133], v[192:195], v[82:85]
	v_mfma_f32_16x16x32_bf16 v[74:77], v[138:141], v[192:195], v[74:77]
	v_mfma_f32_16x16x32_bf16 v[126:129], v[134:137], v[172:175], v[126:129]
	v_mfma_f32_16x16x32_bf16 v[122:125], v[142:145], v[172:175], v[122:125]
	v_mfma_f32_16x16x32_bf16 v[118:121], v[134:137], v[180:183], v[118:121]
	v_mfma_f32_16x16x32_bf16 v[110:113], v[142:145], v[180:183], v[110:113]
	v_mfma_f32_16x16x32_bf16 v[98:101], v[134:137], v[188:191], v[98:101]
	v_mfma_f32_16x16x32_bf16 v[90:93], v[142:145], v[188:191], v[90:93]
	v_mfma_f32_16x16x32_bf16 v[82:85], v[134:137], v[196:199], v[82:85]
	v_mfma_f32_16x16x32_bf16 v[74:77], v[142:145], v[196:199], v[74:77]
	s_barrier
	s_add_i32 s42, 0, 0x1c000
	s_add_i32 s0, s67, s7
	v_add_u32_e32 v171, s42, v167
	v_lshl_add_u64 v[164:165], v[164:165], 0, s[28:29]
	s_mov_b32 m0, s0
	ds_read_b128 v[200:203], v171
	ds_read_b128 v[204:207], v171 offset:1024
	ds_read_b128 v[208:211], v171 offset:2048
	ds_read_b128 v[212:215], v171 offset:3072
	global_load_lds_dwordx4 v[164:165], off
	v_lshl_add_u64 v[164:165], v[216:217], 0, s[28:29]
	s_add_i32 m0, s0, 0x2000
	s_nop 0
	global_load_lds_dwordx4 v[164:165], off
	s_waitcnt vmcnt(10)
	s_barrier
	s_waitcnt lgkmcnt(0)
	s_waitcnt lgkmcnt(0)
	v_mfma_f32_16x16x32_bf16 v[114:117], v[200:203], v[146:149], v[114:117]
	v_mfma_f32_16x16x32_bf16 v[106:109], v[208:211], v[146:149], v[106:109]
	v_mfma_f32_16x16x32_bf16 v[102:105], v[200:203], v[176:179], v[102:105]
	v_mfma_f32_16x16x32_bf16 v[94:97], v[208:211], v[176:179], v[94:97]
	v_mfma_f32_16x16x32_bf16 v[86:89], v[200:203], v[184:187], v[86:89]
	v_mfma_f32_16x16x32_bf16 v[78:81], v[208:211], v[184:187], v[78:81]
	v_mfma_f32_16x16x32_bf16 v[70:73], v[200:203], v[192:195], v[70:73]
	v_mfma_f32_16x16x32_bf16 v[66:69], v[208:211], v[192:195], v[66:69]
	v_mfma_f32_16x16x32_bf16 v[114:117], v[204:207], v[172:175], v[114:117]
	v_mfma_f32_16x16x32_bf16 v[106:109], v[212:215], v[172:175], v[106:109]
	v_mfma_f32_16x16x32_bf16 v[102:105], v[204:207], v[180:183], v[102:105]
	v_mfma_f32_16x16x32_bf16 v[94:97], v[212:215], v[180:183], v[94:97]
	v_mfma_f32_16x16x32_bf16 v[86:89], v[204:207], v[188:191], v[86:89]
	v_mfma_f32_16x16x32_bf16 v[78:81], v[212:215], v[188:191], v[78:81]
	v_mfma_f32_16x16x32_bf16 v[70:73], v[204:207], v[196:199], v[70:73]
	v_mfma_f32_16x16x32_bf16 v[66:69], v[212:215], v[196:199], v[66:69]
	s_mov_b32 m0, s48
	v_lshl_add_u64 v[164:165], v[218:219], 0, s[28:29]
	s_barrier
	ds_read_b128 v[146:149], v169 offset:49152
	ds_read_b128 v[172:175], v169 offset:50176
	ds_read_b128 v[176:179], v169 offset:51200
	ds_read_b128 v[180:183], v169 offset:52224
	ds_read_b128 v[184:187], v169 offset:53248
	ds_read_b128 v[188:191], v169 offset:54272
	ds_read_b128 v[192:195], v169 offset:55296
	ds_read_b128 v[196:199], v169 offset:56320
	global_load_lds_dwordx4 v[164:165], off
	v_lshl_add_u64 v[164:165], v[220:221], 0, s[28:29]
	s_mov_b32 m0, s49
	s_nop 0
	global_load_lds_dwordx4 v[164:165], off
	s_waitcnt vmcnt(10)
	s_barrier
	s_waitcnt lgkmcnt(0)
	s_waitcnt lgkmcnt(0)
	v_mfma_f32_16x16x32_bf16 v[62:65], v[130:133], v[146:149], v[62:65]
	v_mfma_f32_16x16x32_bf16 v[58:61], v[138:141], v[146:149], v[58:61]
	v_mfma_f32_16x16x32_bf16 v[50:53], v[130:133], v[176:179], v[50:53]
	v_mfma_f32_16x16x32_bf16 v[42:45], v[138:141], v[176:179], v[42:45]
	v_mfma_f32_16x16x32_bf16 v[34:37], v[130:133], v[184:187], v[34:37]
	v_mfma_f32_16x16x32_bf16 v[26:29], v[138:141], v[184:187], v[26:29]
	v_mfma_f32_16x16x32_bf16 v[18:21], v[130:133], v[192:195], v[18:21]
	v_mfma_f32_16x16x32_bf16 v[10:13], v[138:141], v[192:195], v[10:13]
	v_mfma_f32_16x16x32_bf16 v[62:65], v[134:137], v[172:175], v[62:65]
	v_mfma_f32_16x16x32_bf16 v[58:61], v[142:145], v[172:175], v[58:61]
	v_mfma_f32_16x16x32_bf16 v[50:53], v[134:137], v[180:183], v[50:53]
	v_mfma_f32_16x16x32_bf16 v[42:45], v[142:145], v[180:183], v[42:45]
	v_mfma_f32_16x16x32_bf16 v[34:37], v[134:137], v[188:191], v[34:37]
	v_mfma_f32_16x16x32_bf16 v[26:29], v[142:145], v[188:191], v[26:29]
	v_mfma_f32_16x16x32_bf16 v[18:21], v[134:137], v[196:199], v[18:21]
	v_mfma_f32_16x16x32_bf16 v[10:13], v[142:145], v[196:199], v[10:13]
	s_barrier
	s_add_u32 s0, s40, 0x40080
	s_addc_u32 s1, s41, 0
	s_add_i32 s40, s42, s7
	v_lshl_add_u64 v[130:131], s[0:1], 0, v[156:157]
	s_mov_b32 m0, s40
	s_nop 0
	global_load_lds_dwordx4 v[130:131], off
	v_lshl_add_u64 v[130:131], s[0:1], 0, v[152:153]
	s_add_i32 m0, s40, 0x2000
	s_nop 0
	global_load_lds_dwordx4 v[130:131], off
	s_waitcnt vmcnt(10)
	s_barrier
	v_mfma_f32_16x16x32_bf16 v[54:57], v[200:203], v[146:149], v[54:57]
	v_mfma_f32_16x16x32_bf16 v[46:49], v[208:211], v[146:149], v[46:49]
	v_mfma_f32_16x16x32_bf16 v[38:41], v[200:203], v[176:179], v[38:41]
	v_mfma_f32_16x16x32_bf16 v[30:33], v[208:211], v[176:179], v[30:33]
	v_mfma_f32_16x16x32_bf16 v[22:25], v[200:203], v[184:187], v[22:25]
	v_mfma_f32_16x16x32_bf16 v[14:17], v[208:211], v[184:187], v[14:17]
	v_mfma_f32_16x16x32_bf16 v[6:9], v[200:203], v[192:195], v[6:9]
	v_mfma_f32_16x16x32_bf16 v[2:5], v[208:211], v[192:195], v[2:5]
	v_mfma_f32_16x16x32_bf16 v[54:57], v[204:207], v[172:175], v[54:57]
	v_mfma_f32_16x16x32_bf16 v[46:49], v[212:215], v[172:175], v[46:49]
	v_mfma_f32_16x16x32_bf16 v[38:41], v[204:207], v[180:183], v[38:41]
	v_mfma_f32_16x16x32_bf16 v[30:33], v[212:215], v[180:183], v[30:33]
	v_mfma_f32_16x16x32_bf16 v[22:25], v[204:207], v[188:191], v[22:25]
	v_mfma_f32_16x16x32_bf16 v[14:17], v[212:215], v[188:191], v[14:17]
	v_mfma_f32_16x16x32_bf16 v[6:9], v[204:207], v[196:199], v[6:9]
	v_mfma_f32_16x16x32_bf16 v[2:5], v[212:215], v[196:199], v[2:5]
	s_add_i32 s66, s66, 2
	s_add_u32 s64, s64, 0x100
	s_addc_u32 s65, s65, 0
	s_add_u32 s38, s38, 0x100
	s_addc_u32 s39, s39, 0
	s_cmp_gt_u32 s66, 13
	s_barrier
	s_cbranch_scc1 .Lpeel_exit_10

.Lpeel_exit_10:
	s_lshl_b32 s0, s58, 8
	v_mov_b32_e32 v130, v151
	v_mov_b32_e32 v131, v166
	s_or_b32 s0, s0, s45
	s_mov_b32 s58, s57
	v_lshl_add_u32 v164, v131, 3, s0
	s_lshl_b32 s0, s59, 8
	s_add_i32 s0, s0, s44
	v_add_u32_e32 v171, s0, v130
	v_mov_b32_e32 v130, v171
	v_ashrrev_i32_e32 v165, 31, v164
	v_ashrrev_i32_e32 v131, 31, v130
	v_lshlrev_b64 v[130:131], 10, v[130:131]
	v_lshl_add_u64 v[130:131], v[130:131], 0, v[164:165]
	v_lshlrev_b64 v[184:185], 1, v[130:131]
	v_lshl_add_u64 v[130:131], s[14:15], 0, v[184:185]
	global_load_dwordx4 v[172:175], v[130:131], off
	global_load_dwordx4 v[176:179], v[130:131], off offset:256
	v_add_co_u32_e32 v132, vcc, s47, v130
	s_mov_b32 s59, s56
	s_nop 0
	v_addc_co_u32_e32 v133, vcc, 0, v131, vcc
	global_load_dwordx4 v[180:183], v[132:133], off
	global_load_dwordx4 v[146:149], v[132:133], off offset:256
	v_add_co_u32_e32 v132, vcc, s31, v130
	s_waitcnt vmcnt(0) lgkmcnt(0)
	v_lshlrev_b32_e32 v186, 16, v172
	v_addc_co_u32_e32 v133, vcc, 0, v131, vcc
	global_load_dwordx4 v[142:145], v[132:133], off
	global_load_dwordx4 v[138:141], v[132:133], off offset:256
	v_add_co_u32_e32 v130, vcc, s46, v130
	v_and_b32_e32 v187, 0xffff0000, v172
	s_nop 0
	v_addc_co_u32_e32 v131, vcc, 0, v131, vcc
	global_load_dwordx4 v[134:137], v[130:131], off
	s_nop 0
	global_load_dwordx4 v[130:133], v[130:131], off offset:256
	v_lshlrev_b32_e32 v172, 16, v173
	v_and_b32_e32 v173, 0xffff0000, v173
	v_lshlrev_b32_e32 v188, 16, v174
	v_and_b32_e32 v189, 0xffff0000, v174
	v_lshlrev_b32_e32 v174, 16, v175
	v_and_b32_e32 v175, 0xffff0000, v175
	v_pk_fma_f32 v[128:129], v[172:173], s[30:31], v[128:129] op_sel_hi:[1,0,1]
	v_pk_fma_f32 v[126:127], v[186:187], s[30:31], v[126:127] op_sel_hi:[1,0,1]
	v_pk_fma_f32 v[172:173], v[174:175], s[30:31], v[124:125] op_sel_hi:[1,0,1]
	v_pk_fma_f32 v[122:123], v[188:189], s[30:31], v[122:123] op_sel_hi:[1,0,1]
	v_cvt_pk_bf16_f32 v124, v126, v127
	v_cvt_pk_bf16_f32 v125, v128, v129
	v_cvt_pk_bf16_f32 v126, v122, v123
	v_cvt_pk_bf16_f32 v127, v172, v173
	v_lshl_add_u64 v[122:123], s[20:21], 0, v[184:185]
	global_store_dwordx4 v[122:123], v[124:127], off
	v_lshlrev_b32_e32 v128, 16, v178
	v_and_b32_e32 v129, 0xffff0000, v178
	v_lshlrev_b32_e32 v124, 16, v176
	v_and_b32_e32 v125, 0xffff0000, v176
	v_lshlrev_b32_e32 v126, 16, v177
	v_and_b32_e32 v127, 0xffff0000, v177
	v_lshlrev_b32_e32 v172, 16, v179
	v_and_b32_e32 v173, 0xffff0000, v179
	v_pk_fma_f32 v[116:117], v[126:127], s[30:31], v[116:117] op_sel_hi:[1,0,1]
	v_pk_fma_f32 v[114:115], v[124:125], s[30:31], v[114:115] op_sel_hi:[1,0,1]
	v_pk_fma_f32 v[124:125], v[172:173], s[30:31], v[108:109] op_sel_hi:[1,0,1]
	v_pk_fma_f32 v[108:109], v[128:129], s[30:31], v[106:107] op_sel_hi:[1,0,1]
	v_cvt_pk_bf16_f32 v106, v114, v115
	v_cvt_pk_bf16_f32 v107, v116, v117
	v_cvt_pk_bf16_f32 v108, v108, v109
	v_cvt_pk_bf16_f32 v109, v124, v125
	global_store_dwordx4 v[122:123], v[106:109], off offset:256
	v_lshlrev_b32_e32 v114, 16, v182
	v_and_b32_e32 v115, 0xffff0000, v182
	v_lshlrev_b32_e32 v106, 16, v180
	v_and_b32_e32 v107, 0xffff0000, v180
	v_lshlrev_b32_e32 v108, 16, v181
	v_and_b32_e32 v109, 0xffff0000, v181
	v_lshlrev_b32_e32 v116, 16, v183
	v_and_b32_e32 v117, 0xffff0000, v183
	v_pk_fma_f32 v[108:109], v[108:109], s[30:31], v[120:121] op_sel_hi:[1,0,1]
	v_pk_fma_f32 v[106:107], v[106:107], s[30:31], v[118:119] op_sel_hi:[1,0,1]
	v_pk_fma_f32 v[110:111], v[114:115], s[30:31], v[110:111] op_sel_hi:[1,0,1]
	v_pk_fma_f32 v[112:113], v[116:117], s[30:31], v[112:113] op_sel_hi:[1,0,1]
	v_cvt_pk_bf16_f32 v106, v106, v107
	v_cvt_pk_bf16_f32 v107, v108, v109
	v_cvt_pk_bf16_f32 v108, v110, v111
	v_add_co_u32_e32 v110, vcc, s47, v122
	v_cvt_pk_bf16_f32 v109, v112, v113
	s_nop 0
	v_addc_co_u32_e32 v111, vcc, 0, v123, vcc
	global_store_dwordx4 v[110:111], v[106:109], off
	v_lshlrev_b32_e32 v112, 16, v148
	v_and_b32_e32 v113, 0xffff0000, v148
	v_lshlrev_b32_e32 v106, 16, v146
	v_and_b32_e32 v107, 0xffff0000, v146
	v_lshlrev_b32_e32 v108, 16, v147
	v_and_b32_e32 v109, 0xffff0000, v147
	v_lshlrev_b32_e32 v114, 16, v149
	v_and_b32_e32 v115, 0xffff0000, v149
	v_pk_fma_f32 v[104:105], v[108:109], s[30:31], v[104:105] op_sel_hi:[1,0,1]
	v_pk_fma_f32 v[102:103], v[106:107], s[30:31], v[102:103] op_sel_hi:[1,0,1]
	v_pk_fma_f32 v[106:107], v[114:115], s[30:31], v[96:97] op_sel_hi:[1,0,1]
	v_pk_fma_f32 v[96:97], v[112:113], s[30:31], v[94:95] op_sel_hi:[1,0,1]
	v_cvt_pk_bf16_f32 v94, v102, v103
	v_cvt_pk_bf16_f32 v95, v104, v105
	v_cvt_pk_bf16_f32 v96, v96, v97
	v_cvt_pk_bf16_f32 v97, v106, v107
	global_store_dwordx4 v[110:111], v[94:97], off offset:256
	s_waitcnt vmcnt(0) lgkmcnt(0)
	v_lshlrev_b32_e32 v102, 16, v144
	v_lshlrev_b32_e32 v94, 16, v142
	v_and_b32_e32 v95, 0xffff0000, v142
	v_lshlrev_b32_e32 v96, 16, v143
	v_and_b32_e32 v97, 0xffff0000, v143
	v_and_b32_e32 v103, 0xffff0000, v144
	v_lshlrev_b32_e32 v104, 16, v145
	v_and_b32_e32 v105, 0xffff0000, v145
	v_pk_fma_f32 v[94:95], v[94:95], s[30:31], v[98:99] op_sel_hi:[1,0,1]
	v_pk_fma_f32 v[96:97], v[96:97], s[30:31], v[100:101] op_sel_hi:[1,0,1]
	v_pk_fma_f32 v[98:99], v[104:105], s[30:31], v[92:93] op_sel_hi:[1,0,1]
	v_pk_fma_f32 v[92:93], v[102:103], s[30:31], v[90:91] op_sel_hi:[1,0,1]
	v_cvt_pk_bf16_f32 v90, v94, v95
	v_add_co_u32_e32 v94, vcc, s31, v122
	v_cvt_pk_bf16_f32 v91, v96, v97
	v_cvt_pk_bf16_f32 v92, v92, v93
	v_cvt_pk_bf16_f32 v93, v98, v99
	v_addc_co_u32_e32 v95, vcc, 0, v123, vcc
	global_store_dwordx4 v[94:95], v[90:93], off
	v_lshlrev_b32_e32 v96, 16, v140
	v_and_b32_e32 v97, 0xffff0000, v140
	v_lshlrev_b32_e32 v90, 16, v138
	v_and_b32_e32 v91, 0xffff0000, v138
	v_lshlrev_b32_e32 v92, 16, v139
	v_and_b32_e32 v93, 0xffff0000, v139
	v_lshlrev_b32_e32 v98, 16, v141
	v_and_b32_e32 v99, 0xffff0000, v141
	v_pk_fma_f32 v[88:89], v[92:93], s[30:31], v[88:89] op_sel_hi:[1,0,1]
	v_pk_fma_f32 v[86:87], v[90:91], s[30:31], v[86:87] op_sel_hi:[1,0,1]
	v_pk_fma_f32 v[90:91], v[98:99], s[30:31], v[80:81] op_sel_hi:[1,0,1]
	v_pk_fma_f32 v[80:81], v[96:97], s[30:31], v[78:79] op_sel_hi:[1,0,1]
	v_cvt_pk_bf16_f32 v78, v86, v87
	v_cvt_pk_bf16_f32 v79, v88, v89
	v_cvt_pk_bf16_f32 v80, v80, v81
	v_cvt_pk_bf16_f32 v81, v90, v91
	global_store_dwordx4 v[94:95], v[78:81], off offset:256
	v_lshlrev_b32_e32 v86, 16, v136
	v_and_b32_e32 v87, 0xffff0000, v136
	v_lshlrev_b32_e32 v78, 16, v134
	v_and_b32_e32 v79, 0xffff0000, v134
	v_lshlrev_b32_e32 v80, 16, v135
	v_and_b32_e32 v81, 0xffff0000, v135
	v_lshlrev_b32_e32 v88, 16, v137
	v_and_b32_e32 v89, 0xffff0000, v137
	v_pk_fma_f32 v[78:79], v[78:79], s[30:31], v[82:83] op_sel_hi:[1,0,1]
	v_pk_fma_f32 v[80:81], v[80:81], s[30:31], v[84:85] op_sel_hi:[1,0,1]
	v_pk_fma_f32 v[82:83], v[88:89], s[30:31], v[76:77] op_sel_hi:[1,0,1]
	v_pk_fma_f32 v[76:77], v[86:87], s[30:31], v[74:75] op_sel_hi:[1,0,1]
	v_cvt_pk_bf16_f32 v74, v78, v79
	v_add_co_u32_e32 v78, vcc, s46, v122
	v_cvt_pk_bf16_f32 v75, v80, v81
	v_cvt_pk_bf16_f32 v76, v76, v77
	v_cvt_pk_bf16_f32 v77, v82, v83
	v_addc_co_u32_e32 v79, vcc, 0, v123, vcc
	global_store_dwordx4 v[78:79], v[74:77], off
	v_lshlrev_b32_e32 v80, 16, v132
	v_and_b32_e32 v81, 0xffff0000, v132
	v_lshlrev_b32_e32 v74, 16, v130
	v_and_b32_e32 v75, 0xffff0000, v130
	v_lshlrev_b32_e32 v76, 16, v131
	v_and_b32_e32 v77, 0xffff0000, v131
	v_lshlrev_b32_e32 v82, 16, v133
	v_and_b32_e32 v83, 0xffff0000, v133
	v_pk_fma_f32 v[72:73], v[76:77], s[30:31], v[72:73] op_sel_hi:[1,0,1]
	v_pk_fma_f32 v[70:71], v[74:75], s[30:31], v[70:71] op_sel_hi:[1,0,1]
	v_pk_fma_f32 v[74:75], v[82:83], s[30:31], v[68:69] op_sel_hi:[1,0,1]
	v_pk_fma_f32 v[68:69], v[80:81], s[30:31], v[66:67] op_sel_hi:[1,0,1]
	v_cvt_pk_bf16_f32 v66, v70, v71
	v_cvt_pk_bf16_f32 v67, v72, v73
	v_cvt_pk_bf16_f32 v68, v68, v69
	v_cvt_pk_bf16_f32 v69, v74, v75
	global_store_dwordx4 v[78:79], v[66:69], off offset:256
	s_nop 1
	v_add_u32_e32 v66, 0x80, v171
	s_nop 0
	v_ashrrev_i32_e32 v67, 31, v66
	v_lshlrev_b64 v[66:67], 10, v[66:67]
	v_lshl_add_u64 v[66:67], v[66:67], 0, v[164:165]
	v_lshlrev_b64 v[98:99], 1, v[66:67]
	v_lshl_add_u64 v[90:91], s[14:15], 0, v[98:99]
	global_load_dwordx4 v[66:69], v[90:91], off
	global_load_dwordx4 v[70:73], v[90:91], off offset:256
	v_add_co_u32_e32 v78, vcc, s47, v90
	s_waitcnt vmcnt(0) lgkmcnt(0)
	v_lshlrev_b32_e32 v100, 16, v66
	v_addc_co_u32_e32 v79, vcc, 0, v91, vcc
	global_load_dwordx4 v[74:77], v[78:79], off
	s_nop 0
	global_load_dwordx4 v[78:81], v[78:79], off offset:256
	v_add_co_u32_e32 v86, vcc, s31, v90
	v_and_b32_e32 v101, 0xffff0000, v66
	s_nop 0
	v_addc_co_u32_e32 v87, vcc, 0, v91, vcc
	global_load_dwordx4 v[82:85], v[86:87], off
	s_nop 0
	global_load_dwordx4 v[86:89], v[86:87], off offset:256
	v_add_co_u32_e32 v94, vcc, s46, v90
	v_lshlrev_b32_e32 v66, 16, v67
	s_nop 0
	v_addc_co_u32_e32 v95, vcc, 0, v91, vcc
	global_load_dwordx4 v[90:93], v[94:95], off
	s_nop 0
	global_load_dwordx4 v[94:97], v[94:95], off offset:256
	v_and_b32_e32 v67, 0xffff0000, v67
	v_lshlrev_b32_e32 v102, 16, v68
	v_and_b32_e32 v103, 0xffff0000, v68
	v_lshlrev_b32_e32 v68, 16, v69
	v_and_b32_e32 v69, 0xffff0000, v69
	v_pk_fma_f32 v[64:65], v[66:67], s[30:31], v[64:65] op_sel_hi:[1,0,1]
	v_pk_fma_f32 v[62:63], v[100:101], s[30:31], v[62:63] op_sel_hi:[1,0,1]
	v_pk_fma_f32 v[66:67], v[68:69], s[30:31], v[60:61] op_sel_hi:[1,0,1]
	v_pk_fma_f32 v[60:61], v[102:103], s[30:31], v[58:59] op_sel_hi:[1,0,1]
	v_cvt_pk_bf16_f32 v58, v62, v63
	v_cvt_pk_bf16_f32 v59, v64, v65
	v_cvt_pk_bf16_f32 v60, v60, v61
	v_cvt_pk_bf16_f32 v61, v66, v67
	v_lshl_add_u64 v[62:63], s[20:21], 0, v[98:99]
	global_store_dwordx4 v[62:63], v[58:61], off
	v_lshlrev_b32_e32 v64, 16, v72
	v_and_b32_e32 v65, 0xffff0000, v72
	v_lshlrev_b32_e32 v58, 16, v70
	v_and_b32_e32 v59, 0xffff0000, v70
	v_lshlrev_b32_e32 v60, 16, v71
	v_and_b32_e32 v61, 0xffff0000, v71
	v_lshlrev_b32_e32 v66, 16, v73
	v_and_b32_e32 v67, 0xffff0000, v73
	v_pk_fma_f32 v[56:57], v[60:61], s[30:31], v[56:57] op_sel_hi:[1,0,1]
	v_pk_fma_f32 v[54:55], v[58:59], s[30:31], v[54:55] op_sel_hi:[1,0,1]
	v_pk_fma_f32 v[58:59], v[66:67], s[30:31], v[48:49] op_sel_hi:[1,0,1]
	v_pk_fma_f32 v[48:49], v[64:65], s[30:31], v[46:47] op_sel_hi:[1,0,1]
	v_cvt_pk_bf16_f32 v46, v54, v55
	v_cvt_pk_bf16_f32 v47, v56, v57
	v_cvt_pk_bf16_f32 v48, v48, v49
	v_cvt_pk_bf16_f32 v49, v58, v59
	global_store_dwordx4 v[62:63], v[46:49], off offset:256
	s_waitcnt vmcnt(0) lgkmcnt(0)
	v_lshlrev_b32_e32 v54, 16, v76
	v_lshlrev_b32_e32 v46, 16, v74
	v_and_b32_e32 v47, 0xffff0000, v74
	v_lshlrev_b32_e32 v48, 16, v75
	v_and_b32_e32 v49, 0xffff0000, v75
	v_and_b32_e32 v55, 0xffff0000, v76
	v_lshlrev_b32_e32 v56, 16, v77
	v_and_b32_e32 v57, 0xffff0000, v77
	v_pk_fma_f32 v[46:47], v[46:47], s[30:31], v[50:51] op_sel_hi:[1,0,1]
	v_pk_fma_f32 v[48:49], v[48:49], s[30:31], v[52:53] op_sel_hi:[1,0,1]
	v_pk_fma_f32 v[50:51], v[56:57], s[30:31], v[44:45] op_sel_hi:[1,0,1]
	v_pk_fma_f32 v[44:45], v[54:55], s[30:31], v[42:43] op_sel_hi:[1,0,1]
	v_cvt_pk_bf16_f32 v42, v46, v47
	v_add_co_u32_e32 v46, vcc, s47, v62
	v_cvt_pk_bf16_f32 v43, v48, v49
	v_cvt_pk_bf16_f32 v44, v44, v45
	v_cvt_pk_bf16_f32 v45, v50, v51
	v_addc_co_u32_e32 v47, vcc, 0, v63, vcc
	global_store_dwordx4 v[46:47], v[42:45], off
	v_lshlrev_b32_e32 v48, 16, v80
	v_and_b32_e32 v49, 0xffff0000, v80
	v_lshlrev_b32_e32 v42, 16, v78
	v_and_b32_e32 v43, 0xffff0000, v78
	v_lshlrev_b32_e32 v44, 16, v79
	v_and_b32_e32 v45, 0xffff0000, v79
	v_lshlrev_b32_e32 v50, 16, v81
	v_and_b32_e32 v51, 0xffff0000, v81
	v_pk_fma_f32 v[40:41], v[44:45], s[30:31], v[40:41] op_sel_hi:[1,0,1]
	v_pk_fma_f32 v[38:39], v[42:43], s[30:31], v[38:39] op_sel_hi:[1,0,1]
	v_pk_fma_f32 v[42:43], v[50:51], s[30:31], v[32:33] op_sel_hi:[1,0,1]
	v_pk_fma_f32 v[32:33], v[48:49], s[30:31], v[30:31] op_sel_hi:[1,0,1]
	v_cvt_pk_bf16_f32 v30, v38, v39
	v_cvt_pk_bf16_f32 v31, v40, v41
	v_cvt_pk_bf16_f32 v32, v32, v33
	v_cvt_pk_bf16_f32 v33, v42, v43
	global_store_dwordx4 v[46:47], v[30:33], off offset:256
	v_lshlrev_b32_e32 v38, 16, v84
	v_and_b32_e32 v39, 0xffff0000, v84
	v_lshlrev_b32_e32 v30, 16, v82
	v_and_b32_e32 v31, 0xffff0000, v82
	v_lshlrev_b32_e32 v32, 16, v83
	v_and_b32_e32 v33, 0xffff0000, v83
	v_lshlrev_b32_e32 v40, 16, v85
	v_and_b32_e32 v41, 0xffff0000, v85
	v_pk_fma_f32 v[30:31], v[30:31], s[30:31], v[34:35] op_sel_hi:[1,0,1]
	v_pk_fma_f32 v[32:33], v[32:33], s[30:31], v[36:37] op_sel_hi:[1,0,1]
	v_pk_fma_f32 v[34:35], v[40:41], s[30:31], v[28:29] op_sel_hi:[1,0,1]
	v_pk_fma_f32 v[28:29], v[38:39], s[30:31], v[26:27] op_sel_hi:[1,0,1]
	v_cvt_pk_bf16_f32 v26, v30, v31
	v_add_co_u32_e32 v30, vcc, s31, v62
	v_cvt_pk_bf16_f32 v27, v32, v33
	v_cvt_pk_bf16_f32 v28, v28, v29
	v_cvt_pk_bf16_f32 v29, v34, v35
	v_addc_co_u32_e32 v31, vcc, 0, v63, vcc
	global_store_dwordx4 v[30:31], v[26:29], off
	v_lshlrev_b32_e32 v32, 16, v88
	v_and_b32_e32 v33, 0xffff0000, v88
	v_lshlrev_b32_e32 v26, 16, v86
	v_and_b32_e32 v27, 0xffff0000, v86
	v_lshlrev_b32_e32 v28, 16, v87
	v_and_b32_e32 v29, 0xffff0000, v87
	v_lshlrev_b32_e32 v34, 16, v89
	v_and_b32_e32 v35, 0xffff0000, v89
	v_pk_fma_f32 v[24:25], v[28:29], s[30:31], v[24:25] op_sel_hi:[1,0,1]
	v_pk_fma_f32 v[22:23], v[26:27], s[30:31], v[22:23] op_sel_hi:[1,0,1]
	v_pk_fma_f32 v[26:27], v[34:35], s[30:31], v[16:17] op_sel_hi:[1,0,1]
	v_pk_fma_f32 v[16:17], v[32:33], s[30:31], v[14:15] op_sel_hi:[1,0,1]
	v_cvt_pk_bf16_f32 v14, v22, v23
	v_cvt_pk_bf16_f32 v15, v24, v25
	v_cvt_pk_bf16_f32 v16, v16, v17
	v_cvt_pk_bf16_f32 v17, v26, v27
	global_store_dwordx4 v[30:31], v[14:17], off offset:256
	v_lshlrev_b32_e32 v22, 16, v92
	v_and_b32_e32 v23, 0xffff0000, v92
	v_lshlrev_b32_e32 v14, 16, v90
	v_and_b32_e32 v15, 0xffff0000, v90
	v_lshlrev_b32_e32 v16, 16, v91
	v_and_b32_e32 v17, 0xffff0000, v91
	v_lshlrev_b32_e32 v24, 16, v93
	v_and_b32_e32 v25, 0xffff0000, v93
	v_pk_fma_f32 v[14:15], v[14:15], s[30:31], v[18:19] op_sel_hi:[1,0,1]
	v_pk_fma_f32 v[16:17], v[16:17], s[30:31], v[20:21] op_sel_hi:[1,0,1]
	v_pk_fma_f32 v[18:19], v[24:25], s[30:31], v[12:13] op_sel_hi:[1,0,1]
	v_pk_fma_f32 v[12:13], v[22:23], s[30:31], v[10:11] op_sel_hi:[1,0,1]
	v_cvt_pk_bf16_f32 v10, v14, v15
	v_add_co_u32_e32 v14, vcc, s46, v62
	v_cvt_pk_bf16_f32 v11, v16, v17
	v_cvt_pk_bf16_f32 v12, v12, v13
	v_cvt_pk_bf16_f32 v13, v18, v19
	v_addc_co_u32_e32 v15, vcc, 0, v63, vcc
	global_store_dwordx4 v[14:15], v[10:13], off
	v_lshlrev_b32_e32 v16, 16, v96
	v_and_b32_e32 v17, 0xffff0000, v96
	v_lshlrev_b32_e32 v10, 16, v94
	v_and_b32_e32 v11, 0xffff0000, v94
	v_lshlrev_b32_e32 v12, 16, v95
	v_and_b32_e32 v13, 0xffff0000, v95
	v_lshlrev_b32_e32 v18, 16, v97
	v_and_b32_e32 v19, 0xffff0000, v97
	v_pk_fma_f32 v[8:9], v[12:13], s[30:31], v[8:9] op_sel_hi:[1,0,1]
	v_pk_fma_f32 v[6:7], v[10:11], s[30:31], v[6:7] op_sel_hi:[1,0,1]
	v_pk_fma_f32 v[10:11], v[18:19], s[30:31], v[4:5] op_sel_hi:[1,0,1]
	v_pk_fma_f32 v[4:5], v[16:17], s[30:31], v[2:3] op_sel_hi:[1,0,1]
	v_cvt_pk_bf16_f32 v2, v6, v7
	v_cvt_pk_bf16_f32 v3, v8, v9
	v_cvt_pk_bf16_f32 v4, v4, v5
	v_cvt_pk_bf16_f32 v5, v10, v11
	s_and_b64 vcc, exec, s[34:35]
	global_store_dwordx4 v[14:15], v[2:5], off offset:256
	s_cbranch_vccz .LBB0_1785
	s_waitcnt vmcnt(0)
	s_cmpk_gt_u32 s4, 0xff
	s_cbranch_scc1 .LBB0_1790
	s_barrier

.LBB0_2040:
	s_ashr_i32 s0, s54, 5
	s_ashr_i32 s1, s0, 31
	s_lshl_b64 s[0:1], s[0:1], 21
	s_add_u32 s16, s4, s0
	s_addc_u32 s17, s5, s1
	s_ashr_i32 s29, s28, 31
	s_lshl_b64 s[0:1], s[28:29], 18
	s_add_u32 s16, s16, s0
	s_addc_u32 s17, s17, s1
	s_and_b64 s[0:1], s[14:15], exec
	s_cselect_b32 s29, s17, s37
	s_cselect_b32 s31, s16, s36
	v_mov_b32_e32 v173, v163
	v_mov_b32_e32 v175, v163
	s_add_u32 s35, s36, 0x100
	s_addc_u32 s55, s37, 0
	v_lshl_add_u64 v[176:177], s[22:23], 0, v[174:175]
	v_lshl_add_u64 v[178:179], s[22:23], 0, v[172:173]
	s_mov_b32 s56, -2
	s_mov_b64 s[38:39], 0
	s_add_u32 s14, s38, 0x100
	s_addc_u32 s15, s39, 0
	s_add_u32 s36, s35, s38
	s_addc_u32 s37, s55, s39
	s_cmpk_eq_i32 s38, 0x300
	s_cselect_b64 vcc, -1, 0
	s_and_b64 s[0:1], vcc, exec
	s_cselect_b32 s1, 0, s14
	s_cselect_b32 s0, 0, s15
	s_cselect_b32 s36, s31, s36
	s_cselect_b32 s37, s29, s37
	s_add_u32 s40, s18, s1
	s_addc_u32 s41, s19, s0
	s_add_i32 s1, 0, 0x10000
	v_add_u32_e32 v14, s1, v197
	ds_read_b128 v[2:5], v14
	ds_read_b128 v[6:9], v14 offset:1024
	ds_read_b128 v[10:13], v14 offset:2048
	ds_read_b128 v[14:17], v14 offset:3072
	v_cndmask_b32_e32 v162, v168, v171, vcc
	v_cndmask_b32_e32 v184, v170, v198, vcc
	v_cndmask_b32_e32 v175, v172, v199, vcc
	v_cndmask_b32_e32 v173, v174, v200, vcc
	v_lshl_add_u64 v[18:19], v[178:179], 0, s[38:39]
	s_add_i32 m0, s45, 0xc000
	ds_read_b128 v[202:205], v169
	ds_read_b128 v[206:209], v169 offset:1024
	ds_read_b128 v[210:213], v169 offset:2048
	ds_read_b128 v[214:217], v169 offset:3072
	ds_read_b128 v[218:221], v169 offset:4096
	ds_read_b128 v[222:225], v169 offset:5120
	ds_read_b128 v[226:229], v169 offset:6144
	ds_read_b128 v[230:233], v169 offset:7168
	global_load_lds_dwordx4 v[18:19], off
	v_lshl_add_u64 v[18:19], v[176:177], 0, s[38:39]
	s_add_i32 m0, s45, 0xe000
	s_nop 0
	global_load_lds_dwordx4 v[18:19], off
	s_waitcnt lgkmcnt(8)
	s_waitcnt vmcnt(10)
	s_barrier
	s_waitcnt lgkmcnt(0)
	s_waitcnt lgkmcnt(0)
	v_mfma_scale_f32_16x16x128_f8f6f4 v[158:161], v[2:9], v[202:209], 0, v188, v188 op_sel_hi:[0,0,0]
	v_mfma_scale_f32_16x16x128_f8f6f4 v[150:153], v[10:17], v[202:209], 0, v188, v188 op_sel_hi:[0,0,0]
	v_mfma_scale_f32_16x16x128_f8f6f4 v[142:145], v[2:9], v[210:217], 0, v188, v188 op_sel_hi:[0,0,0]
	v_mfma_scale_f32_16x16x128_f8f6f4 v[134:137], v[10:17], v[210:217], 0, v188, v188 op_sel_hi:[0,0,0]
	v_mfma_scale_f32_16x16x128_f8f6f4 v[126:129], v[2:9], v[218:225], 0, v188, v188 op_sel_hi:[0,0,0]
	v_mfma_scale_f32_16x16x128_f8f6f4 v[118:121], v[10:17], v[218:225], 0, v188, v188 op_sel_hi:[0,0,0]
	v_mfma_scale_f32_16x16x128_f8f6f4 v[110:113], v[2:9], v[226:233], 0, v188, v188 op_sel_hi:[0,0,0]
	v_mfma_scale_f32_16x16x128_f8f6f4 v[102:105], v[10:17], v[226:233], 0, v188, v188 op_sel_hi:[0,0,0]
	s_barrier
	s_add_i32 s0, 0, 0x14000
	s_add_i32 s1, s1, s43
	v_add_u32_e32 v30, s0, v197
	v_lshl_add_u64 v[180:181], s[36:37], 0, v[164:165]
	s_mov_b32 m0, s1
	ds_read_b128 v[18:21], v30
	ds_read_b128 v[22:25], v30 offset:1024
	ds_read_b128 v[26:29], v30 offset:2048
	ds_read_b128 v[30:33], v30 offset:3072
	global_load_lds_dwordx4 v[180:181], off
	v_lshl_add_u64 v[182:183], s[36:37], 0, v[166:167]
	s_add_i32 m0, s1, 0x2000
	s_nop 0
	global_load_lds_dwordx4 v[182:183], off
	s_waitcnt vmcnt(10)
	s_barrier
	s_waitcnt lgkmcnt(0)
	s_waitcnt lgkmcnt(0)
	v_mfma_scale_f32_16x16x128_f8f6f4 v[154:157], v[18:25], v[202:209], 0, v188, v188 op_sel_hi:[0,0,0]
	v_mfma_scale_f32_16x16x128_f8f6f4 v[146:149], v[26:33], v[202:209], 0, v188, v188 op_sel_hi:[0,0,0]
	v_mfma_scale_f32_16x16x128_f8f6f4 v[138:141], v[18:25], v[210:217], 0, v188, v188 op_sel_hi:[0,0,0]
	v_mfma_scale_f32_16x16x128_f8f6f4 v[130:133], v[26:33], v[210:217], 0, v188, v188 op_sel_hi:[0,0,0]
	v_mfma_scale_f32_16x16x128_f8f6f4 v[122:125], v[18:25], v[218:225], 0, v188, v188 op_sel_hi:[0,0,0]
	v_mfma_scale_f32_16x16x128_f8f6f4 v[114:117], v[26:33], v[218:225], 0, v188, v188 op_sel_hi:[0,0,0]
	v_mfma_scale_f32_16x16x128_f8f6f4 v[106:109], v[18:25], v[226:233], 0, v188, v188 op_sel_hi:[0,0,0]
	v_mfma_scale_f32_16x16x128_f8f6f4 v[98:101], v[26:33], v[226:233], 0, v188, v188 op_sel_hi:[0,0,0]
	s_mov_b32 m0, s45
	s_barrier
	ds_read_b128 v[202:205], v169 offset:16384
	ds_read_b128 v[206:209], v169 offset:17408
	ds_read_b128 v[210:213], v169 offset:18432
	ds_read_b128 v[214:217], v169 offset:19456
	ds_read_b128 v[218:221], v169 offset:20480
	ds_read_b128 v[222:225], v169 offset:21504
	ds_read_b128 v[226:229], v169 offset:22528
	ds_read_b128 v[230:233], v169 offset:23552
	global_load_lds_dwordx4 v162, s[40:41]
	s_mov_b32 m0, s46
	v_mov_b32_e32 v185, v163
	global_load_lds_dwordx4 v184, s[40:41]
	s_waitcnt vmcnt(10)
	s_barrier
	s_waitcnt lgkmcnt(0)
	v_lshl_add_u64 v[186:187], s[40:41], 0, v[162:163]
	v_lshl_add_u64 v[184:185], s[40:41], 0, v[184:185]
	s_waitcnt lgkmcnt(0)
	v_mfma_scale_f32_16x16x128_f8f6f4 v[94:97], v[2:9], v[202:209], 0, v188, v188 op_sel_hi:[0,0,0]
	v_mfma_scale_f32_16x16x128_f8f6f4 v[86:89], v[10:17], v[202:209], 0, v188, v188 op_sel_hi:[0,0,0]
	v_mfma_scale_f32_16x16x128_f8f6f4 v[78:81], v[2:9], v[210:217], 0, v188, v188 op_sel_hi:[0,0,0]
	v_mfma_scale_f32_16x16x128_f8f6f4 v[70:73], v[10:17], v[210:217], 0, v188, v188 op_sel_hi:[0,0,0]
	v_mfma_scale_f32_16x16x128_f8f6f4 v[62:65], v[2:9], v[218:225], 0, v188, v188 op_sel_hi:[0,0,0]
	v_mfma_scale_f32_16x16x128_f8f6f4 v[54:57], v[10:17], v[218:225], 0, v188, v188 op_sel_hi:[0,0,0]
	v_mfma_scale_f32_16x16x128_f8f6f4 v[46:49], v[2:9], v[226:233], 0, v188, v188 op_sel_hi:[0,0,0]
	v_mfma_scale_f32_16x16x128_f8f6f4 v[38:41], v[10:17], v[226:233], 0, v188, v188 op_sel_hi:[0,0,0]
	s_barrier
	s_add_u32 s38, s36, 0x20000
	s_addc_u32 s39, s37, 0
	s_add_i32 s0, s0, s43
	v_lshl_add_u64 v[2:3], s[38:39], 0, v[164:165]
	s_mov_b32 m0, s0
	s_nop 0
	global_load_lds_dwordx4 v[2:3], off
	v_lshl_add_u64 v[2:3], s[38:39], 0, v[166:167]
	s_add_i32 m0, s0, 0x2000
	s_nop 0
	global_load_lds_dwordx4 v[2:3], off
	s_waitcnt vmcnt(10)
	s_barrier
	v_mfma_scale_f32_16x16x128_f8f6f4 v[90:93], v[18:25], v[202:209], 0, v188, v188 op_sel_hi:[0,0,0]
	v_mfma_scale_f32_16x16x128_f8f6f4 v[82:85], v[26:33], v[202:209], 0, v188, v188 op_sel_hi:[0,0,0]
	v_mfma_scale_f32_16x16x128_f8f6f4 v[74:77], v[18:25], v[210:217], 0, v188, v188 op_sel_hi:[0,0,0]
	v_mfma_scale_f32_16x16x128_f8f6f4 v[66:69], v[26:33], v[210:217], 0, v188, v188 op_sel_hi:[0,0,0]
	v_mfma_scale_f32_16x16x128_f8f6f4 v[58:61], v[18:25], v[218:225], 0, v188, v188 op_sel_hi:[0,0,0]
	v_mfma_scale_f32_16x16x128_f8f6f4 v[50:53], v[26:33], v[218:225], 0, v188, v188 op_sel_hi:[0,0,0]
	v_mfma_scale_f32_16x16x128_f8f6f4 v[42:45], v[18:25], v[226:233], 0, v188, v188 op_sel_hi:[0,0,0]
	v_mfma_scale_f32_16x16x128_f8f6f4 v[34:37], v[26:33], v[226:233], 0, v188, v188 op_sel_hi:[0,0,0]
	s_add_i32 s0, 0, 0x18000
	v_add_u32_e32 v14, s0, v197
	s_barrier
	ds_read_b128 v[2:5], v14
	ds_read_b128 v[6:9], v14 offset:1024
	ds_read_b128 v[10:13], v14 offset:2048
	ds_read_b128 v[14:17], v14 offset:3072
	s_mov_b32 m0, s47
	ds_read_b128 v[18:21], v169 offset:32768
	ds_read_b128 v[22:25], v169 offset:33792
	ds_read_b128 v[26:29], v169 offset:34816
	ds_read_b128 v[30:33], v169 offset:35840
	ds_read_b128 v[202:205], v169 offset:36864
	ds_read_b128 v[206:209], v169 offset:37888
	ds_read_b128 v[210:213], v169 offset:38912
	ds_read_b128 v[214:217], v169 offset:39936
	global_load_lds_dwordx4 v175, s[40:41]
	s_mov_b32 m0, s48
	s_nop 0
	global_load_lds_dwordx4 v173, s[40:41]
	s_waitcnt lgkmcnt(8)
	s_waitcnt vmcnt(10)
	s_barrier
	s_waitcnt lgkmcnt(0)
	s_waitcnt lgkmcnt(0)
	v_mfma_scale_f32_16x16x128_f8f6f4 v[158:161], v[2:9], v[18:25], v[158:161], v188, v188 op_sel_hi:[0,0,0]
	v_mfma_scale_f32_16x16x128_f8f6f4 v[150:153], v[10:17], v[18:25], v[150:153], v188, v188 op_sel_hi:[0,0,0]
	v_mfma_scale_f32_16x16x128_f8f6f4 v[142:145], v[2:9], v[26:33], v[142:145], v188, v188 op_sel_hi:[0,0,0]
	v_mfma_scale_f32_16x16x128_f8f6f4 v[134:137], v[10:17], v[26:33], v[134:137], v188, v188 op_sel_hi:[0,0,0]
	v_mfma_scale_f32_16x16x128_f8f6f4 v[126:129], v[2:9], v[202:209], v[126:129], v188, v188 op_sel_hi:[0,0,0]
	v_mfma_scale_f32_16x16x128_f8f6f4 v[118:121], v[10:17], v[202:209], v[118:121], v188, v188 op_sel_hi:[0,0,0]
	v_mfma_scale_f32_16x16x128_f8f6f4 v[110:113], v[2:9], v[210:217], v[110:113], v188, v188 op_sel_hi:[0,0,0]
	v_mfma_scale_f32_16x16x128_f8f6f4 v[102:105], v[10:17], v[210:217], v[102:105], v188, v188 op_sel_hi:[0,0,0]
	s_barrier
	s_add_i32 s38, 0, 0x1c000
	s_add_i32 s0, s0, s43
	v_add_u32_e32 v162, s38, v197
	v_lshl_add_u64 v[180:181], v[180:181], 0, s[24:25]
	s_mov_b32 m0, s0
	ds_read_b128 v[218:221], v162
	ds_read_b128 v[222:225], v162 offset:1024
	ds_read_b128 v[226:229], v162 offset:2048
	ds_read_b128 v[230:233], v162 offset:3072
	global_load_lds_dwordx4 v[180:181], off
	v_lshl_add_u64 v[180:181], v[182:183], 0, s[24:25]
	s_add_i32 m0, s0, 0x2000
	s_nop 0
	global_load_lds_dwordx4 v[180:181], off
	s_waitcnt vmcnt(10)
	s_barrier
	s_waitcnt lgkmcnt(0)
	s_waitcnt lgkmcnt(0)
	v_mfma_scale_f32_16x16x128_f8f6f4 v[154:157], v[218:225], v[18:25], v[154:157], v188, v188 op_sel_hi:[0,0,0]
	v_mfma_scale_f32_16x16x128_f8f6f4 v[146:149], v[226:233], v[18:25], v[146:149], v188, v188 op_sel_hi:[0,0,0]
	v_mfma_scale_f32_16x16x128_f8f6f4 v[138:141], v[218:225], v[26:33], v[138:141], v188, v188 op_sel_hi:[0,0,0]
	v_mfma_scale_f32_16x16x128_f8f6f4 v[130:133], v[226:233], v[26:33], v[130:133], v188, v188 op_sel_hi:[0,0,0]
	v_mfma_scale_f32_16x16x128_f8f6f4 v[122:125], v[218:225], v[202:209], v[122:125], v188, v188 op_sel_hi:[0,0,0]
	v_mfma_scale_f32_16x16x128_f8f6f4 v[114:117], v[226:233], v[202:209], v[114:117], v188, v188 op_sel_hi:[0,0,0]
	v_mfma_scale_f32_16x16x128_f8f6f4 v[106:109], v[218:225], v[210:217], v[106:109], v188, v188 op_sel_hi:[0,0,0]
	v_mfma_scale_f32_16x16x128_f8f6f4 v[98:101], v[226:233], v[210:217], v[98:101], v188, v188 op_sel_hi:[0,0,0]
	s_mov_b32 m0, s51
	v_lshl_add_u64 v[180:181], v[186:187], 0, s[24:25]
	s_barrier
	ds_read_b128 v[18:21], v169 offset:49152
	ds_read_b128 v[22:25], v169 offset:50176
	ds_read_b128 v[26:29], v169 offset:51200
	ds_read_b128 v[30:33], v169 offset:52224
	ds_read_b128 v[202:205], v169 offset:53248
	ds_read_b128 v[206:209], v169 offset:54272
	ds_read_b128 v[210:213], v169 offset:55296
	ds_read_b128 v[214:217], v169 offset:56320
	global_load_lds_dwordx4 v[180:181], off
	v_lshl_add_u64 v[180:181], v[184:185], 0, s[24:25]
	s_mov_b32 m0, s52
	s_nop 0
	global_load_lds_dwordx4 v[180:181], off
	s_waitcnt vmcnt(10)
	s_barrier
	s_waitcnt lgkmcnt(0)
	s_waitcnt lgkmcnt(0)
	v_mfma_scale_f32_16x16x128_f8f6f4 v[94:97], v[2:9], v[18:25], v[94:97], v188, v188 op_sel_hi:[0,0,0]
	v_mfma_scale_f32_16x16x128_f8f6f4 v[86:89], v[10:17], v[18:25], v[86:89], v188, v188 op_sel_hi:[0,0,0]
	v_mfma_scale_f32_16x16x128_f8f6f4 v[78:81], v[2:9], v[26:33], v[78:81], v188, v188 op_sel_hi:[0,0,0]
	v_mfma_scale_f32_16x16x128_f8f6f4 v[70:73], v[10:17], v[26:33], v[70:73], v188, v188 op_sel_hi:[0,0,0]
	v_mfma_scale_f32_16x16x128_f8f6f4 v[62:65], v[2:9], v[202:209], v[62:65], v188, v188 op_sel_hi:[0,0,0]
	v_mfma_scale_f32_16x16x128_f8f6f4 v[54:57], v[10:17], v[202:209], v[54:57], v188, v188 op_sel_hi:[0,0,0]
	v_mfma_scale_f32_16x16x128_f8f6f4 v[46:49], v[2:9], v[210:217], v[46:49], v188, v188 op_sel_hi:[0,0,0]
	v_mfma_scale_f32_16x16x128_f8f6f4 v[38:41], v[10:17], v[210:217], v[38:41], v188, v188 op_sel_hi:[0,0,0]
	s_barrier
	s_add_u32 s0, s36, 0x20080
	s_addc_u32 s1, s37, 0
	s_add_i32 s36, s38, s43
	v_lshl_add_u64 v[2:3], s[0:1], 0, v[164:165]
	s_mov_b32 m0, s36
	s_nop 0
	global_load_lds_dwordx4 v[2:3], off
	v_lshl_add_u64 v[2:3], s[0:1], 0, v[166:167]
	s_add_i32 m0, s36, 0x2000
	s_nop 0
	global_load_lds_dwordx4 v[2:3], off
	s_waitcnt vmcnt(10)
	s_barrier
	v_mfma_scale_f32_16x16x128_f8f6f4 v[90:93], v[218:225], v[18:25], v[90:93], v188, v188 op_sel_hi:[0,0,0]
	v_mfma_scale_f32_16x16x128_f8f6f4 v[82:85], v[226:233], v[18:25], v[82:85], v188, v188 op_sel_hi:[0,0,0]
	v_mfma_scale_f32_16x16x128_f8f6f4 v[74:77], v[218:225], v[26:33], v[74:77], v188, v188 op_sel_hi:[0,0,0]
	v_mfma_scale_f32_16x16x128_f8f6f4 v[66:69], v[226:233], v[26:33], v[66:69], v188, v188 op_sel_hi:[0,0,0]
	v_mfma_scale_f32_16x16x128_f8f6f4 v[58:61], v[218:225], v[202:209], v[58:61], v188, v188 op_sel_hi:[0,0,0]
	v_mfma_scale_f32_16x16x128_f8f6f4 v[50:53], v[226:233], v[202:209], v[50:53], v188, v188 op_sel_hi:[0,0,0]
	v_mfma_scale_f32_16x16x128_f8f6f4 v[42:45], v[218:225], v[210:217], v[42:45], v188, v188 op_sel_hi:[0,0,0]
	v_mfma_scale_f32_16x16x128_f8f6f4 v[34:37], v[226:233], v[210:217], v[34:37], v188, v188 op_sel_hi:[0,0,0]
	s_add_i32 s56, s56, 2
	s_cmp_gt_u32 s56, 5
	s_mov_b64 s[38:39], s[14:15]
	s_barrier
	s_cbranch_scc1 .Lpeel_exit_11

.Lpeel_exit_11:
	v_mul_f32_e32 v5, 0x3b000000, v158
	v_mul_f32_e32 v6, 0xbcb8aa3b, v158
	v_exp_f32_e32 v6, v6
	s_ashr_i32 s35, s34, 31
	s_ashr_i32 s31, s30, 31
	s_lshl_b64 s[14:15], s[34:35], 18
	v_add_f32_e32 v6, 1.0, v6
	v_rcp_f32_e32 v6, v6
	s_lshl_b64 s[30:31], s[30:31], 15
	v_mov_b32_e32 v3, v195
	s_add_u32 s0, s6, s14
	v_mul_f32_e32 v5, v5, v6
	v_mul_f32_e32 v6, 0x3b000000, v159
	v_mul_f32_e32 v7, 0xbcb8aa3b, v159
	v_exp_f32_e32 v7, v7
	v_mul_f32_e32 v5, v5, v154
	v_med3_f32 v5, v5, s10, v190
	v_add_f32_e32 v7, 1.0, v7
	v_rcp_f32_e32 v7, v7
	s_nop 15
	s_nop 15
	v_mov_b32_e32 v2, v196
	v_mul_f32_e32 v6, v6, v7
	v_mul_f32_e32 v7, 0x3b000000, v160
	v_mul_f32_e32 v8, 0xbcb8aa3b, v160
	v_exp_f32_e32 v8, v8
	v_mul_f32_e32 v6, v6, v155
	v_add_u32_e32 v4, s49, v3
	v_add_f32_e32 v8, 1.0, v8
	v_rcp_f32_e32 v8, v8
	s_addc_u32 s1, s7, s15
	s_add_u32 s14, s0, s30
	v_mul_f32_e32 v7, v7, v8
	v_mul_f32_e32 v8, 0x3b000000, v161
	v_mul_f32_e32 v9, 0xbcb8aa3b, v161
	v_exp_f32_e32 v9, v9
	v_mul_f32_e32 v7, v7, v156
	v_lshl_add_u32 v2, v2, 3, s50
	v_add_f32_e32 v9, 1.0, v9
	v_rcp_f32_e32 v9, v9
	s_addc_u32 s15, s1, s31
	v_ashrrev_i32_e32 v3, 31, v2
	s_and_b64 vcc, exec, s[12:13]
	v_mul_f32_e32 v8, v8, v9
	v_mul_f32_e32 v9, 0x3b000000, v150
	v_mul_f32_e32 v10, 0xbcb8aa3b, v150
	v_exp_f32_e32 v10, v10
	v_mul_f32_e32 v8, v8, v157
	v_mov_b32_e32 v174, v200
	v_add_f32_e32 v10, 1.0, v10
	v_rcp_f32_e32 v10, v10
	v_mov_b32_e32 v172, v199
	v_mov_b32_e32 v170, v198
	v_mov_b32_e32 v168, v171
	v_mul_f32_e32 v9, v9, v10
	v_mul_f32_e32 v10, 0x3b000000, v151
	v_mul_f32_e32 v11, 0xbcb8aa3b, v151
	v_exp_f32_e32 v11, v11
	v_mul_f32_e32 v9, v9, v146
	s_mov_b32 s30, s28
	v_add_f32_e32 v11, 1.0, v11
	v_rcp_f32_e32 v11, v11
	s_mov_b32 s34, s54
	s_mov_b64 s[36:37], s[16:17]
	v_mul_f32_e32 v10, v10, v11
	v_mul_f32_e32 v11, 0x3b000000, v152
	v_mul_f32_e32 v12, 0xbcb8aa3b, v152
	v_exp_f32_e32 v12, v12
	v_mul_f32_e32 v10, v10, v147
	v_add_f32_e32 v12, 1.0, v12
	v_rcp_f32_e32 v12, v12
	s_nop 0
	v_mul_f32_e32 v11, v11, v12
	v_mul_f32_e32 v12, 0x3b000000, v153
	v_mul_f32_e32 v13, 0xbcb8aa3b, v153
	v_exp_f32_e32 v13, v13
	v_mul_f32_e32 v11, v11, v148
	v_add_f32_e32 v13, 1.0, v13
	v_rcp_f32_e32 v13, v13
	s_nop 0
	v_mul_f32_e32 v12, v12, v13
	v_med3_f32 v13, v6, s10, v190
	v_mov_b32_e32 v6, v163
	v_cvt_pk_fp8_f32 v6, v5, v13
	v_med3_f32 v5, v7, s10, v190
	v_med3_f32 v7, v8, s10, v190
	v_med3_f32 v8, v10, s10, v190
	v_cvt_pk_fp8_f32 v6, v5, v7 op_sel:[0,0,1]
	v_med3_f32 v5, v9, s10, v190
	v_mov_b32_e32 v7, v163
	v_cvt_pk_fp8_f32 v7, v5, v8
	v_mul_f32_e32 v12, v12, v149
	v_med3_f32 v5, v11, s10, v190
	v_med3_f32 v8, v12, s10, v190
	v_cvt_pk_fp8_f32 v7, v5, v8 op_sel:[0,0,1]
	v_ashrrev_i32_e32 v5, 31, v4
	v_lshlrev_b64 v[8:9], 7, v[4:5]
	v_lshl_add_u64 v[8:9], s[14:15], 0, v[8:9]
	v_lshl_add_u64 v[8:9], v[8:9], 0, v[2:3]
	v_mul_f32_e32 v5, 0x3b000000, v142
	global_store_dwordx2 v[8:9], v[6:7], off
	v_mul_f32_e32 v6, 0xbcb8aa3b, v142
	v_exp_f32_e32 v6, v6
	s_nop 0
	v_add_f32_e32 v6, 1.0, v6
	v_rcp_f32_e32 v6, v6
	s_nop 0
	v_mul_f32_e32 v5, v5, v6
	v_mul_f32_e32 v6, 0x3b000000, v143
	v_mul_f32_e32 v7, 0xbcb8aa3b, v143
	v_exp_f32_e32 v7, v7
	v_mul_f32_e32 v5, v5, v138
	v_med3_f32 v5, v5, s10, v190
	v_add_f32_e32 v7, 1.0, v7
	v_rcp_f32_e32 v7, v7
	s_nop 0
	v_mul_f32_e32 v6, v6, v7
	v_mul_f32_e32 v7, v6, v139
	v_mul_f32_e32 v6, 0x3b000000, v144
	v_mul_f32_e32 v8, 0xbcb8aa3b, v144
	v_exp_f32_e32 v8, v8
	v_med3_f32 v7, v7, s10, v190
	v_add_f32_e32 v8, 1.0, v8
	v_rcp_f32_e32 v8, v8
	s_nop 0
	v_mul_f32_e32 v6, v6, v8
	v_mul_f32_e32 v9, v6, v140
	v_mul_f32_e32 v6, 0x3b000000, v145
	v_mul_f32_e32 v8, 0xbcb8aa3b, v145
	v_exp_f32_e32 v8, v8
	s_nop 0
	v_add_f32_e32 v8, 1.0, v8
	v_rcp_f32_e32 v8, v8
	s_nop 0
	v_mul_f32_e32 v6, v6, v8
	v_mul_f32_e32 v10, v6, v141
	v_mul_f32_e32 v6, 0x3b000000, v134
	v_mul_f32_e32 v8, 0xbcb8aa3b, v134
	v_exp_f32_e32 v8, v8
	s_nop 0
	v_add_f32_e32 v8, 1.0, v8
	v_rcp_f32_e32 v8, v8
	s_nop 0
	v_mul_f32_e32 v6, v6, v8
	v_mul_f32_e32 v11, v6, v130
	v_mul_f32_e32 v6, 0x3b000000, v135
	v_mul_f32_e32 v8, 0xbcb8aa3b, v135
	v_exp_f32_e32 v8, v8
	s_nop 0
	v_add_f32_e32 v8, 1.0, v8
	v_rcp_f32_e32 v8, v8
	s_nop 0
	v_mul_f32_e32 v6, v6, v8
	v_mul_f32_e32 v12, v6, v131
	v_mul_f32_e32 v6, 0x3b000000, v136
	v_mul_f32_e32 v8, 0xbcb8aa3b, v136
	v_exp_f32_e32 v8, v8
	s_nop 0
	v_add_f32_e32 v8, 1.0, v8
	v_rcp_f32_e32 v8, v8
	s_nop 0
	v_mul_f32_e32 v6, v6, v8
	v_mul_f32_e32 v13, v6, v132
	v_mul_f32_e32 v6, 0x3b000000, v137
	v_mul_f32_e32 v8, 0xbcb8aa3b, v137
	v_exp_f32_e32 v8, v8
	s_nop 0
	v_add_f32_e32 v8, 1.0, v8
	v_rcp_f32_e32 v8, v8
	s_nop 0
	v_mul_f32_e32 v6, v6, v8
	v_mov_b32_e32 v8, v163
	v_cvt_pk_fp8_f32 v8, v5, v7
	v_med3_f32 v5, v9, s10, v190
	v_med3_f32 v7, v10, s10, v190
	v_mov_b32_e32 v9, v163
	v_cvt_pk_fp8_f32 v8, v5, v7 op_sel:[0,0,1]
	v_med3_f32 v5, v11, s10, v190
	v_med3_f32 v7, v12, s10, v190
	v_cvt_pk_fp8_f32 v9, v5, v7
	v_mul_f32_e32 v14, v6, v133
	v_add_u32_e32 v6, 16, v4
	v_med3_f32 v5, v13, s10, v190
	v_med3_f32 v7, v14, s10, v190
	v_cvt_pk_fp8_f32 v9, v5, v7 op_sel:[0,0,1]
	v_ashrrev_i32_e32 v7, 31, v6
	v_lshlrev_b64 v[6:7], 7, v[6:7]
	v_lshl_add_u64 v[6:7], s[14:15], 0, v[6:7]
	v_lshl_add_u64 v[6:7], v[6:7], 0, v[2:3]
	v_mul_f32_e32 v5, 0x3b000000, v126
	global_store_dwordx2 v[6:7], v[8:9], off
	v_mul_f32_e32 v6, 0xbcb8aa3b, v126
	v_exp_f32_e32 v6, v6
	s_nop 0
	v_add_f32_e32 v6, 1.0, v6
	v_rcp_f32_e32 v6, v6
	s_nop 0
	v_mul_f32_e32 v5, v5, v6
	v_mul_f32_e32 v6, 0x3b000000, v127
	v_mul_f32_e32 v7, 0xbcb8aa3b, v127
	v_exp_f32_e32 v7, v7
	v_mul_f32_e32 v5, v5, v122
	v_med3_f32 v5, v5, s10, v190
	v_add_f32_e32 v7, 1.0, v7
	v_rcp_f32_e32 v7, v7
	s_nop 0
	v_mul_f32_e32 v6, v6, v7
	v_mul_f32_e32 v7, v6, v123
	v_mul_f32_e32 v6, 0x3b000000, v128
	v_mul_f32_e32 v8, 0xbcb8aa3b, v128
	v_exp_f32_e32 v8, v8
	v_med3_f32 v7, v7, s10, v190
	v_add_f32_e32 v8, 1.0, v8
	v_rcp_f32_e32 v8, v8
	s_nop 0
	v_mul_f32_e32 v6, v6, v8
	v_mul_f32_e32 v9, v6, v124
	v_mul_f32_e32 v6, 0x3b000000, v129
	v_mul_f32_e32 v8, 0xbcb8aa3b, v129
	v_exp_f32_e32 v8, v8
	s_nop 0
	v_add_f32_e32 v8, 1.0, v8
	v_rcp_f32_e32 v8, v8
	s_nop 0
	v_mul_f32_e32 v6, v6, v8
	v_mul_f32_e32 v10, v6, v125
	v_mul_f32_e32 v6, 0x3b000000, v118
	v_mul_f32_e32 v8, 0xbcb8aa3b, v118
	v_exp_f32_e32 v8, v8
	s_nop 0
	v_add_f32_e32 v8, 1.0, v8
	v_rcp_f32_e32 v8, v8
	s_nop 0
	v_mul_f32_e32 v6, v6, v8
	v_mul_f32_e32 v11, v6, v114
	v_mul_f32_e32 v6, 0x3b000000, v119
	v_mul_f32_e32 v8, 0xbcb8aa3b, v119
	v_exp_f32_e32 v8, v8
	s_nop 0
	v_add_f32_e32 v8, 1.0, v8
	v_rcp_f32_e32 v8, v8
	s_nop 0
	v_mul_f32_e32 v6, v6, v8
	v_mul_f32_e32 v12, v6, v115
	v_mul_f32_e32 v6, 0x3b000000, v120
	v_mul_f32_e32 v8, 0xbcb8aa3b, v120
	v_exp_f32_e32 v8, v8
	s_nop 0
	v_add_f32_e32 v8, 1.0, v8
	v_rcp_f32_e32 v8, v8
	s_nop 0
	v_mul_f32_e32 v6, v6, v8
	v_mul_f32_e32 v13, v6, v116
	v_mul_f32_e32 v6, 0x3b000000, v121
	v_mul_f32_e32 v8, 0xbcb8aa3b, v121
	v_exp_f32_e32 v8, v8
	s_nop 0
	v_add_f32_e32 v8, 1.0, v8
	v_rcp_f32_e32 v8, v8
	s_nop 0
	v_mul_f32_e32 v6, v6, v8
	v_mov_b32_e32 v8, v163
	v_cvt_pk_fp8_f32 v8, v5, v7
	v_med3_f32 v5, v9, s10, v190
	v_med3_f32 v7, v10, s10, v190
	v_mov_b32_e32 v9, v163
	v_cvt_pk_fp8_f32 v8, v5, v7 op_sel:[0,0,1]
	v_med3_f32 v5, v11, s10, v190
	v_med3_f32 v7, v12, s10, v190
	v_cvt_pk_fp8_f32 v9, v5, v7
	v_mul_f32_e32 v14, v6, v117
	v_add_u32_e32 v6, 32, v4
	v_med3_f32 v5, v13, s10, v190
	v_med3_f32 v7, v14, s10, v190
	v_cvt_pk_fp8_f32 v9, v5, v7 op_sel:[0,0,1]
	v_ashrrev_i32_e32 v7, 31, v6
	v_lshlrev_b64 v[6:7], 7, v[6:7]
	v_lshl_add_u64 v[6:7], s[14:15], 0, v[6:7]
	v_lshl_add_u64 v[6:7], v[6:7], 0, v[2:3]
	v_mul_f32_e32 v5, 0x3b000000, v110
	global_store_dwordx2 v[6:7], v[8:9], off
	v_mul_f32_e32 v6, 0xbcb8aa3b, v110
	v_exp_f32_e32 v6, v6
	s_nop 0
	v_add_f32_e32 v6, 1.0, v6
	v_rcp_f32_e32 v6, v6
	s_nop 0
	v_mul_f32_e32 v5, v5, v6
	v_mul_f32_e32 v6, 0x3b000000, v111
	v_mul_f32_e32 v7, 0xbcb8aa3b, v111
	v_exp_f32_e32 v7, v7
	v_mul_f32_e32 v5, v5, v106
	v_med3_f32 v5, v5, s10, v190
	v_add_f32_e32 v7, 1.0, v7
	v_rcp_f32_e32 v7, v7
	s_nop 0
	v_mul_f32_e32 v6, v6, v7
	v_mul_f32_e32 v7, v6, v107
	v_mul_f32_e32 v6, 0x3b000000, v112
	v_mul_f32_e32 v8, 0xbcb8aa3b, v112
	v_exp_f32_e32 v8, v8
	v_med3_f32 v7, v7, s10, v190
	v_add_f32_e32 v8, 1.0, v8
	v_rcp_f32_e32 v8, v8
	s_nop 0
	v_mul_f32_e32 v6, v6, v8
	v_mul_f32_e32 v9, v6, v108
	v_mul_f32_e32 v6, 0x3b000000, v113
	v_mul_f32_e32 v8, 0xbcb8aa3b, v113
	v_exp_f32_e32 v8, v8
	s_nop 0
	v_add_f32_e32 v8, 1.0, v8
	v_rcp_f32_e32 v8, v8
	s_nop 0
	v_mul_f32_e32 v6, v6, v8
	v_mul_f32_e32 v10, v6, v109
	v_mul_f32_e32 v6, 0x3b000000, v102
	v_mul_f32_e32 v8, 0xbcb8aa3b, v102
	v_exp_f32_e32 v8, v8
	s_nop 0
	v_add_f32_e32 v8, 1.0, v8
	v_rcp_f32_e32 v8, v8
	s_nop 0
	v_mul_f32_e32 v6, v6, v8
	v_mul_f32_e32 v11, v6, v98
	v_mul_f32_e32 v6, 0x3b000000, v103
	v_mul_f32_e32 v8, 0xbcb8aa3b, v103
	v_exp_f32_e32 v8, v8
	s_nop 0
	v_add_f32_e32 v8, 1.0, v8
	v_rcp_f32_e32 v8, v8
	s_nop 0
	v_mul_f32_e32 v6, v6, v8
	v_mul_f32_e32 v12, v6, v99
	v_mul_f32_e32 v6, 0x3b000000, v104
	v_mul_f32_e32 v8, 0xbcb8aa3b, v104
	v_exp_f32_e32 v8, v8
	s_nop 0
	v_add_f32_e32 v8, 1.0, v8
	v_rcp_f32_e32 v8, v8
	s_nop 0
	v_mul_f32_e32 v6, v6, v8
	v_mul_f32_e32 v13, v6, v100
	v_mul_f32_e32 v6, 0x3b000000, v105
	v_mul_f32_e32 v8, 0xbcb8aa3b, v105
	v_exp_f32_e32 v8, v8
	s_nop 0
	v_add_f32_e32 v8, 1.0, v8
	v_rcp_f32_e32 v8, v8
	s_nop 0
	v_mul_f32_e32 v6, v6, v8
	v_mov_b32_e32 v8, v163
	v_cvt_pk_fp8_f32 v8, v5, v7
	v_med3_f32 v5, v9, s10, v190
	v_med3_f32 v7, v10, s10, v190
	v_mov_b32_e32 v9, v163
	v_cvt_pk_fp8_f32 v8, v5, v7 op_sel:[0,0,1]
	v_med3_f32 v5, v11, s10, v190
	v_med3_f32 v7, v12, s10, v190
	v_cvt_pk_fp8_f32 v9, v5, v7
	v_mul_f32_e32 v14, v6, v101
	v_add_u32_e32 v6, 48, v4
	v_med3_f32 v5, v13, s10, v190
	v_med3_f32 v7, v14, s10, v190
	v_cvt_pk_fp8_f32 v9, v5, v7 op_sel:[0,0,1]
	v_ashrrev_i32_e32 v7, 31, v6
	v_lshlrev_b64 v[6:7], 7, v[6:7]
	v_lshl_add_u64 v[6:7], s[14:15], 0, v[6:7]
	v_lshl_add_u64 v[6:7], v[6:7], 0, v[2:3]
	v_mul_f32_e32 v5, 0x3b000000, v94
	global_store_dwordx2 v[6:7], v[8:9], off
	v_mul_f32_e32 v7, 0xbcb8aa3b, v94
	v_exp_f32_e32 v7, v7
	v_add_u32_e32 v6, 0x80, v4
	v_add_f32_e32 v7, 1.0, v7
	v_rcp_f32_e32 v7, v7
	s_nop 0
	v_mul_f32_e32 v5, v5, v7
	v_mul_f32_e32 v7, 0x3b000000, v95
	v_mul_f32_e32 v8, 0xbcb8aa3b, v95
	v_exp_f32_e32 v8, v8
	v_mul_f32_e32 v5, v5, v90
	v_med3_f32 v5, v5, s10, v190
	v_add_f32_e32 v8, 1.0, v8
	v_rcp_f32_e32 v8, v8
	s_nop 0
	v_mul_f32_e32 v7, v7, v8
	v_mul_f32_e32 v8, 0x3b000000, v96
	v_mul_f32_e32 v9, 0xbcb8aa3b, v96
	v_exp_f32_e32 v9, v9
	v_mul_f32_e32 v7, v7, v91
	v_med3_f32 v7, v7, s10, v190
	v_add_f32_e32 v9, 1.0, v9
	v_rcp_f32_e32 v9, v9
	s_nop 0
	v_mul_f32_e32 v8, v8, v9
	v_mul_f32_e32 v9, v8, v92
	v_mul_f32_e32 v8, 0x3b000000, v97
	v_mul_f32_e32 v10, 0xbcb8aa3b, v97
	v_exp_f32_e32 v10, v10
	s_nop 0
	v_add_f32_e32 v10, 1.0, v10
	v_rcp_f32_e32 v10, v10
	s_nop 0
	v_mul_f32_e32 v8, v8, v10
	v_mul_f32_e32 v10, v8, v93
	v_mul_f32_e32 v8, 0x3b000000, v86
	v_mul_f32_e32 v11, 0xbcb8aa3b, v86
	v_exp_f32_e32 v11, v11
	s_nop 0
	v_add_f32_e32 v11, 1.0, v11
	v_rcp_f32_e32 v11, v11
	s_nop 0
	v_mul_f32_e32 v8, v8, v11
	v_mul_f32_e32 v11, v8, v82
	v_mul_f32_e32 v8, 0x3b000000, v87
	v_mul_f32_e32 v12, 0xbcb8aa3b, v87
	v_exp_f32_e32 v12, v12
	s_nop 0
	v_add_f32_e32 v12, 1.0, v12
	v_rcp_f32_e32 v12, v12
	s_nop 0
	v_mul_f32_e32 v8, v8, v12
	v_mul_f32_e32 v12, v8, v83
	v_mul_f32_e32 v8, 0x3b000000, v88
	v_mul_f32_e32 v13, 0xbcb8aa3b, v88
	v_exp_f32_e32 v13, v13
	s_nop 0
	v_add_f32_e32 v13, 1.0, v13
	v_rcp_f32_e32 v13, v13
	s_nop 0
	v_mul_f32_e32 v8, v8, v13
	v_mul_f32_e32 v13, v8, v84
	v_mul_f32_e32 v8, 0x3b000000, v89
	v_mul_f32_e32 v14, 0xbcb8aa3b, v89
	v_exp_f32_e32 v14, v14
	s_nop 0
	v_add_f32_e32 v14, 1.0, v14
	v_rcp_f32_e32 v14, v14
	s_nop 0
	v_mul_f32_e32 v8, v8, v14
	v_mul_f32_e32 v14, v8, v85
	v_mov_b32_e32 v8, v163
	v_cvt_pk_fp8_f32 v8, v5, v7
	v_med3_f32 v5, v9, s10, v190
	v_med3_f32 v7, v10, s10, v190
	v_mov_b32_e32 v9, v163
	v_cvt_pk_fp8_f32 v8, v5, v7 op_sel:[0,0,1]
	v_med3_f32 v5, v11, s10, v190
	v_med3_f32 v7, v12, s10, v190
	v_cvt_pk_fp8_f32 v9, v5, v7
	v_med3_f32 v5, v13, s10, v190
	v_med3_f32 v7, v14, s10, v190
	v_cvt_pk_fp8_f32 v9, v5, v7 op_sel:[0,0,1]
	v_ashrrev_i32_e32 v7, 31, v6
	v_lshlrev_b64 v[6:7], 7, v[6:7]
	v_lshl_add_u64 v[6:7], s[14:15], 0, v[6:7]
	v_lshl_add_u64 v[6:7], v[6:7], 0, v[2:3]
	v_mul_f32_e32 v5, 0x3b000000, v78
	global_store_dwordx2 v[6:7], v[8:9], off
	v_mul_f32_e32 v6, 0xbcb8aa3b, v78
	v_exp_f32_e32 v6, v6
	s_nop 0
	v_add_f32_e32 v6, 1.0, v6
	v_rcp_f32_e32 v6, v6
	s_nop 0
	v_mul_f32_e32 v5, v5, v6
	v_mul_f32_e32 v6, 0x3b000000, v79
	v_mul_f32_e32 v7, 0xbcb8aa3b, v79
	v_exp_f32_e32 v7, v7
	v_mul_f32_e32 v5, v5, v74
	v_med3_f32 v5, v5, s10, v190
	v_add_f32_e32 v7, 1.0, v7
	v_rcp_f32_e32 v7, v7
	s_nop 0
	v_mul_f32_e32 v6, v6, v7
	v_mul_f32_e32 v7, v6, v75
	v_mul_f32_e32 v6, 0x3b000000, v80
	v_mul_f32_e32 v8, 0xbcb8aa3b, v80
	v_exp_f32_e32 v8, v8
	v_med3_f32 v7, v7, s10, v190
	v_add_f32_e32 v8, 1.0, v8
	v_rcp_f32_e32 v8, v8
	s_nop 0
	v_mul_f32_e32 v6, v6, v8
	v_mul_f32_e32 v9, v6, v76
	v_mul_f32_e32 v6, 0x3b000000, v81
	v_mul_f32_e32 v8, 0xbcb8aa3b, v81
	v_exp_f32_e32 v8, v8
	s_nop 0
	v_add_f32_e32 v8, 1.0, v8
	v_rcp_f32_e32 v8, v8
	s_nop 0
	v_mul_f32_e32 v6, v6, v8
	v_mul_f32_e32 v10, v6, v77
	v_mul_f32_e32 v6, 0x3b000000, v70
	v_mul_f32_e32 v8, 0xbcb8aa3b, v70
	v_exp_f32_e32 v8, v8
	s_nop 0
	v_add_f32_e32 v8, 1.0, v8
	v_rcp_f32_e32 v8, v8
	s_nop 0
	v_mul_f32_e32 v6, v6, v8
	v_mul_f32_e32 v11, v6, v66
	v_mul_f32_e32 v6, 0x3b000000, v71
	v_mul_f32_e32 v8, 0xbcb8aa3b, v71
	v_exp_f32_e32 v8, v8
	s_nop 0
	v_add_f32_e32 v8, 1.0, v8
	v_rcp_f32_e32 v8, v8
	s_nop 0
	v_mul_f32_e32 v6, v6, v8
	v_mul_f32_e32 v12, v6, v67
	v_mul_f32_e32 v6, 0x3b000000, v72
	v_mul_f32_e32 v8, 0xbcb8aa3b, v72
	v_exp_f32_e32 v8, v8
	s_nop 0
	v_add_f32_e32 v8, 1.0, v8
	v_rcp_f32_e32 v8, v8
	s_nop 0
	v_mul_f32_e32 v6, v6, v8
	v_mul_f32_e32 v13, v6, v68
	v_mul_f32_e32 v6, 0x3b000000, v73
	v_mul_f32_e32 v8, 0xbcb8aa3b, v73
	v_exp_f32_e32 v8, v8
	s_nop 0
	v_add_f32_e32 v8, 1.0, v8
	v_rcp_f32_e32 v8, v8
	s_nop 0
	v_mul_f32_e32 v6, v6, v8
	v_mov_b32_e32 v8, v163
	v_cvt_pk_fp8_f32 v8, v5, v7
	v_med3_f32 v5, v9, s10, v190
	v_med3_f32 v7, v10, s10, v190
	v_mov_b32_e32 v9, v163
	v_cvt_pk_fp8_f32 v8, v5, v7 op_sel:[0,0,1]
	v_med3_f32 v5, v11, s10, v190
	v_med3_f32 v7, v12, s10, v190
	v_cvt_pk_fp8_f32 v9, v5, v7
	v_mul_f32_e32 v14, v6, v69
	v_add_u32_e32 v6, 0x90, v4
	v_med3_f32 v5, v13, s10, v190
	v_med3_f32 v7, v14, s10, v190
	v_cvt_pk_fp8_f32 v9, v5, v7 op_sel:[0,0,1]
	v_ashrrev_i32_e32 v7, 31, v6
	v_lshlrev_b64 v[6:7], 7, v[6:7]
	v_lshl_add_u64 v[6:7], s[14:15], 0, v[6:7]
	v_lshl_add_u64 v[6:7], v[6:7], 0, v[2:3]
	v_mul_f32_e32 v5, 0x3b000000, v62
	global_store_dwordx2 v[6:7], v[8:9], off
	v_mul_f32_e32 v6, 0xbcb8aa3b, v62
	v_exp_f32_e32 v6, v6
	s_nop 0
	v_add_f32_e32 v6, 1.0, v6
	v_rcp_f32_e32 v6, v6
	s_nop 0
	v_mul_f32_e32 v5, v5, v6
	v_mul_f32_e32 v6, 0x3b000000, v63
	v_mul_f32_e32 v7, 0xbcb8aa3b, v63
	v_exp_f32_e32 v7, v7
	v_mul_f32_e32 v5, v5, v58
	v_med3_f32 v5, v5, s10, v190
	v_add_f32_e32 v7, 1.0, v7
	v_rcp_f32_e32 v7, v7
	s_nop 0
	v_mul_f32_e32 v6, v6, v7
	v_mul_f32_e32 v7, v6, v59
	v_mul_f32_e32 v6, 0x3b000000, v64
	v_mul_f32_e32 v8, 0xbcb8aa3b, v64
	v_exp_f32_e32 v8, v8
	v_med3_f32 v7, v7, s10, v190
	v_add_f32_e32 v8, 1.0, v8
	v_rcp_f32_e32 v8, v8
	s_nop 0
	v_mul_f32_e32 v6, v6, v8
	v_mul_f32_e32 v9, v6, v60
	v_mul_f32_e32 v6, 0x3b000000, v65
	v_mul_f32_e32 v8, 0xbcb8aa3b, v65
	v_exp_f32_e32 v8, v8
	s_nop 0
	v_add_f32_e32 v8, 1.0, v8
	v_rcp_f32_e32 v8, v8
	s_nop 0
	v_mul_f32_e32 v6, v6, v8
	v_mul_f32_e32 v10, v6, v61
	v_mul_f32_e32 v6, 0x3b000000, v54
	v_mul_f32_e32 v8, 0xbcb8aa3b, v54
	v_exp_f32_e32 v8, v8
	s_nop 0
	v_add_f32_e32 v8, 1.0, v8
	v_rcp_f32_e32 v8, v8
	s_nop 0
	v_mul_f32_e32 v6, v6, v8
	v_mul_f32_e32 v11, v6, v50
	v_mul_f32_e32 v6, 0x3b000000, v55
	v_mul_f32_e32 v8, 0xbcb8aa3b, v55
	v_exp_f32_e32 v8, v8
	s_nop 0
	v_add_f32_e32 v8, 1.0, v8
	v_rcp_f32_e32 v8, v8
	s_nop 0
	v_mul_f32_e32 v6, v6, v8
	v_mul_f32_e32 v12, v6, v51
	v_mul_f32_e32 v6, 0x3b000000, v56
	v_mul_f32_e32 v8, 0xbcb8aa3b, v56
	v_exp_f32_e32 v8, v8
	s_nop 0
	v_add_f32_e32 v8, 1.0, v8
	v_rcp_f32_e32 v8, v8
	s_nop 0
	v_mul_f32_e32 v6, v6, v8
	v_mul_f32_e32 v13, v6, v52
	v_mul_f32_e32 v6, 0x3b000000, v57
	v_mul_f32_e32 v8, 0xbcb8aa3b, v57
	v_exp_f32_e32 v8, v8
	s_nop 0
	v_add_f32_e32 v8, 1.0, v8
	v_rcp_f32_e32 v8, v8
	s_nop 0
	v_mul_f32_e32 v6, v6, v8
	v_mov_b32_e32 v8, v163
	v_cvt_pk_fp8_f32 v8, v5, v7
	v_med3_f32 v5, v9, s10, v190
	v_med3_f32 v7, v10, s10, v190
	v_mov_b32_e32 v9, v163
	v_cvt_pk_fp8_f32 v8, v5, v7 op_sel:[0,0,1]
	v_med3_f32 v5, v11, s10, v190
	v_med3_f32 v7, v12, s10, v190
	v_cvt_pk_fp8_f32 v9, v5, v7
	v_mul_f32_e32 v14, v6, v53
	v_add_u32_e32 v6, 0xa0, v4
	v_med3_f32 v5, v13, s10, v190
	v_med3_f32 v7, v14, s10, v190
	v_cvt_pk_fp8_f32 v9, v5, v7 op_sel:[0,0,1]
	v_ashrrev_i32_e32 v7, 31, v6
	v_lshlrev_b64 v[6:7], 7, v[6:7]
	v_lshl_add_u64 v[6:7], s[14:15], 0, v[6:7]
	v_lshl_add_u64 v[6:7], v[6:7], 0, v[2:3]
	v_mul_f32_e32 v5, 0x3b000000, v46
	global_store_dwordx2 v[6:7], v[8:9], off
	v_mul_f32_e32 v6, 0xbcb8aa3b, v46
	v_exp_f32_e32 v6, v6
	v_add_u32_e32 v4, 0xb0, v4
	v_add_f32_e32 v6, 1.0, v6
	v_rcp_f32_e32 v6, v6
	s_nop 0
	v_mul_f32_e32 v5, v5, v6
	v_mul_f32_e32 v6, 0x3b000000, v47
	v_mul_f32_e32 v7, 0xbcb8aa3b, v47
	v_exp_f32_e32 v7, v7
	v_mul_f32_e32 v5, v5, v42
	v_med3_f32 v5, v5, s10, v190
	v_add_f32_e32 v7, 1.0, v7
	v_rcp_f32_e32 v7, v7
	s_nop 0
	v_mul_f32_e32 v6, v6, v7
	v_mul_f32_e32 v7, 0x3b000000, v48
	v_mul_f32_e32 v8, 0xbcb8aa3b, v48
	v_exp_f32_e32 v8, v8
	v_mul_f32_e32 v6, v6, v43
	v_add_f32_e32 v8, 1.0, v8
	v_rcp_f32_e32 v8, v8
	s_nop 0
	v_mul_f32_e32 v7, v7, v8
	v_mul_f32_e32 v8, 0x3b000000, v49
	v_mul_f32_e32 v9, 0xbcb8aa3b, v49
	v_exp_f32_e32 v9, v9
	v_mul_f32_e32 v7, v7, v44
	v_add_f32_e32 v9, 1.0, v9
	v_rcp_f32_e32 v9, v9
	s_nop 0
	v_mul_f32_e32 v8, v8, v9
	v_mul_f32_e32 v9, 0x3b000000, v38
	v_mul_f32_e32 v10, 0xbcb8aa3b, v38
	v_exp_f32_e32 v10, v10
	v_mul_f32_e32 v8, v8, v45
	v_add_f32_e32 v10, 1.0, v10
	v_rcp_f32_e32 v10, v10
	s_nop 0
	v_mul_f32_e32 v9, v9, v10
	v_mul_f32_e32 v10, 0x3b000000, v39
	v_mul_f32_e32 v11, 0xbcb8aa3b, v39
	v_exp_f32_e32 v11, v11
	v_mul_f32_e32 v9, v9, v34
	v_add_f32_e32 v11, 1.0, v11
	v_rcp_f32_e32 v11, v11
	s_nop 0
	v_mul_f32_e32 v10, v10, v11
	v_mul_f32_e32 v11, 0x3b000000, v40
	v_mul_f32_e32 v12, 0xbcb8aa3b, v40
	v_exp_f32_e32 v12, v12
	v_mul_f32_e32 v10, v10, v35
	v_add_f32_e32 v12, 1.0, v12
	v_rcp_f32_e32 v12, v12
	s_nop 0
	v_mul_f32_e32 v11, v11, v12
	v_mul_f32_e32 v12, 0x3b000000, v41
	v_mul_f32_e32 v13, 0xbcb8aa3b, v41
	v_exp_f32_e32 v13, v13
	v_mul_f32_e32 v11, v11, v36
	v_add_f32_e32 v13, 1.0, v13
	v_rcp_f32_e32 v13, v13
	s_nop 0
	v_mul_f32_e32 v12, v12, v13
	v_med3_f32 v13, v6, s10, v190
	v_mov_b32_e32 v6, v163
	v_cvt_pk_fp8_f32 v6, v5, v13
	v_med3_f32 v5, v7, s10, v190
	v_med3_f32 v7, v8, s10, v190
	v_med3_f32 v8, v10, s10, v190
	v_cvt_pk_fp8_f32 v6, v5, v7 op_sel:[0,0,1]
	v_med3_f32 v5, v9, s10, v190
	v_mov_b32_e32 v7, v163
	v_cvt_pk_fp8_f32 v7, v5, v8
	v_mul_f32_e32 v12, v12, v37
	v_med3_f32 v5, v11, s10, v190
	v_med3_f32 v8, v12, s10, v190
	v_cvt_pk_fp8_f32 v7, v5, v8 op_sel:[0,0,1]
	v_ashrrev_i32_e32 v5, 31, v4
	v_lshlrev_b64 v[4:5], 7, v[4:5]
	v_lshl_add_u64 v[4:5], s[14:15], 0, v[4:5]
	v_lshl_add_u64 v[2:3], v[4:5], 0, v[2:3]
	global_store_dwordx2 v[2:3], v[6:7], off
	s_cbranch_vccz .LBB0_2030
	s_waitcnt vmcnt(0)
	s_cmpk_gt_u32 s42, 0xff
	s_cbranch_scc1 .LBB0_1976
	s_barrier
	s_branch .LBB0_1976

.LBB0_2107:
	s_ashr_i32 s23, s22, 31
	s_lshl_b64 s[0:1], s[22:23], 18
	v_cmp_lt_i64_e32 vcc, s[24:25], v[158:159]
	s_add_u32 s24, s5, s0
	s_addc_u32 s25, s6, s1
	s_and_b64 s[0:1], vcc, exec
	s_cselect_b32 s23, s25, s35
	s_cselect_b32 s49, s24, s34
	s_ashr_i32 s0, s22, 5
	s_ashr_i32 s1, s0, 31
	s_lshl_b64 s[0:1], s[0:1], 20
	s_add_u32 s26, s7, s0
	s_addc_u32 s27, s8, s1
	s_ashr_i32 s21, s20, 31
	s_lshl_b64 s[0:1], s[20:21], 18
	s_add_u32 s26, s26, s0
	s_addc_u32 s27, s27, s1
	s_and_b64 s[0:1], vcc, exec
	s_cselect_b32 s21, s27, s31
	s_cselect_b32 s50, s26, s30
	s_add_u32 s51, s30, 0x100
	s_addc_u32 s52, s31, 0
	s_add_u32 s30, s34, 0xc000
	s_addc_u32 s31, s35, 0
	s_mov_b32 s53, -2
	ds_read_b128 v[2:5], v169
	ds_read_b128 v[6:9], v169 offset:1024
	ds_read_b128 v[10:13], v169 offset:2048
	ds_read_b128 v[14:17], v169 offset:3072
	s_add_u32 s0, s30, 0x4000
	s_addc_u32 s1, s31, 0
	s_cmp_eq_u32 s53, 4
	s_cselect_b32 s38, s49, s0
	s_cselect_b32 s39, s23, s1
	s_cselect_b32 s34, s50, s51
	s_cselect_b32 s35, s21, s52
	s_add_u32 s36, s38, 0x8000
	s_addc_u32 s37, s39, 0
	v_lshl_add_u64 v[162:163], s[30:31], 0, v[156:157]
	s_add_i32 m0, s10, 0xc000
	ds_read_b128 v[174:177], v170
	ds_read_b128 v[178:181], v170 offset:1024
	ds_read_b128 v[182:185], v170 offset:2048
	ds_read_b128 v[186:189], v170 offset:3072
	ds_read_b128 v[190:193], v170 offset:4096
	ds_read_b128 v[194:197], v170 offset:5120
	ds_read_b128 v[198:201], v170 offset:6144
	ds_read_b128 v[202:205], v170 offset:7168
	global_load_lds_dwordx4 v[162:163], off
	v_lshl_add_u64 v[162:163], s[30:31], 0, v[154:155]
	s_add_i32 m0, s10, 0xe000
	s_nop 0
	global_load_lds_dwordx4 v[162:163], off
	s_waitcnt lgkmcnt(8)
	s_waitcnt vmcnt(10)
	s_barrier
	s_waitcnt lgkmcnt(0)
	s_waitcnt lgkmcnt(0)
	v_mfma_scale_f32_16x16x128_f8f6f4 v[142:145], v[2:9], v[174:181], 0, v171, v171 op_sel_hi:[0,0,0]
	v_mfma_scale_f32_16x16x128_f8f6f4 v[138:141], v[10:17], v[174:181], 0, v171, v171 op_sel_hi:[0,0,0]
	v_mfma_scale_f32_16x16x128_f8f6f4 v[126:129], v[2:9], v[182:189], 0, v171, v171 op_sel_hi:[0,0,0]
	v_mfma_scale_f32_16x16x128_f8f6f4 v[122:125], v[10:17], v[182:189], 0, v171, v171 op_sel_hi:[0,0,0]
	v_mfma_scale_f32_16x16x128_f8f6f4 v[110:113], v[2:9], v[190:197], 0, v171, v171 op_sel_hi:[0,0,0]
	v_mfma_scale_f32_16x16x128_f8f6f4 v[106:109], v[10:17], v[190:197], 0, v171, v171 op_sel_hi:[0,0,0]
	v_mfma_scale_f32_16x16x128_f8f6f4 v[94:97], v[2:9], v[198:205], 0, v171, v171 op_sel_hi:[0,0,0]
	v_mfma_scale_f32_16x16x128_f8f6f4 v[90:93], v[10:17], v[198:205], 0, v171, v171 op_sel_hi:[0,0,0]
	s_barrier
	s_add_i32 s0, s45, s9
	v_lshl_add_u64 v[162:163], s[34:35], 0, v[150:151]
	s_mov_b32 m0, s0
	ds_read_b128 v[206:209], v172
	ds_read_b128 v[210:213], v172 offset:1024
	ds_read_b128 v[214:217], v172 offset:2048
	ds_read_b128 v[218:221], v172 offset:3072
	global_load_lds_dwordx4 v[162:163], off
	v_lshl_add_u64 v[164:165], s[34:35], 0, v[146:147]
	s_add_i32 m0, s0, 0x2000
	s_nop 0
	global_load_lds_dwordx4 v[164:165], off
	s_waitcnt vmcnt(10)
	s_barrier
	s_waitcnt lgkmcnt(0)
	s_waitcnt lgkmcnt(0)
	v_mfma_scale_f32_16x16x128_f8f6f4 v[134:137], v[206:213], v[174:181], 0, v171, v171 op_sel_hi:[0,0,0]
	v_mfma_scale_f32_16x16x128_f8f6f4 v[130:133], v[214:221], v[174:181], 0, v171, v171 op_sel_hi:[0,0,0]
	v_mfma_scale_f32_16x16x128_f8f6f4 v[118:121], v[206:213], v[182:189], 0, v171, v171 op_sel_hi:[0,0,0]
	v_mfma_scale_f32_16x16x128_f8f6f4 v[114:117], v[214:221], v[182:189], 0, v171, v171 op_sel_hi:[0,0,0]
	v_mfma_scale_f32_16x16x128_f8f6f4 v[102:105], v[206:213], v[190:197], 0, v171, v171 op_sel_hi:[0,0,0]
	v_mfma_scale_f32_16x16x128_f8f6f4 v[98:101], v[214:221], v[190:197], 0, v171, v171 op_sel_hi:[0,0,0]
	v_mfma_scale_f32_16x16x128_f8f6f4 v[86:89], v[206:213], v[198:205], 0, v171, v171 op_sel_hi:[0,0,0]
	v_mfma_scale_f32_16x16x128_f8f6f4 v[82:85], v[214:221], v[198:205], 0, v171, v171 op_sel_hi:[0,0,0]
	s_mov_b32 m0, s10
	v_lshl_add_u64 v[222:223], s[38:39], 0, v[152:153]
	s_barrier
	ds_read_b128 v[174:177], v170 offset:16384
	ds_read_b128 v[178:181], v170 offset:17408
	ds_read_b128 v[182:185], v170 offset:18432
	ds_read_b128 v[186:189], v170 offset:19456
	ds_read_b128 v[190:193], v170 offset:20480
	ds_read_b128 v[194:197], v170 offset:21504
	ds_read_b128 v[198:201], v170 offset:22528
	ds_read_b128 v[202:205], v170 offset:23552
	global_load_lds_dwordx4 v[222:223], off
	v_lshl_add_u64 v[222:223], s[38:39], 0, v[148:149]
	s_mov_b32 m0, s11
	s_nop 0
	global_load_lds_dwordx4 v[222:223], off
	s_waitcnt vmcnt(10)
	s_barrier
	s_waitcnt lgkmcnt(0)
	s_waitcnt lgkmcnt(0)
	v_mfma_scale_f32_16x16x128_f8f6f4 v[78:81], v[2:9], v[174:181], 0, v171, v171 op_sel_hi:[0,0,0]
	v_mfma_scale_f32_16x16x128_f8f6f4 v[74:77], v[10:17], v[174:181], 0, v171, v171 op_sel_hi:[0,0,0]
	v_mfma_scale_f32_16x16x128_f8f6f4 v[62:65], v[2:9], v[182:189], 0, v171, v171 op_sel_hi:[0,0,0]
	v_mfma_scale_f32_16x16x128_f8f6f4 v[58:61], v[10:17], v[182:189], 0, v171, v171 op_sel_hi:[0,0,0]
	v_mfma_scale_f32_16x16x128_f8f6f4 v[46:49], v[2:9], v[190:197], 0, v171, v171 op_sel_hi:[0,0,0]
	v_mfma_scale_f32_16x16x128_f8f6f4 v[42:45], v[10:17], v[190:197], 0, v171, v171 op_sel_hi:[0,0,0]
	v_mfma_scale_f32_16x16x128_f8f6f4 v[30:33], v[2:9], v[198:205], 0, v171, v171 op_sel_hi:[0,0,0]
	v_mfma_scale_f32_16x16x128_f8f6f4 v[26:29], v[10:17], v[198:205], 0, v171, v171 op_sel_hi:[0,0,0]
	s_barrier
	s_add_u32 s0, s34, 0x20000
	s_addc_u32 s1, s35, 0
	s_add_i32 s54, s46, s9
	v_lshl_add_u64 v[2:3], s[0:1], 0, v[150:151]
	s_mov_b32 m0, s54
	s_nop 0
	global_load_lds_dwordx4 v[2:3], off
	v_lshl_add_u64 v[2:3], s[0:1], 0, v[146:147]
	s_add_i32 m0, s54, 0x2000
	s_nop 0
	global_load_lds_dwordx4 v[2:3], off
	s_waitcnt vmcnt(10)
	s_barrier
	v_mfma_scale_f32_16x16x128_f8f6f4 v[70:73], v[206:213], v[174:181], 0, v171, v171 op_sel_hi:[0,0,0]
	v_mfma_scale_f32_16x16x128_f8f6f4 v[66:69], v[214:221], v[174:181], 0, v171, v171 op_sel_hi:[0,0,0]
	v_mfma_scale_f32_16x16x128_f8f6f4 v[54:57], v[206:213], v[182:189], 0, v171, v171 op_sel_hi:[0,0,0]
	v_mfma_scale_f32_16x16x128_f8f6f4 v[50:53], v[214:221], v[182:189], 0, v171, v171 op_sel_hi:[0,0,0]
	v_mfma_scale_f32_16x16x128_f8f6f4 v[38:41], v[206:213], v[190:197], 0, v171, v171 op_sel_hi:[0,0,0]
	v_mfma_scale_f32_16x16x128_f8f6f4 v[34:37], v[214:221], v[190:197], 0, v171, v171 op_sel_hi:[0,0,0]
	v_mfma_scale_f32_16x16x128_f8f6f4 v[22:25], v[206:213], v[198:205], 0, v171, v171 op_sel_hi:[0,0,0]
	v_mfma_scale_f32_16x16x128_f8f6f4 v[18:21], v[214:221], v[198:205], 0, v171, v171 op_sel_hi:[0,0,0]
	s_add_i32 s54, 0, 0x18000
	v_add_u32_e32 v14, s54, v168
	s_barrier
	ds_read_b128 v[2:5], v14
	ds_read_b128 v[6:9], v14 offset:1024
	ds_read_b128 v[10:13], v14 offset:2048
	ds_read_b128 v[14:17], v14 offset:3072
	s_add_u32 s0, s38, 0x4000
	s_addc_u32 s1, s39, 0
	s_mov_b32 m0, s19
	v_lshl_add_u64 v[206:207], s[0:1], 0, v[152:153]
	ds_read_b128 v[174:177], v170 offset:32768
	ds_read_b128 v[178:181], v170 offset:33792
	ds_read_b128 v[182:185], v170 offset:34816
	ds_read_b128 v[186:189], v170 offset:35840
	ds_read_b128 v[190:193], v170 offset:36864
	ds_read_b128 v[194:197], v170 offset:37888
	ds_read_b128 v[198:201], v170 offset:38912
	ds_read_b128 v[202:205], v170 offset:39936
	global_load_lds_dwordx4 v[206:207], off
	v_lshl_add_u64 v[206:207], s[0:1], 0, v[148:149]
	s_mov_b32 m0, s29
	s_nop 0
	global_load_lds_dwordx4 v[206:207], off
	s_waitcnt lgkmcnt(8)
	s_waitcnt vmcnt(10)
	s_barrier
	s_waitcnt lgkmcnt(0)
	s_waitcnt lgkmcnt(0)
	v_mfma_scale_f32_16x16x128_f8f6f4 v[142:145], v[2:9], v[174:181], v[142:145], v171, v171 op_sel_hi:[0,0,0]
	v_mfma_scale_f32_16x16x128_f8f6f4 v[138:141], v[10:17], v[174:181], v[138:141], v171, v171 op_sel_hi:[0,0,0]
	v_mfma_scale_f32_16x16x128_f8f6f4 v[126:129], v[2:9], v[182:189], v[126:129], v171, v171 op_sel_hi:[0,0,0]
	v_mfma_scale_f32_16x16x128_f8f6f4 v[122:125], v[10:17], v[182:189], v[122:125], v171, v171 op_sel_hi:[0,0,0]
	v_mfma_scale_f32_16x16x128_f8f6f4 v[110:113], v[2:9], v[190:197], v[110:113], v171, v171 op_sel_hi:[0,0,0]
	v_mfma_scale_f32_16x16x128_f8f6f4 v[106:109], v[10:17], v[190:197], v[106:109], v171, v171 op_sel_hi:[0,0,0]
	v_mfma_scale_f32_16x16x128_f8f6f4 v[94:97], v[2:9], v[198:205], v[94:97], v171, v171 op_sel_hi:[0,0,0]
	v_mfma_scale_f32_16x16x128_f8f6f4 v[90:93], v[10:17], v[198:205], v[90:93], v171, v171 op_sel_hi:[0,0,0]
	s_barrier
	s_add_i32 s38, 0, 0x1c000
	s_add_i32 s0, s54, s9
	v_add_u32_e32 v218, s38, v168
	v_lshl_add_u64 v[162:163], v[162:163], 0, s[16:17]
	s_mov_b32 m0, s0
	ds_read_b128 v[206:209], v218
	ds_read_b128 v[210:213], v218 offset:1024
	ds_read_b128 v[214:217], v218 offset:2048
	ds_read_b128 v[218:221], v218 offset:3072
	global_load_lds_dwordx4 v[162:163], off
	v_lshl_add_u64 v[162:163], v[164:165], 0, s[16:17]
	s_add_i32 m0, s0, 0x2000
	s_nop 0
	global_load_lds_dwordx4 v[162:163], off
	s_waitcnt vmcnt(10)
	s_barrier
	s_waitcnt lgkmcnt(0)
	s_waitcnt lgkmcnt(0)
	v_mfma_scale_f32_16x16x128_f8f6f4 v[134:137], v[206:213], v[174:181], v[134:137], v171, v171 op_sel_hi:[0,0,0]
	v_mfma_scale_f32_16x16x128_f8f6f4 v[130:133], v[214:221], v[174:181], v[130:133], v171, v171 op_sel_hi:[0,0,0]
	v_mfma_scale_f32_16x16x128_f8f6f4 v[118:121], v[206:213], v[182:189], v[118:121], v171, v171 op_sel_hi:[0,0,0]
	v_mfma_scale_f32_16x16x128_f8f6f4 v[114:117], v[214:221], v[182:189], v[114:117], v171, v171 op_sel_hi:[0,0,0]
	v_mfma_scale_f32_16x16x128_f8f6f4 v[102:105], v[206:213], v[190:197], v[102:105], v171, v171 op_sel_hi:[0,0,0]
	v_mfma_scale_f32_16x16x128_f8f6f4 v[98:101], v[214:221], v[190:197], v[98:101], v171, v171 op_sel_hi:[0,0,0]
	v_mfma_scale_f32_16x16x128_f8f6f4 v[86:89], v[206:213], v[198:205], v[86:89], v171, v171 op_sel_hi:[0,0,0]
	v_mfma_scale_f32_16x16x128_f8f6f4 v[82:85], v[214:221], v[198:205], v[82:85], v171, v171 op_sel_hi:[0,0,0]
	s_mov_b32 m0, s43
	v_lshl_add_u64 v[162:163], s[36:37], 0, v[152:153]
	s_barrier
	ds_read_b128 v[174:177], v170 offset:49152
	ds_read_b128 v[178:181], v170 offset:50176
	ds_read_b128 v[182:185], v170 offset:51200
	ds_read_b128 v[186:189], v170 offset:52224
	ds_read_b128 v[190:193], v170 offset:53248
	ds_read_b128 v[194:197], v170 offset:54272
	ds_read_b128 v[198:201], v170 offset:55296
	ds_read_b128 v[202:205], v170 offset:56320
	global_load_lds_dwordx4 v[162:163], off
	v_lshl_add_u64 v[162:163], s[36:37], 0, v[148:149]
	s_mov_b32 m0, s44
	s_nop 0
	global_load_lds_dwordx4 v[162:163], off
	s_waitcnt vmcnt(10)
	s_barrier
	s_waitcnt lgkmcnt(0)
	s_waitcnt lgkmcnt(0)
	v_mfma_scale_f32_16x16x128_f8f6f4 v[78:81], v[2:9], v[174:181], v[78:81], v171, v171 op_sel_hi:[0,0,0]
	v_mfma_scale_f32_16x16x128_f8f6f4 v[74:77], v[10:17], v[174:181], v[74:77], v171, v171 op_sel_hi:[0,0,0]
	v_mfma_scale_f32_16x16x128_f8f6f4 v[62:65], v[2:9], v[182:189], v[62:65], v171, v171 op_sel_hi:[0,0,0]
	v_mfma_scale_f32_16x16x128_f8f6f4 v[58:61], v[10:17], v[182:189], v[58:61], v171, v171 op_sel_hi:[0,0,0]
	v_mfma_scale_f32_16x16x128_f8f6f4 v[46:49], v[2:9], v[190:197], v[46:49], v171, v171 op_sel_hi:[0,0,0]
	v_mfma_scale_f32_16x16x128_f8f6f4 v[42:45], v[10:17], v[190:197], v[42:45], v171, v171 op_sel_hi:[0,0,0]
	v_mfma_scale_f32_16x16x128_f8f6f4 v[30:33], v[2:9], v[198:205], v[30:33], v171, v171 op_sel_hi:[0,0,0]
	v_mfma_scale_f32_16x16x128_f8f6f4 v[26:29], v[10:17], v[198:205], v[26:29], v171, v171 op_sel_hi:[0,0,0]
	s_barrier
	s_add_u32 s0, s34, 0x20080
	s_addc_u32 s1, s35, 0
	s_add_i32 s34, s38, s9
	v_lshl_add_u64 v[2:3], s[0:1], 0, v[150:151]
	s_mov_b32 m0, s34
	s_nop 0
	global_load_lds_dwordx4 v[2:3], off
	v_lshl_add_u64 v[2:3], s[0:1], 0, v[146:147]
	s_add_i32 m0, s34, 0x2000
	s_nop 0
	global_load_lds_dwordx4 v[2:3], off
	s_waitcnt vmcnt(10)
	s_barrier
	v_mfma_scale_f32_16x16x128_f8f6f4 v[70:73], v[206:213], v[174:181], v[70:73], v171, v171 op_sel_hi:[0,0,0]
	v_mfma_scale_f32_16x16x128_f8f6f4 v[66:69], v[214:221], v[174:181], v[66:69], v171, v171 op_sel_hi:[0,0,0]
	v_mfma_scale_f32_16x16x128_f8f6f4 v[54:57], v[206:213], v[182:189], v[54:57], v171, v171 op_sel_hi:[0,0,0]
	v_mfma_scale_f32_16x16x128_f8f6f4 v[50:53], v[214:221], v[182:189], v[50:53], v171, v171 op_sel_hi:[0,0,0]
	v_mfma_scale_f32_16x16x128_f8f6f4 v[38:41], v[206:213], v[190:197], v[38:41], v171, v171 op_sel_hi:[0,0,0]
	v_mfma_scale_f32_16x16x128_f8f6f4 v[34:37], v[214:221], v[190:197], v[34:37], v171, v171 op_sel_hi:[0,0,0]
	v_mfma_scale_f32_16x16x128_f8f6f4 v[22:25], v[206:213], v[198:205], v[22:25], v171, v171 op_sel_hi:[0,0,0]
	v_mfma_scale_f32_16x16x128_f8f6f4 v[18:21], v[214:221], v[198:205], v[18:21], v171, v171 op_sel_hi:[0,0,0]
	s_add_i32 s53, s53, 2
	s_add_u32 s51, s51, 0x100
	s_addc_u32 s52, s52, 0
	s_add_u32 s30, s30, 0x10000
	s_addc_u32 s31, s31, 0
	s_cmp_gt_u32 s53, 5
	s_barrier
	s_cbranch_scc1 .Lpeel_exit_12

.Lpeel_exit_12:
	v_pk_mul_f32 v[10:11], v[142:143], s[18:19] op_sel_hi:[1,0]
	v_pk_mul_f32 v[8:9], v[144:145], s[18:19] op_sel_hi:[1,0]
	v_med3_f32 v5, v10, s47, v173
	v_med3_f32 v11, v11, s47, v173
	v_mov_b32_e32 v10, 0
	v_cvt_pk_fp8_f32 v10, v5, v11
	v_mov_b32_e32 v3, v166
	v_mov_b32_e32 v2, v167
	s_lshl_b32 s0, s48, 8
	v_pk_mul_f32 v[14:15], v[138:139], s[18:19] op_sel_hi:[1,0]
	v_med3_f32 v5, v8, s47, v173
	v_med3_f32 v8, v9, s47, v173
	s_nop 15
	s_nop 15
	s_or_b32 s0, s0, s42
	v_cvt_pk_fp8_f32 v10, v5, v8 op_sel:[0,0,1]
	v_med3_f32 v5, v14, s47, v173
	v_med3_f32 v8, v15, s47, v173
	v_mov_b32_e32 v11, 0
	v_lshl_add_u32 v2, v2, 3, s0
	s_lshl_b32 s0, s28, 8
	v_cvt_pk_fp8_f32 v11, v5, v8
	s_add_i32 s0, s0, s41
	v_add_u32_e32 v4, s0, v3
	v_pk_mul_f32 v[12:13], v[140:141], s[18:19] op_sel_hi:[1,0]
	v_mov_b32_e32 v6, v4
	v_med3_f32 v5, v12, s47, v173
	v_med3_f32 v8, v13, s47, v173
	v_cvt_pk_fp8_f32 v11, v5, v8 op_sel:[0,0,1]
	v_ashrrev_i32_e32 v7, 31, v6
	v_lshlrev_b64 v[6:7], 10, v[6:7]
	v_ashrrev_i32_e32 v3, 31, v2
	v_lshl_add_u64 v[6:7], s[14:15], 0, v[6:7]
	v_lshl_add_u64 v[6:7], v[6:7], 0, v[2:3]
	global_store_dwordx2 v[6:7], v[10:11], off
	v_pk_mul_f32 v[10:11], v[134:135], s[18:19] op_sel_hi:[1,0]
	v_pk_mul_f32 v[8:9], v[136:137], s[18:19] op_sel_hi:[1,0]
	v_med3_f32 v5, v10, s47, v173
	v_med3_f32 v11, v11, s47, v173
	v_mov_b32_e32 v10, 0
	v_cvt_pk_fp8_f32 v10, v5, v11
	v_pk_mul_f32 v[14:15], v[130:131], s[18:19] op_sel_hi:[1,0]
	v_med3_f32 v5, v8, s47, v173
	v_med3_f32 v8, v9, s47, v173
	v_cvt_pk_fp8_f32 v10, v5, v8 op_sel:[0,0,1]
	v_med3_f32 v5, v14, s47, v173
	v_med3_f32 v8, v15, s47, v173
	v_mov_b32_e32 v11, 0
	v_cvt_pk_fp8_f32 v11, v5, v8
	v_pk_mul_f32 v[12:13], v[132:133], s[18:19] op_sel_hi:[1,0]
	v_pk_mul_f32 v[14:15], v[122:123], s[18:19] op_sel_hi:[1,0]
	v_med3_f32 v5, v12, s47, v173
	v_med3_f32 v8, v13, s47, v173
	v_cvt_pk_fp8_f32 v11, v5, v8 op_sel:[0,0,1]
	v_pk_mul_f32 v[8:9], v[128:129], s[18:19] op_sel_hi:[1,0]
	v_pk_mul_f32 v[12:13], v[124:125], s[18:19] op_sel_hi:[1,0]
	s_and_b64 vcc, exec, s[12:13]
	global_store_dwordx2 v[6:7], v[10:11], off offset:128
	v_pk_mul_f32 v[10:11], v[126:127], s[18:19] op_sel_hi:[1,0]
	v_add_u32_e32 v6, 16, v4
	v_med3_f32 v5, v10, s47, v173
	v_med3_f32 v11, v11, s47, v173
	v_mov_b32_e32 v10, 0
	v_cvt_pk_fp8_f32 v10, v5, v11
	v_med3_f32 v5, v8, s47, v173
	v_med3_f32 v8, v9, s47, v173
	v_mov_b32_e32 v11, 0
	v_cvt_pk_fp8_f32 v10, v5, v8 op_sel:[0,0,1]
	v_med3_f32 v5, v14, s47, v173
	v_med3_f32 v8, v15, s47, v173
	v_cvt_pk_fp8_f32 v11, v5, v8
	v_med3_f32 v5, v12, s47, v173
	v_med3_f32 v8, v13, s47, v173
	v_cvt_pk_fp8_f32 v11, v5, v8 op_sel:[0,0,1]
	v_ashrrev_i32_e32 v7, 31, v6
	v_lshlrev_b64 v[6:7], 10, v[6:7]
	v_lshl_add_u64 v[6:7], s[14:15], 0, v[6:7]
	v_lshl_add_u64 v[6:7], v[6:7], 0, v[2:3]
	global_store_dwordx2 v[6:7], v[10:11], off
	v_pk_mul_f32 v[10:11], v[118:119], s[18:19] op_sel_hi:[1,0]
	v_pk_mul_f32 v[8:9], v[120:121], s[18:19] op_sel_hi:[1,0]
	v_med3_f32 v5, v10, s47, v173
	v_med3_f32 v11, v11, s47, v173
	v_mov_b32_e32 v10, 0
	v_cvt_pk_fp8_f32 v10, v5, v11
	v_pk_mul_f32 v[14:15], v[114:115], s[18:19] op_sel_hi:[1,0]
	v_med3_f32 v5, v8, s47, v173
	v_med3_f32 v8, v9, s47, v173
	v_cvt_pk_fp8_f32 v10, v5, v8 op_sel:[0,0,1]
	v_med3_f32 v5, v14, s47, v173
	v_med3_f32 v8, v15, s47, v173
	v_mov_b32_e32 v11, 0
	v_cvt_pk_fp8_f32 v11, v5, v8
	v_pk_mul_f32 v[12:13], v[116:117], s[18:19] op_sel_hi:[1,0]
	v_pk_mul_f32 v[14:15], v[106:107], s[18:19] op_sel_hi:[1,0]
	v_med3_f32 v5, v12, s47, v173
	v_med3_f32 v8, v13, s47, v173
	v_cvt_pk_fp8_f32 v11, v5, v8 op_sel:[0,0,1]
	v_pk_mul_f32 v[8:9], v[112:113], s[18:19] op_sel_hi:[1,0]
	v_pk_mul_f32 v[12:13], v[108:109], s[18:19] op_sel_hi:[1,0]
	s_mov_b32 s48, s20
	global_store_dwordx2 v[6:7], v[10:11], off offset:128
	v_pk_mul_f32 v[10:11], v[110:111], s[18:19] op_sel_hi:[1,0]
	v_add_u32_e32 v6, 32, v4
	v_med3_f32 v5, v10, s47, v173
	v_med3_f32 v11, v11, s47, v173
	v_mov_b32_e32 v10, 0
	v_cvt_pk_fp8_f32 v10, v5, v11
	v_med3_f32 v5, v8, s47, v173
	v_med3_f32 v8, v9, s47, v173
	v_mov_b32_e32 v11, 0
	v_cvt_pk_fp8_f32 v10, v5, v8 op_sel:[0,0,1]
	v_med3_f32 v5, v14, s47, v173
	v_med3_f32 v8, v15, s47, v173
	v_cvt_pk_fp8_f32 v11, v5, v8
	v_med3_f32 v5, v12, s47, v173
	v_med3_f32 v8, v13, s47, v173
	v_cvt_pk_fp8_f32 v11, v5, v8 op_sel:[0,0,1]
	v_ashrrev_i32_e32 v7, 31, v6
	v_lshlrev_b64 v[6:7], 10, v[6:7]
	v_lshl_add_u64 v[6:7], s[14:15], 0, v[6:7]
	v_lshl_add_u64 v[6:7], v[6:7], 0, v[2:3]
	global_store_dwordx2 v[6:7], v[10:11], off
	v_pk_mul_f32 v[10:11], v[102:103], s[18:19] op_sel_hi:[1,0]
	v_pk_mul_f32 v[8:9], v[104:105], s[18:19] op_sel_hi:[1,0]
	v_med3_f32 v5, v10, s47, v173
	v_med3_f32 v11, v11, s47, v173
	v_mov_b32_e32 v10, 0
	v_cvt_pk_fp8_f32 v10, v5, v11
	v_pk_mul_f32 v[14:15], v[98:99], s[18:19] op_sel_hi:[1,0]
	v_med3_f32 v5, v8, s47, v173
	v_med3_f32 v8, v9, s47, v173
	v_cvt_pk_fp8_f32 v10, v5, v8 op_sel:[0,0,1]
	v_med3_f32 v5, v14, s47, v173
	v_med3_f32 v8, v15, s47, v173
	v_mov_b32_e32 v11, 0
	v_cvt_pk_fp8_f32 v11, v5, v8
	v_pk_mul_f32 v[12:13], v[100:101], s[18:19] op_sel_hi:[1,0]
	v_pk_mul_f32 v[14:15], v[90:91], s[18:19] op_sel_hi:[1,0]
	v_med3_f32 v5, v12, s47, v173
	v_med3_f32 v8, v13, s47, v173
	v_cvt_pk_fp8_f32 v11, v5, v8 op_sel:[0,0,1]
	v_pk_mul_f32 v[8:9], v[96:97], s[18:19] op_sel_hi:[1,0]
	v_pk_mul_f32 v[12:13], v[92:93], s[18:19] op_sel_hi:[1,0]
	s_mov_b32 s28, s22
	global_store_dwordx2 v[6:7], v[10:11], off offset:128
	v_pk_mul_f32 v[10:11], v[94:95], s[18:19] op_sel_hi:[1,0]
	v_add_u32_e32 v6, 48, v4
	v_med3_f32 v5, v10, s47, v173
	v_med3_f32 v11, v11, s47, v173
	v_mov_b32_e32 v10, 0
	v_cvt_pk_fp8_f32 v10, v5, v11
	v_med3_f32 v5, v8, s47, v173
	v_med3_f32 v8, v9, s47, v173
	v_mov_b32_e32 v11, 0
	v_cvt_pk_fp8_f32 v10, v5, v8 op_sel:[0,0,1]
	v_med3_f32 v5, v14, s47, v173
	v_med3_f32 v8, v15, s47, v173
	v_cvt_pk_fp8_f32 v11, v5, v8
	v_med3_f32 v5, v12, s47, v173
	v_med3_f32 v8, v13, s47, v173
	v_cvt_pk_fp8_f32 v11, v5, v8 op_sel:[0,0,1]
	v_ashrrev_i32_e32 v7, 31, v6
	v_lshlrev_b64 v[6:7], 10, v[6:7]
	v_lshl_add_u64 v[6:7], s[14:15], 0, v[6:7]
	v_lshl_add_u64 v[6:7], v[6:7], 0, v[2:3]
	global_store_dwordx2 v[6:7], v[10:11], off
	v_pk_mul_f32 v[10:11], v[86:87], s[18:19] op_sel_hi:[1,0]
	v_pk_mul_f32 v[8:9], v[88:89], s[18:19] op_sel_hi:[1,0]
	v_med3_f32 v5, v10, s47, v173
	v_med3_f32 v11, v11, s47, v173
	v_mov_b32_e32 v10, 0
	v_cvt_pk_fp8_f32 v10, v5, v11
	v_pk_mul_f32 v[14:15], v[82:83], s[18:19] op_sel_hi:[1,0]
	v_med3_f32 v5, v8, s47, v173
	v_med3_f32 v8, v9, s47, v173
	v_cvt_pk_fp8_f32 v10, v5, v8 op_sel:[0,0,1]
	v_med3_f32 v5, v14, s47, v173
	v_med3_f32 v8, v15, s47, v173
	v_mov_b32_e32 v11, 0
	v_cvt_pk_fp8_f32 v11, v5, v8
	v_pk_mul_f32 v[12:13], v[84:85], s[18:19] op_sel_hi:[1,0]
	v_pk_mul_f32 v[14:15], v[74:75], s[18:19] op_sel_hi:[1,0]
	v_med3_f32 v5, v12, s47, v173
	v_med3_f32 v8, v13, s47, v173
	v_cvt_pk_fp8_f32 v11, v5, v8 op_sel:[0,0,1]
	v_pk_mul_f32 v[8:9], v[80:81], s[18:19] op_sel_hi:[1,0]
	v_pk_mul_f32 v[12:13], v[76:77], s[18:19] op_sel_hi:[1,0]
	s_mov_b64 s[30:31], s[26:27]
	global_store_dwordx2 v[6:7], v[10:11], off offset:128
	v_pk_mul_f32 v[10:11], v[78:79], s[18:19] op_sel_hi:[1,0]
	v_add_u32_e32 v6, 0x80, v4
	v_med3_f32 v5, v10, s47, v173
	v_med3_f32 v11, v11, s47, v173
	v_mov_b32_e32 v10, 0
	v_cvt_pk_fp8_f32 v10, v5, v11
	v_med3_f32 v5, v8, s47, v173
	v_med3_f32 v8, v9, s47, v173
	v_mov_b32_e32 v11, 0
	v_cvt_pk_fp8_f32 v10, v5, v8 op_sel:[0,0,1]
	v_med3_f32 v5, v14, s47, v173
	v_med3_f32 v8, v15, s47, v173
	v_cvt_pk_fp8_f32 v11, v5, v8
	v_med3_f32 v5, v12, s47, v173
	v_med3_f32 v8, v13, s47, v173
	v_cvt_pk_fp8_f32 v11, v5, v8 op_sel:[0,0,1]
	v_ashrrev_i32_e32 v7, 31, v6
	v_lshlrev_b64 v[6:7], 10, v[6:7]
	v_lshl_add_u64 v[6:7], s[14:15], 0, v[6:7]
	v_lshl_add_u64 v[6:7], v[6:7], 0, v[2:3]
	global_store_dwordx2 v[6:7], v[10:11], off
	v_pk_mul_f32 v[10:11], v[70:71], s[18:19] op_sel_hi:[1,0]
	v_pk_mul_f32 v[8:9], v[72:73], s[18:19] op_sel_hi:[1,0]
	v_med3_f32 v5, v10, s47, v173
	v_med3_f32 v11, v11, s47, v173
	v_mov_b32_e32 v10, 0
	v_cvt_pk_fp8_f32 v10, v5, v11
	v_pk_mul_f32 v[14:15], v[66:67], s[18:19] op_sel_hi:[1,0]
	v_med3_f32 v5, v8, s47, v173
	v_med3_f32 v8, v9, s47, v173
	v_cvt_pk_fp8_f32 v10, v5, v8 op_sel:[0,0,1]
	v_med3_f32 v5, v14, s47, v173
	v_med3_f32 v8, v15, s47, v173
	v_mov_b32_e32 v11, 0
	v_cvt_pk_fp8_f32 v11, v5, v8
	v_pk_mul_f32 v[12:13], v[68:69], s[18:19] op_sel_hi:[1,0]
	v_pk_mul_f32 v[14:15], v[58:59], s[18:19] op_sel_hi:[1,0]
	v_med3_f32 v5, v12, s47, v173
	v_med3_f32 v8, v13, s47, v173
	v_cvt_pk_fp8_f32 v11, v5, v8 op_sel:[0,0,1]
	v_pk_mul_f32 v[8:9], v[64:65], s[18:19] op_sel_hi:[1,0]
	v_pk_mul_f32 v[12:13], v[60:61], s[18:19] op_sel_hi:[1,0]
	s_mov_b64 s[34:35], s[24:25]
	global_store_dwordx2 v[6:7], v[10:11], off offset:128
	v_pk_mul_f32 v[10:11], v[62:63], s[18:19] op_sel_hi:[1,0]
	v_add_u32_e32 v6, 0x90, v4
	v_med3_f32 v5, v10, s47, v173
	v_med3_f32 v11, v11, s47, v173
	v_mov_b32_e32 v10, 0
	v_cvt_pk_fp8_f32 v10, v5, v11
	v_med3_f32 v5, v8, s47, v173
	v_med3_f32 v8, v9, s47, v173
	v_mov_b32_e32 v11, 0
	v_cvt_pk_fp8_f32 v10, v5, v8 op_sel:[0,0,1]
	v_med3_f32 v5, v14, s47, v173
	v_med3_f32 v8, v15, s47, v173
	v_cvt_pk_fp8_f32 v11, v5, v8
	v_med3_f32 v5, v12, s47, v173
	v_med3_f32 v8, v13, s47, v173
	v_cvt_pk_fp8_f32 v11, v5, v8 op_sel:[0,0,1]
	v_ashrrev_i32_e32 v7, 31, v6
	v_lshlrev_b64 v[6:7], 10, v[6:7]
	v_lshl_add_u64 v[6:7], s[14:15], 0, v[6:7]
	v_lshl_add_u64 v[6:7], v[6:7], 0, v[2:3]
	global_store_dwordx2 v[6:7], v[10:11], off
	v_pk_mul_f32 v[10:11], v[54:55], s[18:19] op_sel_hi:[1,0]
	v_pk_mul_f32 v[8:9], v[56:57], s[18:19] op_sel_hi:[1,0]
	v_med3_f32 v5, v10, s47, v173
	v_med3_f32 v11, v11, s47, v173
	v_mov_b32_e32 v10, 0
	v_cvt_pk_fp8_f32 v10, v5, v11
	v_pk_mul_f32 v[14:15], v[50:51], s[18:19] op_sel_hi:[1,0]
	v_med3_f32 v5, v8, s47, v173
	v_med3_f32 v8, v9, s47, v173
	v_cvt_pk_fp8_f32 v10, v5, v8 op_sel:[0,0,1]
	v_med3_f32 v5, v14, s47, v173
	v_med3_f32 v8, v15, s47, v173
	v_mov_b32_e32 v11, 0
	v_cvt_pk_fp8_f32 v11, v5, v8
	v_pk_mul_f32 v[12:13], v[52:53], s[18:19] op_sel_hi:[1,0]
	v_pk_mul_f32 v[14:15], v[42:43], s[18:19] op_sel_hi:[1,0]
	v_med3_f32 v5, v12, s47, v173
	v_med3_f32 v8, v13, s47, v173
	v_cvt_pk_fp8_f32 v11, v5, v8 op_sel:[0,0,1]
	v_pk_mul_f32 v[8:9], v[48:49], s[18:19] op_sel_hi:[1,0]
	v_pk_mul_f32 v[12:13], v[44:45], s[18:19] op_sel_hi:[1,0]
	global_store_dwordx2 v[6:7], v[10:11], off offset:128
	v_pk_mul_f32 v[10:11], v[46:47], s[18:19] op_sel_hi:[1,0]
	v_add_u32_e32 v6, 0xa0, v4
	v_med3_f32 v5, v10, s47, v173
	v_med3_f32 v11, v11, s47, v173
	v_mov_b32_e32 v10, 0
	v_cvt_pk_fp8_f32 v10, v5, v11
	v_med3_f32 v5, v8, s47, v173
	v_med3_f32 v8, v9, s47, v173
	v_mov_b32_e32 v11, 0
	v_cvt_pk_fp8_f32 v10, v5, v8 op_sel:[0,0,1]
	v_med3_f32 v5, v14, s47, v173
	v_med3_f32 v8, v15, s47, v173
	v_cvt_pk_fp8_f32 v11, v5, v8
	v_med3_f32 v5, v12, s47, v173
	v_med3_f32 v8, v13, s47, v173
	v_cvt_pk_fp8_f32 v11, v5, v8 op_sel:[0,0,1]
	v_ashrrev_i32_e32 v7, 31, v6
	v_lshlrev_b64 v[6:7], 10, v[6:7]
	v_lshl_add_u64 v[6:7], s[14:15], 0, v[6:7]
	v_lshl_add_u64 v[6:7], v[6:7], 0, v[2:3]
	global_store_dwordx2 v[6:7], v[10:11], off
	v_pk_mul_f32 v[10:11], v[38:39], s[18:19] op_sel_hi:[1,0]
	v_pk_mul_f32 v[8:9], v[40:41], s[18:19] op_sel_hi:[1,0]
	v_med3_f32 v5, v10, s47, v173
	v_med3_f32 v11, v11, s47, v173
	v_mov_b32_e32 v10, 0
	v_cvt_pk_fp8_f32 v10, v5, v11
	v_pk_mul_f32 v[14:15], v[34:35], s[18:19] op_sel_hi:[1,0]
	v_med3_f32 v5, v8, s47, v173
	v_med3_f32 v8, v9, s47, v173
	v_cvt_pk_fp8_f32 v10, v5, v8 op_sel:[0,0,1]
	v_med3_f32 v5, v14, s47, v173
	v_med3_f32 v8, v15, s47, v173
	v_mov_b32_e32 v11, 0
	v_cvt_pk_fp8_f32 v11, v5, v8
	v_pk_mul_f32 v[12:13], v[36:37], s[18:19] op_sel_hi:[1,0]
	v_add_u32_e32 v4, 0xb0, v4
	v_med3_f32 v5, v12, s47, v173
	v_med3_f32 v8, v13, s47, v173
	v_cvt_pk_fp8_f32 v11, v5, v8 op_sel:[0,0,1]
	v_pk_mul_f32 v[8:9], v[28:29], s[18:19] op_sel_hi:[1,0]
	global_store_dwordx2 v[6:7], v[10:11], off offset:128
	v_pk_mul_f32 v[6:7], v[30:31], s[18:19] op_sel_hi:[1,0]
	v_pk_mul_f32 v[10:11], v[26:27], s[18:19] op_sel_hi:[1,0]
	v_ashrrev_i32_e32 v5, 31, v4
	v_med3_f32 v12, v6, s47, v173
	v_med3_f32 v7, v7, s47, v173
	v_mov_b32_e32 v6, 0
	v_lshlrev_b64 v[4:5], 10, v[4:5]
	v_cvt_pk_fp8_f32 v6, v12, v7
	v_lshl_add_u64 v[4:5], s[14:15], 0, v[4:5]
	v_lshl_add_u64 v[2:3], v[4:5], 0, v[2:3]
	v_pk_mul_f32 v[4:5], v[32:33], s[18:19] op_sel_hi:[1,0]
	v_mov_b32_e32 v7, 0
	v_med3_f32 v4, v4, s47, v173
	v_med3_f32 v5, v5, s47, v173
	v_cvt_pk_fp8_f32 v6, v4, v5 op_sel:[0,0,1]
	v_med3_f32 v4, v10, s47, v173
	v_med3_f32 v5, v11, s47, v173
	v_cvt_pk_fp8_f32 v7, v4, v5
	v_med3_f32 v4, v8, s47, v173
	v_med3_f32 v5, v9, s47, v173
	v_pk_mul_f32 v[10:11], v[18:19], s[18:19] op_sel_hi:[1,0]
	v_cvt_pk_fp8_f32 v7, v4, v5 op_sel:[0,0,1]
	v_pk_mul_f32 v[4:5], v[24:25], s[18:19] op_sel_hi:[1,0]
	v_pk_mul_f32 v[8:9], v[20:21], s[18:19] op_sel_hi:[1,0]
	v_med3_f32 v4, v4, s47, v173
	global_store_dwordx2 v[2:3], v[6:7], off
	v_pk_mul_f32 v[6:7], v[22:23], s[18:19] op_sel_hi:[1,0]
	v_med3_f32 v5, v5, s47, v173
	v_med3_f32 v12, v6, s47, v173
	v_med3_f32 v7, v7, s47, v173
	v_mov_b32_e32 v6, 0
	v_cvt_pk_fp8_f32 v6, v12, v7
	v_mov_b32_e32 v7, 0
	v_cvt_pk_fp8_f32 v6, v4, v5 op_sel:[0,0,1]
	v_med3_f32 v4, v10, s47, v173
	v_med3_f32 v5, v11, s47, v173
	v_cvt_pk_fp8_f32 v7, v4, v5
	v_med3_f32 v4, v8, s47, v173
	v_med3_f32 v5, v9, s47, v173
	v_cvt_pk_fp8_f32 v7, v4, v5 op_sel:[0,0,1]
	global_store_dwordx2 v[2:3], v[6:7], off offset:128
	s_cbranch_vccz .LBB0_2101
	s_waitcnt vmcnt(0)
	s_cmpk_gt_u32 s4, 0xff
	s_cbranch_scc1 .LBB0_2112
	s_barrier

.LBB0_2244:
	s_add_i32 s50, s50, 1
	s_mov_b64 s[0:1], s[16:17]
	s_mul_hi_u32 s16, s50, 0xaaaaaaab
	s_lshr_b32 s16, s16, 1
	s_mul_i32 s17, s16, s74
	s_mov_b64 s[30:31], s[28:29]
	s_mov_b32 s29, s51
	s_add_i32 s51, s17, s2
	s_cmpk_lt_i32 s51, 0x100
	s_cselect_b64 s[34:35], -1, 0
	s_cmpk_gt_i32 s51, 0xff
	s_mul_i32 s16, s16, 3
	s_mov_b32 s28, s52
	s_cselect_b64 s[26:27], -1, 0
	s_sub_i32 s52, s50, s16
	s_and_b64 s[16:17], s[34:35], exec
	s_cselect_b32 s16, s51, s29
	s_cselect_b32 s28, s52, s28
	s_ashr_i32 s17, s16, 31
	s_lshl_b64 s[16:17], s[16:17], 19
	s_add_u32 s16, s6, s16
	s_addc_u32 s17, s7, s17
	s_and_b64 s[36:37], s[34:35], exec
	s_cselect_b32 s55, s17, s1
	s_cselect_b32 s56, s16, s0
	s_ashr_i32 s29, s28, 31
	s_lshl_b64 s[28:29], s[28:29], 19
	s_add_u32 s28, s10, s28
	s_addc_u32 s29, s11, s29
	s_and_b64 s[34:35], s[34:35], exec
	s_cselect_b32 s57, s29, s31
	s_cselect_b32 s58, s28, s30
	s_add_u32 s59, s30, 0x100
	s_addc_u32 s60, s31, 0
	s_add_u32 s30, s0, 0x40080
	s_addc_u32 s31, s1, 0
	s_mov_b32 s61, -2
	ds_read_b128 v[150:153], v146
	ds_read_b128 v[154:157], v146 offset:1024
	ds_read_b128 v[158:161], v146 offset:2048
	ds_read_b128 v[162:165], v146 offset:3072
	s_add_u32 s0, s30, 0xfffc0080
	s_addc_u32 s1, s31, -1
	s_cmp_eq_u32 s61, 12
	s_cselect_b32 s37, s55, s1
	s_cselect_b32 s36, s56, s0
	s_cselect_b32 s35, s57, s60
	s_cselect_b32 s34, s58, s59
	s_mov_b32 m0, s46
	v_lshl_add_u64 v[198:199], s[30:31], 0, v[140:141]
	ds_read_b128 v[166:169], v147
	ds_read_b128 v[170:173], v147 offset:1024
	ds_read_b128 v[174:177], v147 offset:2048
	ds_read_b128 v[178:181], v147 offset:3072
	ds_read_b128 v[182:185], v147 offset:4096
	ds_read_b128 v[186:189], v147 offset:5120
	ds_read_b128 v[190:193], v147 offset:6144
	ds_read_b128 v[194:197], v147 offset:7168
	global_load_lds_dwordx4 v[198:199], off
	v_lshl_add_u64 v[198:199], s[30:31], 0, v[138:139]
	s_mov_b32 m0, s47
	s_nop 0
	global_load_lds_dwordx4 v[198:199], off
	s_waitcnt lgkmcnt(8)
	s_waitcnt vmcnt(10)
	s_barrier
	s_waitcnt lgkmcnt(0)
	s_waitcnt lgkmcnt(0)
	v_mfma_f32_16x16x32_bf16 v[126:129], v[150:153], v[166:169], 0
	v_mfma_f32_16x16x32_bf16 v[122:125], v[158:161], v[166:169], 0
	v_mfma_f32_16x16x32_bf16 v[118:121], v[150:153], v[174:177], 0
	v_mfma_f32_16x16x32_bf16 v[114:117], v[158:161], v[174:177], 0
	v_mfma_f32_16x16x32_bf16 v[102:105], v[150:153], v[182:185], 0
	v_mfma_f32_16x16x32_bf16 v[98:101], v[158:161], v[182:185], 0
	v_mfma_f32_16x16x32_bf16 v[86:89], v[150:153], v[190:193], 0
	v_mfma_f32_16x16x32_bf16 v[82:85], v[158:161], v[190:193], 0
	v_mfma_f32_16x16x32_bf16 v[126:129], v[154:157], v[170:173], v[126:129]
	v_mfma_f32_16x16x32_bf16 v[122:125], v[162:165], v[170:173], v[122:125]
	v_mfma_f32_16x16x32_bf16 v[118:121], v[154:157], v[178:181], v[118:121]
	v_mfma_f32_16x16x32_bf16 v[114:117], v[162:165], v[178:181], v[114:117]
	v_mfma_f32_16x16x32_bf16 v[102:105], v[154:157], v[186:189], v[102:105]
	v_mfma_f32_16x16x32_bf16 v[98:101], v[162:165], v[186:189], v[98:101]
	v_mfma_f32_16x16x32_bf16 v[86:89], v[154:157], v[194:197], v[86:89]
	v_mfma_f32_16x16x32_bf16 v[82:85], v[162:165], v[194:197], v[82:85]
	s_barrier
	s_mov_b32 m0, s48
	v_lshl_add_u64 v[214:215], s[34:35], 0, v[134:135]
	ds_read_b128 v[198:201], v148
	ds_read_b128 v[202:205], v148 offset:1024
	ds_read_b128 v[206:209], v148 offset:2048
	ds_read_b128 v[210:213], v148 offset:3072
	global_load_lds_dwordx4 v[214:215], off
	v_lshl_add_u64 v[216:217], s[34:35], 0, v[130:131]
	s_mov_b32 m0, s49
	s_nop 0
	global_load_lds_dwordx4 v[216:217], off
	s_waitcnt vmcnt(10)
	s_barrier
	s_waitcnt lgkmcnt(0)
	s_waitcnt lgkmcnt(0)
	v_mfma_f32_16x16x32_bf16 v[110:113], v[198:201], v[166:169], 0
	v_mfma_f32_16x16x32_bf16 v[106:109], v[206:209], v[166:169], 0
	v_mfma_f32_16x16x32_bf16 v[94:97], v[198:201], v[174:177], 0
	v_mfma_f32_16x16x32_bf16 v[90:93], v[206:209], v[174:177], 0
	v_mfma_f32_16x16x32_bf16 v[78:81], v[198:201], v[182:185], 0
	v_mfma_f32_16x16x32_bf16 v[74:77], v[206:209], v[182:185], 0
	v_mfma_f32_16x16x32_bf16 v[70:73], v[198:201], v[190:193], 0
	v_mfma_f32_16x16x32_bf16 v[66:69], v[206:209], v[190:193], 0
	v_mfma_f32_16x16x32_bf16 v[110:113], v[202:205], v[170:173], v[110:113]
	v_mfma_f32_16x16x32_bf16 v[106:109], v[210:213], v[170:173], v[106:109]
	v_mfma_f32_16x16x32_bf16 v[94:97], v[202:205], v[178:181], v[94:97]
	v_mfma_f32_16x16x32_bf16 v[90:93], v[210:213], v[178:181], v[90:93]
	v_mfma_f32_16x16x32_bf16 v[78:81], v[202:205], v[186:189], v[78:81]
	v_mfma_f32_16x16x32_bf16 v[74:77], v[210:213], v[186:189], v[74:77]
	v_mfma_f32_16x16x32_bf16 v[70:73], v[202:205], v[194:197], v[70:73]
	v_mfma_f32_16x16x32_bf16 v[66:69], v[210:213], v[194:197], v[66:69]
	s_mov_b32 m0, s9
	v_lshl_add_u64 v[218:219], s[36:37], 0, v[136:137]
	s_barrier
	ds_read_b128 v[166:169], v147 offset:16384
	ds_read_b128 v[170:173], v147 offset:17408
	ds_read_b128 v[174:177], v147 offset:18432
	ds_read_b128 v[178:181], v147 offset:19456
	ds_read_b128 v[182:185], v147 offset:20480
	ds_read_b128 v[186:189], v147 offset:21504
	ds_read_b128 v[190:193], v147 offset:22528
	ds_read_b128 v[194:197], v147 offset:23552
	global_load_lds_dwordx4 v[218:219], off
	v_lshl_add_u64 v[220:221], s[36:37], 0, v[132:133]
	s_mov_b32 m0, s21
	s_nop 0
	global_load_lds_dwordx4 v[220:221], off
	s_waitcnt vmcnt(10)
	s_barrier
	s_waitcnt lgkmcnt(0)
	s_waitcnt lgkmcnt(0)
	v_mfma_f32_16x16x32_bf16 v[62:65], v[150:153], v[166:169], 0
	v_mfma_f32_16x16x32_bf16 v[58:61], v[158:161], v[166:169], 0
	v_mfma_f32_16x16x32_bf16 v[54:57], v[150:153], v[174:177], 0
	v_mfma_f32_16x16x32_bf16 v[50:53], v[158:161], v[174:177], 0
	v_mfma_f32_16x16x32_bf16 v[38:41], v[150:153], v[182:185], 0
	v_mfma_f32_16x16x32_bf16 v[34:37], v[158:161], v[182:185], 0
	v_mfma_f32_16x16x32_bf16 v[22:25], v[150:153], v[190:193], 0
	v_mfma_f32_16x16x32_bf16 v[18:21], v[158:161], v[190:193], 0
	v_mfma_f32_16x16x32_bf16 v[62:65], v[154:157], v[170:173], v[62:65]
	v_mfma_f32_16x16x32_bf16 v[58:61], v[162:165], v[170:173], v[58:61]
	v_mfma_f32_16x16x32_bf16 v[54:57], v[154:157], v[178:181], v[54:57]
	v_mfma_f32_16x16x32_bf16 v[50:53], v[162:165], v[178:181], v[50:53]
	v_mfma_f32_16x16x32_bf16 v[38:41], v[154:157], v[186:189], v[38:41]
	v_mfma_f32_16x16x32_bf16 v[34:37], v[162:165], v[186:189], v[34:37]
	v_mfma_f32_16x16x32_bf16 v[22:25], v[154:157], v[194:197], v[22:25]
	v_mfma_f32_16x16x32_bf16 v[18:21], v[162:165], v[194:197], v[18:21]
	s_barrier
	s_add_u32 s0, s34, 0x40000
	s_addc_u32 s1, s35, 0
	s_add_i32 s62, s44, s8
	v_lshl_add_u64 v[150:151], s[0:1], 0, v[134:135]
	s_mov_b32 m0, s62
	s_nop 0
	global_load_lds_dwordx4 v[150:151], off
	v_lshl_add_u64 v[150:151], s[0:1], 0, v[130:131]
	s_add_i32 m0, s62, 0x2000
	s_nop 0
	global_load_lds_dwordx4 v[150:151], off
	s_waitcnt vmcnt(10)
	s_barrier
	v_mfma_f32_16x16x32_bf16 v[46:49], v[198:201], v[166:169], 0
	v_mfma_f32_16x16x32_bf16 v[42:45], v[206:209], v[166:169], 0
	v_mfma_f32_16x16x32_bf16 v[30:33], v[198:201], v[174:177], 0
	v_mfma_f32_16x16x32_bf16 v[26:29], v[206:209], v[174:177], 0
	v_mfma_f32_16x16x32_bf16 v[14:17], v[198:201], v[182:185], 0
	v_mfma_f32_16x16x32_bf16 v[10:13], v[206:209], v[182:185], 0
	v_mfma_f32_16x16x32_bf16 v[6:9], v[198:201], v[190:193], 0
	v_mfma_f32_16x16x32_bf16 v[2:5], v[206:209], v[190:193], 0
	v_mfma_f32_16x16x32_bf16 v[46:49], v[202:205], v[170:173], v[46:49]
	v_mfma_f32_16x16x32_bf16 v[42:45], v[210:213], v[170:173], v[42:45]
	v_mfma_f32_16x16x32_bf16 v[30:33], v[202:205], v[178:181], v[30:33]
	v_mfma_f32_16x16x32_bf16 v[26:29], v[210:213], v[178:181], v[26:29]
	v_mfma_f32_16x16x32_bf16 v[14:17], v[202:205], v[186:189], v[14:17]
	v_mfma_f32_16x16x32_bf16 v[10:13], v[210:213], v[186:189], v[10:13]
	v_mfma_f32_16x16x32_bf16 v[6:9], v[202:205], v[194:197], v[6:9]
	v_mfma_f32_16x16x32_bf16 v[2:5], v[210:213], v[194:197], v[2:5]
	s_add_i32 s62, 0, 0x18000
	v_add_u32_e32 v149, s62, v145
	s_barrier
	ds_read_b128 v[150:153], v149
	ds_read_b128 v[154:157], v149 offset:1024
	ds_read_b128 v[158:161], v149 offset:2048
	ds_read_b128 v[162:165], v149 offset:3072
	s_add_u32 s0, s36, 0x40000
	s_addc_u32 s1, s37, 0
	s_mov_b32 m0, s38
	v_lshl_add_u64 v[198:199], s[0:1], 0, v[136:137]
	ds_read_b128 v[166:169], v147 offset:32768
	ds_read_b128 v[170:173], v147 offset:33792
	ds_read_b128 v[174:177], v147 offset:34816
	ds_read_b128 v[178:181], v147 offset:35840
	ds_read_b128 v[182:185], v147 offset:36864
	ds_read_b128 v[186:189], v147 offset:37888
	ds_read_b128 v[190:193], v147 offset:38912
	ds_read_b128 v[194:197], v147 offset:39936
	global_load_lds_dwordx4 v[198:199], off
	v_lshl_add_u64 v[198:199], s[0:1], 0, v[132:133]
	s_mov_b32 m0, s39
	s_nop 0
	global_load_lds_dwordx4 v[198:199], off
	s_waitcnt lgkmcnt(8)
	s_waitcnt vmcnt(10)
	s_barrier
	s_waitcnt lgkmcnt(0)
	s_waitcnt lgkmcnt(0)
	v_mfma_f32_16x16x32_bf16 v[126:129], v[150:153], v[166:169], v[126:129]
	v_mfma_f32_16x16x32_bf16 v[122:125], v[158:161], v[166:169], v[122:125]
	v_mfma_f32_16x16x32_bf16 v[118:121], v[150:153], v[174:177], v[118:121]
	v_mfma_f32_16x16x32_bf16 v[114:117], v[158:161], v[174:177], v[114:117]
	v_mfma_f32_16x16x32_bf16 v[102:105], v[150:153], v[182:185], v[102:105]
	v_mfma_f32_16x16x32_bf16 v[98:101], v[158:161], v[182:185], v[98:101]
	v_mfma_f32_16x16x32_bf16 v[86:89], v[150:153], v[190:193], v[86:89]
	v_mfma_f32_16x16x32_bf16 v[82:85], v[158:161], v[190:193], v[82:85]
	v_mfma_f32_16x16x32_bf16 v[126:129], v[154:157], v[170:173], v[126:129]
	v_mfma_f32_16x16x32_bf16 v[122:125], v[162:165], v[170:173], v[122:125]
	v_mfma_f32_16x16x32_bf16 v[118:121], v[154:157], v[178:181], v[118:121]
	v_mfma_f32_16x16x32_bf16 v[114:117], v[162:165], v[178:181], v[114:117]
	v_mfma_f32_16x16x32_bf16 v[102:105], v[154:157], v[186:189], v[102:105]
	v_mfma_f32_16x16x32_bf16 v[98:101], v[162:165], v[186:189], v[98:101]
	v_mfma_f32_16x16x32_bf16 v[86:89], v[154:157], v[194:197], v[86:89]
	v_mfma_f32_16x16x32_bf16 v[82:85], v[162:165], v[194:197], v[82:85]
	s_barrier
	s_add_i32 s36, 0, 0x1c000
	s_add_i32 s0, s62, s8
	v_add_u32_e32 v149, s36, v145
	v_lshl_add_u64 v[214:215], v[214:215], 0, s[24:25]
	s_mov_b32 m0, s0
	ds_read_b128 v[198:201], v149
	ds_read_b128 v[202:205], v149 offset:1024
	ds_read_b128 v[206:209], v149 offset:2048
	ds_read_b128 v[210:213], v149 offset:3072
	global_load_lds_dwordx4 v[214:215], off
	v_lshl_add_u64 v[214:215], v[216:217], 0, s[24:25]
	s_add_i32 m0, s0, 0x2000
	s_nop 0
	global_load_lds_dwordx4 v[214:215], off
	s_waitcnt vmcnt(10)
	s_barrier
	s_waitcnt lgkmcnt(0)
	s_waitcnt lgkmcnt(0)
	v_mfma_f32_16x16x32_bf16 v[110:113], v[198:201], v[166:169], v[110:113]
	v_mfma_f32_16x16x32_bf16 v[106:109], v[206:209], v[166:169], v[106:109]
	v_mfma_f32_16x16x32_bf16 v[94:97], v[198:201], v[174:177], v[94:97]
	v_mfma_f32_16x16x32_bf16 v[90:93], v[206:209], v[174:177], v[90:93]
	v_mfma_f32_16x16x32_bf16 v[78:81], v[198:201], v[182:185], v[78:81]
	v_mfma_f32_16x16x32_bf16 v[74:77], v[206:209], v[182:185], v[74:77]
	v_mfma_f32_16x16x32_bf16 v[70:73], v[198:201], v[190:193], v[70:73]
	v_mfma_f32_16x16x32_bf16 v[66:69], v[206:209], v[190:193], v[66:69]
	v_mfma_f32_16x16x32_bf16 v[110:113], v[202:205], v[170:173], v[110:113]
	v_mfma_f32_16x16x32_bf16 v[106:109], v[210:213], v[170:173], v[106:109]
	v_mfma_f32_16x16x32_bf16 v[94:97], v[202:205], v[178:181], v[94:97]
	v_mfma_f32_16x16x32_bf16 v[90:93], v[210:213], v[178:181], v[90:93]
	v_mfma_f32_16x16x32_bf16 v[78:81], v[202:205], v[186:189], v[78:81]
	v_mfma_f32_16x16x32_bf16 v[74:77], v[210:213], v[186:189], v[74:77]
	v_mfma_f32_16x16x32_bf16 v[70:73], v[202:205], v[194:197], v[70:73]
	v_mfma_f32_16x16x32_bf16 v[66:69], v[210:213], v[194:197], v[66:69]
	s_mov_b32 m0, s42
	v_lshl_add_u64 v[214:215], v[218:219], 0, s[24:25]
	s_barrier
	ds_read_b128 v[166:169], v147 offset:49152
	ds_read_b128 v[170:173], v147 offset:50176
	ds_read_b128 v[174:177], v147 offset:51200
	ds_read_b128 v[178:181], v147 offset:52224
	ds_read_b128 v[182:185], v147 offset:53248
	ds_read_b128 v[186:189], v147 offset:54272
	ds_read_b128 v[190:193], v147 offset:55296
	ds_read_b128 v[194:197], v147 offset:56320
	global_load_lds_dwordx4 v[214:215], off
	v_lshl_add_u64 v[214:215], v[220:221], 0, s[24:25]
	s_mov_b32 m0, s43
	s_nop 0
	global_load_lds_dwordx4 v[214:215], off
	s_waitcnt vmcnt(10)
	s_barrier
	s_waitcnt lgkmcnt(0)
	s_waitcnt lgkmcnt(0)
	v_mfma_f32_16x16x32_bf16 v[62:65], v[150:153], v[166:169], v[62:65]
	v_mfma_f32_16x16x32_bf16 v[58:61], v[158:161], v[166:169], v[58:61]
	v_mfma_f32_16x16x32_bf16 v[54:57], v[150:153], v[174:177], v[54:57]
	v_mfma_f32_16x16x32_bf16 v[50:53], v[158:161], v[174:177], v[50:53]
	v_mfma_f32_16x16x32_bf16 v[38:41], v[150:153], v[182:185], v[38:41]
	v_mfma_f32_16x16x32_bf16 v[34:37], v[158:161], v[182:185], v[34:37]
	v_mfma_f32_16x16x32_bf16 v[22:25], v[150:153], v[190:193], v[22:25]
	v_mfma_f32_16x16x32_bf16 v[18:21], v[158:161], v[190:193], v[18:21]
	v_mfma_f32_16x16x32_bf16 v[62:65], v[154:157], v[170:173], v[62:65]
	v_mfma_f32_16x16x32_bf16 v[58:61], v[162:165], v[170:173], v[58:61]
	v_mfma_f32_16x16x32_bf16 v[54:57], v[154:157], v[178:181], v[54:57]
	v_mfma_f32_16x16x32_bf16 v[50:53], v[162:165], v[178:181], v[50:53]
	v_mfma_f32_16x16x32_bf16 v[38:41], v[154:157], v[186:189], v[38:41]
	v_mfma_f32_16x16x32_bf16 v[34:37], v[162:165], v[186:189], v[34:37]
	v_mfma_f32_16x16x32_bf16 v[22:25], v[154:157], v[194:197], v[22:25]
	v_mfma_f32_16x16x32_bf16 v[18:21], v[162:165], v[194:197], v[18:21]
	s_barrier
	s_add_u32 s0, s34, 0x40080
	s_addc_u32 s1, s35, 0
	s_add_i32 s34, s36, s8
	v_lshl_add_u64 v[150:151], s[0:1], 0, v[134:135]
	s_mov_b32 m0, s34
	s_nop 0
	global_load_lds_dwordx4 v[150:151], off
	v_lshl_add_u64 v[150:151], s[0:1], 0, v[130:131]
	s_add_i32 m0, s34, 0x2000
	s_nop 0
	global_load_lds_dwordx4 v[150:151], off
	s_waitcnt vmcnt(10)
	s_barrier
	v_mfma_f32_16x16x32_bf16 v[46:49], v[198:201], v[166:169], v[46:49]
	v_mfma_f32_16x16x32_bf16 v[42:45], v[206:209], v[166:169], v[42:45]
	v_mfma_f32_16x16x32_bf16 v[30:33], v[198:201], v[174:177], v[30:33]
	v_mfma_f32_16x16x32_bf16 v[26:29], v[206:209], v[174:177], v[26:29]
	v_mfma_f32_16x16x32_bf16 v[14:17], v[198:201], v[182:185], v[14:17]
	v_mfma_f32_16x16x32_bf16 v[10:13], v[206:209], v[182:185], v[10:13]
	v_mfma_f32_16x16x32_bf16 v[6:9], v[198:201], v[190:193], v[6:9]
	v_mfma_f32_16x16x32_bf16 v[2:5], v[206:209], v[190:193], v[2:5]
	v_mfma_f32_16x16x32_bf16 v[46:49], v[202:205], v[170:173], v[46:49]
	v_mfma_f32_16x16x32_bf16 v[42:45], v[210:213], v[170:173], v[42:45]
	v_mfma_f32_16x16x32_bf16 v[30:33], v[202:205], v[178:181], v[30:33]
	v_mfma_f32_16x16x32_bf16 v[26:29], v[210:213], v[178:181], v[26:29]
	v_mfma_f32_16x16x32_bf16 v[14:17], v[202:205], v[186:189], v[14:17]
	v_mfma_f32_16x16x32_bf16 v[10:13], v[210:213], v[186:189], v[10:13]
	v_mfma_f32_16x16x32_bf16 v[6:9], v[202:205], v[194:197], v[6:9]
	v_mfma_f32_16x16x32_bf16 v[2:5], v[210:213], v[194:197], v[2:5]
	s_add_i32 s61, s61, 2
	s_add_u32 s59, s59, 0x100
	s_addc_u32 s60, s60, 0
	s_add_u32 s30, s30, 0x100
	s_addc_u32 s31, s31, 0
	s_cmp_gt_u32 s61, 13
	s_barrier
	s_cbranch_scc1 .Lpeel_exit_13

.Lpeel_exit_13:
	v_mov_b32_e32 v149, v143
	v_mov_b32_e32 v150, v144
	s_lshl_b32 s0, s53, 8
	s_or_b32 s0, s0, s41
	v_lshl_add_u32 v150, v150, 3, s0
	s_lshl_b32 s0, s54, 8
	s_add_i32 s0, s0, s40
	v_add_u32_e32 v149, s0, v149
	v_ashrrev_i32_e32 v151, 31, v150
	v_mov_b32_e32 v152, v149
	v_lshl_add_u64 v[150:151], v[150:151], 1, s[18:19]
	v_cvt_pk_bf16_f32 v126, v126, v127
	v_mad_i64_i32 v[152:153], s[0:1], v152, s45, v[150:151]
	v_cvt_pk_bf16_f32 v127, v128, v129
	v_cvt_pk_bf16_f32 v128, v122, v123
	v_cvt_pk_bf16_f32 v129, v124, v125
	v_cvt_pk_bf16_f32 v110, v110, v111
	v_cvt_pk_bf16_f32 v111, v112, v113
	v_cvt_pk_bf16_f32 v112, v106, v107
	v_cvt_pk_bf16_f32 v113, v108, v109
	v_add_u32_e32 v106, 16, v149
	global_store_dwordx4 v[152:153], v[126:129], off
	global_store_dwordx4 v[152:153], v[110:113], off offset:256
	v_cvt_pk_bf16_f32 v107, v120, v121
	v_cvt_pk_bf16_f32 v108, v114, v115
	v_mad_i64_i32 v[110:111], s[0:1], v106, s45, v[150:151]
	v_cvt_pk_bf16_f32 v106, v118, v119
	v_cvt_pk_bf16_f32 v109, v116, v117
	v_cvt_pk_bf16_f32 v94, v94, v95
	v_cvt_pk_bf16_f32 v95, v96, v97
	v_cvt_pk_bf16_f32 v96, v90, v91
	v_cvt_pk_bf16_f32 v97, v92, v93
	v_add_u32_e32 v90, 32, v149
	global_store_dwordx4 v[110:111], v[106:109], off
	global_store_dwordx4 v[110:111], v[94:97], off offset:256
	v_cvt_pk_bf16_f32 v91, v104, v105
	v_cvt_pk_bf16_f32 v92, v98, v99
	v_mad_i64_i32 v[94:95], s[0:1], v90, s45, v[150:151]
	v_cvt_pk_bf16_f32 v90, v102, v103
	v_cvt_pk_bf16_f32 v93, v100, v101
	v_cvt_pk_bf16_f32 v78, v78, v79
	v_cvt_pk_bf16_f32 v79, v80, v81
	v_cvt_pk_bf16_f32 v80, v74, v75
	v_cvt_pk_bf16_f32 v81, v76, v77
	v_add_u32_e32 v74, 48, v149
	global_store_dwordx4 v[94:95], v[90:93], off
	global_store_dwordx4 v[94:95], v[78:81], off offset:256
	v_cvt_pk_bf16_f32 v75, v88, v89
	v_cvt_pk_bf16_f32 v76, v82, v83
	v_mad_i64_i32 v[78:79], s[0:1], v74, s45, v[150:151]
	v_cvt_pk_bf16_f32 v74, v86, v87
	v_cvt_pk_bf16_f32 v77, v84, v85
	v_cvt_pk_bf16_f32 v70, v70, v71
	v_cvt_pk_bf16_f32 v71, v72, v73
	v_cvt_pk_bf16_f32 v72, v66, v67
	v_cvt_pk_bf16_f32 v73, v68, v69
	v_add_u32_e32 v66, 0x80, v149
	global_store_dwordx4 v[78:79], v[74:77], off
	global_store_dwordx4 v[78:79], v[70:73], off offset:256
	v_cvt_pk_bf16_f32 v62, v62, v63
	v_mad_i64_i32 v[66:67], s[0:1], v66, s45, v[150:151]
	v_cvt_pk_bf16_f32 v63, v64, v65
	v_cvt_pk_bf16_f32 v64, v58, v59
	v_cvt_pk_bf16_f32 v65, v60, v61
	v_cvt_pk_bf16_f32 v46, v46, v47
	v_cvt_pk_bf16_f32 v47, v48, v49
	v_cvt_pk_bf16_f32 v48, v42, v43
	v_cvt_pk_bf16_f32 v49, v44, v45
	v_add_u32_e32 v42, 0x90, v149
	global_store_dwordx4 v[66:67], v[62:65], off
	global_store_dwordx4 v[66:67], v[46:49], off offset:256
	v_cvt_pk_bf16_f32 v43, v56, v57
	v_cvt_pk_bf16_f32 v44, v50, v51
	v_mad_i64_i32 v[46:47], s[0:1], v42, s45, v[150:151]
	v_cvt_pk_bf16_f32 v42, v54, v55
	v_cvt_pk_bf16_f32 v45, v52, v53
	v_cvt_pk_bf16_f32 v30, v30, v31
	v_cvt_pk_bf16_f32 v31, v32, v33
	v_cvt_pk_bf16_f32 v32, v26, v27
	v_cvt_pk_bf16_f32 v33, v28, v29
	v_add_u32_e32 v26, 0xa0, v149
	global_store_dwordx4 v[46:47], v[42:45], off
	global_store_dwordx4 v[46:47], v[30:33], off offset:256
	v_cvt_pk_bf16_f32 v27, v40, v41
	v_cvt_pk_bf16_f32 v28, v34, v35
	v_mad_i64_i32 v[30:31], s[0:1], v26, s45, v[150:151]
	v_cvt_pk_bf16_f32 v26, v38, v39
	v_cvt_pk_bf16_f32 v29, v36, v37
	v_cvt_pk_bf16_f32 v14, v14, v15
	v_cvt_pk_bf16_f32 v15, v16, v17
	v_cvt_pk_bf16_f32 v16, v10, v11
	v_cvt_pk_bf16_f32 v17, v12, v13
	v_add_u32_e32 v10, 0xb0, v149
	global_store_dwordx4 v[30:31], v[26:29], off
	global_store_dwordx4 v[30:31], v[14:17], off offset:256
	v_cvt_pk_bf16_f32 v11, v24, v25
	v_cvt_pk_bf16_f32 v12, v18, v19
	v_mad_i64_i32 v[14:15], s[0:1], v10, s45, v[150:151]
	v_cvt_pk_bf16_f32 v10, v22, v23
	v_cvt_pk_bf16_f32 v13, v20, v21
	v_cvt_pk_bf16_f32 v6, v6, v7
	v_cvt_pk_bf16_f32 v7, v8, v9
	v_cvt_pk_bf16_f32 v8, v2, v3
	v_cvt_pk_bf16_f32 v9, v4, v5
	s_and_b64 vcc, exec, s[26:27]
	s_mov_b32 s53, s52
	s_mov_b32 s54, s51
	global_store_dwordx4 v[14:15], v[10:13], off
	global_store_dwordx4 v[14:15], v[6:9], off offset:256
	s_cbranch_vccz .LBB0_2244
	s_waitcnt vmcnt(0)
	s_cmpk_gt_u32 s5, 0xff
	s_cbranch_scc1 .LBB0_2249
	s_barrier

.LBB0_2324:
	s_add_u32 s20, s36, 0x100
	s_addc_u32 s58, s37, 0
	s_mov_b32 s59, -2
	ds_read_b128 v[130:133], v165
	ds_read_b128 v[134:137], v165 offset:1024
	ds_read_b128 v[154:157], v165 offset:2048
	ds_read_b128 v[158:161], v165 offset:3072
	s_add_u32 s36, s34, 0x100
	s_addc_u32 s37, s35, 0
	s_cmp_eq_u32 s59, 2
	s_cselect_b32 s41, s13, s37
	s_cselect_b32 s40, s12, s36
	s_cselect_b32 s39, s15, s58
	s_cselect_b32 s38, s14, s20
	v_lshl_add_u64 v[202:203], s[34:35], 0, v[148:149]
	s_add_i32 m0, s17, 0xc000
	ds_read_b128 v[170:173], v166
	ds_read_b128 v[174:177], v166 offset:1024
	ds_read_b128 v[178:181], v166 offset:2048
	ds_read_b128 v[182:185], v166 offset:3072
	ds_read_b128 v[186:189], v166 offset:4096
	ds_read_b128 v[190:193], v166 offset:5120
	ds_read_b128 v[194:197], v166 offset:6144
	ds_read_b128 v[198:201], v166 offset:7168
	global_load_lds_dwordx4 v[202:203], off
	v_lshl_add_u64 v[202:203], s[34:35], 0, v[146:147]
	s_add_i32 m0, s17, 0xe000
	s_nop 0
	global_load_lds_dwordx4 v[202:203], off
	s_waitcnt lgkmcnt(8)
	s_waitcnt vmcnt(10)
	s_barrier
	s_waitcnt lgkmcnt(0)
	s_waitcnt lgkmcnt(0)
	v_mfma_f32_16x16x32_bf16 v[126:129], v[130:133], v[170:173], 0
	v_mfma_f32_16x16x32_bf16 v[122:125], v[154:157], v[170:173], 0
	v_mfma_f32_16x16x32_bf16 v[114:117], v[130:133], v[178:181], 0
	v_mfma_f32_16x16x32_bf16 v[106:109], v[154:157], v[178:181], 0
	v_mfma_f32_16x16x32_bf16 v[98:101], v[130:133], v[186:189], 0
	v_mfma_f32_16x16x32_bf16 v[90:93], v[154:157], v[186:189], 0
	v_mfma_f32_16x16x32_bf16 v[82:85], v[130:133], v[194:197], 0
	v_mfma_f32_16x16x32_bf16 v[74:77], v[154:157], v[194:197], 0
	v_mfma_f32_16x16x32_bf16 v[126:129], v[134:137], v[174:177], v[126:129]
	v_mfma_f32_16x16x32_bf16 v[122:125], v[158:161], v[174:177], v[122:125]
	v_mfma_f32_16x16x32_bf16 v[114:117], v[134:137], v[182:185], v[114:117]
	v_mfma_f32_16x16x32_bf16 v[106:109], v[158:161], v[182:185], v[106:109]
	v_mfma_f32_16x16x32_bf16 v[98:101], v[134:137], v[190:193], v[98:101]
	v_mfma_f32_16x16x32_bf16 v[90:93], v[158:161], v[190:193], v[90:93]
	v_mfma_f32_16x16x32_bf16 v[82:85], v[134:137], v[198:201], v[82:85]
	v_mfma_f32_16x16x32_bf16 v[74:77], v[158:161], v[198:201], v[74:77]
	s_barrier
	s_add_i32 s0, s49, s8
	v_lshl_add_u64 v[218:219], s[38:39], 0, v[142:143]
	s_mov_b32 m0, s0
	ds_read_b128 v[202:205], v167
	ds_read_b128 v[206:209], v167 offset:1024
	ds_read_b128 v[210:213], v167 offset:2048
	ds_read_b128 v[214:217], v167 offset:3072
	global_load_lds_dwordx4 v[218:219], off
	v_lshl_add_u64 v[220:221], s[38:39], 0, v[138:139]
	s_add_i32 m0, s0, 0x2000
	s_nop 0
	global_load_lds_dwordx4 v[220:221], off
	s_waitcnt vmcnt(10)
	s_barrier
	s_waitcnt lgkmcnt(0)
	s_waitcnt lgkmcnt(0)
	v_mfma_f32_16x16x32_bf16 v[118:121], v[202:205], v[170:173], 0
	v_mfma_f32_16x16x32_bf16 v[110:113], v[210:213], v[170:173], 0
	v_mfma_f32_16x16x32_bf16 v[102:105], v[202:205], v[178:181], 0
	v_mfma_f32_16x16x32_bf16 v[94:97], v[210:213], v[178:181], 0
	v_mfma_f32_16x16x32_bf16 v[86:89], v[202:205], v[186:189], 0
	v_mfma_f32_16x16x32_bf16 v[78:81], v[210:213], v[186:189], 0
	v_mfma_f32_16x16x32_bf16 v[70:73], v[202:205], v[194:197], 0
	v_mfma_f32_16x16x32_bf16 v[66:69], v[210:213], v[194:197], 0
	v_mfma_f32_16x16x32_bf16 v[118:121], v[206:209], v[174:177], v[118:121]
	v_mfma_f32_16x16x32_bf16 v[110:113], v[214:217], v[174:177], v[110:113]
	v_mfma_f32_16x16x32_bf16 v[102:105], v[206:209], v[182:185], v[102:105]
	v_mfma_f32_16x16x32_bf16 v[94:97], v[214:217], v[182:185], v[94:97]
	v_mfma_f32_16x16x32_bf16 v[86:89], v[206:209], v[190:193], v[86:89]
	v_mfma_f32_16x16x32_bf16 v[78:81], v[214:217], v[190:193], v[78:81]
	v_mfma_f32_16x16x32_bf16 v[70:73], v[206:209], v[198:201], v[70:73]
	v_mfma_f32_16x16x32_bf16 v[66:69], v[214:217], v[198:201], v[66:69]
	s_mov_b32 m0, s17
	v_lshl_add_u64 v[222:223], s[40:41], 0, v[144:145]
	s_barrier
	ds_read_b128 v[170:173], v166 offset:16384
	ds_read_b128 v[174:177], v166 offset:17408
	ds_read_b128 v[178:181], v166 offset:18432
	ds_read_b128 v[182:185], v166 offset:19456
	ds_read_b128 v[186:189], v166 offset:20480
	ds_read_b128 v[190:193], v166 offset:21504
	ds_read_b128 v[194:197], v166 offset:22528
	ds_read_b128 v[198:201], v166 offset:23552
	global_load_lds_dwordx4 v[222:223], off
	v_lshl_add_u64 v[224:225], s[40:41], 0, v[140:141]
	s_mov_b32 m0, s42
	s_nop 0
	global_load_lds_dwordx4 v[224:225], off
	s_waitcnt vmcnt(10)
	s_barrier
	s_waitcnt lgkmcnt(0)
	s_waitcnt lgkmcnt(0)
	v_mfma_f32_16x16x32_bf16 v[62:65], v[130:133], v[170:173], 0
	v_mfma_f32_16x16x32_bf16 v[58:61], v[154:157], v[170:173], 0
	v_mfma_f32_16x16x32_bf16 v[50:53], v[130:133], v[178:181], 0
	v_mfma_f32_16x16x32_bf16 v[42:45], v[154:157], v[178:181], 0
	v_mfma_f32_16x16x32_bf16 v[34:37], v[130:133], v[186:189], 0
	v_mfma_f32_16x16x32_bf16 v[26:29], v[154:157], v[186:189], 0
	v_mfma_f32_16x16x32_bf16 v[18:21], v[130:133], v[194:197], 0
	v_mfma_f32_16x16x32_bf16 v[10:13], v[154:157], v[194:197], 0
	v_mfma_f32_16x16x32_bf16 v[62:65], v[134:137], v[174:177], v[62:65]
	v_mfma_f32_16x16x32_bf16 v[58:61], v[158:161], v[174:177], v[58:61]
	v_mfma_f32_16x16x32_bf16 v[50:53], v[134:137], v[182:185], v[50:53]
	v_mfma_f32_16x16x32_bf16 v[42:45], v[158:161], v[182:185], v[42:45]
	v_mfma_f32_16x16x32_bf16 v[34:37], v[134:137], v[190:193], v[34:37]
	v_mfma_f32_16x16x32_bf16 v[26:29], v[158:161], v[190:193], v[26:29]
	v_mfma_f32_16x16x32_bf16 v[18:21], v[134:137], v[198:201], v[18:21]
	v_mfma_f32_16x16x32_bf16 v[10:13], v[158:161], v[198:201], v[10:13]
	s_barrier
	s_add_u32 s0, s38, 0x18000
	s_addc_u32 s1, s39, 0
	s_add_i32 s34, s50, s8
	v_lshl_add_u64 v[130:131], s[0:1], 0, v[142:143]
	s_mov_b32 m0, s34
	s_nop 0
	global_load_lds_dwordx4 v[130:131], off
	v_lshl_add_u64 v[130:131], s[0:1], 0, v[138:139]
	s_add_i32 m0, s34, 0x2000
	s_nop 0
	global_load_lds_dwordx4 v[130:131], off
	s_waitcnt vmcnt(10)
	s_barrier
	v_mfma_f32_16x16x32_bf16 v[54:57], v[202:205], v[170:173], 0
	v_mfma_f32_16x16x32_bf16 v[46:49], v[210:213], v[170:173], 0
	v_mfma_f32_16x16x32_bf16 v[38:41], v[202:205], v[178:181], 0
	v_mfma_f32_16x16x32_bf16 v[30:33], v[210:213], v[178:181], 0
	v_mfma_f32_16x16x32_bf16 v[22:25], v[202:205], v[186:189], 0
	v_mfma_f32_16x16x32_bf16 v[14:17], v[210:213], v[186:189], 0
	v_mfma_f32_16x16x32_bf16 v[6:9], v[202:205], v[194:197], 0
	v_mfma_f32_16x16x32_bf16 v[2:5], v[210:213], v[194:197], 0
	v_mfma_f32_16x16x32_bf16 v[54:57], v[206:209], v[174:177], v[54:57]
	v_mfma_f32_16x16x32_bf16 v[46:49], v[214:217], v[174:177], v[46:49]
	v_mfma_f32_16x16x32_bf16 v[38:41], v[206:209], v[182:185], v[38:41]
	v_mfma_f32_16x16x32_bf16 v[30:33], v[214:217], v[182:185], v[30:33]
	v_mfma_f32_16x16x32_bf16 v[22:25], v[206:209], v[190:193], v[22:25]
	v_mfma_f32_16x16x32_bf16 v[14:17], v[214:217], v[190:193], v[14:17]
	v_mfma_f32_16x16x32_bf16 v[6:9], v[206:209], v[198:201], v[6:9]
	v_mfma_f32_16x16x32_bf16 v[2:5], v[214:217], v[198:201], v[2:5]
	s_add_i32 s34, 0, 0x18000
	v_add_u32_e32 v158, s34, v164
	s_barrier
	ds_read_b128 v[130:133], v158
	ds_read_b128 v[134:137], v158 offset:1024
	ds_read_b128 v[154:157], v158 offset:2048
	ds_read_b128 v[158:161], v158 offset:3072
	s_add_u32 s0, s40, 0x18000
	s_addc_u32 s1, s41, 0
	s_mov_b32 m0, s43
	v_lshl_add_u64 v[202:203], s[0:1], 0, v[144:145]
	ds_read_b128 v[170:173], v166 offset:32768
	ds_read_b128 v[174:177], v166 offset:33792
	ds_read_b128 v[178:181], v166 offset:34816
	ds_read_b128 v[182:185], v166 offset:35840
	ds_read_b128 v[186:189], v166 offset:36864
	ds_read_b128 v[190:193], v166 offset:37888
	ds_read_b128 v[194:197], v166 offset:38912
	ds_read_b128 v[198:201], v166 offset:39936
	global_load_lds_dwordx4 v[202:203], off
	v_lshl_add_u64 v[202:203], s[0:1], 0, v[140:141]
	s_mov_b32 m0, s44
	s_nop 0
	global_load_lds_dwordx4 v[202:203], off
	s_waitcnt lgkmcnt(8)
	s_waitcnt vmcnt(10)
	s_barrier
	s_waitcnt lgkmcnt(0)
	s_waitcnt lgkmcnt(0)
	v_mfma_f32_16x16x32_bf16 v[126:129], v[130:133], v[170:173], v[126:129]
	v_mfma_f32_16x16x32_bf16 v[122:125], v[154:157], v[170:173], v[122:125]
	v_mfma_f32_16x16x32_bf16 v[114:117], v[130:133], v[178:181], v[114:117]
	v_mfma_f32_16x16x32_bf16 v[106:109], v[154:157], v[178:181], v[106:109]
	v_mfma_f32_16x16x32_bf16 v[98:101], v[130:133], v[186:189], v[98:101]
	v_mfma_f32_16x16x32_bf16 v[90:93], v[154:157], v[186:189], v[90:93]
	v_mfma_f32_16x16x32_bf16 v[82:85], v[130:133], v[194:197], v[82:85]
	v_mfma_f32_16x16x32_bf16 v[74:77], v[154:157], v[194:197], v[74:77]
	v_mfma_f32_16x16x32_bf16 v[126:129], v[134:137], v[174:177], v[126:129]
	v_mfma_f32_16x16x32_bf16 v[122:125], v[158:161], v[174:177], v[122:125]
	v_mfma_f32_16x16x32_bf16 v[114:117], v[134:137], v[182:185], v[114:117]
	v_mfma_f32_16x16x32_bf16 v[106:109], v[158:161], v[182:185], v[106:109]
	v_mfma_f32_16x16x32_bf16 v[98:101], v[134:137], v[190:193], v[98:101]
	v_mfma_f32_16x16x32_bf16 v[90:93], v[158:161], v[190:193], v[90:93]
	v_mfma_f32_16x16x32_bf16 v[82:85], v[134:137], v[198:201], v[82:85]
	v_mfma_f32_16x16x32_bf16 v[74:77], v[158:161], v[198:201], v[74:77]
	s_barrier
	s_add_i32 s35, 0, 0x1c000
	s_add_i32 s0, s34, s8
	v_add_u32_e32 v169, s35, v164
	v_lshl_add_u64 v[218:219], v[218:219], 0, s[30:31]
	s_mov_b32 m0, s0
	ds_read_b128 v[202:205], v169
	ds_read_b128 v[206:209], v169 offset:1024
	ds_read_b128 v[210:213], v169 offset:2048
	ds_read_b128 v[214:217], v169 offset:3072
	global_load_lds_dwordx4 v[218:219], off
	v_lshl_add_u64 v[218:219], v[220:221], 0, s[30:31]
	s_add_i32 m0, s0, 0x2000
	s_nop 0
	global_load_lds_dwordx4 v[218:219], off
	s_waitcnt vmcnt(10)
	s_barrier
	s_waitcnt lgkmcnt(0)
	s_waitcnt lgkmcnt(0)
	v_mfma_f32_16x16x32_bf16 v[118:121], v[202:205], v[170:173], v[118:121]
	v_mfma_f32_16x16x32_bf16 v[110:113], v[210:213], v[170:173], v[110:113]
	v_mfma_f32_16x16x32_bf16 v[102:105], v[202:205], v[178:181], v[102:105]
	v_mfma_f32_16x16x32_bf16 v[94:97], v[210:213], v[178:181], v[94:97]
	v_mfma_f32_16x16x32_bf16 v[86:89], v[202:205], v[186:189], v[86:89]
	v_mfma_f32_16x16x32_bf16 v[78:81], v[210:213], v[186:189], v[78:81]
	v_mfma_f32_16x16x32_bf16 v[70:73], v[202:205], v[194:197], v[70:73]
	v_mfma_f32_16x16x32_bf16 v[66:69], v[210:213], v[194:197], v[66:69]
	v_mfma_f32_16x16x32_bf16 v[118:121], v[206:209], v[174:177], v[118:121]
	v_mfma_f32_16x16x32_bf16 v[110:113], v[214:217], v[174:177], v[110:113]
	v_mfma_f32_16x16x32_bf16 v[102:105], v[206:209], v[182:185], v[102:105]
	v_mfma_f32_16x16x32_bf16 v[94:97], v[214:217], v[182:185], v[94:97]
	v_mfma_f32_16x16x32_bf16 v[86:89], v[206:209], v[190:193], v[86:89]
	v_mfma_f32_16x16x32_bf16 v[78:81], v[214:217], v[190:193], v[78:81]
	v_mfma_f32_16x16x32_bf16 v[70:73], v[206:209], v[198:201], v[70:73]
	v_mfma_f32_16x16x32_bf16 v[66:69], v[214:217], v[198:201], v[66:69]
	s_mov_b32 m0, s46
	v_lshl_add_u64 v[218:219], v[222:223], 0, s[30:31]
	s_barrier
	ds_read_b128 v[170:173], v166 offset:49152
	ds_read_b128 v[174:177], v166 offset:50176
	ds_read_b128 v[178:181], v166 offset:51200
	ds_read_b128 v[182:185], v166 offset:52224
	ds_read_b128 v[186:189], v166 offset:53248
	ds_read_b128 v[190:193], v166 offset:54272
	ds_read_b128 v[194:197], v166 offset:55296
	ds_read_b128 v[198:201], v166 offset:56320
	global_load_lds_dwordx4 v[218:219], off
	v_lshl_add_u64 v[218:219], v[224:225], 0, s[30:31]
	s_mov_b32 m0, s47
	s_nop 0
	global_load_lds_dwordx4 v[218:219], off
	s_waitcnt vmcnt(10)
	s_barrier
	s_waitcnt lgkmcnt(0)
	s_waitcnt lgkmcnt(0)
	v_mfma_f32_16x16x32_bf16 v[62:65], v[130:133], v[170:173], v[62:65]
	v_mfma_f32_16x16x32_bf16 v[58:61], v[154:157], v[170:173], v[58:61]
	v_mfma_f32_16x16x32_bf16 v[50:53], v[130:133], v[178:181], v[50:53]
	v_mfma_f32_16x16x32_bf16 v[42:45], v[154:157], v[178:181], v[42:45]
	v_mfma_f32_16x16x32_bf16 v[34:37], v[130:133], v[186:189], v[34:37]
	v_mfma_f32_16x16x32_bf16 v[26:29], v[154:157], v[186:189], v[26:29]
	v_mfma_f32_16x16x32_bf16 v[18:21], v[130:133], v[194:197], v[18:21]
	v_mfma_f32_16x16x32_bf16 v[10:13], v[154:157], v[194:197], v[10:13]
	v_mfma_f32_16x16x32_bf16 v[62:65], v[134:137], v[174:177], v[62:65]
	v_mfma_f32_16x16x32_bf16 v[58:61], v[158:161], v[174:177], v[58:61]
	v_mfma_f32_16x16x32_bf16 v[50:53], v[134:137], v[182:185], v[50:53]
	v_mfma_f32_16x16x32_bf16 v[42:45], v[158:161], v[182:185], v[42:45]
	v_mfma_f32_16x16x32_bf16 v[34:37], v[134:137], v[190:193], v[34:37]
	v_mfma_f32_16x16x32_bf16 v[26:29], v[158:161], v[190:193], v[26:29]
	v_mfma_f32_16x16x32_bf16 v[18:21], v[134:137], v[198:201], v[18:21]
	v_mfma_f32_16x16x32_bf16 v[10:13], v[158:161], v[198:201], v[10:13]
	s_barrier
	s_add_u32 s0, s38, 0x18080
	s_addc_u32 s1, s39, 0
	s_add_i32 s34, s35, s8
	v_lshl_add_u64 v[130:131], s[0:1], 0, v[142:143]
	s_mov_b32 m0, s34
	s_nop 0
	global_load_lds_dwordx4 v[130:131], off
	v_lshl_add_u64 v[130:131], s[0:1], 0, v[138:139]
	s_add_i32 m0, s34, 0x2000
	s_nop 0
	global_load_lds_dwordx4 v[130:131], off
	s_waitcnt vmcnt(10)
	s_barrier
	v_mfma_f32_16x16x32_bf16 v[54:57], v[202:205], v[170:173], v[54:57]
	v_mfma_f32_16x16x32_bf16 v[46:49], v[210:213], v[170:173], v[46:49]
	v_mfma_f32_16x16x32_bf16 v[38:41], v[202:205], v[178:181], v[38:41]
	v_mfma_f32_16x16x32_bf16 v[30:33], v[210:213], v[178:181], v[30:33]
	v_mfma_f32_16x16x32_bf16 v[22:25], v[202:205], v[186:189], v[22:25]
	v_mfma_f32_16x16x32_bf16 v[14:17], v[210:213], v[186:189], v[14:17]
	v_mfma_f32_16x16x32_bf16 v[6:9], v[202:205], v[194:197], v[6:9]
	v_mfma_f32_16x16x32_bf16 v[2:5], v[210:213], v[194:197], v[2:5]
	v_mfma_f32_16x16x32_bf16 v[54:57], v[206:209], v[174:177], v[54:57]
	v_mfma_f32_16x16x32_bf16 v[46:49], v[214:217], v[174:177], v[46:49]
	v_mfma_f32_16x16x32_bf16 v[38:41], v[206:209], v[182:185], v[38:41]
	v_mfma_f32_16x16x32_bf16 v[30:33], v[214:217], v[182:185], v[30:33]
	v_mfma_f32_16x16x32_bf16 v[22:25], v[206:209], v[190:193], v[22:25]
	v_mfma_f32_16x16x32_bf16 v[14:17], v[214:217], v[190:193], v[14:17]
	v_mfma_f32_16x16x32_bf16 v[6:9], v[206:209], v[198:201], v[6:9]
	v_mfma_f32_16x16x32_bf16 v[2:5], v[214:217], v[198:201], v[2:5]
	s_add_i32 s59, s59, 2
	s_add_u32 s20, s20, 0x100
	s_addc_u32 s58, s58, 0
	s_cmp_gt_u32 s59, 3
	s_mov_b64 s[34:35], s[36:37]
	s_barrier
	s_cbranch_scc1 .Lpeel_exit_14

.Lpeel_exit_14:
	v_mov_b32_e32 v169, v162
	v_mov_b32_e32 v130, v163
	s_mov_b64 s[34:35], -1
	v_lshlrev_b32_e32 v154, 3, v130
	s_cmp_gt_i32 s57, 3
	v_ashrrev_i32_e32 v155, 31, v154
	s_cbranch_scc0 .LBB0_2328
	s_lshl_b32 s0, s56, 8
	s_add_i32 s0, s0, s45
	v_add_u32_e32 v248, s0, v169
	v_mov_b32_e32 v136, v248
	v_lshlrev_b64 v[132:133], 2, v[154:155]
	v_ashrrev_i32_e32 v137, 31, v136
	v_lshl_add_u64 v[130:131], s[26:27], 0, v[132:133]
	v_lshlrev_b64 v[134:135], 7, v[136:137]
	v_lshl_add_u64 v[156:157], v[130:131], 0, v[134:135]
	v_lshl_add_u64 v[132:133], s[24:25], 0, v[132:133]
	global_load_dwordx4 v[170:173], v[156:157], off
	global_load_dwordx4 v[174:177], v[156:157], off offset:16
	v_lshl_add_u64 v[134:135], v[132:133], 0, v[134:135]
	global_load_dwordx4 v[178:181], v[134:135], off
	global_load_dwordx4 v[182:185], v[134:135], off offset:16
	v_add_u32_e32 v160, 16, v136
	v_ashrrev_i32_e32 v161, 31, v160
	v_lshlrev_b64 v[134:135], 7, v[160:161]
	v_lshl_add_u64 v[156:157], v[130:131], 0, v[134:135]
	global_load_dwordx4 v[186:189], v[156:157], off
	global_load_dwordx4 v[194:197], v[156:157], off offset:16
	v_lshl_add_u64 v[134:135], v[132:133], 0, v[134:135]
	global_load_dwordx4 v[190:193], v[134:135], off
	global_load_dwordx4 v[198:201], v[134:135], off offset:16
	v_add_u32_e32 v238, 32, v136
	v_add_u32_e32 v134, 48, v136
	v_ashrrev_i32_e32 v239, 31, v238
	v_ashrrev_i32_e32 v135, 31, v134
	v_lshlrev_b64 v[202:203], 7, v[238:239]
	v_lshlrev_b64 v[204:205], 7, v[134:135]
	v_lshl_add_u64 v[206:207], v[132:133], 0, v[202:203]
	v_lshl_add_u64 v[214:215], v[130:131], 0, v[202:203]
	v_lshl_add_u64 v[222:223], v[132:133], 0, v[204:205]
	v_lshl_add_u64 v[230:231], v[130:131], 0, v[204:205]
	global_load_dwordx4 v[202:205], v[206:207], off
	s_nop 0
	global_load_dwordx4 v[206:209], v[206:207], off offset:16
	s_nop 0
	global_load_dwordx4 v[210:213], v[214:215], off
	s_nop 0
	global_load_dwordx4 v[214:217], v[214:215], off offset:16
	s_nop 0
	global_load_dwordx4 v[218:221], v[222:223], off
	s_nop 0
	global_load_dwordx4 v[222:225], v[222:223], off offset:16
	s_nop 0
	global_load_dwordx4 v[226:229], v[230:231], off
	s_nop 0
	global_load_dwordx4 v[230:233], v[230:231], off offset:16
	v_mov_b32_e32 v234, 0
	v_mov_b32_e32 v235, 0
	v_mov_b32_e32 v236, 0
	v_mov_b32_e32 v237, 0
	s_lshl_b32 s0, s57, 2
	s_add_i32 s0, s48, s0
	v_mov_b64_e32 v[156:157], s[22:23]
	s_mul_i32 s20, s0, 0xc0
	v_lshl_add_u64 v[158:159], s[20:21], 0, v[154:155]
	v_mad_i64_i32 v[136:137], s[0:1], v136, s52, v[156:157]
	v_lshl_add_u64 v[136:137], v[136:137], 0, v[158:159]
	s_mov_b64 s[34:35], 0
	s_waitcnt vmcnt(0) lgkmcnt(0)
	v_pk_mul_f32 v[240:241], v[120:121], v[172:173]
	v_pk_mul_f32 v[242:243], v[118:119], v[170:171]
	v_pk_mul_f32 v[172:173], v[128:129], v[172:173]
	v_pk_mul_f32 v[246:247], v[110:111], v[174:175]
	v_pk_mul_f32 v[170:171], v[126:127], v[170:171]
	v_pk_mul_f32 v[174:175], v[122:123], v[174:175]
	v_pk_fma_f32 v[240:241], v[128:129], v[180:181], v[240:241] neg_lo:[0,0,1] neg_hi:[0,0,1]
	v_pk_fma_f32 v[242:243], v[126:127], v[178:179], v[242:243] neg_lo:[0,0,1] neg_hi:[0,0,1]
	v_pk_fma_f32 v[172:173], v[120:121], v[180:181], v[172:173]
	v_pk_fma_f32 v[180:181], v[122:123], v[182:183], v[246:247] neg_lo:[0,0,1] neg_hi:[0,0,1]
	v_pk_fma_f32 v[170:171], v[118:119], v[178:179], v[170:171]
	v_pk_fma_f32 v[174:175], v[110:111], v[182:183], v[174:175]
	v_med3_f32 v135, v242, s51, v168
	v_med3_f32 v161, v243, s51, v168
	v_med3_f32 v180, v180, s51, v168
	v_med3_f32 v181, v181, s51, v168
	v_med3_f32 v170, v170, s51, v168
	v_med3_f32 v171, v171, s51, v168
	v_med3_f32 v174, v174, s51, v168
	v_med3_f32 v175, v175, s51, v168
	v_cvt_pk_fp8_f32 v234, v135, v161
	v_cvt_pk_fp8_f32 v235, v180, v181
	v_pk_mul_f32 v[244:245], v[112:113], v[176:177]
	v_cvt_pk_fp8_f32 v236, v170, v171
	v_cvt_pk_fp8_f32 v237, v174, v175
	v_pk_mul_f32 v[176:177], v[124:125], v[176:177]
	v_pk_fma_f32 v[178:179], v[124:125], v[184:185], v[244:245] neg_lo:[0,0,1] neg_hi:[0,0,1]
	v_pk_fma_f32 v[176:177], v[112:113], v[184:185], v[176:177]
	v_med3_f32 v184, v240, s51, v168
	v_med3_f32 v185, v241, s51, v168
	v_med3_f32 v178, v178, s51, v168
	v_med3_f32 v179, v179, s51, v168
	v_med3_f32 v172, v172, s51, v168
	v_med3_f32 v173, v173, s51, v168
	v_med3_f32 v176, v176, s51, v168
	v_med3_f32 v177, v177, s51, v168
	v_cvt_pk_fp8_f32 v234, v184, v185 op_sel:[0,0,1]
	v_cvt_pk_fp8_f32 v235, v178, v179 op_sel:[0,0,1]
	v_cvt_pk_fp8_f32 v236, v172, v173 op_sel:[0,0,1]
	v_cvt_pk_fp8_f32 v237, v176, v177 op_sel:[0,0,1]
	v_pk_mul_f32 v[170:171], v[102:103], v[186:187]
	v_pk_mul_f32 v[182:183], v[104:105], v[188:189]
	global_store_dwordx2 v[136:137], v[234:235], off offset:128
	global_store_dwordx2 v[136:137], v[236:237], off offset:160
	v_pk_fma_f32 v[136:137], v[114:115], v[190:191], v[170:171] neg_lo:[0,0,1] neg_hi:[0,0,1]
	v_pk_mul_f32 v[178:179], v[94:95], v[194:195]
	v_pk_fma_f32 v[172:173], v[116:117], v[192:193], v[182:183] neg_lo:[0,0,1] neg_hi:[0,0,1]
	v_pk_fma_f32 v[178:179], v[106:107], v[198:199], v[178:179] neg_lo:[0,0,1] neg_hi:[0,0,1]
	v_med3_f32 v135, v136, s51, v168
	v_med3_f32 v137, v137, s51, v168
	v_mov_b32_e32 v136, 0
	v_cvt_pk_fp8_f32 v136, v135, v137
	v_med3_f32 v135, v172, s51, v168
	v_med3_f32 v161, v173, s51, v168
	v_med3_f32 v172, v178, s51, v168
	v_med3_f32 v173, v179, s51, v168
	v_mov_b32_e32 v137, 0
	v_cvt_pk_fp8_f32 v137, v172, v173
	v_pk_mul_f32 v[176:177], v[96:97], v[196:197]
	v_pk_mul_f32 v[174:175], v[114:115], v[186:187]
	v_pk_fma_f32 v[176:177], v[108:109], v[200:201], v[176:177] neg_lo:[0,0,1] neg_hi:[0,0,1]
	v_pk_mul_f32 v[170:171], v[116:117], v[188:189]
	v_pk_fma_f32 v[174:175], v[102:103], v[190:191], v[174:175]
	v_pk_mul_f32 v[182:183], v[106:107], v[194:195]
	v_cvt_pk_fp8_f32 v136, v135, v161 op_sel:[0,0,1]
	v_med3_f32 v135, v176, s51, v168
	v_med3_f32 v161, v177, s51, v168
	v_pk_fma_f32 v[170:171], v[104:105], v[192:193], v[170:171]
	v_pk_fma_f32 v[182:183], v[94:95], v[198:199], v[182:183]
	v_cvt_pk_fp8_f32 v137, v135, v161 op_sel:[0,0,1]
	v_med3_f32 v135, v174, s51, v168
	v_med3_f32 v161, v175, s51, v168
	v_mov_b32_e32 v172, 0
	v_cvt_pk_fp8_f32 v172, v135, v161
	v_med3_f32 v135, v170, s51, v168
	v_med3_f32 v161, v171, s51, v168
	v_med3_f32 v170, v182, s51, v168
	v_med3_f32 v171, v183, s51, v168
	v_mov_b32_e32 v173, 0
	v_cvt_pk_fp8_f32 v173, v170, v171
	v_pk_mul_f32 v[180:181], v[108:109], v[196:197]
	v_cvt_pk_fp8_f32 v172, v135, v161 op_sel:[0,0,1]
	v_pk_fma_f32 v[180:181], v[96:97], v[200:201], v[180:181]
	v_pk_mul_f32 v[176:177], v[78:79], v[214:215]
	v_med3_f32 v135, v180, s51, v168
	v_med3_f32 v161, v181, s51, v168
	v_cvt_pk_fp8_f32 v173, v135, v161 op_sel:[0,0,1]
	v_mad_i64_i32 v[160:161], s[0:1], v160, s52, v[156:157]
	v_lshl_add_u64 v[160:161], v[160:161], 0, v[158:159]
	global_store_dwordx2 v[160:161], v[136:137], off offset:128
	global_store_dwordx2 v[160:161], v[172:173], off offset:160
	v_pk_mul_f32 v[160:161], v[86:87], v[210:211]
	v_pk_mul_f32 v[136:137], v[88:89], v[212:213]
	v_pk_fma_f32 v[160:161], v[98:99], v[202:203], v[160:161] neg_lo:[0,0,1] neg_hi:[0,0,1]
	v_pk_fma_f32 v[136:137], v[100:101], v[204:205], v[136:137] neg_lo:[0,0,1] neg_hi:[0,0,1]
	v_pk_fma_f32 v[176:177], v[90:91], v[206:207], v[176:177] neg_lo:[0,0,1] neg_hi:[0,0,1]
	v_med3_f32 v135, v160, s51, v168
	v_med3_f32 v161, v161, s51, v168
	v_mov_b32_e32 v160, 0
	v_cvt_pk_fp8_f32 v160, v135, v161
	v_med3_f32 v135, v136, s51, v168
	v_med3_f32 v136, v137, s51, v168
	v_med3_f32 v137, v176, s51, v168
	v_med3_f32 v176, v177, s51, v168
	v_mov_b32_e32 v161, 0
	v_cvt_pk_fp8_f32 v161, v137, v176
	v_pk_mul_f32 v[174:175], v[80:81], v[216:217]
	v_pk_mul_f32 v[172:173], v[98:99], v[210:211]
	v_pk_fma_f32 v[174:175], v[92:93], v[208:209], v[174:175] neg_lo:[0,0,1] neg_hi:[0,0,1]
	v_pk_mul_f32 v[170:171], v[100:101], v[212:213]
	v_pk_fma_f32 v[172:173], v[86:87], v[202:203], v[172:173]
	v_pk_mul_f32 v[180:181], v[90:91], v[214:215]
	v_cvt_pk_fp8_f32 v160, v135, v136 op_sel:[0,0,1]
	v_med3_f32 v135, v174, s51, v168
	v_med3_f32 v136, v175, s51, v168
	v_pk_fma_f32 v[170:171], v[88:89], v[204:205], v[170:171]
	v_pk_fma_f32 v[180:181], v[78:79], v[206:207], v[180:181]
	v_cvt_pk_fp8_f32 v161, v135, v136 op_sel:[0,0,1]
	v_med3_f32 v135, v172, s51, v168
	v_med3_f32 v137, v173, s51, v168
	v_mov_b32_e32 v136, 0
	v_cvt_pk_fp8_f32 v136, v135, v137
	v_med3_f32 v135, v170, s51, v168
	v_med3_f32 v170, v171, s51, v168
	v_med3_f32 v171, v180, s51, v168
	v_med3_f32 v172, v181, s51, v168
	v_mov_b32_e32 v137, 0
	v_cvt_pk_fp8_f32 v137, v171, v172
	v_pk_mul_f32 v[178:179], v[92:93], v[216:217]
	v_cvt_pk_fp8_f32 v136, v135, v170 op_sel:[0,0,1]
	v_pk_fma_f32 v[178:179], v[80:81], v[208:209], v[178:179]
	v_pk_mul_f32 v[176:177], v[66:67], v[230:231]
	v_med3_f32 v135, v178, s51, v168
	v_med3_f32 v170, v179, s51, v168
	v_cvt_pk_fp8_f32 v137, v135, v170 op_sel:[0,0,1]
	v_mad_i64_i32 v[170:171], s[0:1], v238, s52, v[156:157]
	v_lshl_add_u64 v[170:171], v[170:171], 0, v[158:159]
	global_store_dwordx2 v[170:171], v[160:161], off offset:128
	global_store_dwordx2 v[170:171], v[136:137], off offset:160
	v_pk_mul_f32 v[160:161], v[70:71], v[226:227]
	v_pk_mul_f32 v[136:137], v[72:73], v[228:229]
	v_pk_fma_f32 v[160:161], v[82:83], v[218:219], v[160:161] neg_lo:[0,0,1] neg_hi:[0,0,1]
	v_pk_fma_f32 v[136:137], v[84:85], v[220:221], v[136:137] neg_lo:[0,0,1] neg_hi:[0,0,1]
	v_pk_fma_f32 v[176:177], v[74:75], v[222:223], v[176:177] neg_lo:[0,0,1] neg_hi:[0,0,1]
	v_med3_f32 v135, v160, s51, v168
	v_med3_f32 v161, v161, s51, v168
	v_mov_b32_e32 v160, 0
	v_cvt_pk_fp8_f32 v160, v135, v161
	v_med3_f32 v135, v136, s51, v168
	v_med3_f32 v136, v137, s51, v168
	v_med3_f32 v137, v176, s51, v168
	v_med3_f32 v176, v177, s51, v168
	v_mov_b32_e32 v161, 0
	v_cvt_pk_fp8_f32 v161, v137, v176
	v_pk_mul_f32 v[174:175], v[68:69], v[232:233]
	v_pk_mul_f32 v[172:173], v[82:83], v[226:227]
	v_pk_fma_f32 v[174:175], v[76:77], v[224:225], v[174:175] neg_lo:[0,0,1] neg_hi:[0,0,1]
	v_pk_mul_f32 v[170:171], v[84:85], v[228:229]
	v_pk_fma_f32 v[172:173], v[70:71], v[218:219], v[172:173]
	v_pk_mul_f32 v[180:181], v[74:75], v[230:231]
	v_cvt_pk_fp8_f32 v160, v135, v136 op_sel:[0,0,1]
	v_med3_f32 v135, v174, s51, v168
	v_med3_f32 v136, v175, s51, v168
	v_pk_fma_f32 v[170:171], v[72:73], v[220:221], v[170:171]
	v_pk_fma_f32 v[180:181], v[66:67], v[222:223], v[180:181]
	v_cvt_pk_fp8_f32 v161, v135, v136 op_sel:[0,0,1]
	v_med3_f32 v135, v172, s51, v168
	v_med3_f32 v137, v173, s51, v168
	v_mov_b32_e32 v136, 0
	v_cvt_pk_fp8_f32 v136, v135, v137
	v_med3_f32 v135, v170, s51, v168
	v_med3_f32 v170, v171, s51, v168
	v_med3_f32 v171, v180, s51, v168
	v_med3_f32 v172, v181, s51, v168
	v_mov_b32_e32 v137, 0
	v_cvt_pk_fp8_f32 v137, v171, v172
	v_pk_mul_f32 v[178:179], v[76:77], v[232:233]
	v_cvt_pk_fp8_f32 v136, v135, v170 op_sel:[0,0,1]
	v_pk_fma_f32 v[178:179], v[68:69], v[224:225], v[178:179]
	v_add_u32_e32 v226, 0x80, v248
	v_med3_f32 v135, v178, s51, v168
	v_med3_f32 v170, v179, s51, v168
	v_cvt_pk_fp8_f32 v137, v135, v170 op_sel:[0,0,1]
	v_mad_i64_i32 v[134:135], s[0:1], v134, s52, v[156:157]
	v_lshl_add_u64 v[134:135], v[134:135], 0, v[158:159]
	global_store_dwordx2 v[134:135], v[160:161], off offset:128
	global_store_dwordx2 v[134:135], v[136:137], off offset:160
	s_nop 0
	v_ashrrev_i32_e32 v227, 31, v226
	v_lshlrev_b64 v[134:135], 7, v[226:227]
	v_lshl_add_u64 v[136:137], v[130:131], 0, v[134:135]
	global_load_dwordx4 v[170:173], v[136:137], off
	v_lshl_add_u64 v[134:135], v[132:133], 0, v[134:135]
	global_load_dwordx4 v[174:177], v[134:135], off
	global_load_dwordx4 v[178:181], v[136:137], off offset:16
	global_load_dwordx4 v[182:185], v[134:135], off offset:16
	v_add_u32_e32 v228, 16, v226
	v_ashrrev_i32_e32 v229, 31, v228
	v_lshlrev_b64 v[134:135], 7, v[228:229]
	v_lshl_add_u64 v[136:137], v[130:131], 0, v[134:135]
	global_load_dwordx4 v[186:189], v[136:137], off
	v_lshl_add_u64 v[134:135], v[132:133], 0, v[134:135]
	global_load_dwordx4 v[190:193], v[134:135], off
	global_load_dwordx4 v[194:197], v[136:137], off offset:16
	global_load_dwordx4 v[198:201], v[134:135], off offset:16
	v_add_u32_e32 v230, 32, v226
	v_ashrrev_i32_e32 v231, 31, v230
	v_lshlrev_b64 v[134:135], 7, v[230:231]
	v_lshl_add_u64 v[136:137], v[132:133], 0, v[134:135]
	v_lshl_add_u64 v[134:135], v[130:131], 0, v[134:135]
	global_load_dwordx4 v[202:205], v[136:137], off
	global_load_dwordx4 v[206:209], v[136:137], off offset:16
	global_load_dwordx4 v[210:213], v[134:135], off
	global_load_dwordx4 v[214:217], v[134:135], off offset:16
	v_add_u32_e32 v160, 48, v226
	v_ashrrev_i32_e32 v161, 31, v160
	v_lshlrev_b64 v[134:135], 7, v[160:161]
	v_lshl_add_u64 v[132:133], v[132:133], 0, v[134:135]
	v_lshl_add_u64 v[134:135], v[130:131], 0, v[134:135]
	global_load_dwordx4 v[218:221], v[132:133], off
	s_nop 0
	global_load_dwordx4 v[130:133], v[132:133], off offset:16
	s_nop 0
	global_load_dwordx4 v[222:225], v[134:135], off
	s_nop 0
	global_load_dwordx4 v[134:137], v[134:135], off offset:16
	s_waitcnt vmcnt(0) lgkmcnt(0)
	v_pk_mul_f32 v[232:233], v[56:57], v[172:173]
	v_pk_mul_f32 v[234:235], v[54:55], v[170:171]
	v_pk_mul_f32 v[172:173], v[64:65], v[172:173]
	v_pk_fma_f32 v[232:233], v[64:65], v[176:177], v[232:233] neg_lo:[0,0,1] neg_hi:[0,0,1]
	v_pk_fma_f32 v[234:235], v[62:63], v[174:175], v[234:235] neg_lo:[0,0,1] neg_hi:[0,0,1]
	v_pk_fma_f32 v[172:173], v[56:57], v[176:177], v[172:173]
	v_pk_mul_f32 v[176:177], v[46:47], v[178:179]
	v_pk_mul_f32 v[178:179], v[58:59], v[178:179]
	v_pk_fma_f32 v[176:177], v[58:59], v[182:183], v[176:177] neg_lo:[0,0,1] neg_hi:[0,0,1]
	v_pk_fma_f32 v[178:179], v[46:47], v[182:183], v[178:179]
	v_med3_f32 v161, v234, s51, v168
	v_med3_f32 v183, v235, s51, v168
	v_mov_b32_e32 v182, 0
	v_cvt_pk_fp8_f32 v182, v161, v183
	v_med3_f32 v176, v176, s51, v168
	v_med3_f32 v177, v177, s51, v168
	v_mov_b32_e32 v183, 0
	v_pk_mul_f32 v[170:171], v[62:63], v[170:171]
	v_cvt_pk_fp8_f32 v183, v176, v177
	v_pk_fma_f32 v[170:171], v[54:55], v[174:175], v[170:171]
	v_pk_mul_f32 v[174:175], v[48:49], v[180:181]
	v_pk_mul_f32 v[180:181], v[60:61], v[180:181]
	v_pk_fma_f32 v[174:175], v[60:61], v[184:185], v[174:175] neg_lo:[0,0,1] neg_hi:[0,0,1]
	v_pk_fma_f32 v[180:181], v[48:49], v[184:185], v[180:181]
	v_med3_f32 v161, v232, s51, v168
	v_med3_f32 v184, v233, s51, v168
	v_cvt_pk_fp8_f32 v182, v161, v184 op_sel:[0,0,1]
	v_med3_f32 v161, v174, s51, v168
	v_med3_f32 v174, v175, s51, v168
	v_cvt_pk_fp8_f32 v183, v161, v174 op_sel:[0,0,1]
	v_med3_f32 v161, v170, s51, v168
	v_med3_f32 v171, v171, s51, v168
	v_mov_b32_e32 v170, 0
	v_cvt_pk_fp8_f32 v170, v161, v171
	v_med3_f32 v161, v172, s51, v168
	v_med3_f32 v172, v173, s51, v168
	v_med3_f32 v173, v178, s51, v168
	v_med3_f32 v174, v179, s51, v168
	v_mov_b32_e32 v171, 0
	v_cvt_pk_fp8_f32 v171, v173, v174
	v_cvt_pk_fp8_f32 v170, v161, v172 op_sel:[0,0,1]
	v_med3_f32 v161, v180, s51, v168
	v_med3_f32 v172, v181, s51, v168
	v_cvt_pk_fp8_f32 v171, v161, v172 op_sel:[0,0,1]
	v_mad_i64_i32 v[172:173], s[0:1], v226, s52, v[156:157]
	v_lshl_add_u64 v[172:173], v[172:173], 0, v[158:159]
	global_store_dwordx2 v[172:173], v[182:183], off offset:128
	global_store_dwordx2 v[172:173], v[170:171], off offset:160
	v_pk_mul_f32 v[172:173], v[38:39], v[186:187]
	v_pk_mul_f32 v[170:171], v[40:41], v[188:189]
	v_pk_fma_f32 v[172:173], v[50:51], v[190:191], v[172:173] neg_lo:[0,0,1] neg_hi:[0,0,1]
	v_pk_mul_f32 v[180:181], v[30:31], v[194:195]
	v_pk_fma_f32 v[170:171], v[52:53], v[192:193], v[170:171] neg_lo:[0,0,1] neg_hi:[0,0,1]
	v_pk_fma_f32 v[180:181], v[42:43], v[198:199], v[180:181] neg_lo:[0,0,1] neg_hi:[0,0,1]
	v_med3_f32 v161, v172, s51, v168
	v_med3_f32 v173, v173, s51, v168
	v_mov_b32_e32 v172, 0
	v_cvt_pk_fp8_f32 v172, v161, v173
	v_med3_f32 v161, v170, s51, v168
	v_med3_f32 v170, v171, s51, v168
	v_med3_f32 v171, v180, s51, v168
	v_med3_f32 v180, v181, s51, v168
	v_mov_b32_e32 v173, 0
	v_cvt_pk_fp8_f32 v173, v171, v180
	v_pk_mul_f32 v[178:179], v[32:33], v[196:197]
	v_pk_mul_f32 v[176:177], v[50:51], v[186:187]
	v_pk_fma_f32 v[178:179], v[44:45], v[200:201], v[178:179] neg_lo:[0,0,1] neg_hi:[0,0,1]
	v_pk_mul_f32 v[174:175], v[52:53], v[188:189]
	v_pk_fma_f32 v[176:177], v[38:39], v[190:191], v[176:177]
	v_pk_mul_f32 v[184:185], v[42:43], v[194:195]
	v_cvt_pk_fp8_f32 v172, v161, v170 op_sel:[0,0,1]
	v_med3_f32 v161, v178, s51, v168
	v_med3_f32 v170, v179, s51, v168
	v_pk_fma_f32 v[174:175], v[40:41], v[192:193], v[174:175]
	v_pk_fma_f32 v[184:185], v[30:31], v[198:199], v[184:185]
	v_cvt_pk_fp8_f32 v173, v161, v170 op_sel:[0,0,1]
	v_med3_f32 v161, v176, s51, v168
	v_med3_f32 v171, v177, s51, v168
	v_mov_b32_e32 v170, 0
	v_cvt_pk_fp8_f32 v170, v161, v171
	v_med3_f32 v161, v174, s51, v168
	v_med3_f32 v174, v175, s51, v168
	v_med3_f32 v175, v184, s51, v168
	v_med3_f32 v176, v185, s51, v168
	v_mov_b32_e32 v171, 0
	v_cvt_pk_fp8_f32 v171, v175, v176
	v_pk_mul_f32 v[182:183], v[44:45], v[196:197]
	v_cvt_pk_fp8_f32 v170, v161, v174 op_sel:[0,0,1]
	v_pk_fma_f32 v[182:183], v[32:33], v[200:201], v[182:183]
	v_pk_mul_f32 v[180:181], v[14:15], v[214:215]
	v_med3_f32 v161, v182, s51, v168
	v_med3_f32 v174, v183, s51, v168
	v_cvt_pk_fp8_f32 v171, v161, v174 op_sel:[0,0,1]
	v_mad_i64_i32 v[174:175], s[0:1], v228, s52, v[156:157]
	v_lshl_add_u64 v[174:175], v[174:175], 0, v[158:159]
	global_store_dwordx2 v[174:175], v[172:173], off offset:128
	global_store_dwordx2 v[174:175], v[170:171], off offset:160
	v_pk_mul_f32 v[172:173], v[22:23], v[210:211]
	v_pk_mul_f32 v[170:171], v[24:25], v[212:213]
	v_pk_fma_f32 v[172:173], v[34:35], v[202:203], v[172:173] neg_lo:[0,0,1] neg_hi:[0,0,1]
	v_pk_fma_f32 v[170:171], v[36:37], v[204:205], v[170:171] neg_lo:[0,0,1] neg_hi:[0,0,1]
	v_pk_fma_f32 v[180:181], v[26:27], v[206:207], v[180:181] neg_lo:[0,0,1] neg_hi:[0,0,1]
	v_med3_f32 v161, v172, s51, v168
	v_med3_f32 v173, v173, s51, v168
	v_mov_b32_e32 v172, 0
	v_cvt_pk_fp8_f32 v172, v161, v173
	v_med3_f32 v161, v170, s51, v168
	v_med3_f32 v170, v171, s51, v168
	v_med3_f32 v171, v180, s51, v168
	v_med3_f32 v180, v181, s51, v168
	v_mov_b32_e32 v173, 0
	v_cvt_pk_fp8_f32 v173, v171, v180
	v_pk_mul_f32 v[178:179], v[16:17], v[216:217]
	v_pk_mul_f32 v[176:177], v[34:35], v[210:211]
	v_pk_fma_f32 v[178:179], v[28:29], v[208:209], v[178:179] neg_lo:[0,0,1] neg_hi:[0,0,1]
	v_pk_mul_f32 v[174:175], v[36:37], v[212:213]
	v_pk_fma_f32 v[176:177], v[22:23], v[202:203], v[176:177]
	v_pk_mul_f32 v[184:185], v[26:27], v[214:215]
	v_cvt_pk_fp8_f32 v172, v161, v170 op_sel:[0,0,1]
	v_med3_f32 v161, v178, s51, v168
	v_med3_f32 v170, v179, s51, v168
	v_pk_fma_f32 v[174:175], v[24:25], v[204:205], v[174:175]
	v_pk_fma_f32 v[184:185], v[14:15], v[206:207], v[184:185]
	v_cvt_pk_fp8_f32 v173, v161, v170 op_sel:[0,0,1]
	v_med3_f32 v161, v176, s51, v168
	v_med3_f32 v171, v177, s51, v168
	v_mov_b32_e32 v170, 0
	v_cvt_pk_fp8_f32 v170, v161, v171
	v_med3_f32 v161, v174, s51, v168
	v_med3_f32 v174, v175, s51, v168
	v_med3_f32 v175, v184, s51, v168
	v_med3_f32 v176, v185, s51, v168
	v_mov_b32_e32 v171, 0
	v_cvt_pk_fp8_f32 v171, v175, v176
	v_pk_mul_f32 v[182:183], v[28:29], v[216:217]
	v_cvt_pk_fp8_f32 v170, v161, v174 op_sel:[0,0,1]
	v_pk_fma_f32 v[182:183], v[16:17], v[208:209], v[182:183]
	v_pk_mul_f32 v[178:179], v[4:5], v[136:137]
	v_med3_f32 v161, v182, s51, v168
	v_med3_f32 v174, v183, s51, v168
	v_cvt_pk_fp8_f32 v171, v161, v174 op_sel:[0,0,1]
	v_mad_i64_i32 v[174:175], s[0:1], v230, s52, v[156:157]
	v_lshl_add_u64 v[174:175], v[174:175], 0, v[158:159]
	global_store_dwordx2 v[174:175], v[172:173], off offset:128
	global_store_dwordx2 v[174:175], v[170:171], off offset:160
	v_pk_mul_f32 v[172:173], v[6:7], v[222:223]
	v_pk_mul_f32 v[170:171], v[8:9], v[224:225]
	v_pk_fma_f32 v[172:173], v[18:19], v[218:219], v[172:173] neg_lo:[0,0,1] neg_hi:[0,0,1]
	v_pk_mul_f32 v[180:181], v[2:3], v[134:135]
	v_pk_mul_f32 v[136:137], v[12:13], v[136:137]
	v_pk_mul_f32 v[134:135], v[10:11], v[134:135]
	v_pk_fma_f32 v[170:171], v[20:21], v[220:221], v[170:171] neg_lo:[0,0,1] neg_hi:[0,0,1]
	v_pk_fma_f32 v[178:179], v[12:13], v[132:133], v[178:179] neg_lo:[0,0,1] neg_hi:[0,0,1]
	v_pk_fma_f32 v[180:181], v[10:11], v[130:131], v[180:181] neg_lo:[0,0,1] neg_hi:[0,0,1]
	v_pk_fma_f32 v[132:133], v[4:5], v[132:133], v[136:137]
	v_pk_fma_f32 v[130:131], v[2:3], v[130:131], v[134:135]
	v_med3_f32 v135, v172, s51, v168
	v_med3_f32 v136, v173, s51, v168
	v_mov_b32_e32 v134, 0
	v_cvt_pk_fp8_f32 v134, v135, v136
	v_med3_f32 v136, v170, s51, v168
	v_med3_f32 v161, v180, s51, v168
	v_med3_f32 v170, v181, s51, v168
	v_mov_b32_e32 v135, 0
	v_cvt_pk_fp8_f32 v135, v161, v170
	v_pk_mul_f32 v[176:177], v[18:19], v[222:223]
	v_med3_f32 v137, v171, s51, v168
	v_pk_fma_f32 v[176:177], v[6:7], v[218:219], v[176:177]
	v_cvt_pk_fp8_f32 v134, v136, v137 op_sel:[0,0,1]
	v_med3_f32 v136, v178, s51, v168
	v_med3_f32 v137, v179, s51, v168
	v_cvt_pk_fp8_f32 v135, v136, v137 op_sel:[0,0,1]
	v_med3_f32 v137, v176, s51, v168
	v_med3_f32 v161, v177, s51, v168
	v_mov_b32_e32 v136, 0
	v_cvt_pk_fp8_f32 v136, v137, v161
	v_med3_f32 v130, v130, s51, v168
	v_med3_f32 v131, v131, s51, v168
	v_mov_b32_e32 v137, 0
	v_cvt_pk_fp8_f32 v137, v130, v131
	v_pk_mul_f32 v[174:175], v[20:21], v[224:225]
	v_med3_f32 v130, v132, s51, v168
	v_pk_fma_f32 v[174:175], v[8:9], v[220:221], v[174:175]
	v_med3_f32 v131, v133, s51, v168
	v_med3_f32 v161, v174, s51, v168
	v_med3_f32 v170, v175, s51, v168
	v_cvt_pk_fp8_f32 v136, v161, v170 op_sel:[0,0,1]
	v_cvt_pk_fp8_f32 v137, v130, v131 op_sel:[0,0,1]
	v_mad_i64_i32 v[130:131], s[0:1], v160, s52, v[156:157]
	v_lshl_add_u64 v[130:131], v[130:131], 0, v[158:159]
	global_store_dwordx2 v[130:131], v[134:135], off offset:128
	global_store_dwordx2 v[130:131], v[136:137], off offset:160

.LBB0_2494:
	s_add_i32 s56, s56, 1
	s_mov_b64 s[0:1], s[24:25]
	s_lshr_b32 s24, s56, 2
	s_mul_i32 s24, s24, s74
	s_mov_b64 s[36:37], s[34:35]
	s_mov_b32 s35, s57
	s_add_i32 s57, s24, s2
	s_cmpk_lt_i32 s57, 0x100
	s_cselect_b64 s[38:39], -1, 0
	s_cmpk_gt_i32 s57, 0xff
	s_mov_b32 s34, s58
	s_cselect_b64 s[30:31], -1, 0
	s_and_b32 s58, s56, 3
	s_and_b64 s[24:25], s[38:39], exec
	s_cselect_b32 s24, s57, s35
	s_cselect_b32 s34, s58, s34
	s_ashr_i32 s25, s24, 31
	s_lshl_b64 s[24:25], s[24:25], 19
	s_add_u32 s24, s6, s24
	s_addc_u32 s25, s7, s25
	s_and_b64 s[40:41], s[38:39], exec
	s_cselect_b32 s61, s25, s1
	s_cselect_b32 s62, s24, s0
	s_ashr_i32 s35, s34, 31
	s_lshl_b64 s[34:35], s[34:35], 19
	s_add_u32 s34, s22, s34
	s_addc_u32 s35, s23, s35
	s_and_b64 s[38:39], s[38:39], exec
	s_cselect_b32 s63, s35, s37
	s_cselect_b32 s64, s34, s36
	s_add_u32 s65, s36, 0x100
	s_addc_u32 s67, s37, 0
	s_add_u32 s36, s0, 0x40080
	s_addc_u32 s37, s1, 0
	s_mov_b32 s69, -2
	ds_read_b128 v[130:133], v168
	ds_read_b128 v[134:137], v168 offset:1024
	ds_read_b128 v[138:141], v168 offset:2048
	ds_read_b128 v[142:145], v168 offset:3072
	s_add_u32 s0, s36, 0xfffc0080
	s_addc_u32 s1, s37, -1
	s_cmp_eq_u32 s69, 12
	s_cselect_b32 s41, s61, s1
	s_cselect_b32 s40, s62, s0
	s_cselect_b32 s39, s63, s67
	s_cselect_b32 s38, s64, s65
	s_mov_b32 m0, s51
	v_lshl_add_u64 v[164:165], s[36:37], 0, v[162:163]
	ds_read_b128 v[146:149], v169
	ds_read_b128 v[172:175], v169 offset:1024
	ds_read_b128 v[176:179], v169 offset:2048
	ds_read_b128 v[180:183], v169 offset:3072
	ds_read_b128 v[184:187], v169 offset:4096
	ds_read_b128 v[188:191], v169 offset:5120
	ds_read_b128 v[192:195], v169 offset:6144
	ds_read_b128 v[196:199], v169 offset:7168
	global_load_lds_dwordx4 v[164:165], off
	v_lshl_add_u64 v[164:165], s[36:37], 0, v[160:161]
	s_mov_b32 m0, s52
	s_nop 0
	global_load_lds_dwordx4 v[164:165], off
	s_waitcnt lgkmcnt(8)
	s_waitcnt vmcnt(10)
	s_barrier
	s_waitcnt lgkmcnt(0)
	s_waitcnt lgkmcnt(0)
	v_mfma_f32_16x16x32_bf16 v[126:129], v[130:133], v[146:149], 0
	v_mfma_f32_16x16x32_bf16 v[122:125], v[138:141], v[146:149], 0
	v_mfma_f32_16x16x32_bf16 v[118:121], v[130:133], v[176:179], 0
	v_mfma_f32_16x16x32_bf16 v[110:113], v[138:141], v[176:179], 0
	v_mfma_f32_16x16x32_bf16 v[98:101], v[130:133], v[184:187], 0
	v_mfma_f32_16x16x32_bf16 v[90:93], v[138:141], v[184:187], 0
	v_mfma_f32_16x16x32_bf16 v[82:85], v[130:133], v[192:195], 0
	v_mfma_f32_16x16x32_bf16 v[74:77], v[138:141], v[192:195], 0
	v_mfma_f32_16x16x32_bf16 v[126:129], v[134:137], v[172:175], v[126:129]
	v_mfma_f32_16x16x32_bf16 v[122:125], v[142:145], v[172:175], v[122:125]
	v_mfma_f32_16x16x32_bf16 v[118:121], v[134:137], v[180:183], v[118:121]
	v_mfma_f32_16x16x32_bf16 v[110:113], v[142:145], v[180:183], v[110:113]
	v_mfma_f32_16x16x32_bf16 v[98:101], v[134:137], v[188:191], v[98:101]
	v_mfma_f32_16x16x32_bf16 v[90:93], v[142:145], v[188:191], v[90:93]
	v_mfma_f32_16x16x32_bf16 v[82:85], v[134:137], v[196:199], v[82:85]
	v_mfma_f32_16x16x32_bf16 v[74:77], v[142:145], v[196:199], v[74:77]
	s_barrier
	s_mov_b32 m0, s53
	v_lshl_add_u64 v[164:165], s[38:39], 0, v[156:157]
	ds_read_b128 v[200:203], v170
	ds_read_b128 v[204:207], v170 offset:1024
	ds_read_b128 v[208:211], v170 offset:2048
	ds_read_b128 v[212:215], v170 offset:3072
	global_load_lds_dwordx4 v[164:165], off
	v_lshl_add_u64 v[216:217], s[38:39], 0, v[152:153]
	s_mov_b32 m0, s54
	s_nop 0
	global_load_lds_dwordx4 v[216:217], off
	s_waitcnt vmcnt(10)
	s_barrier
	s_waitcnt lgkmcnt(0)
	s_waitcnt lgkmcnt(0)
	v_mfma_f32_16x16x32_bf16 v[114:117], v[200:203], v[146:149], 0
	v_mfma_f32_16x16x32_bf16 v[106:109], v[208:211], v[146:149], 0
	v_mfma_f32_16x16x32_bf16 v[102:105], v[200:203], v[176:179], 0
	v_mfma_f32_16x16x32_bf16 v[94:97], v[208:211], v[176:179], 0
	v_mfma_f32_16x16x32_bf16 v[86:89], v[200:203], v[184:187], 0
	v_mfma_f32_16x16x32_bf16 v[78:81], v[208:211], v[184:187], 0
	v_mfma_f32_16x16x32_bf16 v[70:73], v[200:203], v[192:195], 0
	v_mfma_f32_16x16x32_bf16 v[66:69], v[208:211], v[192:195], 0
	v_mfma_f32_16x16x32_bf16 v[114:117], v[204:207], v[172:175], v[114:117]
	v_mfma_f32_16x16x32_bf16 v[106:109], v[212:215], v[172:175], v[106:109]
	v_mfma_f32_16x16x32_bf16 v[102:105], v[204:207], v[180:183], v[102:105]
	v_mfma_f32_16x16x32_bf16 v[94:97], v[212:215], v[180:183], v[94:97]
	v_mfma_f32_16x16x32_bf16 v[86:89], v[204:207], v[188:191], v[86:89]
	v_mfma_f32_16x16x32_bf16 v[78:81], v[212:215], v[188:191], v[78:81]
	v_mfma_f32_16x16x32_bf16 v[70:73], v[204:207], v[196:199], v[70:73]
	v_mfma_f32_16x16x32_bf16 v[66:69], v[212:215], v[196:199], v[66:69]
	s_mov_b32 m0, s9
	v_lshl_add_u64 v[218:219], s[40:41], 0, v[158:159]
	s_barrier
	ds_read_b128 v[146:149], v169 offset:16384
	ds_read_b128 v[172:175], v169 offset:17408
	ds_read_b128 v[176:179], v169 offset:18432
	ds_read_b128 v[180:183], v169 offset:19456
	ds_read_b128 v[184:187], v169 offset:20480
	ds_read_b128 v[188:191], v169 offset:21504
	ds_read_b128 v[192:195], v169 offset:22528
	ds_read_b128 v[196:199], v169 offset:23552
	global_load_lds_dwordx4 v[218:219], off
	v_lshl_add_u64 v[220:221], s[40:41], 0, v[154:155]
	s_mov_b32 m0, s29
	s_nop 0
	global_load_lds_dwordx4 v[220:221], off
	s_waitcnt vmcnt(10)
	s_barrier
	s_waitcnt lgkmcnt(0)
	s_waitcnt lgkmcnt(0)
	v_mfma_f32_16x16x32_bf16 v[62:65], v[130:133], v[146:149], 0
	v_mfma_f32_16x16x32_bf16 v[58:61], v[138:141], v[146:149], 0
	v_mfma_f32_16x16x32_bf16 v[50:53], v[130:133], v[176:179], 0
	v_mfma_f32_16x16x32_bf16 v[42:45], v[138:141], v[176:179], 0
	v_mfma_f32_16x16x32_bf16 v[34:37], v[130:133], v[184:187], 0
	v_mfma_f32_16x16x32_bf16 v[26:29], v[138:141], v[184:187], 0
	v_mfma_f32_16x16x32_bf16 v[18:21], v[130:133], v[192:195], 0
	v_mfma_f32_16x16x32_bf16 v[10:13], v[138:141], v[192:195], 0
	v_mfma_f32_16x16x32_bf16 v[62:65], v[134:137], v[172:175], v[62:65]
	v_mfma_f32_16x16x32_bf16 v[58:61], v[142:145], v[172:175], v[58:61]
	v_mfma_f32_16x16x32_bf16 v[50:53], v[134:137], v[180:183], v[50:53]
	v_mfma_f32_16x16x32_bf16 v[42:45], v[142:145], v[180:183], v[42:45]
	v_mfma_f32_16x16x32_bf16 v[34:37], v[134:137], v[188:191], v[34:37]
	v_mfma_f32_16x16x32_bf16 v[26:29], v[142:145], v[188:191], v[26:29]
	v_mfma_f32_16x16x32_bf16 v[18:21], v[134:137], v[196:199], v[18:21]
	v_mfma_f32_16x16x32_bf16 v[10:13], v[142:145], v[196:199], v[10:13]
	s_barrier
	s_add_u32 s0, s38, 0x40000
	s_addc_u32 s1, s39, 0
	s_mov_b32 m0, s55
	v_lshl_add_u64 v[130:131], s[0:1], 0, v[156:157]
	global_load_lds_dwordx4 v[130:131], off
	v_lshl_add_u64 v[130:131], s[0:1], 0, v[152:153]
	s_add_i32 m0, s55, 0x2000
	s_nop 0
	global_load_lds_dwordx4 v[130:131], off
	s_waitcnt vmcnt(10)
	s_barrier
	v_mfma_f32_16x16x32_bf16 v[54:57], v[200:203], v[146:149], 0
	v_mfma_f32_16x16x32_bf16 v[46:49], v[208:211], v[146:149], 0
	v_mfma_f32_16x16x32_bf16 v[38:41], v[200:203], v[176:179], 0
	v_mfma_f32_16x16x32_bf16 v[30:33], v[208:211], v[176:179], 0
	v_mfma_f32_16x16x32_bf16 v[22:25], v[200:203], v[184:187], 0
	v_mfma_f32_16x16x32_bf16 v[14:17], v[208:211], v[184:187], 0
	v_mfma_f32_16x16x32_bf16 v[6:9], v[200:203], v[192:195], 0
	v_mfma_f32_16x16x32_bf16 v[2:5], v[208:211], v[192:195], 0
	v_mfma_f32_16x16x32_bf16 v[54:57], v[204:207], v[172:175], v[54:57]
	v_mfma_f32_16x16x32_bf16 v[46:49], v[212:215], v[172:175], v[46:49]
	v_mfma_f32_16x16x32_bf16 v[38:41], v[204:207], v[180:183], v[38:41]
	v_mfma_f32_16x16x32_bf16 v[30:33], v[212:215], v[180:183], v[30:33]
	v_mfma_f32_16x16x32_bf16 v[22:25], v[204:207], v[188:191], v[22:25]
	v_mfma_f32_16x16x32_bf16 v[14:17], v[212:215], v[188:191], v[14:17]
	v_mfma_f32_16x16x32_bf16 v[6:9], v[204:207], v[196:199], v[6:9]
	v_mfma_f32_16x16x32_bf16 v[2:5], v[212:215], v[196:199], v[2:5]
	s_add_i32 s70, 0, 0x18000
	v_add_u32_e32 v142, s70, v167
	s_barrier
	ds_read_b128 v[130:133], v142
	ds_read_b128 v[134:137], v142 offset:1024
	ds_read_b128 v[138:141], v142 offset:2048
	ds_read_b128 v[142:145], v142 offset:3072
	s_add_u32 s0, s40, 0x40000
	s_addc_u32 s1, s41, 0
	s_mov_b32 m0, s42
	v_lshl_add_u64 v[200:201], s[0:1], 0, v[158:159]
	ds_read_b128 v[146:149], v169 offset:32768
	ds_read_b128 v[172:175], v169 offset:33792
	ds_read_b128 v[176:179], v169 offset:34816
	ds_read_b128 v[180:183], v169 offset:35840
	ds_read_b128 v[184:187], v169 offset:36864
	ds_read_b128 v[188:191], v169 offset:37888
	ds_read_b128 v[192:195], v169 offset:38912
	ds_read_b128 v[196:199], v169 offset:39936
	global_load_lds_dwordx4 v[200:201], off
	v_lshl_add_u64 v[200:201], s[0:1], 0, v[154:155]
	s_mov_b32 m0, s43
	s_nop 0
	global_load_lds_dwordx4 v[200:201], off
	s_waitcnt lgkmcnt(8)
	s_waitcnt vmcnt(10)
	s_barrier
	s_waitcnt lgkmcnt(0)
	s_waitcnt lgkmcnt(0)
	v_mfma_f32_16x16x32_bf16 v[126:129], v[130:133], v[146:149], v[126:129]
	v_mfma_f32_16x16x32_bf16 v[122:125], v[138:141], v[146:149], v[122:125]
	v_mfma_f32_16x16x32_bf16 v[118:121], v[130:133], v[176:179], v[118:121]
	v_mfma_f32_16x16x32_bf16 v[110:113], v[138:141], v[176:179], v[110:113]
	v_mfma_f32_16x16x32_bf16 v[98:101], v[130:133], v[184:187], v[98:101]
	v_mfma_f32_16x16x32_bf16 v[90:93], v[138:141], v[184:187], v[90:93]
	v_mfma_f32_16x16x32_bf16 v[82:85], v[130:133], v[192:195], v[82:85]
	v_mfma_f32_16x16x32_bf16 v[74:77], v[138:141], v[192:195], v[74:77]
	v_mfma_f32_16x16x32_bf16 v[126:129], v[134:137], v[172:175], v[126:129]
	v_mfma_f32_16x16x32_bf16 v[122:125], v[142:145], v[172:175], v[122:125]
	v_mfma_f32_16x16x32_bf16 v[118:121], v[134:137], v[180:183], v[118:121]
	v_mfma_f32_16x16x32_bf16 v[110:113], v[142:145], v[180:183], v[110:113]
	v_mfma_f32_16x16x32_bf16 v[98:101], v[134:137], v[188:191], v[98:101]
	v_mfma_f32_16x16x32_bf16 v[90:93], v[142:145], v[188:191], v[90:93]
	v_mfma_f32_16x16x32_bf16 v[82:85], v[134:137], v[196:199], v[82:85]
	v_mfma_f32_16x16x32_bf16 v[74:77], v[142:145], v[196:199], v[74:77]
	s_barrier
	s_add_i32 s40, 0, 0x1c000
	s_add_i32 s0, s70, s8
	v_add_u32_e32 v171, s40, v167
	v_lshl_add_u64 v[164:165], v[164:165], 0, s[26:27]
	s_mov_b32 m0, s0
	ds_read_b128 v[200:203], v171
	ds_read_b128 v[204:207], v171 offset:1024
	ds_read_b128 v[208:211], v171 offset:2048
	ds_read_b128 v[212:215], v171 offset:3072
	global_load_lds_dwordx4 v[164:165], off
	v_lshl_add_u64 v[164:165], v[216:217], 0, s[26:27]
	s_add_i32 m0, s0, 0x2000
	s_nop 0
	global_load_lds_dwordx4 v[164:165], off
	s_waitcnt vmcnt(10)
	s_barrier
	s_waitcnt lgkmcnt(0)
	s_waitcnt lgkmcnt(0)
	v_mfma_f32_16x16x32_bf16 v[114:117], v[200:203], v[146:149], v[114:117]
	v_mfma_f32_16x16x32_bf16 v[106:109], v[208:211], v[146:149], v[106:109]
	v_mfma_f32_16x16x32_bf16 v[102:105], v[200:203], v[176:179], v[102:105]
	v_mfma_f32_16x16x32_bf16 v[94:97], v[208:211], v[176:179], v[94:97]
	v_mfma_f32_16x16x32_bf16 v[86:89], v[200:203], v[184:187], v[86:89]
	v_mfma_f32_16x16x32_bf16 v[78:81], v[208:211], v[184:187], v[78:81]
	v_mfma_f32_16x16x32_bf16 v[70:73], v[200:203], v[192:195], v[70:73]
	v_mfma_f32_16x16x32_bf16 v[66:69], v[208:211], v[192:195], v[66:69]
	v_mfma_f32_16x16x32_bf16 v[114:117], v[204:207], v[172:175], v[114:117]
	v_mfma_f32_16x16x32_bf16 v[106:109], v[212:215], v[172:175], v[106:109]
	v_mfma_f32_16x16x32_bf16 v[102:105], v[204:207], v[180:183], v[102:105]
	v_mfma_f32_16x16x32_bf16 v[94:97], v[212:215], v[180:183], v[94:97]
	v_mfma_f32_16x16x32_bf16 v[86:89], v[204:207], v[188:191], v[86:89]
	v_mfma_f32_16x16x32_bf16 v[78:81], v[212:215], v[188:191], v[78:81]
	v_mfma_f32_16x16x32_bf16 v[70:73], v[204:207], v[196:199], v[70:73]
	v_mfma_f32_16x16x32_bf16 v[66:69], v[212:215], v[196:199], v[66:69]
	s_mov_b32 m0, s49
	v_lshl_add_u64 v[164:165], v[218:219], 0, s[26:27]
	s_barrier
	ds_read_b128 v[146:149], v169 offset:49152
	ds_read_b128 v[172:175], v169 offset:50176
	ds_read_b128 v[176:179], v169 offset:51200
	ds_read_b128 v[180:183], v169 offset:52224
	ds_read_b128 v[184:187], v169 offset:53248
	ds_read_b128 v[188:191], v169 offset:54272
	ds_read_b128 v[192:195], v169 offset:55296
	ds_read_b128 v[196:199], v169 offset:56320
	global_load_lds_dwordx4 v[164:165], off
	v_lshl_add_u64 v[164:165], v[220:221], 0, s[26:27]
	s_mov_b32 m0, s50
	s_nop 0
	global_load_lds_dwordx4 v[164:165], off
	s_waitcnt vmcnt(10)
	s_barrier
	s_waitcnt lgkmcnt(0)
	s_waitcnt lgkmcnt(0)
	v_mfma_f32_16x16x32_bf16 v[62:65], v[130:133], v[146:149], v[62:65]
	v_mfma_f32_16x16x32_bf16 v[58:61], v[138:141], v[146:149], v[58:61]
	v_mfma_f32_16x16x32_bf16 v[50:53], v[130:133], v[176:179], v[50:53]
	v_mfma_f32_16x16x32_bf16 v[42:45], v[138:141], v[176:179], v[42:45]
	v_mfma_f32_16x16x32_bf16 v[34:37], v[130:133], v[184:187], v[34:37]
	v_mfma_f32_16x16x32_bf16 v[26:29], v[138:141], v[184:187], v[26:29]
	v_mfma_f32_16x16x32_bf16 v[18:21], v[130:133], v[192:195], v[18:21]
	v_mfma_f32_16x16x32_bf16 v[10:13], v[138:141], v[192:195], v[10:13]
	v_mfma_f32_16x16x32_bf16 v[62:65], v[134:137], v[172:175], v[62:65]
	v_mfma_f32_16x16x32_bf16 v[58:61], v[142:145], v[172:175], v[58:61]
	v_mfma_f32_16x16x32_bf16 v[50:53], v[134:137], v[180:183], v[50:53]
	v_mfma_f32_16x16x32_bf16 v[42:45], v[142:145], v[180:183], v[42:45]
	v_mfma_f32_16x16x32_bf16 v[34:37], v[134:137], v[188:191], v[34:37]
	v_mfma_f32_16x16x32_bf16 v[26:29], v[142:145], v[188:191], v[26:29]
	v_mfma_f32_16x16x32_bf16 v[18:21], v[134:137], v[196:199], v[18:21]
	v_mfma_f32_16x16x32_bf16 v[10:13], v[142:145], v[196:199], v[10:13]
	s_barrier
	s_add_u32 s0, s38, 0x40080
	s_addc_u32 s1, s39, 0
	s_add_i32 s38, s40, s8
	v_lshl_add_u64 v[130:131], s[0:1], 0, v[156:157]
	s_mov_b32 m0, s38
	s_nop 0
	global_load_lds_dwordx4 v[130:131], off
	v_lshl_add_u64 v[130:131], s[0:1], 0, v[152:153]
	s_add_i32 m0, s38, 0x2000
	s_nop 0
	global_load_lds_dwordx4 v[130:131], off
	s_waitcnt vmcnt(10)
	s_barrier
	v_mfma_f32_16x16x32_bf16 v[54:57], v[200:203], v[146:149], v[54:57]
	v_mfma_f32_16x16x32_bf16 v[46:49], v[208:211], v[146:149], v[46:49]
	v_mfma_f32_16x16x32_bf16 v[38:41], v[200:203], v[176:179], v[38:41]
	v_mfma_f32_16x16x32_bf16 v[30:33], v[208:211], v[176:179], v[30:33]
	v_mfma_f32_16x16x32_bf16 v[22:25], v[200:203], v[184:187], v[22:25]
	v_mfma_f32_16x16x32_bf16 v[14:17], v[208:211], v[184:187], v[14:17]
	v_mfma_f32_16x16x32_bf16 v[6:9], v[200:203], v[192:195], v[6:9]
	v_mfma_f32_16x16x32_bf16 v[2:5], v[208:211], v[192:195], v[2:5]
	v_mfma_f32_16x16x32_bf16 v[54:57], v[204:207], v[172:175], v[54:57]
	v_mfma_f32_16x16x32_bf16 v[46:49], v[212:215], v[172:175], v[46:49]
	v_mfma_f32_16x16x32_bf16 v[38:41], v[204:207], v[180:183], v[38:41]
	v_mfma_f32_16x16x32_bf16 v[30:33], v[212:215], v[180:183], v[30:33]
	v_mfma_f32_16x16x32_bf16 v[22:25], v[204:207], v[188:191], v[22:25]
	v_mfma_f32_16x16x32_bf16 v[14:17], v[212:215], v[188:191], v[14:17]
	v_mfma_f32_16x16x32_bf16 v[6:9], v[204:207], v[196:199], v[6:9]
	v_mfma_f32_16x16x32_bf16 v[2:5], v[212:215], v[196:199], v[2:5]
	s_add_i32 s69, s69, 2
	s_add_u32 s65, s65, 0x100
	s_addc_u32 s67, s67, 0
	s_add_u32 s36, s36, 0x100
	s_addc_u32 s37, s37, 0
	s_cmp_gt_u32 s69, 13
	s_barrier
	s_cbranch_scc1 .Lpeel_exit_16

.Lpeel_exit_16:
	s_lshl_b32 s0, s59, 8
	v_mov_b32_e32 v130, v151
	v_mov_b32_e32 v131, v166
	s_or_b32 s0, s0, s46
	s_mov_b32 s59, s58
	v_lshl_add_u32 v164, v131, 3, s0
	s_lshl_b32 s0, s60, 8
	s_add_i32 s0, s0, s45
	v_add_u32_e32 v171, s0, v130
	v_mov_b32_e32 v130, v171
	v_ashrrev_i32_e32 v165, 31, v164
	v_ashrrev_i32_e32 v131, 31, v130
	v_lshlrev_b64 v[130:131], 10, v[130:131]
	v_lshl_add_u64 v[130:131], v[130:131], 0, v[164:165]
	v_lshlrev_b64 v[184:185], 1, v[130:131]
	v_lshl_add_u64 v[130:131], s[10:11], 0, v[184:185]
	global_load_dwordx4 v[172:175], v[130:131], off
	global_load_dwordx4 v[176:179], v[130:131], off offset:256
	v_add_co_u32_e32 v132, vcc, s48, v130
	s_mov_b32 s60, s57
	s_nop 0
	v_addc_co_u32_e32 v133, vcc, 0, v131, vcc
	global_load_dwordx4 v[180:183], v[132:133], off
	global_load_dwordx4 v[146:149], v[132:133], off offset:256
	v_add_co_u32_e32 v132, vcc, s44, v130
	s_waitcnt vmcnt(0) lgkmcnt(0)
	v_lshlrev_b32_e32 v186, 16, v172
	v_addc_co_u32_e32 v133, vcc, 0, v131, vcc
	global_load_dwordx4 v[142:145], v[132:133], off
	global_load_dwordx4 v[138:141], v[132:133], off offset:256
	v_add_co_u32_e32 v130, vcc, s47, v130
	v_and_b32_e32 v187, 0xffff0000, v172
	s_nop 0
	v_addc_co_u32_e32 v131, vcc, 0, v131, vcc
	global_load_dwordx4 v[134:137], v[130:131], off
	s_nop 0
	global_load_dwordx4 v[130:133], v[130:131], off offset:256
	v_lshlrev_b32_e32 v172, 16, v173
	v_and_b32_e32 v173, 0xffff0000, v173
	v_lshlrev_b32_e32 v188, 16, v174
	v_and_b32_e32 v189, 0xffff0000, v174
	v_lshlrev_b32_e32 v174, 16, v175
	v_and_b32_e32 v175, 0xffff0000, v175
	v_pk_fma_f32 v[128:129], v[172:173], s[28:29], v[128:129] op_sel_hi:[1,0,1]
	v_pk_fma_f32 v[126:127], v[186:187], s[28:29], v[126:127] op_sel_hi:[1,0,1]
	v_pk_fma_f32 v[172:173], v[174:175], s[28:29], v[124:125] op_sel_hi:[1,0,1]
	v_pk_fma_f32 v[122:123], v[188:189], s[28:29], v[122:123] op_sel_hi:[1,0,1]
	v_cvt_pk_bf16_f32 v124, v126, v127
	v_cvt_pk_bf16_f32 v125, v128, v129
	v_cvt_pk_bf16_f32 v126, v122, v123
	v_cvt_pk_bf16_f32 v127, v172, v173
	v_lshl_add_u64 v[122:123], s[16:17], 0, v[184:185]
	global_store_dwordx4 v[122:123], v[124:127], off
	v_lshlrev_b32_e32 v128, 16, v178
	v_and_b32_e32 v129, 0xffff0000, v178
	v_lshlrev_b32_e32 v124, 16, v176
	v_and_b32_e32 v125, 0xffff0000, v176
	v_lshlrev_b32_e32 v126, 16, v177
	v_and_b32_e32 v127, 0xffff0000, v177
	v_lshlrev_b32_e32 v172, 16, v179
	v_and_b32_e32 v173, 0xffff0000, v179
	v_pk_fma_f32 v[116:117], v[126:127], s[28:29], v[116:117] op_sel_hi:[1,0,1]
	v_pk_fma_f32 v[114:115], v[124:125], s[28:29], v[114:115] op_sel_hi:[1,0,1]
	v_pk_fma_f32 v[124:125], v[172:173], s[28:29], v[108:109] op_sel_hi:[1,0,1]
	v_pk_fma_f32 v[108:109], v[128:129], s[28:29], v[106:107] op_sel_hi:[1,0,1]
	v_cvt_pk_bf16_f32 v106, v114, v115
	v_cvt_pk_bf16_f32 v107, v116, v117
	v_cvt_pk_bf16_f32 v108, v108, v109
	v_cvt_pk_bf16_f32 v109, v124, v125
	global_store_dwordx4 v[122:123], v[106:109], off offset:256
	v_lshlrev_b32_e32 v114, 16, v182
	v_and_b32_e32 v115, 0xffff0000, v182
	v_lshlrev_b32_e32 v106, 16, v180
	v_and_b32_e32 v107, 0xffff0000, v180
	v_lshlrev_b32_e32 v108, 16, v181
	v_and_b32_e32 v109, 0xffff0000, v181
	v_lshlrev_b32_e32 v116, 16, v183
	v_and_b32_e32 v117, 0xffff0000, v183
	v_pk_fma_f32 v[108:109], v[108:109], s[28:29], v[120:121] op_sel_hi:[1,0,1]
	v_pk_fma_f32 v[106:107], v[106:107], s[28:29], v[118:119] op_sel_hi:[1,0,1]
	v_pk_fma_f32 v[110:111], v[114:115], s[28:29], v[110:111] op_sel_hi:[1,0,1]
	v_pk_fma_f32 v[112:113], v[116:117], s[28:29], v[112:113] op_sel_hi:[1,0,1]
	v_cvt_pk_bf16_f32 v106, v106, v107
	v_cvt_pk_bf16_f32 v107, v108, v109
	v_cvt_pk_bf16_f32 v108, v110, v111
	v_add_co_u32_e32 v110, vcc, s48, v122
	v_cvt_pk_bf16_f32 v109, v112, v113
	s_nop 0
	v_addc_co_u32_e32 v111, vcc, 0, v123, vcc
	global_store_dwordx4 v[110:111], v[106:109], off
	v_lshlrev_b32_e32 v112, 16, v148
	v_and_b32_e32 v113, 0xffff0000, v148
	v_lshlrev_b32_e32 v106, 16, v146
	v_and_b32_e32 v107, 0xffff0000, v146
	v_lshlrev_b32_e32 v108, 16, v147
	v_and_b32_e32 v109, 0xffff0000, v147
	v_lshlrev_b32_e32 v114, 16, v149
	v_and_b32_e32 v115, 0xffff0000, v149
	v_pk_fma_f32 v[104:105], v[108:109], s[28:29], v[104:105] op_sel_hi:[1,0,1]
	v_pk_fma_f32 v[102:103], v[106:107], s[28:29], v[102:103] op_sel_hi:[1,0,1]
	v_pk_fma_f32 v[106:107], v[114:115], s[28:29], v[96:97] op_sel_hi:[1,0,1]
	v_pk_fma_f32 v[96:97], v[112:113], s[28:29], v[94:95] op_sel_hi:[1,0,1]
	v_cvt_pk_bf16_f32 v94, v102, v103
	v_cvt_pk_bf16_f32 v95, v104, v105
	v_cvt_pk_bf16_f32 v96, v96, v97
	v_cvt_pk_bf16_f32 v97, v106, v107
	global_store_dwordx4 v[110:111], v[94:97], off offset:256
	s_waitcnt vmcnt(0) lgkmcnt(0)
	v_lshlrev_b32_e32 v102, 16, v144
	v_lshlrev_b32_e32 v94, 16, v142
	v_and_b32_e32 v95, 0xffff0000, v142
	v_lshlrev_b32_e32 v96, 16, v143
	v_and_b32_e32 v97, 0xffff0000, v143
	v_and_b32_e32 v103, 0xffff0000, v144
	v_lshlrev_b32_e32 v104, 16, v145
	v_and_b32_e32 v105, 0xffff0000, v145
	v_pk_fma_f32 v[94:95], v[94:95], s[28:29], v[98:99] op_sel_hi:[1,0,1]
	v_pk_fma_f32 v[96:97], v[96:97], s[28:29], v[100:101] op_sel_hi:[1,0,1]
	v_pk_fma_f32 v[98:99], v[104:105], s[28:29], v[92:93] op_sel_hi:[1,0,1]
	v_pk_fma_f32 v[92:93], v[102:103], s[28:29], v[90:91] op_sel_hi:[1,0,1]
	v_cvt_pk_bf16_f32 v90, v94, v95
	v_add_co_u32_e32 v94, vcc, s44, v122
	v_cvt_pk_bf16_f32 v91, v96, v97
	v_cvt_pk_bf16_f32 v92, v92, v93
	v_cvt_pk_bf16_f32 v93, v98, v99
	v_addc_co_u32_e32 v95, vcc, 0, v123, vcc
	global_store_dwordx4 v[94:95], v[90:93], off
	v_lshlrev_b32_e32 v96, 16, v140
	v_and_b32_e32 v97, 0xffff0000, v140
	v_lshlrev_b32_e32 v90, 16, v138
	v_and_b32_e32 v91, 0xffff0000, v138
	v_lshlrev_b32_e32 v92, 16, v139
	v_and_b32_e32 v93, 0xffff0000, v139
	v_lshlrev_b32_e32 v98, 16, v141
	v_and_b32_e32 v99, 0xffff0000, v141
	v_pk_fma_f32 v[88:89], v[92:93], s[28:29], v[88:89] op_sel_hi:[1,0,1]
	v_pk_fma_f32 v[86:87], v[90:91], s[28:29], v[86:87] op_sel_hi:[1,0,1]
	v_pk_fma_f32 v[90:91], v[98:99], s[28:29], v[80:81] op_sel_hi:[1,0,1]
	v_pk_fma_f32 v[80:81], v[96:97], s[28:29], v[78:79] op_sel_hi:[1,0,1]
	v_cvt_pk_bf16_f32 v78, v86, v87
	v_cvt_pk_bf16_f32 v79, v88, v89
	v_cvt_pk_bf16_f32 v80, v80, v81
	v_cvt_pk_bf16_f32 v81, v90, v91
	global_store_dwordx4 v[94:95], v[78:81], off offset:256
	v_lshlrev_b32_e32 v86, 16, v136
	v_and_b32_e32 v87, 0xffff0000, v136
	v_lshlrev_b32_e32 v78, 16, v134
	v_and_b32_e32 v79, 0xffff0000, v134
	v_lshlrev_b32_e32 v80, 16, v135
	v_and_b32_e32 v81, 0xffff0000, v135
	v_lshlrev_b32_e32 v88, 16, v137
	v_and_b32_e32 v89, 0xffff0000, v137
	v_pk_fma_f32 v[78:79], v[78:79], s[28:29], v[82:83] op_sel_hi:[1,0,1]
	v_pk_fma_f32 v[80:81], v[80:81], s[28:29], v[84:85] op_sel_hi:[1,0,1]
	v_pk_fma_f32 v[82:83], v[88:89], s[28:29], v[76:77] op_sel_hi:[1,0,1]
	v_pk_fma_f32 v[76:77], v[86:87], s[28:29], v[74:75] op_sel_hi:[1,0,1]
	v_cvt_pk_bf16_f32 v74, v78, v79
	v_add_co_u32_e32 v78, vcc, s47, v122
	v_cvt_pk_bf16_f32 v75, v80, v81
	v_cvt_pk_bf16_f32 v76, v76, v77
	v_cvt_pk_bf16_f32 v77, v82, v83
	v_addc_co_u32_e32 v79, vcc, 0, v123, vcc
	global_store_dwordx4 v[78:79], v[74:77], off
	v_lshlrev_b32_e32 v80, 16, v132
	v_and_b32_e32 v81, 0xffff0000, v132
	v_lshlrev_b32_e32 v74, 16, v130
	v_and_b32_e32 v75, 0xffff0000, v130
	v_lshlrev_b32_e32 v76, 16, v131
	v_and_b32_e32 v77, 0xffff0000, v131
	v_lshlrev_b32_e32 v82, 16, v133
	v_and_b32_e32 v83, 0xffff0000, v133
	v_pk_fma_f32 v[72:73], v[76:77], s[28:29], v[72:73] op_sel_hi:[1,0,1]
	v_pk_fma_f32 v[70:71], v[74:75], s[28:29], v[70:71] op_sel_hi:[1,0,1]
	v_pk_fma_f32 v[74:75], v[82:83], s[28:29], v[68:69] op_sel_hi:[1,0,1]
	v_pk_fma_f32 v[68:69], v[80:81], s[28:29], v[66:67] op_sel_hi:[1,0,1]
	v_cvt_pk_bf16_f32 v66, v70, v71
	v_cvt_pk_bf16_f32 v67, v72, v73
	v_cvt_pk_bf16_f32 v68, v68, v69
	v_cvt_pk_bf16_f32 v69, v74, v75
	global_store_dwordx4 v[78:79], v[66:69], off offset:256
	s_nop 1
	v_add_u32_e32 v66, 0x80, v171
	s_nop 0
	v_ashrrev_i32_e32 v67, 31, v66
	v_lshlrev_b64 v[66:67], 10, v[66:67]
	v_lshl_add_u64 v[66:67], v[66:67], 0, v[164:165]
	v_lshlrev_b64 v[98:99], 1, v[66:67]
	v_lshl_add_u64 v[90:91], s[10:11], 0, v[98:99]
	global_load_dwordx4 v[66:69], v[90:91], off
	global_load_dwordx4 v[70:73], v[90:91], off offset:256
	v_add_co_u32_e32 v78, vcc, s48, v90
	s_waitcnt vmcnt(0) lgkmcnt(0)
	v_lshlrev_b32_e32 v100, 16, v66
	v_addc_co_u32_e32 v79, vcc, 0, v91, vcc
	global_load_dwordx4 v[74:77], v[78:79], off
	s_nop 0
	global_load_dwordx4 v[78:81], v[78:79], off offset:256
	v_add_co_u32_e32 v86, vcc, s44, v90
	v_and_b32_e32 v101, 0xffff0000, v66
	s_nop 0
	v_addc_co_u32_e32 v87, vcc, 0, v91, vcc
	global_load_dwordx4 v[82:85], v[86:87], off
	s_nop 0
	global_load_dwordx4 v[86:89], v[86:87], off offset:256
	v_add_co_u32_e32 v94, vcc, s47, v90
	v_lshlrev_b32_e32 v66, 16, v67
	s_nop 0
	v_addc_co_u32_e32 v95, vcc, 0, v91, vcc
	global_load_dwordx4 v[90:93], v[94:95], off
	s_nop 0
	global_load_dwordx4 v[94:97], v[94:95], off offset:256
	v_and_b32_e32 v67, 0xffff0000, v67
	v_lshlrev_b32_e32 v102, 16, v68
	v_and_b32_e32 v103, 0xffff0000, v68
	v_lshlrev_b32_e32 v68, 16, v69
	v_and_b32_e32 v69, 0xffff0000, v69
	v_pk_fma_f32 v[64:65], v[66:67], s[28:29], v[64:65] op_sel_hi:[1,0,1]
	v_pk_fma_f32 v[62:63], v[100:101], s[28:29], v[62:63] op_sel_hi:[1,0,1]
	v_pk_fma_f32 v[66:67], v[68:69], s[28:29], v[60:61] op_sel_hi:[1,0,1]
	v_pk_fma_f32 v[60:61], v[102:103], s[28:29], v[58:59] op_sel_hi:[1,0,1]
	v_cvt_pk_bf16_f32 v58, v62, v63
	v_cvt_pk_bf16_f32 v59, v64, v65
	v_cvt_pk_bf16_f32 v60, v60, v61
	v_cvt_pk_bf16_f32 v61, v66, v67
	v_lshl_add_u64 v[62:63], s[16:17], 0, v[98:99]
	global_store_dwordx4 v[62:63], v[58:61], off
	v_lshlrev_b32_e32 v64, 16, v72
	v_and_b32_e32 v65, 0xffff0000, v72
	v_lshlrev_b32_e32 v58, 16, v70
	v_and_b32_e32 v59, 0xffff0000, v70
	v_lshlrev_b32_e32 v60, 16, v71
	v_and_b32_e32 v61, 0xffff0000, v71
	v_lshlrev_b32_e32 v66, 16, v73
	v_and_b32_e32 v67, 0xffff0000, v73
	v_pk_fma_f32 v[56:57], v[60:61], s[28:29], v[56:57] op_sel_hi:[1,0,1]
	v_pk_fma_f32 v[54:55], v[58:59], s[28:29], v[54:55] op_sel_hi:[1,0,1]
	v_pk_fma_f32 v[58:59], v[66:67], s[28:29], v[48:49] op_sel_hi:[1,0,1]
	v_pk_fma_f32 v[48:49], v[64:65], s[28:29], v[46:47] op_sel_hi:[1,0,1]
	v_cvt_pk_bf16_f32 v46, v54, v55
	v_cvt_pk_bf16_f32 v47, v56, v57
	v_cvt_pk_bf16_f32 v48, v48, v49
	v_cvt_pk_bf16_f32 v49, v58, v59
	global_store_dwordx4 v[62:63], v[46:49], off offset:256
	s_waitcnt vmcnt(0) lgkmcnt(0)
	v_lshlrev_b32_e32 v54, 16, v76
	v_lshlrev_b32_e32 v46, 16, v74
	v_and_b32_e32 v47, 0xffff0000, v74
	v_lshlrev_b32_e32 v48, 16, v75
	v_and_b32_e32 v49, 0xffff0000, v75
	v_and_b32_e32 v55, 0xffff0000, v76
	v_lshlrev_b32_e32 v56, 16, v77
	v_and_b32_e32 v57, 0xffff0000, v77
	v_pk_fma_f32 v[46:47], v[46:47], s[28:29], v[50:51] op_sel_hi:[1,0,1]
	v_pk_fma_f32 v[48:49], v[48:49], s[28:29], v[52:53] op_sel_hi:[1,0,1]
	v_pk_fma_f32 v[50:51], v[56:57], s[28:29], v[44:45] op_sel_hi:[1,0,1]
	v_pk_fma_f32 v[44:45], v[54:55], s[28:29], v[42:43] op_sel_hi:[1,0,1]
	v_cvt_pk_bf16_f32 v42, v46, v47
	v_add_co_u32_e32 v46, vcc, s48, v62
	v_cvt_pk_bf16_f32 v43, v48, v49
	v_cvt_pk_bf16_f32 v44, v44, v45
	v_cvt_pk_bf16_f32 v45, v50, v51
	v_addc_co_u32_e32 v47, vcc, 0, v63, vcc
	global_store_dwordx4 v[46:47], v[42:45], off
	v_lshlrev_b32_e32 v48, 16, v80
	v_and_b32_e32 v49, 0xffff0000, v80
	v_lshlrev_b32_e32 v42, 16, v78
	v_and_b32_e32 v43, 0xffff0000, v78
	v_lshlrev_b32_e32 v44, 16, v79
	v_and_b32_e32 v45, 0xffff0000, v79
	v_lshlrev_b32_e32 v50, 16, v81
	v_and_b32_e32 v51, 0xffff0000, v81
	v_pk_fma_f32 v[40:41], v[44:45], s[28:29], v[40:41] op_sel_hi:[1,0,1]
	v_pk_fma_f32 v[38:39], v[42:43], s[28:29], v[38:39] op_sel_hi:[1,0,1]
	v_pk_fma_f32 v[42:43], v[50:51], s[28:29], v[32:33] op_sel_hi:[1,0,1]
	v_pk_fma_f32 v[32:33], v[48:49], s[28:29], v[30:31] op_sel_hi:[1,0,1]
	v_cvt_pk_bf16_f32 v30, v38, v39
	v_cvt_pk_bf16_f32 v31, v40, v41
	v_cvt_pk_bf16_f32 v32, v32, v33
	v_cvt_pk_bf16_f32 v33, v42, v43
	global_store_dwordx4 v[46:47], v[30:33], off offset:256
	v_lshlrev_b32_e32 v38, 16, v84
	v_and_b32_e32 v39, 0xffff0000, v84
	v_lshlrev_b32_e32 v30, 16, v82
	v_and_b32_e32 v31, 0xffff0000, v82
	v_lshlrev_b32_e32 v32, 16, v83
	v_and_b32_e32 v33, 0xffff0000, v83
	v_lshlrev_b32_e32 v40, 16, v85
	v_and_b32_e32 v41, 0xffff0000, v85
	v_pk_fma_f32 v[30:31], v[30:31], s[28:29], v[34:35] op_sel_hi:[1,0,1]
	v_pk_fma_f32 v[32:33], v[32:33], s[28:29], v[36:37] op_sel_hi:[1,0,1]
	v_pk_fma_f32 v[34:35], v[40:41], s[28:29], v[28:29] op_sel_hi:[1,0,1]
	v_pk_fma_f32 v[28:29], v[38:39], s[28:29], v[26:27] op_sel_hi:[1,0,1]
	v_cvt_pk_bf16_f32 v26, v30, v31
	v_add_co_u32_e32 v30, vcc, s44, v62
	v_cvt_pk_bf16_f32 v27, v32, v33
	v_cvt_pk_bf16_f32 v28, v28, v29
	v_cvt_pk_bf16_f32 v29, v34, v35
	v_addc_co_u32_e32 v31, vcc, 0, v63, vcc
	global_store_dwordx4 v[30:31], v[26:29], off
	v_lshlrev_b32_e32 v32, 16, v88
	v_and_b32_e32 v33, 0xffff0000, v88
	v_lshlrev_b32_e32 v26, 16, v86
	v_and_b32_e32 v27, 0xffff0000, v86
	v_lshlrev_b32_e32 v28, 16, v87
	v_and_b32_e32 v29, 0xffff0000, v87
	v_lshlrev_b32_e32 v34, 16, v89
	v_and_b32_e32 v35, 0xffff0000, v89
	v_pk_fma_f32 v[24:25], v[28:29], s[28:29], v[24:25] op_sel_hi:[1,0,1]
	v_pk_fma_f32 v[22:23], v[26:27], s[28:29], v[22:23] op_sel_hi:[1,0,1]
	v_pk_fma_f32 v[26:27], v[34:35], s[28:29], v[16:17] op_sel_hi:[1,0,1]
	v_pk_fma_f32 v[16:17], v[32:33], s[28:29], v[14:15] op_sel_hi:[1,0,1]
	v_cvt_pk_bf16_f32 v14, v22, v23
	v_cvt_pk_bf16_f32 v15, v24, v25
	v_cvt_pk_bf16_f32 v16, v16, v17
	v_cvt_pk_bf16_f32 v17, v26, v27
	global_store_dwordx4 v[30:31], v[14:17], off offset:256
	v_lshlrev_b32_e32 v22, 16, v92
	v_and_b32_e32 v23, 0xffff0000, v92
	v_lshlrev_b32_e32 v14, 16, v90
	v_and_b32_e32 v15, 0xffff0000, v90
	v_lshlrev_b32_e32 v16, 16, v91
	v_and_b32_e32 v17, 0xffff0000, v91
	v_lshlrev_b32_e32 v24, 16, v93
	v_and_b32_e32 v25, 0xffff0000, v93
	v_pk_fma_f32 v[14:15], v[14:15], s[28:29], v[18:19] op_sel_hi:[1,0,1]
	v_pk_fma_f32 v[16:17], v[16:17], s[28:29], v[20:21] op_sel_hi:[1,0,1]
	v_pk_fma_f32 v[18:19], v[24:25], s[28:29], v[12:13] op_sel_hi:[1,0,1]
	v_pk_fma_f32 v[12:13], v[22:23], s[28:29], v[10:11] op_sel_hi:[1,0,1]
	v_cvt_pk_bf16_f32 v10, v14, v15
	v_add_co_u32_e32 v14, vcc, s47, v62
	v_cvt_pk_bf16_f32 v11, v16, v17
	v_cvt_pk_bf16_f32 v12, v12, v13
	v_cvt_pk_bf16_f32 v13, v18, v19
	v_addc_co_u32_e32 v15, vcc, 0, v63, vcc
	global_store_dwordx4 v[14:15], v[10:13], off
	v_lshlrev_b32_e32 v16, 16, v96
	v_and_b32_e32 v17, 0xffff0000, v96
	v_lshlrev_b32_e32 v10, 16, v94
	v_and_b32_e32 v11, 0xffff0000, v94
	v_lshlrev_b32_e32 v12, 16, v95
	v_and_b32_e32 v13, 0xffff0000, v95
	v_lshlrev_b32_e32 v18, 16, v97
	v_and_b32_e32 v19, 0xffff0000, v97
	v_pk_fma_f32 v[8:9], v[12:13], s[28:29], v[8:9] op_sel_hi:[1,0,1]
	v_pk_fma_f32 v[6:7], v[10:11], s[28:29], v[6:7] op_sel_hi:[1,0,1]
	v_pk_fma_f32 v[10:11], v[18:19], s[28:29], v[4:5] op_sel_hi:[1,0,1]
	v_pk_fma_f32 v[4:5], v[16:17], s[28:29], v[2:3] op_sel_hi:[1,0,1]
	v_cvt_pk_bf16_f32 v2, v6, v7
	v_cvt_pk_bf16_f32 v3, v8, v9
	v_cvt_pk_bf16_f32 v4, v4, v5
	v_cvt_pk_bf16_f32 v5, v10, v11
	s_and_b64 vcc, exec, s[30:31]
	global_store_dwordx4 v[14:15], v[2:5], off offset:256
	s_cbranch_vccz .LBB0_2494
	s_waitcnt vmcnt(0)
	s_cmpk_gt_u32 s5, 0xff
	s_cbranch_scc1 .LBB0_2499
	s_barrier

.LBB0_2748:
	s_ashr_i32 s0, s54, 5
	s_ashr_i32 s1, s0, 31
	s_lshl_b64 s[0:1], s[0:1], 21
	s_add_u32 s12, s4, s0
	s_addc_u32 s13, s5, s1
	s_ashr_i32 s25, s24, 31
	s_lshl_b64 s[0:1], s[24:25], 18
	s_add_u32 s12, s12, s0
	s_addc_u32 s13, s13, s1
	s_and_b64 s[0:1], s[10:11], exec
	s_cselect_b32 s25, s13, s31
	s_cselect_b32 s27, s12, s30
	v_mov_b32_e32 v173, v163
	v_mov_b32_e32 v175, v163
	s_add_u32 s29, s30, 0x100
	s_addc_u32 s55, s31, 0
	v_lshl_add_u64 v[176:177], s[18:19], 0, v[174:175]
	v_lshl_add_u64 v[178:179], s[18:19], 0, v[172:173]
	s_mov_b32 s56, -2
	s_mov_b64 s[34:35], 0
	s_add_u32 s10, s34, 0x100
	s_addc_u32 s11, s35, 0
	s_add_u32 s30, s29, s34
	s_addc_u32 s31, s55, s35
	s_cmpk_eq_i32 s34, 0x300
	s_cselect_b64 vcc, -1, 0
	s_and_b64 s[0:1], vcc, exec
	s_cselect_b32 s1, 0, s10
	s_cselect_b32 s0, 0, s11
	s_cselect_b32 s30, s27, s30
	s_cselect_b32 s31, s25, s31
	s_add_u32 s36, s14, s1
	s_addc_u32 s37, s15, s0
	s_add_i32 s1, 0, 0x10000
	v_add_u32_e32 v14, s1, v196
	ds_read_b128 v[2:5], v14
	ds_read_b128 v[6:9], v14 offset:1024
	ds_read_b128 v[10:13], v14 offset:2048
	ds_read_b128 v[14:17], v14 offset:3072
	v_cndmask_b32_e32 v162, v168, v171, vcc
	v_cndmask_b32_e32 v184, v170, v197, vcc
	v_cndmask_b32_e32 v175, v172, v198, vcc
	v_cndmask_b32_e32 v173, v174, v199, vcc
	v_lshl_add_u64 v[18:19], v[178:179], 0, s[34:35]
	s_add_i32 m0, s45, 0xc000
	ds_read_b128 v[200:203], v169
	ds_read_b128 v[204:207], v169 offset:1024
	ds_read_b128 v[208:211], v169 offset:2048
	ds_read_b128 v[212:215], v169 offset:3072
	ds_read_b128 v[216:219], v169 offset:4096
	ds_read_b128 v[220:223], v169 offset:5120
	ds_read_b128 v[224:227], v169 offset:6144
	ds_read_b128 v[228:231], v169 offset:7168
	global_load_lds_dwordx4 v[18:19], off
	v_lshl_add_u64 v[18:19], v[176:177], 0, s[34:35]
	s_add_i32 m0, s45, 0xe000
	s_nop 0
	global_load_lds_dwordx4 v[18:19], off
	s_waitcnt lgkmcnt(8)
	s_waitcnt vmcnt(10)
	s_barrier
	s_waitcnt lgkmcnt(0)
	s_waitcnt lgkmcnt(0)
	v_mfma_scale_f32_16x16x128_f8f6f4 v[158:161], v[2:9], v[200:207], 0, v1, v1 op_sel_hi:[0,0,0]
	v_mfma_scale_f32_16x16x128_f8f6f4 v[150:153], v[10:17], v[200:207], 0, v1, v1 op_sel_hi:[0,0,0]
	v_mfma_scale_f32_16x16x128_f8f6f4 v[142:145], v[2:9], v[208:215], 0, v1, v1 op_sel_hi:[0,0,0]
	v_mfma_scale_f32_16x16x128_f8f6f4 v[134:137], v[10:17], v[208:215], 0, v1, v1 op_sel_hi:[0,0,0]
	v_mfma_scale_f32_16x16x128_f8f6f4 v[126:129], v[2:9], v[216:223], 0, v1, v1 op_sel_hi:[0,0,0]
	v_mfma_scale_f32_16x16x128_f8f6f4 v[118:121], v[10:17], v[216:223], 0, v1, v1 op_sel_hi:[0,0,0]
	v_mfma_scale_f32_16x16x128_f8f6f4 v[110:113], v[2:9], v[224:231], 0, v1, v1 op_sel_hi:[0,0,0]
	v_mfma_scale_f32_16x16x128_f8f6f4 v[102:105], v[10:17], v[224:231], 0, v1, v1 op_sel_hi:[0,0,0]
	s_barrier
	s_add_i32 s0, 0, 0x14000
	s_add_i32 s1, s1, s43
	v_add_u32_e32 v30, s0, v196
	v_lshl_add_u64 v[180:181], s[30:31], 0, v[164:165]
	s_mov_b32 m0, s1
	ds_read_b128 v[18:21], v30
	ds_read_b128 v[22:25], v30 offset:1024
	ds_read_b128 v[26:29], v30 offset:2048
	ds_read_b128 v[30:33], v30 offset:3072
	global_load_lds_dwordx4 v[180:181], off
	v_lshl_add_u64 v[182:183], s[30:31], 0, v[166:167]
	s_add_i32 m0, s1, 0x2000
	s_nop 0
	global_load_lds_dwordx4 v[182:183], off
	s_waitcnt vmcnt(10)
	s_barrier
	s_waitcnt lgkmcnt(0)
	s_waitcnt lgkmcnt(0)
	v_mfma_scale_f32_16x16x128_f8f6f4 v[154:157], v[18:25], v[200:207], 0, v1, v1 op_sel_hi:[0,0,0]
	v_mfma_scale_f32_16x16x128_f8f6f4 v[146:149], v[26:33], v[200:207], 0, v1, v1 op_sel_hi:[0,0,0]
	v_mfma_scale_f32_16x16x128_f8f6f4 v[138:141], v[18:25], v[208:215], 0, v1, v1 op_sel_hi:[0,0,0]
	v_mfma_scale_f32_16x16x128_f8f6f4 v[130:133], v[26:33], v[208:215], 0, v1, v1 op_sel_hi:[0,0,0]
	v_mfma_scale_f32_16x16x128_f8f6f4 v[122:125], v[18:25], v[216:223], 0, v1, v1 op_sel_hi:[0,0,0]
	v_mfma_scale_f32_16x16x128_f8f6f4 v[114:117], v[26:33], v[216:223], 0, v1, v1 op_sel_hi:[0,0,0]
	v_mfma_scale_f32_16x16x128_f8f6f4 v[106:109], v[18:25], v[224:231], 0, v1, v1 op_sel_hi:[0,0,0]
	v_mfma_scale_f32_16x16x128_f8f6f4 v[98:101], v[26:33], v[224:231], 0, v1, v1 op_sel_hi:[0,0,0]
	s_mov_b32 m0, s45
	s_barrier
	ds_read_b128 v[200:203], v169 offset:16384
	ds_read_b128 v[204:207], v169 offset:17408
	ds_read_b128 v[208:211], v169 offset:18432
	ds_read_b128 v[212:215], v169 offset:19456
	ds_read_b128 v[216:219], v169 offset:20480
	ds_read_b128 v[220:223], v169 offset:21504
	ds_read_b128 v[224:227], v169 offset:22528
	ds_read_b128 v[228:231], v169 offset:23552
	global_load_lds_dwordx4 v162, s[36:37]
	s_mov_b32 m0, s46
	v_mov_b32_e32 v185, v163
	global_load_lds_dwordx4 v184, s[36:37]
	s_waitcnt vmcnt(10)
	s_barrier
	s_waitcnt lgkmcnt(0)
	v_lshl_add_u64 v[186:187], s[36:37], 0, v[162:163]
	v_lshl_add_u64 v[184:185], s[36:37], 0, v[184:185]
	s_waitcnt lgkmcnt(0)
	v_mfma_scale_f32_16x16x128_f8f6f4 v[94:97], v[2:9], v[200:207], 0, v1, v1 op_sel_hi:[0,0,0]
	v_mfma_scale_f32_16x16x128_f8f6f4 v[86:89], v[10:17], v[200:207], 0, v1, v1 op_sel_hi:[0,0,0]
	v_mfma_scale_f32_16x16x128_f8f6f4 v[78:81], v[2:9], v[208:215], 0, v1, v1 op_sel_hi:[0,0,0]
	v_mfma_scale_f32_16x16x128_f8f6f4 v[70:73], v[10:17], v[208:215], 0, v1, v1 op_sel_hi:[0,0,0]
	v_mfma_scale_f32_16x16x128_f8f6f4 v[62:65], v[2:9], v[216:223], 0, v1, v1 op_sel_hi:[0,0,0]
	v_mfma_scale_f32_16x16x128_f8f6f4 v[54:57], v[10:17], v[216:223], 0, v1, v1 op_sel_hi:[0,0,0]
	v_mfma_scale_f32_16x16x128_f8f6f4 v[46:49], v[2:9], v[224:231], 0, v1, v1 op_sel_hi:[0,0,0]
	v_mfma_scale_f32_16x16x128_f8f6f4 v[38:41], v[10:17], v[224:231], 0, v1, v1 op_sel_hi:[0,0,0]
	s_barrier
	s_add_u32 s34, s30, 0x20000
	s_addc_u32 s35, s31, 0
	s_add_i32 s0, s0, s43
	v_lshl_add_u64 v[2:3], s[34:35], 0, v[164:165]
	s_mov_b32 m0, s0
	s_nop 0
	global_load_lds_dwordx4 v[2:3], off
	v_lshl_add_u64 v[2:3], s[34:35], 0, v[166:167]
	s_add_i32 m0, s0, 0x2000
	s_nop 0
	global_load_lds_dwordx4 v[2:3], off
	s_waitcnt vmcnt(10)
	s_barrier
	v_mfma_scale_f32_16x16x128_f8f6f4 v[90:93], v[18:25], v[200:207], 0, v1, v1 op_sel_hi:[0,0,0]
	v_mfma_scale_f32_16x16x128_f8f6f4 v[82:85], v[26:33], v[200:207], 0, v1, v1 op_sel_hi:[0,0,0]
	v_mfma_scale_f32_16x16x128_f8f6f4 v[74:77], v[18:25], v[208:215], 0, v1, v1 op_sel_hi:[0,0,0]
	v_mfma_scale_f32_16x16x128_f8f6f4 v[66:69], v[26:33], v[208:215], 0, v1, v1 op_sel_hi:[0,0,0]
	v_mfma_scale_f32_16x16x128_f8f6f4 v[58:61], v[18:25], v[216:223], 0, v1, v1 op_sel_hi:[0,0,0]
	v_mfma_scale_f32_16x16x128_f8f6f4 v[50:53], v[26:33], v[216:223], 0, v1, v1 op_sel_hi:[0,0,0]
	v_mfma_scale_f32_16x16x128_f8f6f4 v[42:45], v[18:25], v[224:231], 0, v1, v1 op_sel_hi:[0,0,0]
	v_mfma_scale_f32_16x16x128_f8f6f4 v[34:37], v[26:33], v[224:231], 0, v1, v1 op_sel_hi:[0,0,0]
	s_add_i32 s0, 0, 0x18000
	v_add_u32_e32 v14, s0, v196
	s_barrier
	ds_read_b128 v[2:5], v14
	ds_read_b128 v[6:9], v14 offset:1024
	ds_read_b128 v[10:13], v14 offset:2048
	ds_read_b128 v[14:17], v14 offset:3072
	s_mov_b32 m0, s47
	ds_read_b128 v[18:21], v169 offset:32768
	ds_read_b128 v[22:25], v169 offset:33792
	ds_read_b128 v[26:29], v169 offset:34816
	ds_read_b128 v[30:33], v169 offset:35840
	ds_read_b128 v[200:203], v169 offset:36864
	ds_read_b128 v[204:207], v169 offset:37888
	ds_read_b128 v[208:211], v169 offset:38912
	ds_read_b128 v[212:215], v169 offset:39936
	global_load_lds_dwordx4 v175, s[36:37]
	s_mov_b32 m0, s48
	s_nop 0
	global_load_lds_dwordx4 v173, s[36:37]
	s_waitcnt lgkmcnt(8)
	s_waitcnt vmcnt(10)
	s_barrier
	s_waitcnt lgkmcnt(0)
	s_waitcnt lgkmcnt(0)
	v_mfma_scale_f32_16x16x128_f8f6f4 v[158:161], v[2:9], v[18:25], v[158:161], v1, v1 op_sel_hi:[0,0,0]
	v_mfma_scale_f32_16x16x128_f8f6f4 v[150:153], v[10:17], v[18:25], v[150:153], v1, v1 op_sel_hi:[0,0,0]
	v_mfma_scale_f32_16x16x128_f8f6f4 v[142:145], v[2:9], v[26:33], v[142:145], v1, v1 op_sel_hi:[0,0,0]
	v_mfma_scale_f32_16x16x128_f8f6f4 v[134:137], v[10:17], v[26:33], v[134:137], v1, v1 op_sel_hi:[0,0,0]
	v_mfma_scale_f32_16x16x128_f8f6f4 v[126:129], v[2:9], v[200:207], v[126:129], v1, v1 op_sel_hi:[0,0,0]
	v_mfma_scale_f32_16x16x128_f8f6f4 v[118:121], v[10:17], v[200:207], v[118:121], v1, v1 op_sel_hi:[0,0,0]
	v_mfma_scale_f32_16x16x128_f8f6f4 v[110:113], v[2:9], v[208:215], v[110:113], v1, v1 op_sel_hi:[0,0,0]
	v_mfma_scale_f32_16x16x128_f8f6f4 v[102:105], v[10:17], v[208:215], v[102:105], v1, v1 op_sel_hi:[0,0,0]
	s_barrier
	s_add_i32 s34, 0, 0x1c000
	s_add_i32 s0, s0, s43
	v_add_u32_e32 v162, s34, v196
	v_lshl_add_u64 v[180:181], v[180:181], 0, s[20:21]
	s_mov_b32 m0, s0
	ds_read_b128 v[216:219], v162
	ds_read_b128 v[220:223], v162 offset:1024
	ds_read_b128 v[224:227], v162 offset:2048
	ds_read_b128 v[228:231], v162 offset:3072
	global_load_lds_dwordx4 v[180:181], off
	v_lshl_add_u64 v[180:181], v[182:183], 0, s[20:21]
	s_add_i32 m0, s0, 0x2000
	s_nop 0
	global_load_lds_dwordx4 v[180:181], off
	s_waitcnt vmcnt(10)
	s_barrier
	s_waitcnt lgkmcnt(0)
	s_waitcnt lgkmcnt(0)
	v_mfma_scale_f32_16x16x128_f8f6f4 v[154:157], v[216:223], v[18:25], v[154:157], v1, v1 op_sel_hi:[0,0,0]
	v_mfma_scale_f32_16x16x128_f8f6f4 v[146:149], v[224:231], v[18:25], v[146:149], v1, v1 op_sel_hi:[0,0,0]
	v_mfma_scale_f32_16x16x128_f8f6f4 v[138:141], v[216:223], v[26:33], v[138:141], v1, v1 op_sel_hi:[0,0,0]
	v_mfma_scale_f32_16x16x128_f8f6f4 v[130:133], v[224:231], v[26:33], v[130:133], v1, v1 op_sel_hi:[0,0,0]
	v_mfma_scale_f32_16x16x128_f8f6f4 v[122:125], v[216:223], v[200:207], v[122:125], v1, v1 op_sel_hi:[0,0,0]
	v_mfma_scale_f32_16x16x128_f8f6f4 v[114:117], v[224:231], v[200:207], v[114:117], v1, v1 op_sel_hi:[0,0,0]
	v_mfma_scale_f32_16x16x128_f8f6f4 v[106:109], v[216:223], v[208:215], v[106:109], v1, v1 op_sel_hi:[0,0,0]
	v_mfma_scale_f32_16x16x128_f8f6f4 v[98:101], v[224:231], v[208:215], v[98:101], v1, v1 op_sel_hi:[0,0,0]
	s_mov_b32 m0, s51
	v_lshl_add_u64 v[180:181], v[186:187], 0, s[20:21]
	s_barrier
	ds_read_b128 v[18:21], v169 offset:49152
	ds_read_b128 v[22:25], v169 offset:50176
	ds_read_b128 v[26:29], v169 offset:51200
	ds_read_b128 v[30:33], v169 offset:52224
	ds_read_b128 v[200:203], v169 offset:53248
	ds_read_b128 v[204:207], v169 offset:54272
	ds_read_b128 v[208:211], v169 offset:55296
	ds_read_b128 v[212:215], v169 offset:56320
	global_load_lds_dwordx4 v[180:181], off
	v_lshl_add_u64 v[180:181], v[184:185], 0, s[20:21]
	s_mov_b32 m0, s52
	s_nop 0
	global_load_lds_dwordx4 v[180:181], off
	s_waitcnt vmcnt(10)
	s_barrier
	s_waitcnt lgkmcnt(0)
	s_waitcnt lgkmcnt(0)
	v_mfma_scale_f32_16x16x128_f8f6f4 v[94:97], v[2:9], v[18:25], v[94:97], v1, v1 op_sel_hi:[0,0,0]
	v_mfma_scale_f32_16x16x128_f8f6f4 v[86:89], v[10:17], v[18:25], v[86:89], v1, v1 op_sel_hi:[0,0,0]
	v_mfma_scale_f32_16x16x128_f8f6f4 v[78:81], v[2:9], v[26:33], v[78:81], v1, v1 op_sel_hi:[0,0,0]
	v_mfma_scale_f32_16x16x128_f8f6f4 v[70:73], v[10:17], v[26:33], v[70:73], v1, v1 op_sel_hi:[0,0,0]
	v_mfma_scale_f32_16x16x128_f8f6f4 v[62:65], v[2:9], v[200:207], v[62:65], v1, v1 op_sel_hi:[0,0,0]
	v_mfma_scale_f32_16x16x128_f8f6f4 v[54:57], v[10:17], v[200:207], v[54:57], v1, v1 op_sel_hi:[0,0,0]
	v_mfma_scale_f32_16x16x128_f8f6f4 v[46:49], v[2:9], v[208:215], v[46:49], v1, v1 op_sel_hi:[0,0,0]
	v_mfma_scale_f32_16x16x128_f8f6f4 v[38:41], v[10:17], v[208:215], v[38:41], v1, v1 op_sel_hi:[0,0,0]
	s_barrier
	s_add_u32 s0, s30, 0x20080
	s_addc_u32 s1, s31, 0
	s_add_i32 s30, s34, s43
	v_lshl_add_u64 v[2:3], s[0:1], 0, v[164:165]
	s_mov_b32 m0, s30
	s_nop 0
	global_load_lds_dwordx4 v[2:3], off
	v_lshl_add_u64 v[2:3], s[0:1], 0, v[166:167]
	s_add_i32 m0, s30, 0x2000
	s_nop 0
	global_load_lds_dwordx4 v[2:3], off
	s_waitcnt vmcnt(10)
	s_barrier
	v_mfma_scale_f32_16x16x128_f8f6f4 v[90:93], v[216:223], v[18:25], v[90:93], v1, v1 op_sel_hi:[0,0,0]
	v_mfma_scale_f32_16x16x128_f8f6f4 v[82:85], v[224:231], v[18:25], v[82:85], v1, v1 op_sel_hi:[0,0,0]
	v_mfma_scale_f32_16x16x128_f8f6f4 v[74:77], v[216:223], v[26:33], v[74:77], v1, v1 op_sel_hi:[0,0,0]
	v_mfma_scale_f32_16x16x128_f8f6f4 v[66:69], v[224:231], v[26:33], v[66:69], v1, v1 op_sel_hi:[0,0,0]
	v_mfma_scale_f32_16x16x128_f8f6f4 v[58:61], v[216:223], v[200:207], v[58:61], v1, v1 op_sel_hi:[0,0,0]
	v_mfma_scale_f32_16x16x128_f8f6f4 v[50:53], v[224:231], v[200:207], v[50:53], v1, v1 op_sel_hi:[0,0,0]
	v_mfma_scale_f32_16x16x128_f8f6f4 v[42:45], v[216:223], v[208:215], v[42:45], v1, v1 op_sel_hi:[0,0,0]
	v_mfma_scale_f32_16x16x128_f8f6f4 v[34:37], v[224:231], v[208:215], v[34:37], v1, v1 op_sel_hi:[0,0,0]
	s_add_i32 s56, s56, 2
	s_cmp_gt_u32 s56, 5
	s_mov_b64 s[34:35], s[10:11]
	s_barrier
	s_cbranch_scc1 .Lpeel_exit_17

.Lpeel_exit_17:
	v_mul_f32_e32 v5, 0x3b000000, v158
	v_mul_f32_e32 v6, 0xbcb8aa3b, v158
	v_exp_f32_e32 v6, v6
	s_ashr_i32 s29, s28, 31
	s_ashr_i32 s27, s26, 31
	s_lshl_b64 s[10:11], s[28:29], 18
	v_add_f32_e32 v6, 1.0, v6
	v_rcp_f32_e32 v6, v6
	s_lshl_b64 s[26:27], s[26:27], 15
	v_mov_b32_e32 v3, v194
	s_add_u32 s0, s8, s10
	v_mul_f32_e32 v5, v5, v6
	v_mul_f32_e32 v6, 0x3b000000, v159
	v_mul_f32_e32 v7, 0xbcb8aa3b, v159
	v_exp_f32_e32 v7, v7
	v_mul_f32_e32 v5, v5, v154
	v_med3_f32 v5, v5, s40, v189
	v_add_f32_e32 v7, 1.0, v7
	v_rcp_f32_e32 v7, v7
	s_nop 15
	s_nop 15
	v_mov_b32_e32 v2, v195
	v_mul_f32_e32 v6, v6, v7
	v_mul_f32_e32 v7, 0x3b000000, v160
	v_mul_f32_e32 v8, 0xbcb8aa3b, v160
	v_exp_f32_e32 v8, v8
	v_mul_f32_e32 v6, v6, v155
	v_add_u32_e32 v4, s49, v3
	v_add_f32_e32 v8, 1.0, v8
	v_rcp_f32_e32 v8, v8
	s_addc_u32 s1, s9, s11
	s_add_u32 s10, s0, s26
	v_mul_f32_e32 v7, v7, v8
	v_mul_f32_e32 v8, 0x3b000000, v161
	v_mul_f32_e32 v9, 0xbcb8aa3b, v161
	v_exp_f32_e32 v9, v9
	v_mul_f32_e32 v7, v7, v156
	v_lshl_add_u32 v2, v2, 3, s50
	v_add_f32_e32 v9, 1.0, v9
	v_rcp_f32_e32 v9, v9
	s_addc_u32 s11, s1, s27
	v_ashrrev_i32_e32 v3, 31, v2
	s_and_b64 vcc, exec, s[6:7]
	v_mul_f32_e32 v8, v8, v9
	v_mul_f32_e32 v9, 0x3b000000, v150
	v_mul_f32_e32 v10, 0xbcb8aa3b, v150
	v_exp_f32_e32 v10, v10
	v_mul_f32_e32 v8, v8, v157
	v_mov_b32_e32 v174, v199
	v_add_f32_e32 v10, 1.0, v10
	v_rcp_f32_e32 v10, v10
	v_mov_b32_e32 v172, v198
	v_mov_b32_e32 v170, v197
	v_mov_b32_e32 v168, v171
	v_mul_f32_e32 v9, v9, v10
	v_mul_f32_e32 v10, 0x3b000000, v151
	v_mul_f32_e32 v11, 0xbcb8aa3b, v151
	v_exp_f32_e32 v11, v11
	v_mul_f32_e32 v9, v9, v146
	s_mov_b32 s26, s24
	v_add_f32_e32 v11, 1.0, v11
	v_rcp_f32_e32 v11, v11
	s_mov_b32 s28, s54
	s_mov_b64 s[30:31], s[12:13]
	v_mul_f32_e32 v10, v10, v11
	v_mul_f32_e32 v11, 0x3b000000, v152
	v_mul_f32_e32 v12, 0xbcb8aa3b, v152
	v_exp_f32_e32 v12, v12
	v_mul_f32_e32 v10, v10, v147
	v_add_f32_e32 v12, 1.0, v12
	v_rcp_f32_e32 v12, v12
	s_nop 0
	v_mul_f32_e32 v11, v11, v12
	v_mul_f32_e32 v12, 0x3b000000, v153
	v_mul_f32_e32 v13, 0xbcb8aa3b, v153
	v_exp_f32_e32 v13, v13
	v_mul_f32_e32 v11, v11, v148
	v_add_f32_e32 v13, 1.0, v13
	v_rcp_f32_e32 v13, v13
	s_nop 0
	v_mul_f32_e32 v12, v12, v13
	v_med3_f32 v13, v6, s40, v189
	v_mov_b32_e32 v6, v163
	v_cvt_pk_fp8_f32 v6, v5, v13
	v_med3_f32 v5, v7, s40, v189
	v_med3_f32 v7, v8, s40, v189
	v_med3_f32 v8, v10, s40, v189
	v_cvt_pk_fp8_f32 v6, v5, v7 op_sel:[0,0,1]
	v_med3_f32 v5, v9, s40, v189
	v_mov_b32_e32 v7, v163
	v_cvt_pk_fp8_f32 v7, v5, v8
	v_mul_f32_e32 v12, v12, v149
	v_med3_f32 v5, v11, s40, v189
	v_med3_f32 v8, v12, s40, v189
	v_cvt_pk_fp8_f32 v7, v5, v8 op_sel:[0,0,1]
	v_ashrrev_i32_e32 v5, 31, v4
	v_lshlrev_b64 v[8:9], 7, v[4:5]
	v_lshl_add_u64 v[8:9], s[10:11], 0, v[8:9]
	v_lshl_add_u64 v[8:9], v[8:9], 0, v[2:3]
	v_mul_f32_e32 v5, 0x3b000000, v142
	global_store_dwordx2 v[8:9], v[6:7], off
	v_mul_f32_e32 v6, 0xbcb8aa3b, v142
	v_exp_f32_e32 v6, v6
	s_nop 0
	v_add_f32_e32 v6, 1.0, v6
	v_rcp_f32_e32 v6, v6
	s_nop 0
	v_mul_f32_e32 v5, v5, v6
	v_mul_f32_e32 v6, 0x3b000000, v143
	v_mul_f32_e32 v7, 0xbcb8aa3b, v143
	v_exp_f32_e32 v7, v7
	v_mul_f32_e32 v5, v5, v138
	v_med3_f32 v5, v5, s40, v189
	v_add_f32_e32 v7, 1.0, v7
	v_rcp_f32_e32 v7, v7
	s_nop 0
	v_mul_f32_e32 v6, v6, v7
	v_mul_f32_e32 v7, v6, v139
	v_mul_f32_e32 v6, 0x3b000000, v144
	v_mul_f32_e32 v8, 0xbcb8aa3b, v144
	v_exp_f32_e32 v8, v8
	v_med3_f32 v7, v7, s40, v189
	v_add_f32_e32 v8, 1.0, v8
	v_rcp_f32_e32 v8, v8
	s_nop 0
	v_mul_f32_e32 v6, v6, v8
	v_mul_f32_e32 v9, v6, v140
	v_mul_f32_e32 v6, 0x3b000000, v145
	v_mul_f32_e32 v8, 0xbcb8aa3b, v145
	v_exp_f32_e32 v8, v8
	s_nop 0
	v_add_f32_e32 v8, 1.0, v8
	v_rcp_f32_e32 v8, v8
	s_nop 0
	v_mul_f32_e32 v6, v6, v8
	v_mul_f32_e32 v10, v6, v141
	v_mul_f32_e32 v6, 0x3b000000, v134
	v_mul_f32_e32 v8, 0xbcb8aa3b, v134
	v_exp_f32_e32 v8, v8
	s_nop 0
	v_add_f32_e32 v8, 1.0, v8
	v_rcp_f32_e32 v8, v8
	s_nop 0
	v_mul_f32_e32 v6, v6, v8
	v_mul_f32_e32 v11, v6, v130
	v_mul_f32_e32 v6, 0x3b000000, v135
	v_mul_f32_e32 v8, 0xbcb8aa3b, v135
	v_exp_f32_e32 v8, v8
	s_nop 0
	v_add_f32_e32 v8, 1.0, v8
	v_rcp_f32_e32 v8, v8
	s_nop 0
	v_mul_f32_e32 v6, v6, v8
	v_mul_f32_e32 v12, v6, v131
	v_mul_f32_e32 v6, 0x3b000000, v136
	v_mul_f32_e32 v8, 0xbcb8aa3b, v136
	v_exp_f32_e32 v8, v8
	s_nop 0
	v_add_f32_e32 v8, 1.0, v8
	v_rcp_f32_e32 v8, v8
	s_nop 0
	v_mul_f32_e32 v6, v6, v8
	v_mul_f32_e32 v13, v6, v132
	v_mul_f32_e32 v6, 0x3b000000, v137
	v_mul_f32_e32 v8, 0xbcb8aa3b, v137
	v_exp_f32_e32 v8, v8
	s_nop 0
	v_add_f32_e32 v8, 1.0, v8
	v_rcp_f32_e32 v8, v8
	s_nop 0
	v_mul_f32_e32 v6, v6, v8
	v_mov_b32_e32 v8, v163
	v_cvt_pk_fp8_f32 v8, v5, v7
	v_med3_f32 v5, v9, s40, v189
	v_med3_f32 v7, v10, s40, v189
	v_mov_b32_e32 v9, v163
	v_cvt_pk_fp8_f32 v8, v5, v7 op_sel:[0,0,1]
	v_med3_f32 v5, v11, s40, v189
	v_med3_f32 v7, v12, s40, v189
	v_cvt_pk_fp8_f32 v9, v5, v7
	v_mul_f32_e32 v14, v6, v133
	v_add_u32_e32 v6, 16, v4
	v_med3_f32 v5, v13, s40, v189
	v_med3_f32 v7, v14, s40, v189
	v_cvt_pk_fp8_f32 v9, v5, v7 op_sel:[0,0,1]
	v_ashrrev_i32_e32 v7, 31, v6
	v_lshlrev_b64 v[6:7], 7, v[6:7]
	v_lshl_add_u64 v[6:7], s[10:11], 0, v[6:7]
	v_lshl_add_u64 v[6:7], v[6:7], 0, v[2:3]
	v_mul_f32_e32 v5, 0x3b000000, v126
	global_store_dwordx2 v[6:7], v[8:9], off
	v_mul_f32_e32 v6, 0xbcb8aa3b, v126
	v_exp_f32_e32 v6, v6
	s_nop 0
	v_add_f32_e32 v6, 1.0, v6
	v_rcp_f32_e32 v6, v6
	s_nop 0
	v_mul_f32_e32 v5, v5, v6
	v_mul_f32_e32 v6, 0x3b000000, v127
	v_mul_f32_e32 v7, 0xbcb8aa3b, v127
	v_exp_f32_e32 v7, v7
	v_mul_f32_e32 v5, v5, v122
	v_med3_f32 v5, v5, s40, v189
	v_add_f32_e32 v7, 1.0, v7
	v_rcp_f32_e32 v7, v7
	s_nop 0
	v_mul_f32_e32 v6, v6, v7
	v_mul_f32_e32 v7, v6, v123
	v_mul_f32_e32 v6, 0x3b000000, v128
	v_mul_f32_e32 v8, 0xbcb8aa3b, v128
	v_exp_f32_e32 v8, v8
	v_med3_f32 v7, v7, s40, v189
	v_add_f32_e32 v8, 1.0, v8
	v_rcp_f32_e32 v8, v8
	s_nop 0
	v_mul_f32_e32 v6, v6, v8
	v_mul_f32_e32 v9, v6, v124
	v_mul_f32_e32 v6, 0x3b000000, v129
	v_mul_f32_e32 v8, 0xbcb8aa3b, v129
	v_exp_f32_e32 v8, v8
	s_nop 0
	v_add_f32_e32 v8, 1.0, v8
	v_rcp_f32_e32 v8, v8
	s_nop 0
	v_mul_f32_e32 v6, v6, v8
	v_mul_f32_e32 v10, v6, v125
	v_mul_f32_e32 v6, 0x3b000000, v118
	v_mul_f32_e32 v8, 0xbcb8aa3b, v118
	v_exp_f32_e32 v8, v8
	s_nop 0
	v_add_f32_e32 v8, 1.0, v8
	v_rcp_f32_e32 v8, v8
	s_nop 0
	v_mul_f32_e32 v6, v6, v8
	v_mul_f32_e32 v11, v6, v114
	v_mul_f32_e32 v6, 0x3b000000, v119
	v_mul_f32_e32 v8, 0xbcb8aa3b, v119
	v_exp_f32_e32 v8, v8
	s_nop 0
	v_add_f32_e32 v8, 1.0, v8
	v_rcp_f32_e32 v8, v8
	s_nop 0
	v_mul_f32_e32 v6, v6, v8
	v_mul_f32_e32 v12, v6, v115
	v_mul_f32_e32 v6, 0x3b000000, v120
	v_mul_f32_e32 v8, 0xbcb8aa3b, v120
	v_exp_f32_e32 v8, v8
	s_nop 0
	v_add_f32_e32 v8, 1.0, v8
	v_rcp_f32_e32 v8, v8
	s_nop 0
	v_mul_f32_e32 v6, v6, v8
	v_mul_f32_e32 v13, v6, v116
	v_mul_f32_e32 v6, 0x3b000000, v121
	v_mul_f32_e32 v8, 0xbcb8aa3b, v121
	v_exp_f32_e32 v8, v8
	s_nop 0
	v_add_f32_e32 v8, 1.0, v8
	v_rcp_f32_e32 v8, v8
	s_nop 0
	v_mul_f32_e32 v6, v6, v8
	v_mov_b32_e32 v8, v163
	v_cvt_pk_fp8_f32 v8, v5, v7
	v_med3_f32 v5, v9, s40, v189
	v_med3_f32 v7, v10, s40, v189
	v_mov_b32_e32 v9, v163
	v_cvt_pk_fp8_f32 v8, v5, v7 op_sel:[0,0,1]
	v_med3_f32 v5, v11, s40, v189
	v_med3_f32 v7, v12, s40, v189
	v_cvt_pk_fp8_f32 v9, v5, v7
	v_mul_f32_e32 v14, v6, v117
	v_add_u32_e32 v6, 32, v4
	v_med3_f32 v5, v13, s40, v189
	v_med3_f32 v7, v14, s40, v189
	v_cvt_pk_fp8_f32 v9, v5, v7 op_sel:[0,0,1]
	v_ashrrev_i32_e32 v7, 31, v6
	v_lshlrev_b64 v[6:7], 7, v[6:7]
	v_lshl_add_u64 v[6:7], s[10:11], 0, v[6:7]
	v_lshl_add_u64 v[6:7], v[6:7], 0, v[2:3]
	v_mul_f32_e32 v5, 0x3b000000, v110
	global_store_dwordx2 v[6:7], v[8:9], off
	v_mul_f32_e32 v6, 0xbcb8aa3b, v110
	v_exp_f32_e32 v6, v6
	s_nop 0
	v_add_f32_e32 v6, 1.0, v6
	v_rcp_f32_e32 v6, v6
	s_nop 0
	v_mul_f32_e32 v5, v5, v6
	v_mul_f32_e32 v6, 0x3b000000, v111
	v_mul_f32_e32 v7, 0xbcb8aa3b, v111
	v_exp_f32_e32 v7, v7
	v_mul_f32_e32 v5, v5, v106
	v_med3_f32 v5, v5, s40, v189
	v_add_f32_e32 v7, 1.0, v7
	v_rcp_f32_e32 v7, v7
	s_nop 0
	v_mul_f32_e32 v6, v6, v7
	v_mul_f32_e32 v7, v6, v107
	v_mul_f32_e32 v6, 0x3b000000, v112
	v_mul_f32_e32 v8, 0xbcb8aa3b, v112
	v_exp_f32_e32 v8, v8
	v_med3_f32 v7, v7, s40, v189
	v_add_f32_e32 v8, 1.0, v8
	v_rcp_f32_e32 v8, v8
	s_nop 0
	v_mul_f32_e32 v6, v6, v8
	v_mul_f32_e32 v9, v6, v108
	v_mul_f32_e32 v6, 0x3b000000, v113
	v_mul_f32_e32 v8, 0xbcb8aa3b, v113
	v_exp_f32_e32 v8, v8
	s_nop 0
	v_add_f32_e32 v8, 1.0, v8
	v_rcp_f32_e32 v8, v8
	s_nop 0
	v_mul_f32_e32 v6, v6, v8
	v_mul_f32_e32 v10, v6, v109
	v_mul_f32_e32 v6, 0x3b000000, v102
	v_mul_f32_e32 v8, 0xbcb8aa3b, v102
	v_exp_f32_e32 v8, v8
	s_nop 0
	v_add_f32_e32 v8, 1.0, v8
	v_rcp_f32_e32 v8, v8
	s_nop 0
	v_mul_f32_e32 v6, v6, v8
	v_mul_f32_e32 v11, v6, v98
	v_mul_f32_e32 v6, 0x3b000000, v103
	v_mul_f32_e32 v8, 0xbcb8aa3b, v103
	v_exp_f32_e32 v8, v8
	s_nop 0
	v_add_f32_e32 v8, 1.0, v8
	v_rcp_f32_e32 v8, v8
	s_nop 0
	v_mul_f32_e32 v6, v6, v8
	v_mul_f32_e32 v12, v6, v99
	v_mul_f32_e32 v6, 0x3b000000, v104
	v_mul_f32_e32 v8, 0xbcb8aa3b, v104
	v_exp_f32_e32 v8, v8
	s_nop 0
	v_add_f32_e32 v8, 1.0, v8
	v_rcp_f32_e32 v8, v8
	s_nop 0
	v_mul_f32_e32 v6, v6, v8
	v_mul_f32_e32 v13, v6, v100
	v_mul_f32_e32 v6, 0x3b000000, v105
	v_mul_f32_e32 v8, 0xbcb8aa3b, v105
	v_exp_f32_e32 v8, v8
	s_nop 0
	v_add_f32_e32 v8, 1.0, v8
	v_rcp_f32_e32 v8, v8
	s_nop 0
	v_mul_f32_e32 v6, v6, v8
	v_mov_b32_e32 v8, v163
	v_cvt_pk_fp8_f32 v8, v5, v7
	v_med3_f32 v5, v9, s40, v189
	v_med3_f32 v7, v10, s40, v189
	v_mov_b32_e32 v9, v163
	v_cvt_pk_fp8_f32 v8, v5, v7 op_sel:[0,0,1]
	v_med3_f32 v5, v11, s40, v189
	v_med3_f32 v7, v12, s40, v189
	v_cvt_pk_fp8_f32 v9, v5, v7
	v_mul_f32_e32 v14, v6, v101
	v_add_u32_e32 v6, 48, v4
	v_med3_f32 v5, v13, s40, v189
	v_med3_f32 v7, v14, s40, v189
	v_cvt_pk_fp8_f32 v9, v5, v7 op_sel:[0,0,1]
	v_ashrrev_i32_e32 v7, 31, v6
	v_lshlrev_b64 v[6:7], 7, v[6:7]
	v_lshl_add_u64 v[6:7], s[10:11], 0, v[6:7]
	v_lshl_add_u64 v[6:7], v[6:7], 0, v[2:3]
	v_mul_f32_e32 v5, 0x3b000000, v94
	global_store_dwordx2 v[6:7], v[8:9], off
	v_mul_f32_e32 v7, 0xbcb8aa3b, v94
	v_exp_f32_e32 v7, v7
	v_add_u32_e32 v6, 0x80, v4
	v_add_f32_e32 v7, 1.0, v7
	v_rcp_f32_e32 v7, v7
	s_nop 0
	v_mul_f32_e32 v5, v5, v7
	v_mul_f32_e32 v7, 0x3b000000, v95
	v_mul_f32_e32 v8, 0xbcb8aa3b, v95
	v_exp_f32_e32 v8, v8
	v_mul_f32_e32 v5, v5, v90
	v_med3_f32 v5, v5, s40, v189
	v_add_f32_e32 v8, 1.0, v8
	v_rcp_f32_e32 v8, v8
	s_nop 0
	v_mul_f32_e32 v7, v7, v8
	v_mul_f32_e32 v8, 0x3b000000, v96
	v_mul_f32_e32 v9, 0xbcb8aa3b, v96
	v_exp_f32_e32 v9, v9
	v_mul_f32_e32 v7, v7, v91
	v_med3_f32 v7, v7, s40, v189
	v_add_f32_e32 v9, 1.0, v9
	v_rcp_f32_e32 v9, v9
	s_nop 0
	v_mul_f32_e32 v8, v8, v9
	v_mul_f32_e32 v9, v8, v92
	v_mul_f32_e32 v8, 0x3b000000, v97
	v_mul_f32_e32 v10, 0xbcb8aa3b, v97
	v_exp_f32_e32 v10, v10
	s_nop 0
	v_add_f32_e32 v10, 1.0, v10
	v_rcp_f32_e32 v10, v10
	s_nop 0
	v_mul_f32_e32 v8, v8, v10
	v_mul_f32_e32 v10, v8, v93
	v_mul_f32_e32 v8, 0x3b000000, v86
	v_mul_f32_e32 v11, 0xbcb8aa3b, v86
	v_exp_f32_e32 v11, v11
	s_nop 0
	v_add_f32_e32 v11, 1.0, v11
	v_rcp_f32_e32 v11, v11
	s_nop 0
	v_mul_f32_e32 v8, v8, v11
	v_mul_f32_e32 v11, v8, v82
	v_mul_f32_e32 v8, 0x3b000000, v87
	v_mul_f32_e32 v12, 0xbcb8aa3b, v87
	v_exp_f32_e32 v12, v12
	s_nop 0
	v_add_f32_e32 v12, 1.0, v12
	v_rcp_f32_e32 v12, v12
	s_nop 0
	v_mul_f32_e32 v8, v8, v12
	v_mul_f32_e32 v12, v8, v83
	v_mul_f32_e32 v8, 0x3b000000, v88
	v_mul_f32_e32 v13, 0xbcb8aa3b, v88
	v_exp_f32_e32 v13, v13
	s_nop 0
	v_add_f32_e32 v13, 1.0, v13
	v_rcp_f32_e32 v13, v13
	s_nop 0
	v_mul_f32_e32 v8, v8, v13
	v_mul_f32_e32 v13, v8, v84
	v_mul_f32_e32 v8, 0x3b000000, v89
	v_mul_f32_e32 v14, 0xbcb8aa3b, v89
	v_exp_f32_e32 v14, v14
	s_nop 0
	v_add_f32_e32 v14, 1.0, v14
	v_rcp_f32_e32 v14, v14
	s_nop 0
	v_mul_f32_e32 v8, v8, v14
	v_mul_f32_e32 v14, v8, v85
	v_mov_b32_e32 v8, v163
	v_cvt_pk_fp8_f32 v8, v5, v7
	v_med3_f32 v5, v9, s40, v189
	v_med3_f32 v7, v10, s40, v189
	v_mov_b32_e32 v9, v163
	v_cvt_pk_fp8_f32 v8, v5, v7 op_sel:[0,0,1]
	v_med3_f32 v5, v11, s40, v189
	v_med3_f32 v7, v12, s40, v189
	v_cvt_pk_fp8_f32 v9, v5, v7
	v_med3_f32 v5, v13, s40, v189
	v_med3_f32 v7, v14, s40, v189
	v_cvt_pk_fp8_f32 v9, v5, v7 op_sel:[0,0,1]
	v_ashrrev_i32_e32 v7, 31, v6
	v_lshlrev_b64 v[6:7], 7, v[6:7]
	v_lshl_add_u64 v[6:7], s[10:11], 0, v[6:7]
	v_lshl_add_u64 v[6:7], v[6:7], 0, v[2:3]
	v_mul_f32_e32 v5, 0x3b000000, v78
	global_store_dwordx2 v[6:7], v[8:9], off
	v_mul_f32_e32 v6, 0xbcb8aa3b, v78
	v_exp_f32_e32 v6, v6
	s_nop 0
	v_add_f32_e32 v6, 1.0, v6
	v_rcp_f32_e32 v6, v6
	s_nop 0
	v_mul_f32_e32 v5, v5, v6
	v_mul_f32_e32 v6, 0x3b000000, v79
	v_mul_f32_e32 v7, 0xbcb8aa3b, v79
	v_exp_f32_e32 v7, v7
	v_mul_f32_e32 v5, v5, v74
	v_med3_f32 v5, v5, s40, v189
	v_add_f32_e32 v7, 1.0, v7
	v_rcp_f32_e32 v7, v7
	s_nop 0
	v_mul_f32_e32 v6, v6, v7
	v_mul_f32_e32 v7, v6, v75
	v_mul_f32_e32 v6, 0x3b000000, v80
	v_mul_f32_e32 v8, 0xbcb8aa3b, v80
	v_exp_f32_e32 v8, v8
	v_med3_f32 v7, v7, s40, v189
	v_add_f32_e32 v8, 1.0, v8
	v_rcp_f32_e32 v8, v8
	s_nop 0
	v_mul_f32_e32 v6, v6, v8
	v_mul_f32_e32 v9, v6, v76
	v_mul_f32_e32 v6, 0x3b000000, v81
	v_mul_f32_e32 v8, 0xbcb8aa3b, v81
	v_exp_f32_e32 v8, v8
	s_nop 0
	v_add_f32_e32 v8, 1.0, v8
	v_rcp_f32_e32 v8, v8
	s_nop 0
	v_mul_f32_e32 v6, v6, v8
	v_mul_f32_e32 v10, v6, v77
	v_mul_f32_e32 v6, 0x3b000000, v70
	v_mul_f32_e32 v8, 0xbcb8aa3b, v70
	v_exp_f32_e32 v8, v8
	s_nop 0
	v_add_f32_e32 v8, 1.0, v8
	v_rcp_f32_e32 v8, v8
	s_nop 0
	v_mul_f32_e32 v6, v6, v8
	v_mul_f32_e32 v11, v6, v66
	v_mul_f32_e32 v6, 0x3b000000, v71
	v_mul_f32_e32 v8, 0xbcb8aa3b, v71
	v_exp_f32_e32 v8, v8
	s_nop 0
	v_add_f32_e32 v8, 1.0, v8
	v_rcp_f32_e32 v8, v8
	s_nop 0
	v_mul_f32_e32 v6, v6, v8
	v_mul_f32_e32 v12, v6, v67
	v_mul_f32_e32 v6, 0x3b000000, v72
	v_mul_f32_e32 v8, 0xbcb8aa3b, v72
	v_exp_f32_e32 v8, v8
	s_nop 0
	v_add_f32_e32 v8, 1.0, v8
	v_rcp_f32_e32 v8, v8
	s_nop 0
	v_mul_f32_e32 v6, v6, v8
	v_mul_f32_e32 v13, v6, v68
	v_mul_f32_e32 v6, 0x3b000000, v73
	v_mul_f32_e32 v8, 0xbcb8aa3b, v73
	v_exp_f32_e32 v8, v8
	s_nop 0
	v_add_f32_e32 v8, 1.0, v8
	v_rcp_f32_e32 v8, v8
	s_nop 0
	v_mul_f32_e32 v6, v6, v8
	v_mov_b32_e32 v8, v163
	v_cvt_pk_fp8_f32 v8, v5, v7
	v_med3_f32 v5, v9, s40, v189
	v_med3_f32 v7, v10, s40, v189
	v_mov_b32_e32 v9, v163
	v_cvt_pk_fp8_f32 v8, v5, v7 op_sel:[0,0,1]
	v_med3_f32 v5, v11, s40, v189
	v_med3_f32 v7, v12, s40, v189
	v_cvt_pk_fp8_f32 v9, v5, v7
	v_mul_f32_e32 v14, v6, v69
	v_add_u32_e32 v6, 0x90, v4
	v_med3_f32 v5, v13, s40, v189
	v_med3_f32 v7, v14, s40, v189
	v_cvt_pk_fp8_f32 v9, v5, v7 op_sel:[0,0,1]
	v_ashrrev_i32_e32 v7, 31, v6
	v_lshlrev_b64 v[6:7], 7, v[6:7]
	v_lshl_add_u64 v[6:7], s[10:11], 0, v[6:7]
	v_lshl_add_u64 v[6:7], v[6:7], 0, v[2:3]
	v_mul_f32_e32 v5, 0x3b000000, v62
	global_store_dwordx2 v[6:7], v[8:9], off
	v_mul_f32_e32 v6, 0xbcb8aa3b, v62
	v_exp_f32_e32 v6, v6
	s_nop 0
	v_add_f32_e32 v6, 1.0, v6
	v_rcp_f32_e32 v6, v6
	s_nop 0
	v_mul_f32_e32 v5, v5, v6
	v_mul_f32_e32 v6, 0x3b000000, v63
	v_mul_f32_e32 v7, 0xbcb8aa3b, v63
	v_exp_f32_e32 v7, v7
	v_mul_f32_e32 v5, v5, v58
	v_med3_f32 v5, v5, s40, v189
	v_add_f32_e32 v7, 1.0, v7
	v_rcp_f32_e32 v7, v7
	s_nop 0
	v_mul_f32_e32 v6, v6, v7
	v_mul_f32_e32 v7, v6, v59
	v_mul_f32_e32 v6, 0x3b000000, v64
	v_mul_f32_e32 v8, 0xbcb8aa3b, v64
	v_exp_f32_e32 v8, v8
	v_med3_f32 v7, v7, s40, v189
	v_add_f32_e32 v8, 1.0, v8
	v_rcp_f32_e32 v8, v8
	s_nop 0
	v_mul_f32_e32 v6, v6, v8
	v_mul_f32_e32 v9, v6, v60
	v_mul_f32_e32 v6, 0x3b000000, v65
	v_mul_f32_e32 v8, 0xbcb8aa3b, v65
	v_exp_f32_e32 v8, v8
	s_nop 0
	v_add_f32_e32 v8, 1.0, v8
	v_rcp_f32_e32 v8, v8
	s_nop 0
	v_mul_f32_e32 v6, v6, v8
	v_mul_f32_e32 v10, v6, v61
	v_mul_f32_e32 v6, 0x3b000000, v54
	v_mul_f32_e32 v8, 0xbcb8aa3b, v54
	v_exp_f32_e32 v8, v8
	s_nop 0
	v_add_f32_e32 v8, 1.0, v8
	v_rcp_f32_e32 v8, v8
	s_nop 0
	v_mul_f32_e32 v6, v6, v8
	v_mul_f32_e32 v11, v6, v50
	v_mul_f32_e32 v6, 0x3b000000, v55
	v_mul_f32_e32 v8, 0xbcb8aa3b, v55
	v_exp_f32_e32 v8, v8
	s_nop 0
	v_add_f32_e32 v8, 1.0, v8
	v_rcp_f32_e32 v8, v8
	s_nop 0
	v_mul_f32_e32 v6, v6, v8
	v_mul_f32_e32 v12, v6, v51
	v_mul_f32_e32 v6, 0x3b000000, v56
	v_mul_f32_e32 v8, 0xbcb8aa3b, v56
	v_exp_f32_e32 v8, v8
	s_nop 0
	v_add_f32_e32 v8, 1.0, v8
	v_rcp_f32_e32 v8, v8
	s_nop 0
	v_mul_f32_e32 v6, v6, v8
	v_mul_f32_e32 v13, v6, v52
	v_mul_f32_e32 v6, 0x3b000000, v57
	v_mul_f32_e32 v8, 0xbcb8aa3b, v57
	v_exp_f32_e32 v8, v8
	s_nop 0
	v_add_f32_e32 v8, 1.0, v8
	v_rcp_f32_e32 v8, v8
	s_nop 0
	v_mul_f32_e32 v6, v6, v8
	v_mov_b32_e32 v8, v163
	v_cvt_pk_fp8_f32 v8, v5, v7
	v_med3_f32 v5, v9, s40, v189
	v_med3_f32 v7, v10, s40, v189
	v_mov_b32_e32 v9, v163
	v_cvt_pk_fp8_f32 v8, v5, v7 op_sel:[0,0,1]
	v_med3_f32 v5, v11, s40, v189
	v_med3_f32 v7, v12, s40, v189
	v_cvt_pk_fp8_f32 v9, v5, v7
	v_mul_f32_e32 v14, v6, v53
	v_add_u32_e32 v6, 0xa0, v4
	v_med3_f32 v5, v13, s40, v189
	v_med3_f32 v7, v14, s40, v189
	v_cvt_pk_fp8_f32 v9, v5, v7 op_sel:[0,0,1]
	v_ashrrev_i32_e32 v7, 31, v6
	v_lshlrev_b64 v[6:7], 7, v[6:7]
	v_lshl_add_u64 v[6:7], s[10:11], 0, v[6:7]
	v_lshl_add_u64 v[6:7], v[6:7], 0, v[2:3]
	v_mul_f32_e32 v5, 0x3b000000, v46
	global_store_dwordx2 v[6:7], v[8:9], off
	v_mul_f32_e32 v6, 0xbcb8aa3b, v46
	v_exp_f32_e32 v6, v6
	v_add_u32_e32 v4, 0xb0, v4
	v_add_f32_e32 v6, 1.0, v6
	v_rcp_f32_e32 v6, v6
	s_nop 0
	v_mul_f32_e32 v5, v5, v6
	v_mul_f32_e32 v6, 0x3b000000, v47
	v_mul_f32_e32 v7, 0xbcb8aa3b, v47
	v_exp_f32_e32 v7, v7
	v_mul_f32_e32 v5, v5, v42
	v_med3_f32 v5, v5, s40, v189
	v_add_f32_e32 v7, 1.0, v7
	v_rcp_f32_e32 v7, v7
	s_nop 0
	v_mul_f32_e32 v6, v6, v7
	v_mul_f32_e32 v7, 0x3b000000, v48
	v_mul_f32_e32 v8, 0xbcb8aa3b, v48
	v_exp_f32_e32 v8, v8
	v_mul_f32_e32 v6, v6, v43
	v_add_f32_e32 v8, 1.0, v8
	v_rcp_f32_e32 v8, v8
	s_nop 0
	v_mul_f32_e32 v7, v7, v8
	v_mul_f32_e32 v8, 0x3b000000, v49
	v_mul_f32_e32 v9, 0xbcb8aa3b, v49
	v_exp_f32_e32 v9, v9
	v_mul_f32_e32 v7, v7, v44
	v_add_f32_e32 v9, 1.0, v9
	v_rcp_f32_e32 v9, v9
	s_nop 0
	v_mul_f32_e32 v8, v8, v9
	v_mul_f32_e32 v9, 0x3b000000, v38
	v_mul_f32_e32 v10, 0xbcb8aa3b, v38
	v_exp_f32_e32 v10, v10
	v_mul_f32_e32 v8, v8, v45
	v_add_f32_e32 v10, 1.0, v10
	v_rcp_f32_e32 v10, v10
	s_nop 0
	v_mul_f32_e32 v9, v9, v10
	v_mul_f32_e32 v10, 0x3b000000, v39
	v_mul_f32_e32 v11, 0xbcb8aa3b, v39
	v_exp_f32_e32 v11, v11
	v_mul_f32_e32 v9, v9, v34
	v_add_f32_e32 v11, 1.0, v11
	v_rcp_f32_e32 v11, v11
	s_nop 0
	v_mul_f32_e32 v10, v10, v11
	v_mul_f32_e32 v11, 0x3b000000, v40
	v_mul_f32_e32 v12, 0xbcb8aa3b, v40
	v_exp_f32_e32 v12, v12
	v_mul_f32_e32 v10, v10, v35
	v_add_f32_e32 v12, 1.0, v12
	v_rcp_f32_e32 v12, v12
	s_nop 0
	v_mul_f32_e32 v11, v11, v12
	v_mul_f32_e32 v12, 0x3b000000, v41
	v_mul_f32_e32 v13, 0xbcb8aa3b, v41
	v_exp_f32_e32 v13, v13
	v_mul_f32_e32 v11, v11, v36
	v_add_f32_e32 v13, 1.0, v13
	v_rcp_f32_e32 v13, v13
	s_nop 0
	v_mul_f32_e32 v12, v12, v13
	v_med3_f32 v13, v6, s40, v189
	v_mov_b32_e32 v6, v163
	v_cvt_pk_fp8_f32 v6, v5, v13
	v_med3_f32 v5, v7, s40, v189
	v_med3_f32 v7, v8, s40, v189
	v_med3_f32 v8, v10, s40, v189
	v_cvt_pk_fp8_f32 v6, v5, v7 op_sel:[0,0,1]
	v_med3_f32 v5, v9, s40, v189
	v_mov_b32_e32 v7, v163
	v_cvt_pk_fp8_f32 v7, v5, v8
	v_mul_f32_e32 v12, v12, v37
	v_med3_f32 v5, v11, s40, v189
	v_med3_f32 v8, v12, s40, v189
	v_cvt_pk_fp8_f32 v7, v5, v8 op_sel:[0,0,1]
	v_ashrrev_i32_e32 v5, 31, v4
	v_lshlrev_b64 v[4:5], 7, v[4:5]
	v_lshl_add_u64 v[4:5], s[10:11], 0, v[4:5]
	v_lshl_add_u64 v[2:3], v[4:5], 0, v[2:3]
	global_store_dwordx2 v[2:3], v[6:7], off
	s_cbranch_vccz .LBB0_2738
	s_waitcnt vmcnt(0)
	s_cmpk_gt_u32 s42, 0xff
	s_cbranch_scc1 .LBB0_2684
	s_barrier
	s_branch .LBB0_2684

.LBB0_2815:
	s_ashr_i32 s19, s18, 31
	s_lshl_b64 s[0:1], s[18:19], 18
	v_cmp_lt_i64_e32 vcc, s[20:21], v[158:159]
	s_add_u32 s20, s5, s0
	s_addc_u32 s21, s8, s1
	s_and_b64 s[0:1], vcc, exec
	s_cselect_b32 s19, s21, s29
	s_cselect_b32 s49, s20, s28
	s_ashr_i32 s0, s18, 5
	s_ashr_i32 s1, s0, 31
	s_lshl_b64 s[0:1], s[0:1], 20
	s_add_u32 s22, s9, s0
	s_addc_u32 s23, s36, s1
	s_ashr_i32 s17, s16, 31
	s_lshl_b64 s[0:1], s[16:17], 18
	s_add_u32 s22, s22, s0
	s_addc_u32 s23, s23, s1
	s_and_b64 s[0:1], vcc, exec
	s_cselect_b32 s17, s23, s27
	s_cselect_b32 s50, s22, s26
	s_add_u32 s51, s26, 0x100
	s_addc_u32 s52, s27, 0
	s_add_u32 s26, s28, 0xc000
	s_addc_u32 s27, s29, 0
	s_mov_b32 s53, -2
	ds_read_b128 v[2:5], v168
	ds_read_b128 v[6:9], v168 offset:1024
	ds_read_b128 v[10:13], v168 offset:2048
	ds_read_b128 v[14:17], v168 offset:3072
	s_add_u32 s0, s26, 0x4000
	s_addc_u32 s1, s27, 0
	s_cmp_eq_u32 s53, 4
	s_cselect_b32 s34, s49, s0
	s_cselect_b32 s35, s19, s1
	s_cselect_b32 s28, s50, s51
	s_cselect_b32 s29, s17, s52
	s_add_u32 s30, s34, 0x8000
	s_addc_u32 s31, s35, 0
	v_lshl_add_u64 v[162:163], s[26:27], 0, v[156:157]
	s_add_i32 m0, s25, 0xc000
	ds_read_b128 v[174:177], v169
	ds_read_b128 v[178:181], v169 offset:1024
	ds_read_b128 v[182:185], v169 offset:2048
	ds_read_b128 v[186:189], v169 offset:3072
	ds_read_b128 v[190:193], v169 offset:4096
	ds_read_b128 v[194:197], v169 offset:5120
	ds_read_b128 v[198:201], v169 offset:6144
	ds_read_b128 v[202:205], v169 offset:7168
	global_load_lds_dwordx4 v[162:163], off
	v_lshl_add_u64 v[162:163], s[26:27], 0, v[154:155]
	s_add_i32 m0, s25, 0xe000
	s_nop 0
	global_load_lds_dwordx4 v[162:163], off
	s_waitcnt lgkmcnt(8)
	s_waitcnt vmcnt(10)
	s_barrier
	s_waitcnt lgkmcnt(0)
	s_waitcnt lgkmcnt(0)
	v_mfma_scale_f32_16x16x128_f8f6f4 v[142:145], v[2:9], v[174:181], 0, v170, v170 op_sel_hi:[0,0,0]
	v_mfma_scale_f32_16x16x128_f8f6f4 v[138:141], v[10:17], v[174:181], 0, v170, v170 op_sel_hi:[0,0,0]
	v_mfma_scale_f32_16x16x128_f8f6f4 v[126:129], v[2:9], v[182:189], 0, v170, v170 op_sel_hi:[0,0,0]
	v_mfma_scale_f32_16x16x128_f8f6f4 v[122:125], v[10:17], v[182:189], 0, v170, v170 op_sel_hi:[0,0,0]
	v_mfma_scale_f32_16x16x128_f8f6f4 v[110:113], v[2:9], v[190:197], 0, v170, v170 op_sel_hi:[0,0,0]
	v_mfma_scale_f32_16x16x128_f8f6f4 v[106:109], v[10:17], v[190:197], 0, v170, v170 op_sel_hi:[0,0,0]
	v_mfma_scale_f32_16x16x128_f8f6f4 v[94:97], v[2:9], v[198:205], 0, v170, v170 op_sel_hi:[0,0,0]
	v_mfma_scale_f32_16x16x128_f8f6f4 v[90:93], v[10:17], v[198:205], 0, v170, v170 op_sel_hi:[0,0,0]
	s_barrier
	s_add_i32 s0, s45, s37
	v_lshl_add_u64 v[162:163], s[28:29], 0, v[150:151]
	s_mov_b32 m0, s0
	ds_read_b128 v[206:209], v171
	ds_read_b128 v[210:213], v171 offset:1024
	ds_read_b128 v[214:217], v171 offset:2048
	ds_read_b128 v[218:221], v171 offset:3072
	global_load_lds_dwordx4 v[162:163], off
	v_lshl_add_u64 v[164:165], s[28:29], 0, v[146:147]
	s_add_i32 m0, s0, 0x2000
	s_nop 0
	global_load_lds_dwordx4 v[164:165], off
	s_waitcnt vmcnt(10)
	s_barrier
	s_waitcnt lgkmcnt(0)
	s_waitcnt lgkmcnt(0)
	v_mfma_scale_f32_16x16x128_f8f6f4 v[134:137], v[206:213], v[174:181], 0, v170, v170 op_sel_hi:[0,0,0]
	v_mfma_scale_f32_16x16x128_f8f6f4 v[130:133], v[214:221], v[174:181], 0, v170, v170 op_sel_hi:[0,0,0]
	v_mfma_scale_f32_16x16x128_f8f6f4 v[118:121], v[206:213], v[182:189], 0, v170, v170 op_sel_hi:[0,0,0]
	v_mfma_scale_f32_16x16x128_f8f6f4 v[114:117], v[214:221], v[182:189], 0, v170, v170 op_sel_hi:[0,0,0]
	v_mfma_scale_f32_16x16x128_f8f6f4 v[102:105], v[206:213], v[190:197], 0, v170, v170 op_sel_hi:[0,0,0]
	v_mfma_scale_f32_16x16x128_f8f6f4 v[98:101], v[214:221], v[190:197], 0, v170, v170 op_sel_hi:[0,0,0]
	v_mfma_scale_f32_16x16x128_f8f6f4 v[86:89], v[206:213], v[198:205], 0, v170, v170 op_sel_hi:[0,0,0]
	v_mfma_scale_f32_16x16x128_f8f6f4 v[82:85], v[214:221], v[198:205], 0, v170, v170 op_sel_hi:[0,0,0]
	s_mov_b32 m0, s25
	v_lshl_add_u64 v[222:223], s[34:35], 0, v[152:153]
	s_barrier
	ds_read_b128 v[174:177], v169 offset:16384
	ds_read_b128 v[178:181], v169 offset:17408
	ds_read_b128 v[182:185], v169 offset:18432
	ds_read_b128 v[186:189], v169 offset:19456
	ds_read_b128 v[190:193], v169 offset:20480
	ds_read_b128 v[194:197], v169 offset:21504
	ds_read_b128 v[198:201], v169 offset:22528
	ds_read_b128 v[202:205], v169 offset:23552
	global_load_lds_dwordx4 v[222:223], off
	v_lshl_add_u64 v[222:223], s[34:35], 0, v[148:149]
	s_mov_b32 m0, s38
	s_nop 0
	global_load_lds_dwordx4 v[222:223], off
	s_waitcnt vmcnt(10)
	s_barrier
	s_waitcnt lgkmcnt(0)
	s_waitcnt lgkmcnt(0)
	v_mfma_scale_f32_16x16x128_f8f6f4 v[78:81], v[2:9], v[174:181], 0, v170, v170 op_sel_hi:[0,0,0]
	v_mfma_scale_f32_16x16x128_f8f6f4 v[74:77], v[10:17], v[174:181], 0, v170, v170 op_sel_hi:[0,0,0]
	v_mfma_scale_f32_16x16x128_f8f6f4 v[62:65], v[2:9], v[182:189], 0, v170, v170 op_sel_hi:[0,0,0]
	v_mfma_scale_f32_16x16x128_f8f6f4 v[58:61], v[10:17], v[182:189], 0, v170, v170 op_sel_hi:[0,0,0]
	v_mfma_scale_f32_16x16x128_f8f6f4 v[46:49], v[2:9], v[190:197], 0, v170, v170 op_sel_hi:[0,0,0]
	v_mfma_scale_f32_16x16x128_f8f6f4 v[42:45], v[10:17], v[190:197], 0, v170, v170 op_sel_hi:[0,0,0]
	v_mfma_scale_f32_16x16x128_f8f6f4 v[30:33], v[2:9], v[198:205], 0, v170, v170 op_sel_hi:[0,0,0]
	v_mfma_scale_f32_16x16x128_f8f6f4 v[26:29], v[10:17], v[198:205], 0, v170, v170 op_sel_hi:[0,0,0]
	s_barrier
	s_add_u32 s0, s28, 0x20000
	s_addc_u32 s1, s29, 0
	s_add_i32 s54, s46, s37
	v_lshl_add_u64 v[2:3], s[0:1], 0, v[150:151]
	s_mov_b32 m0, s54
	s_nop 0
	global_load_lds_dwordx4 v[2:3], off
	v_lshl_add_u64 v[2:3], s[0:1], 0, v[146:147]
	s_add_i32 m0, s54, 0x2000
	s_nop 0
	global_load_lds_dwordx4 v[2:3], off
	s_waitcnt vmcnt(10)
	s_barrier
	v_mfma_scale_f32_16x16x128_f8f6f4 v[70:73], v[206:213], v[174:181], 0, v170, v170 op_sel_hi:[0,0,0]
	v_mfma_scale_f32_16x16x128_f8f6f4 v[66:69], v[214:221], v[174:181], 0, v170, v170 op_sel_hi:[0,0,0]
	v_mfma_scale_f32_16x16x128_f8f6f4 v[54:57], v[206:213], v[182:189], 0, v170, v170 op_sel_hi:[0,0,0]
	v_mfma_scale_f32_16x16x128_f8f6f4 v[50:53], v[214:221], v[182:189], 0, v170, v170 op_sel_hi:[0,0,0]
	v_mfma_scale_f32_16x16x128_f8f6f4 v[38:41], v[206:213], v[190:197], 0, v170, v170 op_sel_hi:[0,0,0]
	v_mfma_scale_f32_16x16x128_f8f6f4 v[34:37], v[214:221], v[190:197], 0, v170, v170 op_sel_hi:[0,0,0]
	v_mfma_scale_f32_16x16x128_f8f6f4 v[22:25], v[206:213], v[198:205], 0, v170, v170 op_sel_hi:[0,0,0]
	v_mfma_scale_f32_16x16x128_f8f6f4 v[18:21], v[214:221], v[198:205], 0, v170, v170 op_sel_hi:[0,0,0]
	s_add_i32 s54, 0, 0x18000
	v_add_u32_e32 v14, s54, v167
	s_barrier
	ds_read_b128 v[2:5], v14
	ds_read_b128 v[6:9], v14 offset:1024
	ds_read_b128 v[10:13], v14 offset:2048
	ds_read_b128 v[14:17], v14 offset:3072
	s_add_u32 s0, s34, 0x4000
	s_addc_u32 s1, s35, 0
	s_mov_b32 m0, s39
	v_lshl_add_u64 v[206:207], s[0:1], 0, v[152:153]
	ds_read_b128 v[174:177], v169 offset:32768
	ds_read_b128 v[178:181], v169 offset:33792
	ds_read_b128 v[182:185], v169 offset:34816
	ds_read_b128 v[186:189], v169 offset:35840
	ds_read_b128 v[190:193], v169 offset:36864
	ds_read_b128 v[194:197], v169 offset:37888
	ds_read_b128 v[198:201], v169 offset:38912
	ds_read_b128 v[202:205], v169 offset:39936
	global_load_lds_dwordx4 v[206:207], off
	v_lshl_add_u64 v[206:207], s[0:1], 0, v[148:149]
	s_mov_b32 m0, s40
	s_nop 0
	global_load_lds_dwordx4 v[206:207], off
	s_waitcnt lgkmcnt(8)
	s_waitcnt vmcnt(10)
	s_barrier
	s_waitcnt lgkmcnt(0)
	s_waitcnt lgkmcnt(0)
	v_mfma_scale_f32_16x16x128_f8f6f4 v[142:145], v[2:9], v[174:181], v[142:145], v170, v170 op_sel_hi:[0,0,0]
	v_mfma_scale_f32_16x16x128_f8f6f4 v[138:141], v[10:17], v[174:181], v[138:141], v170, v170 op_sel_hi:[0,0,0]
	v_mfma_scale_f32_16x16x128_f8f6f4 v[126:129], v[2:9], v[182:189], v[126:129], v170, v170 op_sel_hi:[0,0,0]
	v_mfma_scale_f32_16x16x128_f8f6f4 v[122:125], v[10:17], v[182:189], v[122:125], v170, v170 op_sel_hi:[0,0,0]
	v_mfma_scale_f32_16x16x128_f8f6f4 v[110:113], v[2:9], v[190:197], v[110:113], v170, v170 op_sel_hi:[0,0,0]
	v_mfma_scale_f32_16x16x128_f8f6f4 v[106:109], v[10:17], v[190:197], v[106:109], v170, v170 op_sel_hi:[0,0,0]
	v_mfma_scale_f32_16x16x128_f8f6f4 v[94:97], v[2:9], v[198:205], v[94:97], v170, v170 op_sel_hi:[0,0,0]
	v_mfma_scale_f32_16x16x128_f8f6f4 v[90:93], v[10:17], v[198:205], v[90:93], v170, v170 op_sel_hi:[0,0,0]
	s_barrier
	s_add_i32 s34, 0, 0x1c000
	s_add_i32 s0, s54, s37
	v_add_u32_e32 v173, s34, v167
	v_lshl_add_u64 v[162:163], v[162:163], 0, s[12:13]
	s_mov_b32 m0, s0
	ds_read_b128 v[206:209], v173
	ds_read_b128 v[210:213], v173 offset:1024
	ds_read_b128 v[214:217], v173 offset:2048
	ds_read_b128 v[218:221], v173 offset:3072
	global_load_lds_dwordx4 v[162:163], off
	v_lshl_add_u64 v[162:163], v[164:165], 0, s[12:13]
	s_add_i32 m0, s0, 0x2000
	s_nop 0
	global_load_lds_dwordx4 v[162:163], off
	s_waitcnt vmcnt(10)
	s_barrier
	s_waitcnt lgkmcnt(0)
	s_waitcnt lgkmcnt(0)
	v_mfma_scale_f32_16x16x128_f8f6f4 v[134:137], v[206:213], v[174:181], v[134:137], v170, v170 op_sel_hi:[0,0,0]
	v_mfma_scale_f32_16x16x128_f8f6f4 v[130:133], v[214:221], v[174:181], v[130:133], v170, v170 op_sel_hi:[0,0,0]
	v_mfma_scale_f32_16x16x128_f8f6f4 v[118:121], v[206:213], v[182:189], v[118:121], v170, v170 op_sel_hi:[0,0,0]
	v_mfma_scale_f32_16x16x128_f8f6f4 v[114:117], v[214:221], v[182:189], v[114:117], v170, v170 op_sel_hi:[0,0,0]
	v_mfma_scale_f32_16x16x128_f8f6f4 v[102:105], v[206:213], v[190:197], v[102:105], v170, v170 op_sel_hi:[0,0,0]
	v_mfma_scale_f32_16x16x128_f8f6f4 v[98:101], v[214:221], v[190:197], v[98:101], v170, v170 op_sel_hi:[0,0,0]
	v_mfma_scale_f32_16x16x128_f8f6f4 v[86:89], v[206:213], v[198:205], v[86:89], v170, v170 op_sel_hi:[0,0,0]
	v_mfma_scale_f32_16x16x128_f8f6f4 v[82:85], v[214:221], v[198:205], v[82:85], v170, v170 op_sel_hi:[0,0,0]
	s_mov_b32 m0, s43
	v_lshl_add_u64 v[162:163], s[30:31], 0, v[152:153]
	s_barrier
	ds_read_b128 v[174:177], v169 offset:49152
	ds_read_b128 v[178:181], v169 offset:50176
	ds_read_b128 v[182:185], v169 offset:51200
	ds_read_b128 v[186:189], v169 offset:52224
	ds_read_b128 v[190:193], v169 offset:53248
	ds_read_b128 v[194:197], v169 offset:54272
	ds_read_b128 v[198:201], v169 offset:55296
	ds_read_b128 v[202:205], v169 offset:56320
	global_load_lds_dwordx4 v[162:163], off
	v_lshl_add_u64 v[162:163], s[30:31], 0, v[148:149]
	s_mov_b32 m0, s44
	s_nop 0
	global_load_lds_dwordx4 v[162:163], off
	s_waitcnt vmcnt(10)
	s_barrier
	s_waitcnt lgkmcnt(0)
	s_waitcnt lgkmcnt(0)
	v_mfma_scale_f32_16x16x128_f8f6f4 v[78:81], v[2:9], v[174:181], v[78:81], v170, v170 op_sel_hi:[0,0,0]
	v_mfma_scale_f32_16x16x128_f8f6f4 v[74:77], v[10:17], v[174:181], v[74:77], v170, v170 op_sel_hi:[0,0,0]
	v_mfma_scale_f32_16x16x128_f8f6f4 v[62:65], v[2:9], v[182:189], v[62:65], v170, v170 op_sel_hi:[0,0,0]
	v_mfma_scale_f32_16x16x128_f8f6f4 v[58:61], v[10:17], v[182:189], v[58:61], v170, v170 op_sel_hi:[0,0,0]
	v_mfma_scale_f32_16x16x128_f8f6f4 v[46:49], v[2:9], v[190:197], v[46:49], v170, v170 op_sel_hi:[0,0,0]
	v_mfma_scale_f32_16x16x128_f8f6f4 v[42:45], v[10:17], v[190:197], v[42:45], v170, v170 op_sel_hi:[0,0,0]
	v_mfma_scale_f32_16x16x128_f8f6f4 v[30:33], v[2:9], v[198:205], v[30:33], v170, v170 op_sel_hi:[0,0,0]
	v_mfma_scale_f32_16x16x128_f8f6f4 v[26:29], v[10:17], v[198:205], v[26:29], v170, v170 op_sel_hi:[0,0,0]
	s_barrier
	s_add_u32 s0, s28, 0x20080
	s_addc_u32 s1, s29, 0
	s_add_i32 s28, s34, s37
	v_lshl_add_u64 v[2:3], s[0:1], 0, v[150:151]
	s_mov_b32 m0, s28
	s_nop 0
	global_load_lds_dwordx4 v[2:3], off
	v_lshl_add_u64 v[2:3], s[0:1], 0, v[146:147]
	s_add_i32 m0, s28, 0x2000
	s_nop 0
	global_load_lds_dwordx4 v[2:3], off
	s_waitcnt vmcnt(10)
	s_barrier
	v_mfma_scale_f32_16x16x128_f8f6f4 v[70:73], v[206:213], v[174:181], v[70:73], v170, v170 op_sel_hi:[0,0,0]
	v_mfma_scale_f32_16x16x128_f8f6f4 v[66:69], v[214:221], v[174:181], v[66:69], v170, v170 op_sel_hi:[0,0,0]
	v_mfma_scale_f32_16x16x128_f8f6f4 v[54:57], v[206:213], v[182:189], v[54:57], v170, v170 op_sel_hi:[0,0,0]
	v_mfma_scale_f32_16x16x128_f8f6f4 v[50:53], v[214:221], v[182:189], v[50:53], v170, v170 op_sel_hi:[0,0,0]
	v_mfma_scale_f32_16x16x128_f8f6f4 v[38:41], v[206:213], v[190:197], v[38:41], v170, v170 op_sel_hi:[0,0,0]
	v_mfma_scale_f32_16x16x128_f8f6f4 v[34:37], v[214:221], v[190:197], v[34:37], v170, v170 op_sel_hi:[0,0,0]
	v_mfma_scale_f32_16x16x128_f8f6f4 v[22:25], v[206:213], v[198:205], v[22:25], v170, v170 op_sel_hi:[0,0,0]
	v_mfma_scale_f32_16x16x128_f8f6f4 v[18:21], v[214:221], v[198:205], v[18:21], v170, v170 op_sel_hi:[0,0,0]
	s_add_i32 s53, s53, 2
	s_add_u32 s51, s51, 0x100
	s_addc_u32 s52, s52, 0
	s_add_u32 s26, s26, 0x10000
	s_addc_u32 s27, s27, 0
	s_cmp_gt_u32 s53, 5
	s_barrier
	s_cbranch_scc1 .Lpeel_exit_18

.Lpeel_exit_18:
	v_pk_mul_f32 v[8:9], v[142:143], s[14:15] op_sel_hi:[1,0]
	v_pk_mul_f32 v[6:7], v[144:145], s[14:15] op_sel_hi:[1,0]
	v_med3_f32 v14, v8, s47, v172
	v_med3_f32 v9, v9, s47, v172
	v_mov_b32_e32 v8, 0
	v_cvt_pk_fp8_f32 v8, v14, v9
	v_pk_mul_f32 v[12:13], v[138:139], s[14:15] op_sel_hi:[1,0]
	v_pk_mul_f32 v[10:11], v[140:141], s[14:15] op_sel_hi:[1,0]
	v_med3_f32 v6, v6, s47, v172
	v_med3_f32 v7, v7, s47, v172
	v_med3_f32 v12, v12, s47, v172
	v_med3_f32 v13, v13, s47, v172
	v_mov_b32_e32 v9, 0
	v_mov_b32_e32 v3, v1
	v_mov_b32_e32 v2, v166
	s_lshl_b32 s0, s48, 8
	v_cvt_pk_fp8_f32 v9, v12, v13
	v_cvt_pk_fp8_f32 v8, v6, v7 op_sel:[0,0,1]
	v_med3_f32 v6, v10, s47, v172
	v_med3_f32 v7, v11, s47, v172
	v_pk_mul_f32 v[10:11], v[134:135], s[14:15] op_sel_hi:[1,0]
	s_nop 15
	s_nop 15
	s_or_b32 s0, s0, s42
	v_pk_mul_f32 v[14:15], v[130:131], s[14:15] op_sel_hi:[1,0]
	v_med3_f32 v17, v10, s47, v172
	v_med3_f32 v11, v11, s47, v172
	v_mov_b32_e32 v10, 0
	v_lshl_add_u32 v2, v2, 3, s0
	s_lshl_b32 s0, s24, 8
	v_cvt_pk_fp8_f32 v10, v17, v11
	v_med3_f32 v14, v14, s47, v172
	v_med3_f32 v15, v15, s47, v172
	v_mov_b32_e32 v11, 0
	s_add_i32 s0, s0, s15
	v_cvt_pk_fp8_f32 v11, v14, v15
	v_add_u32_e32 v16, s0, v3
	v_cvt_pk_fp8_f32 v9, v6, v7 op_sel:[0,0,1]
	v_pk_mul_f32 v[6:7], v[136:137], s[14:15] op_sel_hi:[1,0]
	v_mov_b32_e32 v4, v16
	v_pk_mul_f32 v[12:13], v[132:133], s[14:15] op_sel_hi:[1,0]
	v_med3_f32 v6, v6, s47, v172
	v_med3_f32 v7, v7, s47, v172
	v_cvt_pk_fp8_f32 v10, v6, v7 op_sel:[0,0,1]
	v_ashrrev_i32_e32 v5, 31, v4
	v_med3_f32 v6, v12, s47, v172
	v_med3_f32 v7, v13, s47, v172
	v_lshlrev_b64 v[4:5], 10, v[4:5]
	v_cvt_pk_fp8_f32 v11, v6, v7 op_sel:[0,0,1]
	v_ashrrev_i32_e32 v3, 31, v2
	v_lshl_add_u64 v[4:5], s[10:11], 0, v[4:5]
	v_lshl_add_u64 v[4:5], v[4:5], 0, v[2:3]
	global_store_dwordx2 v[4:5], v[8:9], off
	global_store_dwordx2 v[4:5], v[10:11], off offset:128
	v_pk_mul_f32 v[8:9], v[126:127], s[14:15] op_sel_hi:[1,0]
	v_pk_mul_f32 v[6:7], v[128:129], s[14:15] op_sel_hi:[1,0]
	v_med3_f32 v14, v8, s47, v172
	v_med3_f32 v9, v9, s47, v172
	v_mov_b32_e32 v8, 0
	v_cvt_pk_fp8_f32 v8, v14, v9
	v_pk_mul_f32 v[12:13], v[122:123], s[14:15] op_sel_hi:[1,0]
	v_pk_mul_f32 v[10:11], v[124:125], s[14:15] op_sel_hi:[1,0]
	v_med3_f32 v6, v6, s47, v172
	v_med3_f32 v7, v7, s47, v172
	v_med3_f32 v12, v12, s47, v172
	v_med3_f32 v13, v13, s47, v172
	v_mov_b32_e32 v9, 0
	v_cvt_pk_fp8_f32 v9, v12, v13
	v_cvt_pk_fp8_f32 v8, v6, v7 op_sel:[0,0,1]
	v_med3_f32 v6, v10, s47, v172
	v_med3_f32 v7, v11, s47, v172
	v_pk_mul_f32 v[10:11], v[118:119], s[14:15] op_sel_hi:[1,0]
	v_pk_mul_f32 v[14:15], v[114:115], s[14:15] op_sel_hi:[1,0]
	v_med3_f32 v17, v10, s47, v172
	v_med3_f32 v11, v11, s47, v172
	v_mov_b32_e32 v10, 0
	v_cvt_pk_fp8_f32 v10, v17, v11
	v_med3_f32 v14, v14, s47, v172
	v_med3_f32 v15, v15, s47, v172
	v_mov_b32_e32 v11, 0
	v_cvt_pk_fp8_f32 v11, v14, v15
	v_cvt_pk_fp8_f32 v9, v6, v7 op_sel:[0,0,1]
	v_pk_mul_f32 v[6:7], v[120:121], s[14:15] op_sel_hi:[1,0]
	v_add_u32_e32 v4, 16, v16
	v_pk_mul_f32 v[12:13], v[116:117], s[14:15] op_sel_hi:[1,0]
	v_med3_f32 v6, v6, s47, v172
	v_med3_f32 v7, v7, s47, v172
	v_cvt_pk_fp8_f32 v10, v6, v7 op_sel:[0,0,1]
	v_ashrrev_i32_e32 v5, 31, v4
	v_med3_f32 v6, v12, s47, v172
	v_med3_f32 v7, v13, s47, v172
	v_lshlrev_b64 v[4:5], 10, v[4:5]
	v_cvt_pk_fp8_f32 v11, v6, v7 op_sel:[0,0,1]
	v_lshl_add_u64 v[4:5], s[10:11], 0, v[4:5]
	v_lshl_add_u64 v[4:5], v[4:5], 0, v[2:3]
	global_store_dwordx2 v[4:5], v[8:9], off
	global_store_dwordx2 v[4:5], v[10:11], off offset:128
	v_pk_mul_f32 v[8:9], v[110:111], s[14:15] op_sel_hi:[1,0]
	v_pk_mul_f32 v[6:7], v[112:113], s[14:15] op_sel_hi:[1,0]
	v_med3_f32 v14, v8, s47, v172
	v_med3_f32 v9, v9, s47, v172
	v_mov_b32_e32 v8, 0
	v_cvt_pk_fp8_f32 v8, v14, v9
	v_pk_mul_f32 v[12:13], v[106:107], s[14:15] op_sel_hi:[1,0]
	v_pk_mul_f32 v[10:11], v[108:109], s[14:15] op_sel_hi:[1,0]
	v_med3_f32 v6, v6, s47, v172
	v_med3_f32 v7, v7, s47, v172
	v_med3_f32 v12, v12, s47, v172
	v_med3_f32 v13, v13, s47, v172
	v_mov_b32_e32 v9, 0
	v_cvt_pk_fp8_f32 v9, v12, v13
	v_cvt_pk_fp8_f32 v8, v6, v7 op_sel:[0,0,1]
	v_med3_f32 v6, v10, s47, v172
	v_med3_f32 v7, v11, s47, v172
	v_pk_mul_f32 v[10:11], v[102:103], s[14:15] op_sel_hi:[1,0]
	v_pk_mul_f32 v[14:15], v[98:99], s[14:15] op_sel_hi:[1,0]
	v_med3_f32 v17, v10, s47, v172
	v_med3_f32 v11, v11, s47, v172
	v_mov_b32_e32 v10, 0
	v_cvt_pk_fp8_f32 v10, v17, v11
	v_med3_f32 v14, v14, s47, v172
	v_med3_f32 v15, v15, s47, v172
	v_mov_b32_e32 v11, 0
	v_cvt_pk_fp8_f32 v11, v14, v15
	v_cvt_pk_fp8_f32 v9, v6, v7 op_sel:[0,0,1]
	v_pk_mul_f32 v[6:7], v[104:105], s[14:15] op_sel_hi:[1,0]
	v_add_u32_e32 v4, 32, v16
	v_pk_mul_f32 v[12:13], v[100:101], s[14:15] op_sel_hi:[1,0]
	v_med3_f32 v6, v6, s47, v172
	v_med3_f32 v7, v7, s47, v172
	v_cvt_pk_fp8_f32 v10, v6, v7 op_sel:[0,0,1]
	v_ashrrev_i32_e32 v5, 31, v4
	v_med3_f32 v6, v12, s47, v172
	v_med3_f32 v7, v13, s47, v172
	v_lshlrev_b64 v[4:5], 10, v[4:5]
	v_cvt_pk_fp8_f32 v11, v6, v7 op_sel:[0,0,1]
	v_lshl_add_u64 v[4:5], s[10:11], 0, v[4:5]
	v_lshl_add_u64 v[4:5], v[4:5], 0, v[2:3]
	global_store_dwordx2 v[4:5], v[8:9], off
	global_store_dwordx2 v[4:5], v[10:11], off offset:128
	v_pk_mul_f32 v[8:9], v[94:95], s[14:15] op_sel_hi:[1,0]
	v_pk_mul_f32 v[6:7], v[96:97], s[14:15] op_sel_hi:[1,0]
	v_med3_f32 v14, v8, s47, v172
	v_med3_f32 v9, v9, s47, v172
	v_mov_b32_e32 v8, 0
	v_cvt_pk_fp8_f32 v8, v14, v9
	v_pk_mul_f32 v[12:13], v[90:91], s[14:15] op_sel_hi:[1,0]
	v_pk_mul_f32 v[10:11], v[92:93], s[14:15] op_sel_hi:[1,0]
	v_med3_f32 v6, v6, s47, v172
	v_med3_f32 v7, v7, s47, v172
	v_med3_f32 v12, v12, s47, v172
	v_med3_f32 v13, v13, s47, v172
	v_mov_b32_e32 v9, 0
	v_cvt_pk_fp8_f32 v9, v12, v13
	v_cvt_pk_fp8_f32 v8, v6, v7 op_sel:[0,0,1]
	v_med3_f32 v6, v10, s47, v172
	v_med3_f32 v7, v11, s47, v172
	v_pk_mul_f32 v[10:11], v[86:87], s[14:15] op_sel_hi:[1,0]
	v_pk_mul_f32 v[14:15], v[82:83], s[14:15] op_sel_hi:[1,0]
	v_med3_f32 v17, v10, s47, v172
	v_med3_f32 v11, v11, s47, v172
	v_mov_b32_e32 v10, 0
	v_cvt_pk_fp8_f32 v10, v17, v11
	v_med3_f32 v14, v14, s47, v172
	v_med3_f32 v15, v15, s47, v172
	v_mov_b32_e32 v11, 0
	v_cvt_pk_fp8_f32 v11, v14, v15
	v_cvt_pk_fp8_f32 v9, v6, v7 op_sel:[0,0,1]
	v_pk_mul_f32 v[6:7], v[88:89], s[14:15] op_sel_hi:[1,0]
	v_add_u32_e32 v4, 48, v16
	v_pk_mul_f32 v[12:13], v[84:85], s[14:15] op_sel_hi:[1,0]
	v_med3_f32 v6, v6, s47, v172
	v_med3_f32 v7, v7, s47, v172
	v_cvt_pk_fp8_f32 v10, v6, v7 op_sel:[0,0,1]
	v_ashrrev_i32_e32 v5, 31, v4
	v_med3_f32 v6, v12, s47, v172
	v_med3_f32 v7, v13, s47, v172
	v_lshlrev_b64 v[4:5], 10, v[4:5]
	v_cvt_pk_fp8_f32 v11, v6, v7 op_sel:[0,0,1]
	v_lshl_add_u64 v[4:5], s[10:11], 0, v[4:5]
	v_lshl_add_u64 v[4:5], v[4:5], 0, v[2:3]
	global_store_dwordx2 v[4:5], v[8:9], off
	global_store_dwordx2 v[4:5], v[10:11], off offset:128
	v_pk_mul_f32 v[8:9], v[78:79], s[14:15] op_sel_hi:[1,0]
	v_pk_mul_f32 v[6:7], v[80:81], s[14:15] op_sel_hi:[1,0]
	v_med3_f32 v14, v8, s47, v172
	v_med3_f32 v9, v9, s47, v172
	v_mov_b32_e32 v8, 0
	v_cvt_pk_fp8_f32 v8, v14, v9
	v_pk_mul_f32 v[12:13], v[74:75], s[14:15] op_sel_hi:[1,0]
	v_pk_mul_f32 v[10:11], v[76:77], s[14:15] op_sel_hi:[1,0]
	v_med3_f32 v6, v6, s47, v172
	v_med3_f32 v7, v7, s47, v172
	v_med3_f32 v12, v12, s47, v172
	v_med3_f32 v13, v13, s47, v172
	v_mov_b32_e32 v9, 0
	v_cvt_pk_fp8_f32 v9, v12, v13
	v_cvt_pk_fp8_f32 v8, v6, v7 op_sel:[0,0,1]
	v_med3_f32 v6, v10, s47, v172
	v_med3_f32 v7, v11, s47, v172
	v_pk_mul_f32 v[10:11], v[70:71], s[14:15] op_sel_hi:[1,0]
	v_pk_mul_f32 v[14:15], v[66:67], s[14:15] op_sel_hi:[1,0]
	v_med3_f32 v17, v10, s47, v172
	v_med3_f32 v11, v11, s47, v172
	v_mov_b32_e32 v10, 0
	v_cvt_pk_fp8_f32 v10, v17, v11
	v_med3_f32 v14, v14, s47, v172
	v_med3_f32 v15, v15, s47, v172
	v_mov_b32_e32 v11, 0
	v_cvt_pk_fp8_f32 v11, v14, v15
	v_cvt_pk_fp8_f32 v9, v6, v7 op_sel:[0,0,1]
	v_pk_mul_f32 v[6:7], v[72:73], s[14:15] op_sel_hi:[1,0]
	v_add_u32_e32 v4, 0x80, v16
	v_pk_mul_f32 v[12:13], v[68:69], s[14:15] op_sel_hi:[1,0]
	v_med3_f32 v6, v6, s47, v172
	v_med3_f32 v7, v7, s47, v172
	v_cvt_pk_fp8_f32 v10, v6, v7 op_sel:[0,0,1]
	v_ashrrev_i32_e32 v5, 31, v4
	v_med3_f32 v6, v12, s47, v172
	v_med3_f32 v7, v13, s47, v172
	v_lshlrev_b64 v[4:5], 10, v[4:5]
	v_cvt_pk_fp8_f32 v11, v6, v7 op_sel:[0,0,1]
	v_lshl_add_u64 v[4:5], s[10:11], 0, v[4:5]
	v_lshl_add_u64 v[4:5], v[4:5], 0, v[2:3]
	global_store_dwordx2 v[4:5], v[8:9], off
	global_store_dwordx2 v[4:5], v[10:11], off offset:128
	v_pk_mul_f32 v[8:9], v[62:63], s[14:15] op_sel_hi:[1,0]
	v_pk_mul_f32 v[6:7], v[64:65], s[14:15] op_sel_hi:[1,0]
	v_med3_f32 v14, v8, s47, v172
	v_med3_f32 v9, v9, s47, v172
	v_mov_b32_e32 v8, 0
	v_cvt_pk_fp8_f32 v8, v14, v9
	v_pk_mul_f32 v[12:13], v[58:59], s[14:15] op_sel_hi:[1,0]
	v_pk_mul_f32 v[10:11], v[60:61], s[14:15] op_sel_hi:[1,0]
	v_med3_f32 v6, v6, s47, v172
	v_med3_f32 v7, v7, s47, v172
	v_med3_f32 v12, v12, s47, v172
	v_med3_f32 v13, v13, s47, v172
	v_mov_b32_e32 v9, 0
	v_cvt_pk_fp8_f32 v9, v12, v13
	v_cvt_pk_fp8_f32 v8, v6, v7 op_sel:[0,0,1]
	v_med3_f32 v6, v10, s47, v172
	v_med3_f32 v7, v11, s47, v172
	v_pk_mul_f32 v[10:11], v[54:55], s[14:15] op_sel_hi:[1,0]
	v_pk_mul_f32 v[14:15], v[50:51], s[14:15] op_sel_hi:[1,0]
	v_med3_f32 v17, v10, s47, v172
	v_med3_f32 v11, v11, s47, v172
	v_mov_b32_e32 v10, 0
	v_cvt_pk_fp8_f32 v10, v17, v11
	v_med3_f32 v14, v14, s47, v172
	v_med3_f32 v15, v15, s47, v172
	v_mov_b32_e32 v11, 0
	v_cvt_pk_fp8_f32 v11, v14, v15
	v_cvt_pk_fp8_f32 v9, v6, v7 op_sel:[0,0,1]
	v_pk_mul_f32 v[6:7], v[56:57], s[14:15] op_sel_hi:[1,0]
	v_add_u32_e32 v4, 0x90, v16
	v_pk_mul_f32 v[12:13], v[52:53], s[14:15] op_sel_hi:[1,0]
	v_med3_f32 v6, v6, s47, v172
	v_med3_f32 v7, v7, s47, v172
	v_cvt_pk_fp8_f32 v10, v6, v7 op_sel:[0,0,1]
	v_ashrrev_i32_e32 v5, 31, v4
	v_med3_f32 v6, v12, s47, v172
	v_med3_f32 v7, v13, s47, v172
	v_lshlrev_b64 v[4:5], 10, v[4:5]
	v_cvt_pk_fp8_f32 v11, v6, v7 op_sel:[0,0,1]
	v_lshl_add_u64 v[4:5], s[10:11], 0, v[4:5]
	v_lshl_add_u64 v[4:5], v[4:5], 0, v[2:3]
	global_store_dwordx2 v[4:5], v[8:9], off
	global_store_dwordx2 v[4:5], v[10:11], off offset:128
	v_pk_mul_f32 v[8:9], v[46:47], s[14:15] op_sel_hi:[1,0]
	v_pk_mul_f32 v[6:7], v[48:49], s[14:15] op_sel_hi:[1,0]
	v_med3_f32 v14, v8, s47, v172
	v_med3_f32 v9, v9, s47, v172
	v_mov_b32_e32 v8, 0
	v_cvt_pk_fp8_f32 v8, v14, v9
	v_pk_mul_f32 v[12:13], v[42:43], s[14:15] op_sel_hi:[1,0]
	v_pk_mul_f32 v[10:11], v[44:45], s[14:15] op_sel_hi:[1,0]
	v_med3_f32 v6, v6, s47, v172
	v_med3_f32 v7, v7, s47, v172
	v_med3_f32 v12, v12, s47, v172
	v_med3_f32 v13, v13, s47, v172
	v_mov_b32_e32 v9, 0
	v_cvt_pk_fp8_f32 v9, v12, v13
	v_cvt_pk_fp8_f32 v8, v6, v7 op_sel:[0,0,1]
	v_med3_f32 v6, v10, s47, v172
	v_med3_f32 v7, v11, s47, v172
	v_pk_mul_f32 v[10:11], v[38:39], s[14:15] op_sel_hi:[1,0]
	v_pk_mul_f32 v[14:15], v[34:35], s[14:15] op_sel_hi:[1,0]
	v_med3_f32 v17, v10, s47, v172
	v_med3_f32 v11, v11, s47, v172
	v_mov_b32_e32 v10, 0
	v_cvt_pk_fp8_f32 v10, v17, v11
	v_med3_f32 v14, v14, s47, v172
	v_med3_f32 v15, v15, s47, v172
	v_mov_b32_e32 v11, 0
	v_cvt_pk_fp8_f32 v11, v14, v15
	v_cvt_pk_fp8_f32 v9, v6, v7 op_sel:[0,0,1]
	v_pk_mul_f32 v[6:7], v[40:41], s[14:15] op_sel_hi:[1,0]
	v_add_u32_e32 v4, 0xa0, v16
	v_pk_mul_f32 v[12:13], v[36:37], s[14:15] op_sel_hi:[1,0]
	v_med3_f32 v6, v6, s47, v172
	v_med3_f32 v7, v7, s47, v172
	v_cvt_pk_fp8_f32 v10, v6, v7 op_sel:[0,0,1]
	v_ashrrev_i32_e32 v5, 31, v4
	v_med3_f32 v6, v12, s47, v172
	v_med3_f32 v7, v13, s47, v172
	v_lshlrev_b64 v[4:5], 10, v[4:5]
	v_cvt_pk_fp8_f32 v11, v6, v7 op_sel:[0,0,1]
	v_lshl_add_u64 v[4:5], s[10:11], 0, v[4:5]
	v_lshl_add_u64 v[4:5], v[4:5], 0, v[2:3]
	global_store_dwordx2 v[4:5], v[8:9], off
	global_store_dwordx2 v[4:5], v[10:11], off offset:128
	v_pk_mul_f32 v[8:9], v[30:31], s[14:15] op_sel_hi:[1,0]
	v_pk_mul_f32 v[6:7], v[32:33], s[14:15] op_sel_hi:[1,0]
	v_med3_f32 v14, v8, s47, v172
	v_med3_f32 v9, v9, s47, v172
	v_mov_b32_e32 v8, 0
	v_cvt_pk_fp8_f32 v8, v14, v9
	v_pk_mul_f32 v[12:13], v[26:27], s[14:15] op_sel_hi:[1,0]
	v_pk_mul_f32 v[10:11], v[28:29], s[14:15] op_sel_hi:[1,0]
	v_med3_f32 v6, v6, s47, v172
	v_med3_f32 v7, v7, s47, v172
	v_med3_f32 v12, v12, s47, v172
	v_med3_f32 v13, v13, s47, v172
	v_mov_b32_e32 v9, 0
	v_cvt_pk_fp8_f32 v9, v12, v13
	v_cvt_pk_fp8_f32 v8, v6, v7 op_sel:[0,0,1]
	v_med3_f32 v6, v10, s47, v172
	v_med3_f32 v7, v11, s47, v172
	v_pk_mul_f32 v[10:11], v[22:23], s[14:15] op_sel_hi:[1,0]
	v_add_u32_e32 v4, 0xb0, v16
	v_pk_mul_f32 v[14:15], v[18:19], s[14:15] op_sel_hi:[1,0]
	v_med3_f32 v16, v10, s47, v172
	v_med3_f32 v11, v11, s47, v172
	v_mov_b32_e32 v10, 0
	v_cvt_pk_fp8_f32 v10, v16, v11
	v_med3_f32 v14, v14, s47, v172
	v_med3_f32 v15, v15, s47, v172
	v_mov_b32_e32 v11, 0
	v_cvt_pk_fp8_f32 v11, v14, v15
	v_cvt_pk_fp8_f32 v9, v6, v7 op_sel:[0,0,1]
	v_pk_mul_f32 v[6:7], v[24:25], s[14:15] op_sel_hi:[1,0]
	v_pk_mul_f32 v[12:13], v[20:21], s[14:15] op_sel_hi:[1,0]
	v_med3_f32 v6, v6, s47, v172
	v_med3_f32 v7, v7, s47, v172
	v_cvt_pk_fp8_f32 v10, v6, v7 op_sel:[0,0,1]
	v_ashrrev_i32_e32 v5, 31, v4
	v_med3_f32 v6, v12, s47, v172
	v_med3_f32 v7, v13, s47, v172
	v_lshlrev_b64 v[4:5], 10, v[4:5]
	v_cvt_pk_fp8_f32 v11, v6, v7 op_sel:[0,0,1]
	v_lshl_add_u64 v[4:5], s[10:11], 0, v[4:5]
	v_lshl_add_u64 v[2:3], v[4:5], 0, v[2:3]
	s_and_b64 vcc, exec, s[6:7]
	s_mov_b32 s48, s16
	s_mov_b32 s24, s18
	s_mov_b64 s[26:27], s[22:23]
	s_mov_b64 s[28:29], s[20:21]
	global_store_dwordx2 v[2:3], v[8:9], off
	global_store_dwordx2 v[2:3], v[10:11], off offset:128
	s_cbranch_vccz .LBB0_2809
	s_waitcnt vmcnt(0)
	s_cmpk_gt_u32 s4, 0xff
	s_cbranch_scc1 .LBB0_2820
	s_barrier
